# b-fragment-lds-addresses-as-ds_read-offsets-no-valu-adds
# speedup vs baseline: 1.0098x; 1.0009x over previous
; #define PG8_STAGE(bufoff, gbase, hoff, imm) do { _Pragma("unroll") for (int _i = 0; _i < 2; ++_i) { \
;         asm volatile("s_mov_b32 m0, %0\n\ts_nop 0\n\tglobal_load_lds_dwordx4 %1, %2" \
;             :: "s"(lds0 + (unsigned)((bufoff) + _i * 8192)), "v"(voff0), "s"((const char*)(gbase) + (size_t)(hoff) + (size_t)(_i * 8192)) : "memory"); } } while (0)
; #define PG8_WAIT_V(n) asm volatile("s_waitcnt vmcnt(" #n ")" ::: "memory")
; #define PG8_BAR __builtin_amdgcn_s_barrier()
; template <class Epi>
; __device__ __forceinline__ void gemm_phase(LAS unsigned char* lds, const Gemm g, const StaticOrder& S, const Epi& E) {
;     ...
;     const unsigned lds0 = (unsigned)__builtin_amdgcn_readfirstlane((int)((unsigned)(size_t)lds + (unsigned)wid * 1024u));
;     const int aoff = lds_byte(wr * 64 + fr, fq * 8), boff = lds_byte(wc * 32 + fr, fq * 8);
;     ...
;     PG8_STAGE(PG8_SB(0, 0), cB, 0, 0); PG8_STAGE(PG8_SA(0, 0), cA, 0, 0); PG8_STAGE(PG8_SB(0, 1), cB, hB, 0); PG8_STAGE(PG8_SA(0, 1), cA, hA, 0);
;     if (wr == 1) PG8_BAR;
;     PG8_WAIT_V(4); PG8_BAR;
;     PG8_STAGE(PG8_SB(1, 0), cB + KS, 0, 0); PG8_STAGE(PG8_SA(1, 0), cA + KS, 0, 0); PG8_STAGE(PG8_SB(1, 1), cB + KS, hB, 0);
;     PG8_WAIT_V(6); PG8_BAR;
.LBB0_426:
	s_add_u32 s2, s2, 0x12630000
	v_lshrrev_b32_e32 v2, 1, v0
	s_addc_u32 s3, s3, 0
	v_and_b32_e32 v2, 24, v2
	s_lshl_b32 s0, s0, 5
	v_and_b32_e32 v1, 15, v0
	v_lshlrev_b32_e32 v3, 1, v2
	v_lshlrev_b32_e32 v0, 2, v0
	s_and_b32 s4, s0, 0x60
	v_lshl_or_b32 v131, s1, 6, v1
	v_lshl_or_b32 v1, v1, 6, v3
	s_lshl_b32 s1, s1, 13
	v_and_b32_e32 v0, 32, v0
	s_lshl_b32 s0, s4, 7
	s_add_i32 s38, s25, 0x18000
	v_bitop3_b32 v3, v1, s1, v0 bitop3:0xde
	v_bitop3_b32 v0, v1, s0, v0 bitop3:0xde
	s_add_u32 s0, s56, 0x4000
	s_addc_u32 s1, s57, 0
	s_add_i32 s39, s25, 0x1a000
	s_waitcnt vmcnt(4)
	s_barrier
	s_mov_b32 m0, s38
	s_nop 0
	global_load_lds_dwordx4 v130, s[0:1]
	s_add_u32 s0, s56, 0x6000
	s_addc_u32 s1, s57, 0
	s_add_i32 s40, s25, 0x8000
	s_mov_b32 m0, s39
	s_nop 0
	global_load_lds_dwordx4 v130, s[0:1]
	s_add_u32 s0, s54, 0x4000
	s_addc_u32 s1, s55, 0
	s_add_i32 s41, s25, 0xa000
	s_mov_b32 m0, s40
	s_nop 0
	global_load_lds_dwordx4 v130, s[0:1]
	s_add_u32 s0, s54, 0x6000
	s_addc_u32 s1, s55, 0
	s_add_i32 s42, s25, 0x1c000
	s_mov_b32 m0, s41
	s_nop 0
	global_load_lds_dwordx4 v130, s[0:1]
	s_add_u32 s0, s56, 0x84000
	s_addc_u32 s1, s57, 0
	s_add_i32 s43, s25, 0x1e000
	s_mov_b32 m0, s42
	s_nop 0
	global_load_lds_dwordx4 v130, s[0:1]
	s_add_u32 s0, s56, 0x86000
	s_addc_u32 s1, s57, 0
	s_mov_b32 m0, s43
	s_nop 0
	global_load_lds_dwordx4 v130, s[0:1]
	s_waitcnt vmcnt(6)
	v_readlane_b32 s0, v255, 15
	s_add_i32 s50, s25, 0xc000
	s_add_i32 s51, s25, 0xe000
	v_or_b32_e32 v132, s4, v2
	s_mov_b32 s60, 0
	v_add_u32_e32 v133, 0x10000, v0
	v_add_u32_e32 v134, 0, v3
	v_readlane_b32 s61, v255, 14
	s_mov_b32 s62, s0
	s_barrier
	v_readlane_b32 s1, v255, 16
	s_waitcnt vmcnt(0)

; #define PG8_STAGE(bufoff, gbase, hoff, imm) do { _Pragma("unroll") for (int _i = 0; _i < 2; ++_i) { \
;         asm volatile("s_mov_b32 m0, %0\n\ts_nop 0\n\tglobal_load_lds_dwordx4 %1, %2" \
;             :: "s"(lds0 + (unsigned)((bufoff) + _i * 8192)), "v"(voff0), "s"((const char*)(gbase) + (size_t)(hoff) + (size_t)(_i * 8192)) : "memory"); } } while (0)
; #define PG8_LDA(dst, b, h) do { _Pragma("unroll") for (int m = 0; m < 4; ++m) _Pragma("unroll") for (int k = 0; k < 2; ++k) dst[m][k] = *(const LAS bf16x8*)(lds + PG8_SA(b, h) + aoff + m * 2048 + k * 1024); } while (0)
; #define PG8_LDB(dst, b, h) do { _Pragma("unroll") for (int n = 0; n < 2; ++n) _Pragma("unroll") for (int k = 0; k < 2; ++k) dst[n][k] = *(const LAS bf16x8*)(lds + PG8_SB(b, h) + boff + n * 2048 + k * 1024); } while (0)
; #define PG8_WAIT_L(n) asm volatile("s_waitcnt lgkmcnt(" #n ")" ::: "memory")
; #define PG8_BAR __builtin_amdgcn_s_barrier()
; #define PG8_SCHED __builtin_amdgcn_sched_barrier(0)
; template <class Epi>
; __device__ __forceinline__ void gemm_phase(LAS unsigned char* lds, const Gemm g, const StaticOrder& S, const Epi& E) {
;     ...
;         const bool has_next = S.next(ui + 1, nxt);
;         const char* nA = has_next ? (const char*)g.A + (size_t)nxt.pm * tstepA + (size_t)(nxt.pn >> g.gshift) * g.gstride : cA;
;         const char* nB = has_next ? (const char*)g.Bt + (size_t)nxt.pn * tstepB : cB;
;         for (int t = 0; t < nt; t += 2) {
;             const bool last = (t == nt - 2);
;             if (last) E.pre(cur, wid, lane, (unsigned)(size_t)(lds + STAGE_BYTES));
;             const char* aT = cA + (size_t)t * KS;
;             const char* a2 = last ? nA : aT + 2 * KS; const char* b2 = last ? nB : cB + (size_t)(t + 2) * KS;
;             PG8_LDB(B0, 0, 0); PG8_SCHED; PG8_LDA(At, 0, 0); PG8_STAGE(PG8_SA(1, 1), aT + KS, hA, 0);
;             PG8_WAIT_L(8); PG8_BAR; PG8_WAIT_L(0); PG8_MMA(0, 0, At, B0); PG8_BAR; PG8_SCHED;
;             PG8_LDB(B1, 0, 1); PG8_STAGE(PG8_SB(0, 0), b2, 0, 0);
;             PG8_BAR; PG8_WAIT_L(0); PG8_MMA(0, 1, At, B1); PG8_BAR;
;             PG8_LDA(At, 0, 1); PG8_STAGE(PG8_SA(0, 0), a2, 0, 0);
;             PG8_BAR; PG8_WAIT_L(0); PG8_MMA(1, 0, At, B0); PG8_BAR; PG8_SCHED;
.LBB0_433:
	s_ashr_i32 s9, s8, 31
	s_lshl_b64 s[0:1], s[8:9], 20
	v_cmp_lt_i64_e32 vcc, s[10:11], v[192:193]
	s_add_u32 s10, s17, s0
	s_addc_u32 s11, s21, s1
	s_and_b64 s[0:1], vcc, exec
	s_cselect_b32 s0, s11, s55
	s_cselect_b32 s1, s10, s54
	s_ashr_i32 s7, s6, 31
	s_lshl_b64 s[52:53], s[6:7], 20
	s_add_u32 s52, s22, s52
	s_addc_u32 s53, s24, s53
	s_and_b64 s[58:59], vcc, exec
	s_cselect_b32 s7, s53, s57
	s_cselect_b32 s9, s52, s56
	s_add_u32 s63, s56, 0x8000
	s_addc_u32 s64, s57, 0
	s_mov_b32 s65, -2
	s_add_u32 s56, s54, 0x8000
	s_addc_u32 s57, s55, 0
	ds_read_b128 v[136:139], v133
	ds_read_b128 v[140:143], v133 offset:1024
	ds_read_b128 v[144:147], v133 offset:2048
	ds_read_b128 v[148:151], v133 offset:3072
	s_add_u32 s58, s54, 0x84000
	s_addc_u32 s59, s55, 0
	s_add_u32 s66, s54, 0x86000
	s_addc_u32 s67, s55, 0
	s_cmp_eq_u32 s65, 28
	s_cselect_b32 s55, s0, s57
	s_cselect_b32 s54, s1, s56
	ds_read_b128 v[152:155], v134
	ds_read_b128 v[156:159], v134 offset:1024
	ds_read_b128 v[160:163], v134 offset:2048
	ds_read_b128 v[164:167], v134 offset:3072
	ds_read_b128 v[168:171], v134 offset:4096
	ds_read_b128 v[172:175], v134 offset:5120
	ds_read_b128 v[176:179], v134 offset:6144
	ds_read_b128 v[180:183], v134 offset:7168
	s_mov_b32 m0, s50
	s_nop 0
	global_load_lds_dwordx4 v130, s[58:59]
	s_mov_b32 m0, s51
	s_nop 0
	global_load_lds_dwordx4 v130, s[66:67]
	s_waitcnt lgkmcnt(8)
	s_waitcnt vmcnt(10)
	s_barrier
	s_waitcnt lgkmcnt(7)
	v_mfma_f32_16x16x32_bf16 v[124:127], v[136:139], v[152:155], 0
	v_mfma_f32_16x16x32_bf16 v[120:123], v[144:147], v[152:155], 0
	s_waitcnt lgkmcnt(5)
	v_mfma_f32_16x16x32_bf16 v[116:119], v[136:139], v[160:163], 0
	v_mfma_f32_16x16x32_bf16 v[108:111], v[144:147], v[160:163], 0
	s_waitcnt lgkmcnt(3)
	v_mfma_f32_16x16x32_bf16 v[100:103], v[136:139], v[168:171], 0
	v_mfma_f32_16x16x32_bf16 v[92:95], v[144:147], v[168:171], 0
	s_waitcnt lgkmcnt(1)
	v_mfma_f32_16x16x32_bf16 v[84:87], v[136:139], v[176:179], 0
	v_mfma_f32_16x16x32_bf16 v[76:79], v[144:147], v[176:179], 0
	v_mfma_f32_16x16x32_bf16 v[124:127], v[140:143], v[156:159], v[124:127]
	v_mfma_f32_16x16x32_bf16 v[120:123], v[148:151], v[156:159], v[120:123]
	v_mfma_f32_16x16x32_bf16 v[116:119], v[140:143], v[164:167], v[116:119]
	v_mfma_f32_16x16x32_bf16 v[108:111], v[148:151], v[164:167], v[108:111]
	v_mfma_f32_16x16x32_bf16 v[100:103], v[140:143], v[172:175], v[100:103]
	v_mfma_f32_16x16x32_bf16 v[92:95], v[148:151], v[172:175], v[92:95]
	s_waitcnt lgkmcnt(0)
	v_mfma_f32_16x16x32_bf16 v[84:87], v[140:143], v[180:183], v[84:87]
	v_mfma_f32_16x16x32_bf16 v[76:79], v[148:151], v[180:183], v[76:79]
	s_barrier
	ds_read_b128 v[184:187], v133 offset:16384
	ds_read_b128 v[200:203], v133 offset:17408
	ds_read_b128 v[204:207], v133 offset:18432
	ds_read_b128 v[208:211], v133 offset:19456
	s_cselect_b32 s58, s9, s63
	s_cselect_b32 s59, s7, s64
	s_mov_b32 m0, s26
	s_nop 0
	global_load_lds_dwordx4 v130, s[58:59]
	s_add_u32 s66, s58, 0x2000
	s_addc_u32 s67, s59, 0
	s_mov_b32 m0, s27
	s_nop 0
	global_load_lds_dwordx4 v130, s[66:67]
	s_waitcnt vmcnt(10)
	s_barrier
	s_waitcnt lgkmcnt(3)
	v_mfma_f32_16x16x32_bf16 v[112:115], v[184:187], v[152:155], 0
	s_waitcnt lgkmcnt(1)
	v_mfma_f32_16x16x32_bf16 v[104:107], v[204:207], v[152:155], 0
	v_mfma_f32_16x16x32_bf16 v[96:99], v[184:187], v[160:163], 0
	v_mfma_f32_16x16x32_bf16 v[88:91], v[204:207], v[160:163], 0
	v_mfma_f32_16x16x32_bf16 v[80:83], v[184:187], v[168:171], 0
	v_mfma_f32_16x16x32_bf16 v[72:75], v[204:207], v[168:171], 0
	v_mfma_f32_16x16x32_bf16 v[68:71], v[184:187], v[176:179], 0
	v_mfma_f32_16x16x32_bf16 v[64:67], v[204:207], v[176:179], 0
	v_mfma_f32_16x16x32_bf16 v[112:115], v[200:203], v[156:159], v[112:115]
	s_waitcnt lgkmcnt(0)
	v_mfma_f32_16x16x32_bf16 v[104:107], v[208:211], v[156:159], v[104:107]
	v_mfma_f32_16x16x32_bf16 v[96:99], v[200:203], v[164:167], v[96:99]
	v_mfma_f32_16x16x32_bf16 v[88:91], v[208:211], v[164:167], v[88:91]
	v_mfma_f32_16x16x32_bf16 v[80:83], v[200:203], v[172:175], v[80:83]
	v_mfma_f32_16x16x32_bf16 v[72:75], v[208:211], v[172:175], v[72:75]
	v_mfma_f32_16x16x32_bf16 v[68:71], v[200:203], v[180:183], v[68:71]
	v_mfma_f32_16x16x32_bf16 v[64:67], v[208:211], v[180:183], v[64:67]
	s_barrier
	ds_read_b128 v[152:155], v134 offset:16384
	ds_read_b128 v[156:159], v134 offset:17408
	ds_read_b128 v[160:163], v134 offset:18432
	ds_read_b128 v[164:167], v134 offset:19456
	ds_read_b128 v[168:171], v134 offset:20480
	ds_read_b128 v[172:175], v134 offset:21504
	ds_read_b128 v[176:179], v134 offset:22528
	ds_read_b128 v[180:183], v134 offset:23552
	s_mov_b32 m0, s25
	s_nop 0
	global_load_lds_dwordx4 v130, s[54:55]
	s_add_u32 s66, s54, 0x2000
	s_addc_u32 s67, s55, 0
	s_mov_b32 m0, s28
	s_nop 0
	global_load_lds_dwordx4 v130, s[66:67]
	s_barrier
	s_waitcnt lgkmcnt(7)
	v_mfma_f32_16x16x32_bf16 v[60:63], v[136:139], v[152:155], 0
	v_mfma_f32_16x16x32_bf16 v[56:59], v[144:147], v[152:155], 0
	s_waitcnt lgkmcnt(5)
	v_mfma_f32_16x16x32_bf16 v[52:55], v[136:139], v[160:163], 0
	v_mfma_f32_16x16x32_bf16 v[44:47], v[144:147], v[160:163], 0
	s_waitcnt lgkmcnt(3)
	v_mfma_f32_16x16x32_bf16 v[36:39], v[136:139], v[168:171], 0
	v_mfma_f32_16x16x32_bf16 v[28:31], v[144:147], v[168:171], 0
	s_waitcnt lgkmcnt(1)
	v_mfma_f32_16x16x32_bf16 v[20:23], v[136:139], v[176:179], 0
	v_mfma_f32_16x16x32_bf16 v[12:15], v[144:147], v[176:179], 0
	v_mfma_f32_16x16x32_bf16 v[60:63], v[140:143], v[156:159], v[60:63]
	v_mfma_f32_16x16x32_bf16 v[56:59], v[148:151], v[156:159], v[56:59]
	v_mfma_f32_16x16x32_bf16 v[52:55], v[140:143], v[164:167], v[52:55]
	v_mfma_f32_16x16x32_bf16 v[44:47], v[148:151], v[164:167], v[44:47]
	v_mfma_f32_16x16x32_bf16 v[36:39], v[140:143], v[172:175], v[36:39]
	v_mfma_f32_16x16x32_bf16 v[28:31], v[148:151], v[172:175], v[28:31]
	s_waitcnt lgkmcnt(0)
	v_mfma_f32_16x16x32_bf16 v[20:23], v[140:143], v[180:183], v[20:23]
	v_mfma_f32_16x16x32_bf16 v[12:15], v[148:151], v[180:183], v[12:15]
	s_barrier
; #define PG8_STAGE(bufoff, gbase, hoff, imm) do { _Pragma("unroll") for (int _i = 0; _i < 2; ++_i) { \
;         asm volatile("s_mov_b32 m0, %0\n\ts_nop 0\n\tglobal_load_lds_dwordx4 %1, %2" \
;             :: "s"(lds0 + (unsigned)((bufoff) + _i * 8192)), "v"(voff0), "s"((const char*)(gbase) + (size_t)(hoff) + (size_t)(_i * 8192)) : "memory"); } } while (0)
; #define PG8_LDA(dst, b, h) do { _Pragma("unroll") for (int m = 0; m < 4; ++m) _Pragma("unroll") for (int k = 0; k < 2; ++k) dst[m][k] = *(const LAS bf16x8*)(lds + PG8_SA(b, h) + aoff + m * 2048 + k * 1024); } while (0)
; #define PG8_LDB(dst, b, h) do { _Pragma("unroll") for (int n = 0; n < 2; ++n) _Pragma("unroll") for (int k = 0; k < 2; ++k) dst[n][k] = *(const LAS bf16x8*)(lds + PG8_SB(b, h) + boff + n * 2048 + k * 1024); } while (0)
; #define PG8_MMA(ai, bj, At, Bt) do { __builtin_amdgcn_s_setprio(1); _Pragma("unroll") for (int m = 0; m < 4; ++m) _Pragma("unroll") for (int n = 0; n < 2; ++n) _Pragma("unroll") for (int k = 0; k < 2; ++k) \
;         acc[ai][bj][m][n] = __builtin_amdgcn_mfma_f32_16x16x32_bf16(Bt[n][k], At[m][k], acc[ai][bj][m][n], 0, 0, 0); __builtin_amdgcn_s_setprio(0); } while (0)
; #define PG8_WAIT_V(n) asm volatile("s_waitcnt vmcnt(" #n ")" ::: "memory")
; #define PG8_WAIT_L(n) asm volatile("s_waitcnt lgkmcnt(" #n ")" ::: "memory")
; #define PG8_BAR __builtin_amdgcn_s_barrier()
; #define PG8_SCHED __builtin_amdgcn_sched_barrier(0)
; template <class Epi>
; __device__ __forceinline__ void gemm_phase(LAS unsigned char* lds, const Gemm g, const StaticOrder& S, const Epi& E) {
;     ...
;             PG8_STAGE(PG8_SB(0, 1), b2, hB, 0);
;             PG8_WAIT_V(6); PG8_BAR; PG8_MMA(1, 1, At, B1); PG8_BAR;
;             PG8_LDB(B0, 1, 0); PG8_SCHED; PG8_LDA(At, 1, 0); PG8_STAGE(PG8_SA(0, 1), a2, hA, 0);
;             PG8_WAIT_L(8); PG8_BAR; PG8_WAIT_L(0); PG8_MMA(0, 0, At, B0); PG8_BAR; PG8_SCHED;
;             PG8_LDB(B1, 1, 1); PG8_STAGE(PG8_SB(1, 0), b2 + KS, 0, 0);
;             PG8_BAR; PG8_WAIT_L(0); PG8_MMA(0, 1, At, B1); PG8_BAR;
;             PG8_LDA(At, 1, 1); PG8_STAGE(PG8_SA(1, 0), a2 + KS, 0, 0);
	s_add_u32 s66, s58, 0x80000
	s_addc_u32 s67, s59, 0
	s_mov_b32 m0, s29
	s_nop 0
	global_load_lds_dwordx4 v130, s[66:67]
	s_add_u32 s66, s58, 0x82000
	s_addc_u32 s67, s59, 0
	s_mov_b32 m0, s30
	s_nop 0
	global_load_lds_dwordx4 v130, s[66:67]
	s_waitcnt vmcnt(10)
	s_barrier
	v_mfma_f32_16x16x32_bf16 v[48:51], v[184:187], v[152:155], 0
	v_mfma_f32_16x16x32_bf16 v[40:43], v[204:207], v[152:155], 0
	v_mfma_f32_16x16x32_bf16 v[32:35], v[184:187], v[160:163], 0
	v_mfma_f32_16x16x32_bf16 v[24:27], v[204:207], v[160:163], 0
	v_mfma_f32_16x16x32_bf16 v[16:19], v[184:187], v[168:171], 0
	v_mfma_f32_16x16x32_bf16 v[8:11], v[204:207], v[168:171], 0
	v_mfma_f32_16x16x32_bf16 v[4:7], v[184:187], v[176:179], 0
	v_mfma_f32_16x16x32_bf16 v[0:3], v[204:207], v[176:179], 0
	v_mfma_f32_16x16x32_bf16 v[48:51], v[200:203], v[156:159], v[48:51]
	v_mfma_f32_16x16x32_bf16 v[40:43], v[208:211], v[156:159], v[40:43]
	v_mfma_f32_16x16x32_bf16 v[32:35], v[200:203], v[164:167], v[32:35]
	v_mfma_f32_16x16x32_bf16 v[24:27], v[208:211], v[164:167], v[24:27]
	v_mfma_f32_16x16x32_bf16 v[16:19], v[200:203], v[172:175], v[16:19]
	v_mfma_f32_16x16x32_bf16 v[8:11], v[208:211], v[172:175], v[8:11]
	v_mfma_f32_16x16x32_bf16 v[4:7], v[200:203], v[180:183], v[4:7]
	v_mfma_f32_16x16x32_bf16 v[0:3], v[208:211], v[180:183], v[0:3]
	s_barrier
	ds_read_b128 v[136:139], v133 offset:32768
	ds_read_b128 v[140:143], v133 offset:33792
	ds_read_b128 v[144:147], v133 offset:34816
	ds_read_b128 v[148:151], v133 offset:35840
	ds_read_b128 v[152:155], v134 offset:32768
	ds_read_b128 v[156:159], v134 offset:33792
	ds_read_b128 v[160:163], v134 offset:34816
	ds_read_b128 v[164:167], v134 offset:35840
	ds_read_b128 v[168:171], v134 offset:36864
	ds_read_b128 v[172:175], v134 offset:37888
	ds_read_b128 v[176:179], v134 offset:38912
	ds_read_b128 v[180:183], v134 offset:39936
	s_add_u32 s66, s54, 0x80000
	s_addc_u32 s67, s55, 0
	s_mov_b32 m0, s34
	s_nop 0
	global_load_lds_dwordx4 v130, s[66:67]
	s_add_u32 s66, s54, 0x82000
	s_addc_u32 s67, s55, 0
	s_mov_b32 m0, s37
	s_nop 0
	global_load_lds_dwordx4 v130, s[66:67]
	s_waitcnt lgkmcnt(8)
	s_waitcnt vmcnt(10)
	s_barrier
	s_waitcnt lgkmcnt(7)
	v_mfma_f32_16x16x32_bf16 v[124:127], v[136:139], v[152:155], v[124:127]
	v_mfma_f32_16x16x32_bf16 v[120:123], v[144:147], v[152:155], v[120:123]
	s_waitcnt lgkmcnt(5)
	v_mfma_f32_16x16x32_bf16 v[116:119], v[136:139], v[160:163], v[116:119]
	v_mfma_f32_16x16x32_bf16 v[108:111], v[144:147], v[160:163], v[108:111]
	s_waitcnt lgkmcnt(3)
	v_mfma_f32_16x16x32_bf16 v[100:103], v[136:139], v[168:171], v[100:103]
	v_mfma_f32_16x16x32_bf16 v[92:95], v[144:147], v[168:171], v[92:95]
	s_waitcnt lgkmcnt(1)
	v_mfma_f32_16x16x32_bf16 v[84:87], v[136:139], v[176:179], v[84:87]
	v_mfma_f32_16x16x32_bf16 v[76:79], v[144:147], v[176:179], v[76:79]
	v_mfma_f32_16x16x32_bf16 v[124:127], v[140:143], v[156:159], v[124:127]
	v_mfma_f32_16x16x32_bf16 v[120:123], v[148:151], v[156:159], v[120:123]
	v_mfma_f32_16x16x32_bf16 v[116:119], v[140:143], v[164:167], v[116:119]
	v_mfma_f32_16x16x32_bf16 v[108:111], v[148:151], v[164:167], v[108:111]
	v_mfma_f32_16x16x32_bf16 v[100:103], v[140:143], v[172:175], v[100:103]
	v_mfma_f32_16x16x32_bf16 v[92:95], v[148:151], v[172:175], v[92:95]
	s_waitcnt lgkmcnt(0)
	v_mfma_f32_16x16x32_bf16 v[84:87], v[140:143], v[180:183], v[84:87]
	v_mfma_f32_16x16x32_bf16 v[76:79], v[148:151], v[180:183], v[76:79]
	s_barrier
	ds_read_b128 v[184:187], v133 offset:49152
	ds_read_b128 v[200:203], v133 offset:50176
	ds_read_b128 v[204:207], v133 offset:51200
	ds_read_b128 v[208:211], v133 offset:52224
	s_add_u32 s66, s58, 0x4000
	s_addc_u32 s67, s59, 0
	s_mov_b32 m0, s38
	s_nop 0
	global_load_lds_dwordx4 v130, s[66:67]
	s_add_u32 s66, s58, 0x6000
	s_addc_u32 s67, s59, 0
	s_mov_b32 m0, s39
	s_nop 0
	global_load_lds_dwordx4 v130, s[66:67]
	s_waitcnt vmcnt(10)
	s_barrier
	s_waitcnt lgkmcnt(3)
	v_mfma_f32_16x16x32_bf16 v[112:115], v[184:187], v[152:155], v[112:115]
	s_waitcnt lgkmcnt(1)
	v_mfma_f32_16x16x32_bf16 v[104:107], v[204:207], v[152:155], v[104:107]
	v_mfma_f32_16x16x32_bf16 v[96:99], v[184:187], v[160:163], v[96:99]
	v_mfma_f32_16x16x32_bf16 v[88:91], v[204:207], v[160:163], v[88:91]
	v_mfma_f32_16x16x32_bf16 v[80:83], v[184:187], v[168:171], v[80:83]
	v_mfma_f32_16x16x32_bf16 v[72:75], v[204:207], v[168:171], v[72:75]
	v_mfma_f32_16x16x32_bf16 v[68:71], v[184:187], v[176:179], v[68:71]
	v_mfma_f32_16x16x32_bf16 v[64:67], v[204:207], v[176:179], v[64:67]
	v_mfma_f32_16x16x32_bf16 v[112:115], v[200:203], v[156:159], v[112:115]
	s_waitcnt lgkmcnt(0)
	v_mfma_f32_16x16x32_bf16 v[104:107], v[208:211], v[156:159], v[104:107]
	v_mfma_f32_16x16x32_bf16 v[96:99], v[200:203], v[164:167], v[96:99]
	v_mfma_f32_16x16x32_bf16 v[88:91], v[208:211], v[164:167], v[88:91]
	v_mfma_f32_16x16x32_bf16 v[80:83], v[200:203], v[172:175], v[80:83]
	v_mfma_f32_16x16x32_bf16 v[72:75], v[208:211], v[172:175], v[72:75]
	v_mfma_f32_16x16x32_bf16 v[68:71], v[200:203], v[180:183], v[68:71]
	v_mfma_f32_16x16x32_bf16 v[64:67], v[208:211], v[180:183], v[64:67]
	s_barrier
	ds_read_b128 v[152:155], v134 offset:49152
	ds_read_b128 v[156:159], v134 offset:50176
	ds_read_b128 v[160:163], v134 offset:51200
	ds_read_b128 v[164:167], v134 offset:52224
	ds_read_b128 v[168:171], v134 offset:53248
	ds_read_b128 v[172:175], v134 offset:54272
	ds_read_b128 v[176:179], v134 offset:55296
	ds_read_b128 v[180:183], v134 offset:56320
	s_add_u32 s66, s54, 0x4000
	s_addc_u32 s67, s55, 0
	s_mov_b32 m0, s40
	s_nop 0
	global_load_lds_dwordx4 v130, s[66:67]
	s_add_u32 s54, s54, 0x6000
	s_addc_u32 s55, s55, 0
	s_mov_b32 m0, s41
	s_nop 0
	global_load_lds_dwordx4 v130, s[54:55]
	s_barrier
; #define PG8_STAGE(bufoff, gbase, hoff, imm) do { _Pragma("unroll") for (int _i = 0; _i < 2; ++_i) { \
;         asm volatile("s_mov_b32 m0, %0\n\ts_nop 0\n\tglobal_load_lds_dwordx4 %1, %2" \
;             :: "s"(lds0 + (unsigned)((bufoff) + _i * 8192)), "v"(voff0), "s"((const char*)(gbase) + (size_t)(hoff) + (size_t)(_i * 8192)) : "memory"); } } while (0)
; #define PG8_LDA(dst, b, h) do { _Pragma("unroll") for (int m = 0; m < 4; ++m) _Pragma("unroll") for (int k = 0; k < 2; ++k) dst[m][k] = *(const LAS bf16x8*)(lds + PG8_SA(b, h) + aoff + m * 2048 + k * 1024); } while (0)
; #define PG8_LDB(dst, b, h) do { _Pragma("unroll") for (int n = 0; n < 2; ++n) _Pragma("unroll") for (int k = 0; k < 2; ++k) dst[n][k] = *(const LAS bf16x8*)(lds + PG8_SB(b, h) + boff + n * 2048 + k * 1024); } while (0)
; #define PG8_MMA(ai, bj, At, Bt) do { __builtin_amdgcn_s_setprio(1); _Pragma("unroll") for (int m = 0; m < 4; ++m) _Pragma("unroll") for (int n = 0; n < 2; ++n) _Pragma("unroll") for (int k = 0; k < 2; ++k) \
;         acc[ai][bj][m][n] = __builtin_amdgcn_mfma_f32_16x16x32_bf16(Bt[n][k], At[m][k], acc[ai][bj][m][n], 0, 0, 0); __builtin_amdgcn_s_setprio(0); } while (0)
; #define PG8_WAIT_V(n) asm volatile("s_waitcnt vmcnt(" #n ")" ::: "memory")
; #define PG8_WAIT_L(n) asm volatile("s_waitcnt lgkmcnt(" #n ")" ::: "memory")
; #define PG8_BAR __builtin_amdgcn_s_barrier()
; #define PG8_SCHED __builtin_amdgcn_sched_barrier(0)
; template <class Epi>
; __device__ __forceinline__ void gemm_phase(LAS unsigned char* lds, const Gemm g, const StaticOrder& S, const Epi& E) {
;     ...
;             const char* aT = cA + (size_t)t * KS;
;             const char* a2 = last ? nA : aT + 2 * KS; const char* b2 = last ? nB : cB + (size_t)(t + 2) * KS;
;             PG8_LDB(B0, 0, 0); PG8_SCHED; PG8_LDA(At, 0, 0); PG8_STAGE(PG8_SA(1, 1), aT + KS, hA, 0);
;             PG8_WAIT_L(8); PG8_BAR; PG8_WAIT_L(0); PG8_MMA(0, 0, At, B0); PG8_BAR; PG8_SCHED;
;             PG8_LDB(B1, 0, 1); PG8_STAGE(PG8_SB(0, 0), b2, 0, 0);
;     ...
;             PG8_BAR; PG8_WAIT_L(0); PG8_MMA(1, 0, At, B0); PG8_BAR; PG8_SCHED;
;             PG8_STAGE(PG8_SB(1, 1), b2 + KS, hB, 0);
;             PG8_WAIT_V(6); PG8_BAR; PG8_MMA(1, 1, At, B1); PG8_BAR;
	s_waitcnt lgkmcnt(7)
	v_mfma_f32_16x16x32_bf16 v[60:63], v[136:139], v[152:155], v[60:63]
	v_mfma_f32_16x16x32_bf16 v[56:59], v[144:147], v[152:155], v[56:59]
	s_waitcnt lgkmcnt(5)
	v_mfma_f32_16x16x32_bf16 v[52:55], v[136:139], v[160:163], v[52:55]
	v_mfma_f32_16x16x32_bf16 v[44:47], v[144:147], v[160:163], v[44:47]
	s_waitcnt lgkmcnt(3)
	v_mfma_f32_16x16x32_bf16 v[36:39], v[136:139], v[168:171], v[36:39]
	v_mfma_f32_16x16x32_bf16 v[28:31], v[144:147], v[168:171], v[28:31]
	s_waitcnt lgkmcnt(1)
	v_mfma_f32_16x16x32_bf16 v[20:23], v[136:139], v[176:179], v[20:23]
	v_mfma_f32_16x16x32_bf16 v[12:15], v[144:147], v[176:179], v[12:15]
	v_mfma_f32_16x16x32_bf16 v[60:63], v[140:143], v[156:159], v[60:63]
	v_mfma_f32_16x16x32_bf16 v[56:59], v[148:151], v[156:159], v[56:59]
	v_mfma_f32_16x16x32_bf16 v[52:55], v[140:143], v[164:167], v[52:55]
	v_mfma_f32_16x16x32_bf16 v[44:47], v[148:151], v[164:167], v[44:47]
	v_mfma_f32_16x16x32_bf16 v[36:39], v[140:143], v[172:175], v[36:39]
	v_mfma_f32_16x16x32_bf16 v[28:31], v[148:151], v[172:175], v[28:31]
	s_waitcnt lgkmcnt(0)
	v_mfma_f32_16x16x32_bf16 v[20:23], v[140:143], v[180:183], v[20:23]
	v_mfma_f32_16x16x32_bf16 v[12:15], v[148:151], v[180:183], v[12:15]
	s_barrier
	s_add_u32 s54, s58, 0x84000
	s_addc_u32 s55, s59, 0
	s_mov_b32 m0, s42
	s_nop 0
	global_load_lds_dwordx4 v130, s[54:55]
	s_add_u32 s54, s58, 0x86000
	s_addc_u32 s55, s59, 0
	s_mov_b32 m0, s43
	s_nop 0
	global_load_lds_dwordx4 v130, s[54:55]
	s_waitcnt vmcnt(10)
	s_barrier
	v_mfma_f32_16x16x32_bf16 v[48:51], v[184:187], v[152:155], v[48:51]
	v_mfma_f32_16x16x32_bf16 v[40:43], v[204:207], v[152:155], v[40:43]
	v_mfma_f32_16x16x32_bf16 v[32:35], v[184:187], v[160:163], v[32:35]
	v_mfma_f32_16x16x32_bf16 v[24:27], v[204:207], v[160:163], v[24:27]
	v_mfma_f32_16x16x32_bf16 v[16:19], v[184:187], v[168:171], v[16:19]
	v_mfma_f32_16x16x32_bf16 v[8:11], v[204:207], v[168:171], v[8:11]
	v_mfma_f32_16x16x32_bf16 v[4:7], v[184:187], v[176:179], v[4:7]
	v_mfma_f32_16x16x32_bf16 v[0:3], v[204:207], v[176:179], v[0:3]
	v_mfma_f32_16x16x32_bf16 v[48:51], v[200:203], v[156:159], v[48:51]
	v_mfma_f32_16x16x32_bf16 v[40:43], v[208:211], v[156:159], v[40:43]
	v_mfma_f32_16x16x32_bf16 v[32:35], v[200:203], v[164:167], v[32:35]
	v_mfma_f32_16x16x32_bf16 v[24:27], v[208:211], v[164:167], v[24:27]
	v_mfma_f32_16x16x32_bf16 v[16:19], v[200:203], v[172:175], v[16:19]
	v_mfma_f32_16x16x32_bf16 v[8:11], v[208:211], v[172:175], v[8:11]
	v_mfma_f32_16x16x32_bf16 v[4:7], v[200:203], v[180:183], v[4:7]
	v_mfma_f32_16x16x32_bf16 v[0:3], v[208:211], v[180:183], v[0:3]
	s_add_i32 s65, s65, 2
	s_add_u32 s63, s63, 0x8000
	s_addc_u32 s64, s64, 0
	s_cmp_gt_u32 s65, 29
	s_mov_b64 s[54:55], s[56:57]
	s_barrier
.LBB0_434:
	s_add_u32 s56, s54, 0x8000
	s_addc_u32 s57, s55, 0
	ds_read_b128 v[136:139], v133
	ds_read_b128 v[140:143], v133 offset:1024
	ds_read_b128 v[144:147], v133 offset:2048
	ds_read_b128 v[148:151], v133 offset:3072
	s_add_u32 s58, s54, 0x84000
	s_addc_u32 s59, s55, 0
	s_add_u32 s66, s54, 0x86000
	s_addc_u32 s67, s55, 0
	s_cmp_eq_u32 s65, 28
	s_cselect_b32 s55, s0, s57
	s_cselect_b32 s54, s1, s56
	ds_read_b128 v[152:155], v134
	ds_read_b128 v[156:159], v134 offset:1024
	ds_read_b128 v[160:163], v134 offset:2048
	ds_read_b128 v[164:167], v134 offset:3072
	ds_read_b128 v[168:171], v134 offset:4096
	ds_read_b128 v[172:175], v134 offset:5120
	ds_read_b128 v[176:179], v134 offset:6144
	ds_read_b128 v[180:183], v134 offset:7168
	s_mov_b32 m0, s50
	s_nop 0
	global_load_lds_dwordx4 v130, s[58:59]
	s_mov_b32 m0, s51
	s_nop 0
	global_load_lds_dwordx4 v130, s[66:67]
	s_waitcnt lgkmcnt(8)
	s_waitcnt vmcnt(10)
	s_barrier
	s_waitcnt lgkmcnt(7)
	v_mfma_f32_16x16x32_bf16 v[124:127], v[136:139], v[152:155], v[124:127]
	v_mfma_f32_16x16x32_bf16 v[120:123], v[144:147], v[152:155], v[120:123]
	s_waitcnt lgkmcnt(5)
	v_mfma_f32_16x16x32_bf16 v[116:119], v[136:139], v[160:163], v[116:119]
	v_mfma_f32_16x16x32_bf16 v[108:111], v[144:147], v[160:163], v[108:111]
	s_waitcnt lgkmcnt(3)
	v_mfma_f32_16x16x32_bf16 v[100:103], v[136:139], v[168:171], v[100:103]
	v_mfma_f32_16x16x32_bf16 v[92:95], v[144:147], v[168:171], v[92:95]
	s_waitcnt lgkmcnt(1)
	v_mfma_f32_16x16x32_bf16 v[84:87], v[136:139], v[176:179], v[84:87]
	v_mfma_f32_16x16x32_bf16 v[76:79], v[144:147], v[176:179], v[76:79]
	v_mfma_f32_16x16x32_bf16 v[124:127], v[140:143], v[156:159], v[124:127]
	v_mfma_f32_16x16x32_bf16 v[120:123], v[148:151], v[156:159], v[120:123]
	v_mfma_f32_16x16x32_bf16 v[116:119], v[140:143], v[164:167], v[116:119]
	v_mfma_f32_16x16x32_bf16 v[108:111], v[148:151], v[164:167], v[108:111]
	v_mfma_f32_16x16x32_bf16 v[100:103], v[140:143], v[172:175], v[100:103]
	v_mfma_f32_16x16x32_bf16 v[92:95], v[148:151], v[172:175], v[92:95]
	s_waitcnt lgkmcnt(0)
	v_mfma_f32_16x16x32_bf16 v[84:87], v[140:143], v[180:183], v[84:87]
	v_mfma_f32_16x16x32_bf16 v[76:79], v[148:151], v[180:183], v[76:79]
	s_barrier
	ds_read_b128 v[184:187], v133 offset:16384
	ds_read_b128 v[200:203], v133 offset:17408
	ds_read_b128 v[204:207], v133 offset:18432
	ds_read_b128 v[208:211], v133 offset:19456
	s_cselect_b32 s58, s9, s63
	s_cselect_b32 s59, s7, s64
	s_mov_b32 m0, s26
	s_nop 0
	global_load_lds_dwordx4 v130, s[58:59]
	s_add_u32 s66, s58, 0x2000
	s_addc_u32 s67, s59, 0
	s_mov_b32 m0, s27
	s_nop 0
	global_load_lds_dwordx4 v130, s[66:67]
	s_waitcnt vmcnt(10)
	s_barrier
; #define PG8_STAGE(bufoff, gbase, hoff, imm) do { _Pragma("unroll") for (int _i = 0; _i < 2; ++_i) { \
;         asm volatile("s_mov_b32 m0, %0\n\ts_nop 0\n\tglobal_load_lds_dwordx4 %1, %2" \
;             :: "s"(lds0 + (unsigned)((bufoff) + _i * 8192)), "v"(voff0), "s"((const char*)(gbase) + (size_t)(hoff) + (size_t)(_i * 8192)) : "memory"); } } while (0)
; #define PG8_LDA(dst, b, h) do { _Pragma("unroll") for (int m = 0; m < 4; ++m) _Pragma("unroll") for (int k = 0; k < 2; ++k) dst[m][k] = *(const LAS bf16x8*)(lds + PG8_SA(b, h) + aoff + m * 2048 + k * 1024); } while (0)
; #define PG8_LDB(dst, b, h) do { _Pragma("unroll") for (int n = 0; n < 2; ++n) _Pragma("unroll") for (int k = 0; k < 2; ++k) dst[n][k] = *(const LAS bf16x8*)(lds + PG8_SB(b, h) + boff + n * 2048 + k * 1024); } while (0)
; #define PG8_MMA(ai, bj, At, Bt) do { __builtin_amdgcn_s_setprio(1); _Pragma("unroll") for (int m = 0; m < 4; ++m) _Pragma("unroll") for (int n = 0; n < 2; ++n) _Pragma("unroll") for (int k = 0; k < 2; ++k) \
;         acc[ai][bj][m][n] = __builtin_amdgcn_mfma_f32_16x16x32_bf16(Bt[n][k], At[m][k], acc[ai][bj][m][n], 0, 0, 0); __builtin_amdgcn_s_setprio(0); } while (0)
; #define PG8_WAIT_V(n) asm volatile("s_waitcnt vmcnt(" #n ")" ::: "memory")
; #define PG8_WAIT_L(n) asm volatile("s_waitcnt lgkmcnt(" #n ")" ::: "memory")
; #define PG8_BAR __builtin_amdgcn_s_barrier()
; #define PG8_SCHED __builtin_amdgcn_sched_barrier(0)
; template <class Epi>
; __device__ __forceinline__ void gemm_phase(LAS unsigned char* lds, const Gemm g, const StaticOrder& S, const Epi& E) {
;     ...
;             PG8_BAR; PG8_WAIT_L(0); PG8_MMA(0, 1, At, B1); PG8_BAR;
;             PG8_LDA(At, 0, 1); PG8_STAGE(PG8_SA(0, 0), a2, 0, 0);
;             PG8_BAR; PG8_WAIT_L(0); PG8_MMA(1, 0, At, B0); PG8_BAR; PG8_SCHED;
;             PG8_STAGE(PG8_SB(0, 1), b2, hB, 0);
;             PG8_WAIT_V(6); PG8_BAR; PG8_MMA(1, 1, At, B1); PG8_BAR;
;             PG8_LDB(B0, 1, 0); PG8_SCHED; PG8_LDA(At, 1, 0); PG8_STAGE(PG8_SA(0, 1), a2, hA, 0);
	s_waitcnt lgkmcnt(3)
	v_mfma_f32_16x16x32_bf16 v[112:115], v[184:187], v[152:155], v[112:115]
	s_waitcnt lgkmcnt(1)
	v_mfma_f32_16x16x32_bf16 v[104:107], v[204:207], v[152:155], v[104:107]
	v_mfma_f32_16x16x32_bf16 v[96:99], v[184:187], v[160:163], v[96:99]
	v_mfma_f32_16x16x32_bf16 v[88:91], v[204:207], v[160:163], v[88:91]
	v_mfma_f32_16x16x32_bf16 v[80:83], v[184:187], v[168:171], v[80:83]
	v_mfma_f32_16x16x32_bf16 v[72:75], v[204:207], v[168:171], v[72:75]
	v_mfma_f32_16x16x32_bf16 v[68:71], v[184:187], v[176:179], v[68:71]
	v_mfma_f32_16x16x32_bf16 v[64:67], v[204:207], v[176:179], v[64:67]
	v_mfma_f32_16x16x32_bf16 v[112:115], v[200:203], v[156:159], v[112:115]
	s_waitcnt lgkmcnt(0)
	v_mfma_f32_16x16x32_bf16 v[104:107], v[208:211], v[156:159], v[104:107]
	v_mfma_f32_16x16x32_bf16 v[96:99], v[200:203], v[164:167], v[96:99]
	v_mfma_f32_16x16x32_bf16 v[88:91], v[208:211], v[164:167], v[88:91]
	v_mfma_f32_16x16x32_bf16 v[80:83], v[200:203], v[172:175], v[80:83]
	v_mfma_f32_16x16x32_bf16 v[72:75], v[208:211], v[172:175], v[72:75]
	v_mfma_f32_16x16x32_bf16 v[68:71], v[200:203], v[180:183], v[68:71]
	v_mfma_f32_16x16x32_bf16 v[64:67], v[208:211], v[180:183], v[64:67]
	s_barrier
	ds_read_b128 v[152:155], v134 offset:16384
	ds_read_b128 v[156:159], v134 offset:17408
	ds_read_b128 v[160:163], v134 offset:18432
	ds_read_b128 v[164:167], v134 offset:19456
	ds_read_b128 v[168:171], v134 offset:20480
	ds_read_b128 v[172:175], v134 offset:21504
	ds_read_b128 v[176:179], v134 offset:22528
	ds_read_b128 v[180:183], v134 offset:23552
	s_mov_b32 m0, s25
	s_nop 0
	global_load_lds_dwordx4 v130, s[54:55]
	s_add_u32 s66, s54, 0x2000
	s_addc_u32 s67, s55, 0
	s_mov_b32 m0, s28
	s_nop 0
	global_load_lds_dwordx4 v130, s[66:67]
	s_barrier
	s_waitcnt lgkmcnt(7)
	v_mfma_f32_16x16x32_bf16 v[60:63], v[136:139], v[152:155], v[60:63]
	v_mfma_f32_16x16x32_bf16 v[56:59], v[144:147], v[152:155], v[56:59]
	s_waitcnt lgkmcnt(5)
	v_mfma_f32_16x16x32_bf16 v[52:55], v[136:139], v[160:163], v[52:55]
	v_mfma_f32_16x16x32_bf16 v[44:47], v[144:147], v[160:163], v[44:47]
	s_waitcnt lgkmcnt(3)
	v_mfma_f32_16x16x32_bf16 v[36:39], v[136:139], v[168:171], v[36:39]
	v_mfma_f32_16x16x32_bf16 v[28:31], v[144:147], v[168:171], v[28:31]
	s_waitcnt lgkmcnt(1)
	v_mfma_f32_16x16x32_bf16 v[20:23], v[136:139], v[176:179], v[20:23]
	v_mfma_f32_16x16x32_bf16 v[12:15], v[144:147], v[176:179], v[12:15]
	v_mfma_f32_16x16x32_bf16 v[60:63], v[140:143], v[156:159], v[60:63]
	v_mfma_f32_16x16x32_bf16 v[56:59], v[148:151], v[156:159], v[56:59]
	v_mfma_f32_16x16x32_bf16 v[52:55], v[140:143], v[164:167], v[52:55]
	v_mfma_f32_16x16x32_bf16 v[44:47], v[148:151], v[164:167], v[44:47]
	v_mfma_f32_16x16x32_bf16 v[36:39], v[140:143], v[172:175], v[36:39]
	v_mfma_f32_16x16x32_bf16 v[28:31], v[148:151], v[172:175], v[28:31]
	s_waitcnt lgkmcnt(0)
	v_mfma_f32_16x16x32_bf16 v[20:23], v[140:143], v[180:183], v[20:23]
	v_mfma_f32_16x16x32_bf16 v[12:15], v[148:151], v[180:183], v[12:15]
	s_barrier
	s_add_u32 s66, s58, 0x80000
	s_addc_u32 s67, s59, 0
	s_mov_b32 m0, s29
	s_nop 0
	global_load_lds_dwordx4 v130, s[66:67]
	s_add_u32 s66, s58, 0x82000
	s_addc_u32 s67, s59, 0
	s_mov_b32 m0, s30
	s_nop 0
	global_load_lds_dwordx4 v130, s[66:67]
	s_waitcnt vmcnt(10)
	s_barrier
	v_mfma_f32_16x16x32_bf16 v[48:51], v[184:187], v[152:155], v[48:51]
	v_mfma_f32_16x16x32_bf16 v[40:43], v[204:207], v[152:155], v[40:43]
	v_mfma_f32_16x16x32_bf16 v[32:35], v[184:187], v[160:163], v[32:35]
	v_mfma_f32_16x16x32_bf16 v[24:27], v[204:207], v[160:163], v[24:27]
	v_mfma_f32_16x16x32_bf16 v[16:19], v[184:187], v[168:171], v[16:19]
	v_mfma_f32_16x16x32_bf16 v[8:11], v[204:207], v[168:171], v[8:11]
	v_mfma_f32_16x16x32_bf16 v[4:7], v[184:187], v[176:179], v[4:7]
	v_mfma_f32_16x16x32_bf16 v[0:3], v[204:207], v[176:179], v[0:3]
	v_mfma_f32_16x16x32_bf16 v[48:51], v[200:203], v[156:159], v[48:51]
	v_mfma_f32_16x16x32_bf16 v[40:43], v[208:211], v[156:159], v[40:43]
	v_mfma_f32_16x16x32_bf16 v[32:35], v[200:203], v[164:167], v[32:35]
	v_mfma_f32_16x16x32_bf16 v[24:27], v[208:211], v[164:167], v[24:27]
	v_mfma_f32_16x16x32_bf16 v[16:19], v[200:203], v[172:175], v[16:19]
	v_mfma_f32_16x16x32_bf16 v[8:11], v[208:211], v[172:175], v[8:11]
	v_mfma_f32_16x16x32_bf16 v[4:7], v[200:203], v[180:183], v[4:7]
	v_mfma_f32_16x16x32_bf16 v[0:3], v[208:211], v[180:183], v[0:3]
	s_barrier
	ds_read_b128 v[136:139], v133 offset:32768
	ds_read_b128 v[140:143], v133 offset:33792
	ds_read_b128 v[144:147], v133 offset:34816
	ds_read_b128 v[148:151], v133 offset:35840
	ds_read_b128 v[152:155], v134 offset:32768
	ds_read_b128 v[156:159], v134 offset:33792
	ds_read_b128 v[160:163], v134 offset:34816
	ds_read_b128 v[164:167], v134 offset:35840
	ds_read_b128 v[168:171], v134 offset:36864
	ds_read_b128 v[172:175], v134 offset:37888
	ds_read_b128 v[176:179], v134 offset:38912
	ds_read_b128 v[180:183], v134 offset:39936
	s_add_u32 s66, s54, 0x80000
	s_addc_u32 s67, s55, 0
	s_mov_b32 m0, s34
	s_nop 0
	global_load_lds_dwordx4 v130, s[66:67]
	s_add_u32 s66, s54, 0x82000
	s_addc_u32 s67, s55, 0
	s_mov_b32 m0, s37
	s_nop 0
	global_load_lds_dwordx4 v130, s[66:67]
	s_waitcnt lgkmcnt(8)
	s_waitcnt vmcnt(10)
	s_barrier
; #define PG8_STAGE(bufoff, gbase, hoff, imm) do { _Pragma("unroll") for (int _i = 0; _i < 2; ++_i) { \
;         asm volatile("s_mov_b32 m0, %0\n\ts_nop 0\n\tglobal_load_lds_dwordx4 %1, %2" \
;             :: "s"(lds0 + (unsigned)((bufoff) + _i * 8192)), "v"(voff0), "s"((const char*)(gbase) + (size_t)(hoff) + (size_t)(_i * 8192)) : "memory"); } } while (0)
; #define PG8_LDA(dst, b, h) do { _Pragma("unroll") for (int m = 0; m < 4; ++m) _Pragma("unroll") for (int k = 0; k < 2; ++k) dst[m][k] = *(const LAS bf16x8*)(lds + PG8_SA(b, h) + aoff + m * 2048 + k * 1024); } while (0)
; #define PG8_LDB(dst, b, h) do { _Pragma("unroll") for (int n = 0; n < 2; ++n) _Pragma("unroll") for (int k = 0; k < 2; ++k) dst[n][k] = *(const LAS bf16x8*)(lds + PG8_SB(b, h) + boff + n * 2048 + k * 1024); } while (0)
; #define PG8_MMA(ai, bj, At, Bt) do { __builtin_amdgcn_s_setprio(1); _Pragma("unroll") for (int m = 0; m < 4; ++m) _Pragma("unroll") for (int n = 0; n < 2; ++n) _Pragma("unroll") for (int k = 0; k < 2; ++k) \
;         acc[ai][bj][m][n] = __builtin_amdgcn_mfma_f32_16x16x32_bf16(Bt[n][k], At[m][k], acc[ai][bj][m][n], 0, 0, 0); __builtin_amdgcn_s_setprio(0); } while (0)
; #define PG8_WAIT_V(n) asm volatile("s_waitcnt vmcnt(" #n ")" ::: "memory")
; #define PG8_WAIT_L(n) asm volatile("s_waitcnt lgkmcnt(" #n ")" ::: "memory")
; #define PG8_BAR __builtin_amdgcn_s_barrier()
; #define PG8_SCHED __builtin_amdgcn_sched_barrier(0)
; template <class Epi>
; __device__ __forceinline__ void gemm_phase(LAS unsigned char* lds, const Gemm g, const StaticOrder& S, const Epi& E) {
;     ...
;             PG8_WAIT_L(8); PG8_BAR; PG8_WAIT_L(0); PG8_MMA(0, 0, At, B0); PG8_BAR; PG8_SCHED;
;             PG8_LDB(B1, 1, 1); PG8_STAGE(PG8_SB(1, 0), b2 + KS, 0, 0);
;             PG8_BAR; PG8_WAIT_L(0); PG8_MMA(0, 1, At, B1); PG8_BAR;
;             PG8_LDA(At, 1, 1); PG8_STAGE(PG8_SA(1, 0), a2 + KS, 0, 0);
;             PG8_BAR; PG8_WAIT_L(0); PG8_MMA(1, 0, At, B0); PG8_BAR; PG8_SCHED;
;             PG8_STAGE(PG8_SB(1, 1), b2 + KS, hB, 0);
;             PG8_WAIT_V(6); PG8_BAR; PG8_MMA(1, 1, At, B1); PG8_BAR;
	s_waitcnt lgkmcnt(7)
	v_mfma_f32_16x16x32_bf16 v[124:127], v[136:139], v[152:155], v[124:127]
	v_mfma_f32_16x16x32_bf16 v[120:123], v[144:147], v[152:155], v[120:123]
	s_waitcnt lgkmcnt(5)
	v_mfma_f32_16x16x32_bf16 v[116:119], v[136:139], v[160:163], v[116:119]
	v_mfma_f32_16x16x32_bf16 v[108:111], v[144:147], v[160:163], v[108:111]
	s_waitcnt lgkmcnt(3)
	v_mfma_f32_16x16x32_bf16 v[100:103], v[136:139], v[168:171], v[100:103]
	v_mfma_f32_16x16x32_bf16 v[92:95], v[144:147], v[168:171], v[92:95]
	s_waitcnt lgkmcnt(1)
	v_mfma_f32_16x16x32_bf16 v[84:87], v[136:139], v[176:179], v[84:87]
	v_mfma_f32_16x16x32_bf16 v[76:79], v[144:147], v[176:179], v[76:79]
	v_mfma_f32_16x16x32_bf16 v[124:127], v[140:143], v[156:159], v[124:127]
	v_mfma_f32_16x16x32_bf16 v[120:123], v[148:151], v[156:159], v[120:123]
	v_mfma_f32_16x16x32_bf16 v[116:119], v[140:143], v[164:167], v[116:119]
	v_mfma_f32_16x16x32_bf16 v[108:111], v[148:151], v[164:167], v[108:111]
	v_mfma_f32_16x16x32_bf16 v[100:103], v[140:143], v[172:175], v[100:103]
	v_mfma_f32_16x16x32_bf16 v[92:95], v[148:151], v[172:175], v[92:95]
	s_waitcnt lgkmcnt(0)
	v_mfma_f32_16x16x32_bf16 v[84:87], v[140:143], v[180:183], v[84:87]
	v_mfma_f32_16x16x32_bf16 v[76:79], v[148:151], v[180:183], v[76:79]
	s_barrier
	ds_read_b128 v[184:187], v133 offset:49152
	ds_read_b128 v[200:203], v133 offset:50176
	ds_read_b128 v[204:207], v133 offset:51200
	ds_read_b128 v[208:211], v133 offset:52224
	s_add_u32 s66, s58, 0x4000
	s_addc_u32 s67, s59, 0
	s_mov_b32 m0, s38
	s_nop 0
	global_load_lds_dwordx4 v130, s[66:67]
	s_add_u32 s66, s58, 0x6000
	s_addc_u32 s67, s59, 0
	s_mov_b32 m0, s39
	s_nop 0
	global_load_lds_dwordx4 v130, s[66:67]
	s_waitcnt vmcnt(10)
	s_barrier
	s_waitcnt lgkmcnt(3)
	v_mfma_f32_16x16x32_bf16 v[112:115], v[184:187], v[152:155], v[112:115]
	s_waitcnt lgkmcnt(1)
	v_mfma_f32_16x16x32_bf16 v[104:107], v[204:207], v[152:155], v[104:107]
	v_mfma_f32_16x16x32_bf16 v[96:99], v[184:187], v[160:163], v[96:99]
	v_mfma_f32_16x16x32_bf16 v[88:91], v[204:207], v[160:163], v[88:91]
	v_mfma_f32_16x16x32_bf16 v[80:83], v[184:187], v[168:171], v[80:83]
	v_mfma_f32_16x16x32_bf16 v[72:75], v[204:207], v[168:171], v[72:75]
	v_mfma_f32_16x16x32_bf16 v[68:71], v[184:187], v[176:179], v[68:71]
	v_mfma_f32_16x16x32_bf16 v[64:67], v[204:207], v[176:179], v[64:67]
	v_mfma_f32_16x16x32_bf16 v[112:115], v[200:203], v[156:159], v[112:115]
	s_waitcnt lgkmcnt(0)
	v_mfma_f32_16x16x32_bf16 v[104:107], v[208:211], v[156:159], v[104:107]
	v_mfma_f32_16x16x32_bf16 v[96:99], v[200:203], v[164:167], v[96:99]
	v_mfma_f32_16x16x32_bf16 v[88:91], v[208:211], v[164:167], v[88:91]
	v_mfma_f32_16x16x32_bf16 v[80:83], v[200:203], v[172:175], v[80:83]
	v_mfma_f32_16x16x32_bf16 v[72:75], v[208:211], v[172:175], v[72:75]
	v_mfma_f32_16x16x32_bf16 v[68:71], v[200:203], v[180:183], v[68:71]
	v_mfma_f32_16x16x32_bf16 v[64:67], v[208:211], v[180:183], v[64:67]
	s_barrier
	ds_read_b128 v[152:155], v134 offset:49152
	ds_read_b128 v[156:159], v134 offset:50176
	ds_read_b128 v[160:163], v134 offset:51200
	ds_read_b128 v[164:167], v134 offset:52224
	ds_read_b128 v[168:171], v134 offset:53248
	ds_read_b128 v[172:175], v134 offset:54272
	ds_read_b128 v[176:179], v134 offset:55296
	ds_read_b128 v[180:183], v134 offset:56320
	s_add_u32 s66, s54, 0x4000
	s_addc_u32 s67, s55, 0
	s_mov_b32 m0, s40
	s_nop 0
	global_load_lds_dwordx4 v130, s[66:67]
	s_add_u32 s54, s54, 0x6000
	s_addc_u32 s55, s55, 0
	s_mov_b32 m0, s41
	s_nop 0
	global_load_lds_dwordx4 v130, s[54:55]
	s_barrier
	s_waitcnt lgkmcnt(7)
	v_mfma_f32_16x16x32_bf16 v[60:63], v[136:139], v[152:155], v[60:63]
	v_mfma_f32_16x16x32_bf16 v[56:59], v[144:147], v[152:155], v[56:59]
	s_waitcnt lgkmcnt(5)
	v_mfma_f32_16x16x32_bf16 v[52:55], v[136:139], v[160:163], v[52:55]
	v_mfma_f32_16x16x32_bf16 v[44:47], v[144:147], v[160:163], v[44:47]
	s_waitcnt lgkmcnt(3)
	v_mfma_f32_16x16x32_bf16 v[36:39], v[136:139], v[168:171], v[36:39]
	v_mfma_f32_16x16x32_bf16 v[28:31], v[144:147], v[168:171], v[28:31]
	s_waitcnt lgkmcnt(1)
	v_mfma_f32_16x16x32_bf16 v[20:23], v[136:139], v[176:179], v[20:23]
	v_mfma_f32_16x16x32_bf16 v[12:15], v[144:147], v[176:179], v[12:15]
	v_mfma_f32_16x16x32_bf16 v[60:63], v[140:143], v[156:159], v[60:63]
	v_mfma_f32_16x16x32_bf16 v[56:59], v[148:151], v[156:159], v[56:59]
	v_mfma_f32_16x16x32_bf16 v[52:55], v[140:143], v[164:167], v[52:55]
	v_mfma_f32_16x16x32_bf16 v[44:47], v[148:151], v[164:167], v[44:47]
	v_mfma_f32_16x16x32_bf16 v[36:39], v[140:143], v[172:175], v[36:39]
	v_mfma_f32_16x16x32_bf16 v[28:31], v[148:151], v[172:175], v[28:31]
	s_waitcnt lgkmcnt(0)
	v_mfma_f32_16x16x32_bf16 v[20:23], v[140:143], v[180:183], v[20:23]
	v_mfma_f32_16x16x32_bf16 v[12:15], v[148:151], v[180:183], v[12:15]
	s_barrier
	s_add_u32 s54, s58, 0x84000
	s_addc_u32 s55, s59, 0
	s_mov_b32 m0, s42
	s_nop 0
	global_load_lds_dwordx4 v130, s[54:55]
	s_add_u32 s54, s58, 0x86000
	s_addc_u32 s55, s59, 0
	s_mov_b32 m0, s43
	s_nop 0
	global_load_lds_dwordx4 v130, s[54:55]
	s_waitcnt vmcnt(10)
	s_barrier
; #define LAS __attribute__((address_space(3)))
; __device__ __forceinline__ unsigned cvt_pk_bf16(float lo, float hi) { unsigned r; asm volatile("v_cvt_pk_bf16_f32 %0, %1, %2" : "=v"(r) : "v"(lo), "v"(hi)); return r; }
; #define PG8_WAIT_V(n) asm volatile("s_waitcnt vmcnt(" #n ")" ::: "memory")
; #define PG8_BAR __builtin_amdgcn_s_barrier()
; template <class Epi>
; __device__ __forceinline__ void gemm_phase(LAS unsigned char* lds, const Gemm g, const StaticOrder& S, const Epi& E) {
;     ...
;     PG8_WAIT_V(0);
;     if (wr == 0) PG8_BAR;
;     PG8_BAR;
;     __device__ __forceinline__ void operator()(f32x4 (&acc)[2][2][4][2], const Unit& u, int wr, int wc, int fr, int fq, LAS unsigned char*) const {
;         const int row0 = u.pm * BM + wr * 64 + fr, col0 = u.pn * BM + wc * 32 + 8 * fq;
; #pragma unroll
;         for (int ai = 0; ai < 2; ++ai)
; #pragma unroll
;             for (int m = 0; m < 4; ++m) { bf16_t* rowp = O + (size_t)(row0 + ai * HALF + m * 16) * ldc + col0;
; #pragma unroll
;                 for (int bj = 0; bj < 2; ++bj) { const f32x4 v0 = acc[ai][bj][m][0], v1 = acc[ai][bj][m][1];
;                     u32x4 w; w.x = cvt_pk_bf16(v0[0], v0[1]); w.y = cvt_pk_bf16(v0[2], v0[3]); w.z = cvt_pk_bf16(v1[0], v1[1]); w.w = cvt_pk_bf16(v1[2], v1[3]);
;                     *(u32x4*)(rowp + bj * HALF) = w; } }
;     }
	v_mfma_f32_16x16x32_bf16 v[48:51], v[184:187], v[152:155], v[48:51]
	v_mfma_f32_16x16x32_bf16 v[40:43], v[204:207], v[152:155], v[40:43]
	v_mfma_f32_16x16x32_bf16 v[32:35], v[184:187], v[160:163], v[32:35]
	v_mfma_f32_16x16x32_bf16 v[24:27], v[204:207], v[160:163], v[24:27]
	v_mfma_f32_16x16x32_bf16 v[16:19], v[184:187], v[168:171], v[16:19]
	v_mfma_f32_16x16x32_bf16 v[8:11], v[204:207], v[168:171], v[8:11]
	v_mfma_f32_16x16x32_bf16 v[4:7], v[184:187], v[176:179], v[4:7]
	v_mfma_f32_16x16x32_bf16 v[0:3], v[204:207], v[176:179], v[0:3]
	v_mfma_f32_16x16x32_bf16 v[48:51], v[200:203], v[156:159], v[48:51]
	v_mfma_f32_16x16x32_bf16 v[40:43], v[208:211], v[156:159], v[40:43]
	v_mfma_f32_16x16x32_bf16 v[32:35], v[200:203], v[164:167], v[32:35]
	v_mfma_f32_16x16x32_bf16 v[24:27], v[208:211], v[164:167], v[24:27]
	v_mfma_f32_16x16x32_bf16 v[16:19], v[200:203], v[172:175], v[16:19]
	v_mfma_f32_16x16x32_bf16 v[8:11], v[208:211], v[172:175], v[8:11]
	v_mfma_f32_16x16x32_bf16 v[4:7], v[200:203], v[180:183], v[4:7]
	v_mfma_f32_16x16x32_bf16 v[0:3], v[208:211], v[180:183], v[0:3]
	s_add_i32 s65, s65, 2
	s_add_u32 s63, s63, 0x8000
	s_addc_u32 s64, s64, 0
	s_cmp_gt_u32 s65, 29
	s_mov_b64 s[54:55], s[56:57]
	s_barrier
	s_cbranch_scc0 .LBB0_434
	v_lshl_add_u32 v136, s62, 8, v131
	v_lshl_or_b32 v128, s61, 8, v132
	v_ashrrev_i32_e32 v137, 31, v136
	v_ashrrev_i32_e32 v129, 31, v128
	v_lshlrev_b64 v[138:139], 12, v[136:137]
	v_lshl_add_u64 v[138:139], s[2:3], 0, v[138:139]
	v_lshlrev_b64 v[140:141], 1, v[128:129]
	v_lshl_add_u64 v[128:129], v[138:139], 0, v[140:141]
	v_cvt_pk_bf16_f32 v124, v124, v125
	v_cvt_pk_bf16_f32 v125, v126, v127
	v_cvt_pk_bf16_f32 v126, v120, v121
	v_cvt_pk_bf16_f32 v127, v122, v123
	global_store_dwordx4 v[128:129], v[124:127], off
	v_cvt_pk_bf16_f32 v112, v112, v113
	v_cvt_pk_bf16_f32 v113, v114, v115
	v_cvt_pk_bf16_f32 v114, v104, v105
	v_or_b32_e32 v104, 16, v136
	v_ashrrev_i32_e32 v105, 31, v104
	v_lshlrev_b64 v[104:105], 12, v[104:105]
	v_lshl_add_u64 v[104:105], s[2:3], 0, v[104:105]
	v_cvt_pk_bf16_f32 v115, v106, v107
	global_store_dwordx4 v[128:129], v[112:115], off offset:256
	s_mov_b64 s[0:1], 0x80000
	s_mov_b32 s61, s6
	v_lshl_add_u64 v[112:113], v[104:105], 0, v[140:141]
	v_cvt_pk_bf16_f32 v104, v116, v117
	v_cvt_pk_bf16_f32 v105, v118, v119
	v_cvt_pk_bf16_f32 v106, v108, v109
	v_cvt_pk_bf16_f32 v107, v110, v111
	global_store_dwordx4 v[112:113], v[104:107], off
	v_cvt_pk_bf16_f32 v96, v96, v97
	v_cvt_pk_bf16_f32 v97, v98, v99
	v_cvt_pk_bf16_f32 v98, v88, v89
	v_or_b32_e32 v88, 32, v136
	v_ashrrev_i32_e32 v89, 31, v88
	v_lshlrev_b64 v[88:89], 12, v[88:89]
	v_lshl_add_u64 v[88:89], s[2:3], 0, v[88:89]
	v_cvt_pk_bf16_f32 v99, v90, v91
	global_store_dwordx4 v[112:113], v[96:99], off offset:256
	s_mov_b32 s62, s8
	s_mov_b64 s[56:57], s[52:53]
	v_lshl_add_u64 v[96:97], v[88:89], 0, v[140:141]
	v_cvt_pk_bf16_f32 v88, v100, v101
	v_cvt_pk_bf16_f32 v89, v102, v103
	v_cvt_pk_bf16_f32 v90, v92, v93
	v_cvt_pk_bf16_f32 v91, v94, v95
	global_store_dwordx4 v[96:97], v[88:91], off
	v_cvt_pk_bf16_f32 v80, v80, v81
	v_cvt_pk_bf16_f32 v81, v82, v83
	v_cvt_pk_bf16_f32 v82, v72, v73
	v_or_b32_e32 v72, 48, v136
	v_ashrrev_i32_e32 v73, 31, v72
	v_lshlrev_b64 v[72:73], 12, v[72:73]
	v_lshl_add_u64 v[72:73], s[2:3], 0, v[72:73]
	v_cvt_pk_bf16_f32 v83, v74, v75
	global_store_dwordx4 v[96:97], v[80:83], off offset:256
	s_mov_b64 s[54:55], s[10:11]
	s_nop 0
	v_lshl_add_u64 v[80:81], v[72:73], 0, v[140:141]
	v_cvt_pk_bf16_f32 v72, v84, v85
	v_cvt_pk_bf16_f32 v73, v86, v87
	v_cvt_pk_bf16_f32 v74, v76, v77
	v_cvt_pk_bf16_f32 v75, v78, v79
	global_store_dwordx4 v[80:81], v[72:75], off
	v_cvt_pk_bf16_f32 v68, v68, v69
	v_cvt_pk_bf16_f32 v69, v70, v71
	v_cvt_pk_bf16_f32 v70, v64, v65
	v_cvt_pk_bf16_f32 v71, v66, v67
	global_store_dwordx4 v[80:81], v[68:71], off offset:256
	v_cvt_pk_bf16_f32 v60, v60, v61
	v_cvt_pk_bf16_f32 v61, v62, v63
	v_cvt_pk_bf16_f32 v62, v56, v57
	v_add_co_u32_e32 v56, vcc, s93, v128
	v_lshl_add_u64 v[64:65], v[128:129], 0, s[0:1]
	s_nop 0
	v_addc_co_u32_e32 v57, vcc, 0, v129, vcc
	v_cvt_pk_bf16_f32 v63, v58, v59
	global_store_dwordx4 v[56:57], v[60:63], off
	v_cvt_pk_bf16_f32 v48, v48, v49
	v_cvt_pk_bf16_f32 v49, v50, v51
	v_cvt_pk_bf16_f32 v50, v40, v41
	v_cvt_pk_bf16_f32 v51, v42, v43
	global_store_dwordx4 v[64:65], v[48:51], off offset:256
	s_mov_b64 s[0:1], 0x90000
	v_cvt_pk_bf16_f32 v40, v52, v53
	v_cvt_pk_bf16_f32 v41, v54, v55
	v_cvt_pk_bf16_f32 v42, v44, v45
	v_add_co_u32_e32 v44, vcc, s33, v128
	v_lshl_add_u64 v[48:49], v[128:129], 0, s[0:1]
	s_nop 0
	v_addc_co_u32_e32 v45, vcc, 0, v129, vcc
	v_cvt_pk_bf16_f32 v43, v46, v47
	global_store_dwordx4 v[44:45], v[40:43], off
	v_cvt_pk_bf16_f32 v32, v32, v33
	v_cvt_pk_bf16_f32 v33, v34, v35
	v_cvt_pk_bf16_f32 v34, v24, v25
	v_cvt_pk_bf16_f32 v35, v26, v27
	global_store_dwordx4 v[48:49], v[32:35], off offset:256
	s_mov_b64 s[0:1], 0xa0000
	v_cvt_pk_bf16_f32 v24, v36, v37
	v_cvt_pk_bf16_f32 v25, v38, v39
	v_cvt_pk_bf16_f32 v26, v28, v29
	v_add_co_u32_e32 v28, vcc, s18, v128
	v_lshl_add_u64 v[32:33], v[128:129], 0, s[0:1]
	s_nop 0
	v_addc_co_u32_e32 v29, vcc, 0, v129, vcc
	v_cvt_pk_bf16_f32 v27, v30, v31
	global_store_dwordx4 v[28:29], v[24:27], off
	v_cvt_pk_bf16_f32 v16, v16, v17
	v_cvt_pk_bf16_f32 v17, v18, v19
	v_cvt_pk_bf16_f32 v18, v8, v9
	v_cvt_pk_bf16_f32 v19, v10, v11
	global_store_dwordx4 v[32:33], v[16:19], off offset:256
	v_cvt_pk_bf16_f32 v8, v20, v21
	v_cvt_pk_bf16_f32 v9, v22, v23
	v_cvt_pk_bf16_f32 v10, v12, v13
	v_add_co_u32_e32 v12, vcc, s19, v128
	s_mov_b64 s[0:1], 0xb0000
	s_nop 0
	v_addc_co_u32_e32 v13, vcc, 0, v129, vcc
	v_lshl_add_u64 v[16:17], v[128:129], 0, s[0:1]
	s_and_b64 vcc, exec, s[4:5]
	v_cvt_pk_bf16_f32 v11, v14, v15
	global_store_dwordx4 v[12:13], v[8:11], off
	v_cvt_pk_bf16_f32 v4, v4, v5
	v_cvt_pk_bf16_f32 v5, v6, v7
	v_cvt_pk_bf16_f32 v6, v0, v1
	v_cvt_pk_bf16_f32 v7, v2, v3
	global_store_dwordx4 v[16:17], v[4:7], off offset:256
	s_cbranch_vccz .LBB0_427
	s_waitcnt vmcnt(0)
	s_cmpk_gt_u32 s16, 0xff
	v_readlane_b32 s38, v255, 44
	s_cbranch_scc1 .LBB0_438
	s_barrier

; #define PG8_STAGE(bufoff, gbase, hoff, imm) do { _Pragma("unroll") for (int _i = 0; _i < 2; ++_i) { \
;         asm volatile("s_mov_b32 m0, %0\n\ts_nop 0\n\tglobal_load_lds_dwordx4 %1, %2" \
;             :: "s"(lds0 + (unsigned)((bufoff) + _i * 8192)), "v"(voff0), "s"((const char*)(gbase) + (size_t)(hoff) + (size_t)(_i * 8192)) : "memory"); } } while (0)
; #define PG8_WAIT_V(n) asm volatile("s_waitcnt vmcnt(" #n ")" ::: "memory")
; #define PG8_BAR __builtin_amdgcn_s_barrier()
; template <class Epi>
; __device__ __forceinline__ void gemm_phase(LAS unsigned char* lds, const Gemm g, const StaticOrder& S, const Epi& E) {
;     ...
;     const int wid = __builtin_amdgcn_readfirstlane(tid >> 6), lane = tid & 63, wr = wid >> 2, wc = wid & 3, fr = lane & 15, fq = lane >> 4;
;     const int K = g.K, nt = K / BK;
;     const unsigned voff0 = (unsigned)(tid * 16);
;     const unsigned hA = (unsigned)(g.lda * 256), hB = (unsigned)(K * 256);
;     constexpr int KS = 16384;
;     const size_t tstepA = (size_t)BM * g.lda * 2, tstepB = (size_t)BM * K * 2;
;     const unsigned lds0 = (unsigned)__builtin_amdgcn_readfirstlane((int)((unsigned)(size_t)lds + (unsigned)wid * 1024u));
;     const int aoff = lds_byte(wr * 64 + fr, fq * 8), boff = lds_byte(wc * 32 + fr, fq * 8);
;     ...
;     PG8_STAGE(PG8_SB(0, 0), cB, 0, 0); PG8_STAGE(PG8_SA(0, 0), cA, 0, 0); PG8_STAGE(PG8_SB(0, 1), cB, hB, 0); PG8_STAGE(PG8_SA(0, 1), cA, hA, 0);
;     if (wr == 1) PG8_BAR;
;     PG8_WAIT_V(4); PG8_BAR;
;     PG8_STAGE(PG8_SB(1, 0), cB + KS, 0, 0); PG8_STAGE(PG8_SA(1, 0), cA + KS, 0, 0); PG8_STAGE(PG8_SB(1, 1), cB + KS, hB, 0);
;     PG8_WAIT_V(6); PG8_BAR;
.LBB0_497:
	s_add_u32 s10, s56, 0x1a630000
	s_addc_u32 s11, s57, 0
	s_add_u32 s52, s56, 0x12630000
	s_addc_u32 s53, s57, 0
	s_add_u32 s54, s56, 0x28630000
	s_addc_u32 s55, s57, 0
	s_add_u32 s56, s56, 0x29130000
	v_and_b32_e32 v169, 15, v0
	v_lshrrev_b32_e32 v1, 1, v0
	v_and_b32_e32 v171, 48, v0
	v_lshlrev_b32_e32 v0, 2, v0
	s_addc_u32 s57, s57, 0
	s_and_b32 s48, s8, 3
	s_lshl_b32 s9, s1, 13
	v_lshl_or_b32 v2, v169, 6, v171
	v_and_b32_e32 v0, 32, v0
	s_lshl_b32 s37, s1, 6
	v_bitop3_b32 v3, v2, s9, v0 bitop3:0xde
	s_lshl_b32 s9, s48, 12
	s_add_i32 s38, s24, 0x18000
	s_add_u32 s40, s80, 0x4000
	s_addc_u32 s41, s81, 0
	s_add_i32 s39, s24, 0x1a000
	s_waitcnt vmcnt(4)
	s_barrier
	s_mov_b32 m0, s38
	s_nop 0
	global_load_lds_dwordx4 v168, s[40:41]
	s_add_u32 s40, s80, 0x6000
	s_addc_u32 s41, s81, 0
	s_mov_b32 m0, s39
	s_nop 0
	global_load_lds_dwordx4 v168, s[40:41]
	s_add_i32 s40, s24, 0x8000
	s_add_u32 s42, s78, 0x4000
	s_addc_u32 s43, s79, 0
	s_add_i32 s41, s24, 0xa000
	s_mov_b32 m0, s40
	s_nop 0
	global_load_lds_dwordx4 v168, s[42:43]
	s_add_u32 s42, s78, 0x6000
	s_addc_u32 s43, s79, 0
	s_mov_b32 m0, s41
	s_nop 0
	global_load_lds_dwordx4 v168, s[42:43]
	s_add_i32 s42, s24, 0x1c000
	s_add_u32 s50, s80, 0x84000
	s_addc_u32 s51, s81, 0
	s_add_i32 s43, s24, 0x1e000
	s_mov_b32 m0, s42
	s_nop 0
	global_load_lds_dwordx4 v168, s[50:51]
	s_add_u32 s50, s80, 0x86000
	s_addc_u32 s51, s81, 0
	s_cmp_lt_i32 s8, 4
	v_readlane_b32 s49, v255, 38
	s_cselect_b64 s[58:59], -1, 0
	s_add_i32 s12, s49, s12
	v_bitop3_b32 v0, v2, s9, v0 bitop3:0xde
	s_ashr_i32 s9, s8, 31
	s_add_i32 s86, s12, 0x2000
	s_add_i32 s87, s24, 0xc000
	s_lshl_b32 s12, s1, 11
	s_cmp_gt_i32 s1, 0
	s_cselect_b64 s[60:61], -1, 0
	s_cmp_gt_i32 s1, -2
	s_cselect_b64 s[64:65], -1, 0
	s_add_i32 s12, s49, s12
	s_cmpk_lt_u32 s0, 0x100
	s_mov_b32 m0, s43
	s_nop 0
	global_load_lds_dwordx4 v168, s[50:51]
	s_cselect_b64 s[50:51], -1, 0
	s_bfe_u32 s89, s0, 0x10006
	s_lshl_b32 s0, s1, 3
	s_and_b32 s0, s0, 8
	v_cmp_gt_u32_e32 vcc, 2, v169
	s_or_b32 s0, s0, s89
	v_writelane_b32 v255, s50, 48
	s_and_b64 s[66:67], s[50:51], vcc
	s_lshl_b32 s92, s0, 10
	s_add_i32 s96, s24, 0xe000
	s_lshl_b64 s[0:1], s[8:9], 13
	v_and_b32_e32 v1, 24, v1
	s_add_u32 s0, s4, s0
	v_writelane_b32 v255, s51, 49
	s_addc_u32 s1, s5, s1
	v_lshl_or_b32 v173, s48, 5, v1
	s_cmp_eq_u32 s8, 3
	v_lshlrev_b32_e32 v1, 2, v173
	v_readlane_b32 s8, v255, 39
	v_readlane_b32 s9, v255, 40
	v_readlane_b32 s48, v255, 41
	v_readlane_b32 s49, v255, 42
	s_waitcnt vmcnt(6)
	v_lshlrev_b32_e32 v2, 10, v169
	v_add_u32_e32 v174, s12, v1
	v_add_u32_e32 v180, s8, v1
	v_add_u32_e32 v181, s9, v1
	v_add_u32_e32 v182, s48, v1
	v_add_u32_e32 v183, s49, v1
	v_or_b32_e32 v1, 16, v1
	s_waitcnt vmcnt(0)
	v_add_u32_e32 v4, v174, v2
	v_or_b32_e32 v184, 0xfffff800, v2
	v_add_u32_e32 v185, s8, v1
	v_add_u32_e32 v186, s9, v1
	v_add_u32_e32 v187, s48, v1
	v_add_u32_e32 v200, s49, v1
	v_add_u32_e32 v1, s12, v1
	s_cselect_b32 s97, s7, s1
	s_cselect_b32 s12, s6, s0
	v_readlane_b32 s6, v255, 23
	v_or_b32_e32 v170, s37, v169
	v_and_b32_e32 v172, 0x1f0, v168
	s_mov_b32 s88, 0
	v_cmp_lt_u32_e64 s[4:5], 13, v169
	v_add_u32_e32 v175, 0xffffc800, v4
	v_add_u32_e32 v176, 0xffffc810, v4
	v_add_u32_e32 v177, 0xffffd800, v4
	v_add_u32_e32 v178, 0xffffd810, v4
	v_add_u32_e32 v179, -14, v169
	v_add_u32_e32 v201, v1, v184
	v_add_u32_e32 v202, 0x10000, v0
	v_add_u32_e32 v203, 0, v3
	v_readlane_b32 s0, v255, 21
	s_mov_b32 s50, s6
	s_barrier
	v_readlane_b32 s7, v255, 24
	s_branch .LBB0_499

; #define PG8_STAGE(bufoff, gbase, hoff, imm) do { _Pragma("unroll") for (int _i = 0; _i < 2; ++_i) { \
;         asm volatile("s_mov_b32 m0, %0\n\ts_nop 0\n\tglobal_load_lds_dwordx4 %1, %2" \
;             :: "s"(lds0 + (unsigned)((bufoff) + _i * 8192)), "v"(voff0), "s"((const char*)(gbase) + (size_t)(hoff) + (size_t)(_i * 8192)) : "memory"); } } while (0)
; #define PG8_LDA(dst, b, h) do { _Pragma("unroll") for (int m = 0; m < 4; ++m) _Pragma("unroll") for (int k = 0; k < 2; ++k) dst[m][k] = *(const LAS bf16x8*)(lds + PG8_SA(b, h) + aoff + m * 2048 + k * 1024); } while (0)
; #define PG8_LDB(dst, b, h) do { _Pragma("unroll") for (int n = 0; n < 2; ++n) _Pragma("unroll") for (int k = 0; k < 2; ++k) dst[n][k] = *(const LAS bf16x8*)(lds + PG8_SB(b, h) + boff + n * 2048 + k * 1024); } while (0)
; #define PG8_WAIT_L(n) asm volatile("s_waitcnt lgkmcnt(" #n ")" ::: "memory")
; #define PG8_BAR __builtin_amdgcn_s_barrier()
; #define PG8_SCHED __builtin_amdgcn_sched_barrier(0)
; template <class Epi>
; __device__ __forceinline__ void gemm_phase(LAS unsigned char* lds, const Gemm g, const StaticOrder& S, const Epi& E) {
;     ...
;         const bool has_next = S.next(ui + 1, nxt);
;         const char* nA = has_next ? (const char*)g.A + (size_t)nxt.pm * tstepA + (size_t)(nxt.pn >> g.gshift) * g.gstride : cA;
;         const char* nB = has_next ? (const char*)g.Bt + (size_t)nxt.pn * tstepB : cB;
;         for (int t = 0; t < nt; t += 2) {
;             const bool last = (t == nt - 2);
;             if (last) E.pre(cur, wid, lane, (unsigned)(size_t)(lds + STAGE_BYTES));
;             const char* aT = cA + (size_t)t * KS;
;             const char* a2 = last ? nA : aT + 2 * KS; const char* b2 = last ? nB : cB + (size_t)(t + 2) * KS;
;             PG8_LDB(B0, 0, 0); PG8_SCHED; PG8_LDA(At, 0, 0); PG8_STAGE(PG8_SA(1, 1), aT + KS, hA, 0);
;             PG8_WAIT_L(8); PG8_BAR; PG8_WAIT_L(0); PG8_MMA(0, 0, At, B0); PG8_BAR; PG8_SCHED;
;             PG8_LDB(B1, 0, 1); PG8_STAGE(PG8_SB(0, 0), b2, 0, 0);
;             PG8_BAR; PG8_WAIT_L(0); PG8_MMA(0, 1, At, B1); PG8_BAR;
;             PG8_LDA(At, 0, 1); PG8_STAGE(PG8_SA(0, 0), a2, 0, 0);
;             PG8_BAR; PG8_WAIT_L(0); PG8_MMA(1, 0, At, B0); PG8_BAR; PG8_SCHED;
.LBB0_505:
	s_ashr_i32 s71, s70, 31
	v_cmp_lt_i64_e32 vcc, s[8:9], v[194:195]
	s_lshl_b64 s[8:9], s[70:71], 20
	s_add_u32 s72, s16, s8
	s_addc_u32 s73, s17, s9
	s_and_b64 s[8:9], vcc, exec
	s_cselect_b32 s51, s73, s79
	s_cselect_b32 s71, s72, s78
	s_ashr_i32 s69, s68, 31
	s_lshl_b64 s[8:9], s[68:69], 20
	s_add_u32 s74, s21, s8
	s_addc_u32 s75, s22, s9
	s_and_b64 s[8:9], vcc, exec
	s_cselect_b32 s69, s75, s81
	s_cselect_b32 s62, s74, s80
	s_lshl_b32 s8, s0, 7
	s_ashr_i32 s9, s8, 31
	s_lshl_b64 s[0:1], s[8:9], 2
	s_add_u32 s76, s12, s0
	s_addc_u32 s77, s97, s1
	s_add_u32 s9, s80, 0x8000
	s_addc_u32 s63, s81, 0
	s_mov_b32 s0, -2
	s_mov_b64 s[84:85], 0
	ds_read_b128 v[128:131], v202
	ds_read_b128 v[132:135], v202 offset:1024
	ds_read_b128 v[136:139], v202 offset:2048
	ds_read_b128 v[140:143], v202 offset:3072
	s_add_u32 s80, s78, 0x8000
	s_addc_u32 s81, s79, 0
	s_and_b64 s[82:83], s[84:85], exec
	s_cselect_b32 s83, s51, s81
	s_cselect_b32 s82, s71, s80
	ds_read_b128 v[144:147], v203
	ds_read_b128 v[148:151], v203 offset:1024
	ds_read_b128 v[152:155], v203 offset:2048
	ds_read_b128 v[156:159], v203 offset:3072
	ds_read_b128 v[160:163], v203 offset:4096
	ds_read_b128 v[164:167], v203 offset:5120
	ds_read_b128 v[204:207], v203 offset:6144
	ds_read_b128 v[208:211], v203 offset:7168
	s_add_u32 s48, s78, 0x84000
	s_addc_u32 s49, s79, 0
	s_mov_b32 m0, s87
	s_nop 0
	global_load_lds_dwordx4 v168, s[48:49]
	s_add_u32 s48, s78, 0x86000
	s_addc_u32 s49, s79, 0
	s_mov_b32 m0, s96
	s_nop 0
	global_load_lds_dwordx4 v168, s[48:49]
	s_waitcnt lgkmcnt(8)
	s_waitcnt vmcnt(10)
	s_barrier
	s_waitcnt lgkmcnt(7)
	v_mfma_f32_16x16x32_bf16 v[96:99], v[128:131], v[144:147], 0
	v_mfma_f32_16x16x32_bf16 v[44:47], v[136:139], v[144:147], 0
	s_waitcnt lgkmcnt(5)
	v_mfma_f32_16x16x32_bf16 v[92:95], v[128:131], v[152:155], 0
	v_mfma_f32_16x16x32_bf16 v[40:43], v[136:139], v[152:155], 0
	s_waitcnt lgkmcnt(3)
	v_mfma_f32_16x16x32_bf16 v[84:87], v[128:131], v[160:163], 0
	v_mfma_f32_16x16x32_bf16 v[36:39], v[136:139], v[160:163], 0
	s_waitcnt lgkmcnt(1)
	v_mfma_f32_16x16x32_bf16 v[124:127], v[128:131], v[204:207], 0
	v_mfma_f32_16x16x32_bf16 v[120:123], v[136:139], v[204:207], 0
	v_mfma_f32_16x16x32_bf16 v[96:99], v[132:135], v[148:151], v[96:99]
	v_mfma_f32_16x16x32_bf16 v[44:47], v[140:143], v[148:151], v[44:47]
	v_mfma_f32_16x16x32_bf16 v[92:95], v[132:135], v[156:159], v[92:95]
	v_mfma_f32_16x16x32_bf16 v[40:43], v[140:143], v[156:159], v[40:43]
	v_mfma_f32_16x16x32_bf16 v[84:87], v[132:135], v[164:167], v[84:87]
	v_mfma_f32_16x16x32_bf16 v[36:39], v[140:143], v[164:167], v[36:39]
	s_waitcnt lgkmcnt(0)
	v_mfma_f32_16x16x32_bf16 v[124:127], v[132:135], v[208:211], v[124:127]
	v_mfma_f32_16x16x32_bf16 v[120:123], v[140:143], v[208:211], v[120:123]
	s_barrier
	ds_read_b128 v[212:215], v202 offset:16384
	ds_read_b128 v[236:239], v202 offset:17408
	ds_read_b128 v[240:243], v202 offset:18432
	ds_read_b128 v[244:247], v202 offset:19456
	s_and_b64 s[48:49], s[84:85], exec
	s_cselect_b32 s78, s62, s9
	s_cselect_b32 s79, s69, s63
	s_mov_b32 m0, s25
	s_nop 0
	global_load_lds_dwordx4 v168, s[78:79]
	s_add_u32 s48, s78, 0x2000
	s_addc_u32 s49, s79, 0
	s_mov_b32 m0, s26
	s_nop 0
	global_load_lds_dwordx4 v168, s[48:49]
	s_waitcnt vmcnt(10)
	s_barrier
	s_waitcnt lgkmcnt(3)
	v_mfma_f32_16x16x32_bf16 v[80:83], v[212:215], v[144:147], 0
	s_waitcnt lgkmcnt(1)
	v_mfma_f32_16x16x32_bf16 v[32:35], v[240:243], v[144:147], 0
	v_mfma_f32_16x16x32_bf16 v[76:79], v[212:215], v[152:155], 0
	v_mfma_f32_16x16x32_bf16 v[28:31], v[240:243], v[152:155], 0
	v_mfma_f32_16x16x32_bf16 v[72:75], v[212:215], v[160:163], 0
	v_mfma_f32_16x16x32_bf16 v[24:27], v[240:243], v[160:163], 0
	v_mfma_f32_16x16x32_bf16 v[116:119], v[212:215], v[204:207], 0
	v_mfma_f32_16x16x32_bf16 v[112:115], v[240:243], v[204:207], 0
	v_mfma_f32_16x16x32_bf16 v[80:83], v[236:239], v[148:151], v[80:83]
	s_waitcnt lgkmcnt(0)
	v_mfma_f32_16x16x32_bf16 v[32:35], v[244:247], v[148:151], v[32:35]
	v_mfma_f32_16x16x32_bf16 v[76:79], v[236:239], v[156:159], v[76:79]
	v_mfma_f32_16x16x32_bf16 v[28:31], v[244:247], v[156:159], v[28:31]
	v_mfma_f32_16x16x32_bf16 v[72:75], v[236:239], v[164:167], v[72:75]
	v_mfma_f32_16x16x32_bf16 v[24:27], v[244:247], v[164:167], v[24:27]
	v_mfma_f32_16x16x32_bf16 v[116:119], v[236:239], v[208:211], v[116:119]
	v_mfma_f32_16x16x32_bf16 v[112:115], v[244:247], v[208:211], v[112:115]
	s_barrier
	ds_read_b128 v[144:147], v203 offset:16384
	ds_read_b128 v[148:151], v203 offset:17408
	ds_read_b128 v[152:155], v203 offset:18432
	ds_read_b128 v[156:159], v203 offset:19456
	ds_read_b128 v[160:163], v203 offset:20480
	ds_read_b128 v[164:167], v203 offset:21504
	ds_read_b128 v[204:207], v203 offset:22528
	ds_read_b128 v[208:211], v203 offset:23552
	s_mov_b32 m0, s24
	s_nop 0
	global_load_lds_dwordx4 v168, s[82:83]
	s_add_u32 s48, s82, 0x2000
	s_addc_u32 s49, s83, 0
	s_mov_b32 m0, s27
	s_nop 0
	global_load_lds_dwordx4 v168, s[48:49]
	s_barrier
	s_waitcnt lgkmcnt(7)
	v_mfma_f32_16x16x32_bf16 v[68:71], v[128:131], v[144:147], 0
	v_mfma_f32_16x16x32_bf16 v[20:23], v[136:139], v[144:147], 0
	s_waitcnt lgkmcnt(5)
	v_mfma_f32_16x16x32_bf16 v[64:67], v[128:131], v[152:155], 0
	v_mfma_f32_16x16x32_bf16 v[16:19], v[136:139], v[152:155], 0
	s_waitcnt lgkmcnt(3)
	v_mfma_f32_16x16x32_bf16 v[60:63], v[128:131], v[160:163], 0
	v_mfma_f32_16x16x32_bf16 v[12:15], v[136:139], v[160:163], 0
	s_waitcnt lgkmcnt(1)
	v_mfma_f32_16x16x32_bf16 v[108:111], v[128:131], v[204:207], 0
	v_mfma_f32_16x16x32_bf16 v[104:107], v[136:139], v[204:207], 0
	v_mfma_f32_16x16x32_bf16 v[68:71], v[132:135], v[148:151], v[68:71]
	v_mfma_f32_16x16x32_bf16 v[20:23], v[140:143], v[148:151], v[20:23]
	v_mfma_f32_16x16x32_bf16 v[64:67], v[132:135], v[156:159], v[64:67]
	v_mfma_f32_16x16x32_bf16 v[16:19], v[140:143], v[156:159], v[16:19]
	v_mfma_f32_16x16x32_bf16 v[60:63], v[132:135], v[164:167], v[60:63]
	v_mfma_f32_16x16x32_bf16 v[12:15], v[140:143], v[164:167], v[12:15]
	s_waitcnt lgkmcnt(0)
	v_mfma_f32_16x16x32_bf16 v[108:111], v[132:135], v[208:211], v[108:111]
	v_mfma_f32_16x16x32_bf16 v[104:107], v[140:143], v[208:211], v[104:107]
	s_barrier
; #define PG8_STAGE(bufoff, gbase, hoff, imm) do { _Pragma("unroll") for (int _i = 0; _i < 2; ++_i) { \
;         asm volatile("s_mov_b32 m0, %0\n\ts_nop 0\n\tglobal_load_lds_dwordx4 %1, %2" \
;             :: "s"(lds0 + (unsigned)((bufoff) + _i * 8192)), "v"(voff0), "s"((const char*)(gbase) + (size_t)(hoff) + (size_t)(_i * 8192)) : "memory"); } } while (0)
; #define PG8_LDA(dst, b, h) do { _Pragma("unroll") for (int m = 0; m < 4; ++m) _Pragma("unroll") for (int k = 0; k < 2; ++k) dst[m][k] = *(const LAS bf16x8*)(lds + PG8_SA(b, h) + aoff + m * 2048 + k * 1024); } while (0)
; #define PG8_LDB(dst, b, h) do { _Pragma("unroll") for (int n = 0; n < 2; ++n) _Pragma("unroll") for (int k = 0; k < 2; ++k) dst[n][k] = *(const LAS bf16x8*)(lds + PG8_SB(b, h) + boff + n * 2048 + k * 1024); } while (0)
; #define PG8_MMA(ai, bj, At, Bt) do { __builtin_amdgcn_s_setprio(1); _Pragma("unroll") for (int m = 0; m < 4; ++m) _Pragma("unroll") for (int n = 0; n < 2; ++n) _Pragma("unroll") for (int k = 0; k < 2; ++k) \
;         acc[ai][bj][m][n] = __builtin_amdgcn_mfma_f32_16x16x32_bf16(Bt[n][k], At[m][k], acc[ai][bj][m][n], 0, 0, 0); __builtin_amdgcn_s_setprio(0); } while (0)
; #define PG8_WAIT_V(n) asm volatile("s_waitcnt vmcnt(" #n ")" ::: "memory")
; #define PG8_WAIT_L(n) asm volatile("s_waitcnt lgkmcnt(" #n ")" ::: "memory")
; #define PG8_BAR __builtin_amdgcn_s_barrier()
; #define PG8_SCHED __builtin_amdgcn_sched_barrier(0)
; template <class Epi>
; __device__ __forceinline__ void gemm_phase(LAS unsigned char* lds, const Gemm g, const StaticOrder& S, const Epi& E) {
;     ...
;             PG8_STAGE(PG8_SB(0, 1), b2, hB, 0);
;             PG8_WAIT_V(6); PG8_BAR; PG8_MMA(1, 1, At, B1); PG8_BAR;
;             PG8_LDB(B0, 1, 0); PG8_SCHED; PG8_LDA(At, 1, 0); PG8_STAGE(PG8_SA(0, 1), a2, hA, 0);
;             PG8_WAIT_L(8); PG8_BAR; PG8_WAIT_L(0); PG8_MMA(0, 0, At, B0); PG8_BAR; PG8_SCHED;
;             PG8_LDB(B1, 1, 1); PG8_STAGE(PG8_SB(1, 0), b2 + KS, 0, 0);
;             PG8_BAR; PG8_WAIT_L(0); PG8_MMA(0, 1, At, B1); PG8_BAR;
;             PG8_LDA(At, 1, 1); PG8_STAGE(PG8_SA(1, 0), a2 + KS, 0, 0);
	s_add_u32 s48, s78, 0x80000
	s_addc_u32 s49, s79, 0
	s_mov_b32 m0, s28
	s_nop 0
	global_load_lds_dwordx4 v168, s[48:49]
	s_add_u32 s48, s78, 0x82000
	s_addc_u32 s49, s79, 0
	s_mov_b32 m0, s29
	s_nop 0
	global_load_lds_dwordx4 v168, s[48:49]
	s_waitcnt vmcnt(10)
	s_barrier
	v_mfma_f32_16x16x32_bf16 v[56:59], v[212:215], v[144:147], 0
	v_mfma_f32_16x16x32_bf16 v[8:11], v[240:243], v[144:147], 0
	v_mfma_f32_16x16x32_bf16 v[52:55], v[212:215], v[152:155], 0
	v_mfma_f32_16x16x32_bf16 v[4:7], v[240:243], v[152:155], 0
	v_mfma_f32_16x16x32_bf16 v[48:51], v[212:215], v[160:163], 0
	v_mfma_f32_16x16x32_bf16 v[0:3], v[240:243], v[160:163], 0
	v_mfma_f32_16x16x32_bf16 v[100:103], v[212:215], v[204:207], 0
	v_mfma_f32_16x16x32_bf16 v[88:91], v[240:243], v[204:207], 0
	v_mfma_f32_16x16x32_bf16 v[56:59], v[236:239], v[148:151], v[56:59]
	v_mfma_f32_16x16x32_bf16 v[8:11], v[244:247], v[148:151], v[8:11]
	v_mfma_f32_16x16x32_bf16 v[52:55], v[236:239], v[156:159], v[52:55]
	v_mfma_f32_16x16x32_bf16 v[4:7], v[244:247], v[156:159], v[4:7]
	v_mfma_f32_16x16x32_bf16 v[48:51], v[236:239], v[164:167], v[48:51]
	v_mfma_f32_16x16x32_bf16 v[0:3], v[244:247], v[164:167], v[0:3]
	v_mfma_f32_16x16x32_bf16 v[100:103], v[236:239], v[208:211], v[100:103]
	v_mfma_f32_16x16x32_bf16 v[88:91], v[244:247], v[208:211], v[88:91]
	s_barrier
	ds_read_b128 v[128:131], v202 offset:32768
	ds_read_b128 v[132:135], v202 offset:33792
	ds_read_b128 v[136:139], v202 offset:34816
	ds_read_b128 v[140:143], v202 offset:35840
	ds_read_b128 v[144:147], v203 offset:32768
	ds_read_b128 v[148:151], v203 offset:33792
	ds_read_b128 v[152:155], v203 offset:34816
	ds_read_b128 v[156:159], v203 offset:35840
	ds_read_b128 v[160:163], v203 offset:36864
	ds_read_b128 v[164:167], v203 offset:37888
	ds_read_b128 v[204:207], v203 offset:38912
	ds_read_b128 v[208:211], v203 offset:39936
	s_add_u32 s48, s82, 0x80000
	s_addc_u32 s49, s83, 0
	s_mov_b32 m0, s30
	s_nop 0
	global_load_lds_dwordx4 v168, s[48:49]
	s_add_u32 s48, s82, 0x82000
	s_addc_u32 s49, s83, 0
	s_mov_b32 m0, s34
	s_nop 0
	global_load_lds_dwordx4 v168, s[48:49]
	s_waitcnt lgkmcnt(8)
	s_waitcnt vmcnt(10)
	s_barrier
	s_waitcnt lgkmcnt(7)
	v_mfma_f32_16x16x32_bf16 v[96:99], v[128:131], v[144:147], v[96:99]
	v_mfma_f32_16x16x32_bf16 v[44:47], v[136:139], v[144:147], v[44:47]
	s_waitcnt lgkmcnt(5)
	v_mfma_f32_16x16x32_bf16 v[92:95], v[128:131], v[152:155], v[92:95]
	v_mfma_f32_16x16x32_bf16 v[40:43], v[136:139], v[152:155], v[40:43]
	s_waitcnt lgkmcnt(3)
	v_mfma_f32_16x16x32_bf16 v[84:87], v[128:131], v[160:163], v[84:87]
	v_mfma_f32_16x16x32_bf16 v[36:39], v[136:139], v[160:163], v[36:39]
	s_waitcnt lgkmcnt(1)
	v_mfma_f32_16x16x32_bf16 v[124:127], v[128:131], v[204:207], v[124:127]
	v_mfma_f32_16x16x32_bf16 v[120:123], v[136:139], v[204:207], v[120:123]
	v_mfma_f32_16x16x32_bf16 v[96:99], v[132:135], v[148:151], v[96:99]
	v_mfma_f32_16x16x32_bf16 v[44:47], v[140:143], v[148:151], v[44:47]
	v_mfma_f32_16x16x32_bf16 v[92:95], v[132:135], v[156:159], v[92:95]
	v_mfma_f32_16x16x32_bf16 v[40:43], v[140:143], v[156:159], v[40:43]
	v_mfma_f32_16x16x32_bf16 v[84:87], v[132:135], v[164:167], v[84:87]
	v_mfma_f32_16x16x32_bf16 v[36:39], v[140:143], v[164:167], v[36:39]
	s_waitcnt lgkmcnt(0)
	v_mfma_f32_16x16x32_bf16 v[124:127], v[132:135], v[208:211], v[124:127]
	v_mfma_f32_16x16x32_bf16 v[120:123], v[140:143], v[208:211], v[120:123]
	s_barrier
	ds_read_b128 v[212:215], v202 offset:49152
	ds_read_b128 v[236:239], v202 offset:50176
	ds_read_b128 v[240:243], v202 offset:51200
	ds_read_b128 v[244:247], v202 offset:52224
	s_add_u32 s48, s78, 0x4000
	s_addc_u32 s49, s79, 0
	s_mov_b32 m0, s38
	s_nop 0
	global_load_lds_dwordx4 v168, s[48:49]
	s_add_u32 s48, s78, 0x6000
	s_addc_u32 s49, s79, 0
	s_mov_b32 m0, s39
	s_nop 0
	global_load_lds_dwordx4 v168, s[48:49]
	s_waitcnt vmcnt(10)
	s_barrier
	s_waitcnt lgkmcnt(3)
	v_mfma_f32_16x16x32_bf16 v[80:83], v[212:215], v[144:147], v[80:83]
	s_waitcnt lgkmcnt(1)
	v_mfma_f32_16x16x32_bf16 v[32:35], v[240:243], v[144:147], v[32:35]
	v_mfma_f32_16x16x32_bf16 v[76:79], v[212:215], v[152:155], v[76:79]
	v_mfma_f32_16x16x32_bf16 v[28:31], v[240:243], v[152:155], v[28:31]
	v_mfma_f32_16x16x32_bf16 v[72:75], v[212:215], v[160:163], v[72:75]
	v_mfma_f32_16x16x32_bf16 v[24:27], v[240:243], v[160:163], v[24:27]
	v_mfma_f32_16x16x32_bf16 v[116:119], v[212:215], v[204:207], v[116:119]
	v_mfma_f32_16x16x32_bf16 v[112:115], v[240:243], v[204:207], v[112:115]
	v_mfma_f32_16x16x32_bf16 v[80:83], v[236:239], v[148:151], v[80:83]
	s_waitcnt lgkmcnt(0)
	v_mfma_f32_16x16x32_bf16 v[32:35], v[244:247], v[148:151], v[32:35]
	v_mfma_f32_16x16x32_bf16 v[76:79], v[236:239], v[156:159], v[76:79]
	v_mfma_f32_16x16x32_bf16 v[28:31], v[244:247], v[156:159], v[28:31]
	v_mfma_f32_16x16x32_bf16 v[72:75], v[236:239], v[164:167], v[72:75]
	v_mfma_f32_16x16x32_bf16 v[24:27], v[244:247], v[164:167], v[24:27]
	v_mfma_f32_16x16x32_bf16 v[116:119], v[236:239], v[208:211], v[116:119]
	v_mfma_f32_16x16x32_bf16 v[112:115], v[244:247], v[208:211], v[112:115]
	s_barrier
	ds_read_b128 v[144:147], v203 offset:49152
	ds_read_b128 v[148:151], v203 offset:50176
	ds_read_b128 v[152:155], v203 offset:51200
	ds_read_b128 v[156:159], v203 offset:52224
	ds_read_b128 v[160:163], v203 offset:53248
	ds_read_b128 v[164:167], v203 offset:54272
	ds_read_b128 v[204:207], v203 offset:55296
	ds_read_b128 v[208:211], v203 offset:56320
	s_add_u32 s48, s82, 0x4000
	s_addc_u32 s49, s83, 0
	s_mov_b32 m0, s40
	s_nop 0
	global_load_lds_dwordx4 v168, s[48:49]
	s_add_u32 s48, s82, 0x6000
	s_addc_u32 s49, s83, 0
	s_mov_b32 m0, s41
	s_nop 0
	global_load_lds_dwordx4 v168, s[48:49]
	s_barrier
; #define PG8_STAGE(bufoff, gbase, hoff, imm) do { _Pragma("unroll") for (int _i = 0; _i < 2; ++_i) { \
;         asm volatile("s_mov_b32 m0, %0\n\ts_nop 0\n\tglobal_load_lds_dwordx4 %1, %2" \
;             :: "s"(lds0 + (unsigned)((bufoff) + _i * 8192)), "v"(voff0), "s"((const char*)(gbase) + (size_t)(hoff) + (size_t)(_i * 8192)) : "memory"); } } while (0)
; #define PG8_LDA(dst, b, h) do { _Pragma("unroll") for (int m = 0; m < 4; ++m) _Pragma("unroll") for (int k = 0; k < 2; ++k) dst[m][k] = *(const LAS bf16x8*)(lds + PG8_SA(b, h) + aoff + m * 2048 + k * 1024); } while (0)
; #define PG8_LDB(dst, b, h) do { _Pragma("unroll") for (int n = 0; n < 2; ++n) _Pragma("unroll") for (int k = 0; k < 2; ++k) dst[n][k] = *(const LAS bf16x8*)(lds + PG8_SB(b, h) + boff + n * 2048 + k * 1024); } while (0)
; #define PG8_MMA(ai, bj, At, Bt) do { __builtin_amdgcn_s_setprio(1); _Pragma("unroll") for (int m = 0; m < 4; ++m) _Pragma("unroll") for (int n = 0; n < 2; ++n) _Pragma("unroll") for (int k = 0; k < 2; ++k) \
;         acc[ai][bj][m][n] = __builtin_amdgcn_mfma_f32_16x16x32_bf16(Bt[n][k], At[m][k], acc[ai][bj][m][n], 0, 0, 0); __builtin_amdgcn_s_setprio(0); } while (0)
; #define PG8_WAIT_V(n) asm volatile("s_waitcnt vmcnt(" #n ")" ::: "memory")
; #define PG8_WAIT_L(n) asm volatile("s_waitcnt lgkmcnt(" #n ")" ::: "memory")
; #define PG8_BAR __builtin_amdgcn_s_barrier()
; #define PG8_SCHED __builtin_amdgcn_sched_barrier(0)
; template <class Epi>
; __device__ __forceinline__ void gemm_phase(LAS unsigned char* lds, const Gemm g, const StaticOrder& S, const Epi& E) {
;     ...
;             const char* aT = cA + (size_t)t * KS;
;             const char* a2 = last ? nA : aT + 2 * KS; const char* b2 = last ? nB : cB + (size_t)(t + 2) * KS;
;             PG8_LDB(B0, 0, 0); PG8_SCHED; PG8_LDA(At, 0, 0); PG8_STAGE(PG8_SA(1, 1), aT + KS, hA, 0);
;             PG8_WAIT_L(8); PG8_BAR; PG8_WAIT_L(0); PG8_MMA(0, 0, At, B0); PG8_BAR; PG8_SCHED;
;             PG8_LDB(B1, 0, 1); PG8_STAGE(PG8_SB(0, 0), b2, 0, 0);
;     ...
;             PG8_BAR; PG8_WAIT_L(0); PG8_MMA(1, 0, At, B0); PG8_BAR; PG8_SCHED;
;             PG8_STAGE(PG8_SB(1, 1), b2 + KS, hB, 0);
;             PG8_WAIT_V(6); PG8_BAR; PG8_MMA(1, 1, At, B1); PG8_BAR;
	s_waitcnt lgkmcnt(7)
	v_mfma_f32_16x16x32_bf16 v[68:71], v[128:131], v[144:147], v[68:71]
	v_mfma_f32_16x16x32_bf16 v[20:23], v[136:139], v[144:147], v[20:23]
	s_waitcnt lgkmcnt(5)
	v_mfma_f32_16x16x32_bf16 v[64:67], v[128:131], v[152:155], v[64:67]
	v_mfma_f32_16x16x32_bf16 v[16:19], v[136:139], v[152:155], v[16:19]
	s_waitcnt lgkmcnt(3)
	v_mfma_f32_16x16x32_bf16 v[60:63], v[128:131], v[160:163], v[60:63]
	v_mfma_f32_16x16x32_bf16 v[12:15], v[136:139], v[160:163], v[12:15]
	s_waitcnt lgkmcnt(1)
	v_mfma_f32_16x16x32_bf16 v[108:111], v[128:131], v[204:207], v[108:111]
	v_mfma_f32_16x16x32_bf16 v[104:107], v[136:139], v[204:207], v[104:107]
	v_mfma_f32_16x16x32_bf16 v[68:71], v[132:135], v[148:151], v[68:71]
	v_mfma_f32_16x16x32_bf16 v[20:23], v[140:143], v[148:151], v[20:23]
	v_mfma_f32_16x16x32_bf16 v[64:67], v[132:135], v[156:159], v[64:67]
	v_mfma_f32_16x16x32_bf16 v[16:19], v[140:143], v[156:159], v[16:19]
	v_mfma_f32_16x16x32_bf16 v[60:63], v[132:135], v[164:167], v[60:63]
	v_mfma_f32_16x16x32_bf16 v[12:15], v[140:143], v[164:167], v[12:15]
	s_waitcnt lgkmcnt(0)
	v_mfma_f32_16x16x32_bf16 v[108:111], v[132:135], v[208:211], v[108:111]
	v_mfma_f32_16x16x32_bf16 v[104:107], v[140:143], v[208:211], v[104:107]
	s_barrier
	s_add_u32 s48, s78, 0x84000
	s_addc_u32 s49, s79, 0
	s_mov_b32 m0, s42
	s_nop 0
	global_load_lds_dwordx4 v168, s[48:49]
	s_add_u32 s48, s78, 0x86000
	s_addc_u32 s49, s79, 0
	s_mov_b32 m0, s43
	s_nop 0
	global_load_lds_dwordx4 v168, s[48:49]
	s_waitcnt vmcnt(10)
	s_barrier
	v_mfma_f32_16x16x32_bf16 v[56:59], v[212:215], v[144:147], v[56:59]
	v_mfma_f32_16x16x32_bf16 v[8:11], v[240:243], v[144:147], v[8:11]
	v_mfma_f32_16x16x32_bf16 v[52:55], v[212:215], v[152:155], v[52:55]
	v_mfma_f32_16x16x32_bf16 v[4:7], v[240:243], v[152:155], v[4:7]
	v_mfma_f32_16x16x32_bf16 v[48:51], v[212:215], v[160:163], v[48:51]
	v_mfma_f32_16x16x32_bf16 v[0:3], v[240:243], v[160:163], v[0:3]
	v_mfma_f32_16x16x32_bf16 v[100:103], v[212:215], v[204:207], v[100:103]
	v_mfma_f32_16x16x32_bf16 v[88:91], v[240:243], v[204:207], v[88:91]
	v_mfma_f32_16x16x32_bf16 v[56:59], v[236:239], v[148:151], v[56:59]
	v_mfma_f32_16x16x32_bf16 v[8:11], v[244:247], v[148:151], v[8:11]
	v_mfma_f32_16x16x32_bf16 v[52:55], v[236:239], v[156:159], v[52:55]
	v_mfma_f32_16x16x32_bf16 v[4:7], v[244:247], v[156:159], v[4:7]
	v_mfma_f32_16x16x32_bf16 v[48:51], v[236:239], v[164:167], v[48:51]
	v_mfma_f32_16x16x32_bf16 v[0:3], v[244:247], v[164:167], v[0:3]
	v_mfma_f32_16x16x32_bf16 v[100:103], v[236:239], v[208:211], v[100:103]
	v_mfma_f32_16x16x32_bf16 v[88:91], v[244:247], v[208:211], v[88:91]
	s_add_i32 s0, s0, 2
	s_add_u32 s9, s9, 0x8000
	s_addc_u32 s63, s63, 0
	s_cmp_gt_u32 s0, 29
	s_mov_b64 s[78:79], s[80:81]
	s_barrier
	s_branch .LBB0_507
.LBB0_506:
	ds_read_b128 v[128:131], v202
	ds_read_b128 v[132:135], v202 offset:1024
	ds_read_b128 v[136:139], v202 offset:2048
	ds_read_b128 v[140:143], v202 offset:3072
	s_add_u32 s80, s78, 0x8000
	s_addc_u32 s81, s79, 0
	s_and_b64 s[82:83], s[84:85], exec
	s_cselect_b32 s83, s51, s81
	s_cselect_b32 s82, s71, s80
	ds_read_b128 v[144:147], v203
	ds_read_b128 v[148:151], v203 offset:1024
	ds_read_b128 v[152:155], v203 offset:2048
	ds_read_b128 v[156:159], v203 offset:3072
	ds_read_b128 v[160:163], v203 offset:4096
	ds_read_b128 v[164:167], v203 offset:5120
	ds_read_b128 v[204:207], v203 offset:6144
	ds_read_b128 v[208:211], v203 offset:7168
	s_add_u32 s48, s78, 0x84000
	s_addc_u32 s49, s79, 0
	s_mov_b32 m0, s87
	s_nop 0
	global_load_lds_dwordx4 v168, s[48:49]
	s_add_u32 s48, s78, 0x86000
	s_addc_u32 s49, s79, 0
	s_mov_b32 m0, s96
	s_nop 0
	global_load_lds_dwordx4 v168, s[48:49]
	s_waitcnt lgkmcnt(8)
	s_waitcnt vmcnt(10)
	s_barrier
	s_waitcnt lgkmcnt(7)
	v_mfma_f32_16x16x32_bf16 v[96:99], v[128:131], v[144:147], v[96:99]
	v_mfma_f32_16x16x32_bf16 v[44:47], v[136:139], v[144:147], v[44:47]
	s_waitcnt lgkmcnt(5)
	v_mfma_f32_16x16x32_bf16 v[92:95], v[128:131], v[152:155], v[92:95]
	v_mfma_f32_16x16x32_bf16 v[40:43], v[136:139], v[152:155], v[40:43]
	s_waitcnt lgkmcnt(3)
	v_mfma_f32_16x16x32_bf16 v[84:87], v[128:131], v[160:163], v[84:87]
	v_mfma_f32_16x16x32_bf16 v[36:39], v[136:139], v[160:163], v[36:39]
	s_waitcnt lgkmcnt(1)
	v_mfma_f32_16x16x32_bf16 v[124:127], v[128:131], v[204:207], v[124:127]
	v_mfma_f32_16x16x32_bf16 v[120:123], v[136:139], v[204:207], v[120:123]
	v_mfma_f32_16x16x32_bf16 v[96:99], v[132:135], v[148:151], v[96:99]
	v_mfma_f32_16x16x32_bf16 v[44:47], v[140:143], v[148:151], v[44:47]
	v_mfma_f32_16x16x32_bf16 v[92:95], v[132:135], v[156:159], v[92:95]
	v_mfma_f32_16x16x32_bf16 v[40:43], v[140:143], v[156:159], v[40:43]
	v_mfma_f32_16x16x32_bf16 v[84:87], v[132:135], v[164:167], v[84:87]
	v_mfma_f32_16x16x32_bf16 v[36:39], v[140:143], v[164:167], v[36:39]
	s_waitcnt lgkmcnt(0)
	v_mfma_f32_16x16x32_bf16 v[124:127], v[132:135], v[208:211], v[124:127]
	v_mfma_f32_16x16x32_bf16 v[120:123], v[140:143], v[208:211], v[120:123]
	s_barrier
	ds_read_b128 v[212:215], v202 offset:16384
	ds_read_b128 v[236:239], v202 offset:17408
	ds_read_b128 v[240:243], v202 offset:18432
	ds_read_b128 v[244:247], v202 offset:19456
	s_and_b64 s[48:49], s[84:85], exec
	s_cselect_b32 s78, s62, s9
	s_cselect_b32 s79, s69, s63
	s_mov_b32 m0, s25
	s_nop 0
	global_load_lds_dwordx4 v168, s[78:79]
	s_add_u32 s48, s78, 0x2000
	s_addc_u32 s49, s79, 0
	s_mov_b32 m0, s26
	s_nop 0
	global_load_lds_dwordx4 v168, s[48:49]
	s_waitcnt vmcnt(10)
	s_barrier
; #define PG8_STAGE(bufoff, gbase, hoff, imm) do { _Pragma("unroll") for (int _i = 0; _i < 2; ++_i) { \
;         asm volatile("s_mov_b32 m0, %0\n\ts_nop 0\n\tglobal_load_lds_dwordx4 %1, %2" \
;             :: "s"(lds0 + (unsigned)((bufoff) + _i * 8192)), "v"(voff0), "s"((const char*)(gbase) + (size_t)(hoff) + (size_t)(_i * 8192)) : "memory"); } } while (0)
; #define PG8_LDA(dst, b, h) do { _Pragma("unroll") for (int m = 0; m < 4; ++m) _Pragma("unroll") for (int k = 0; k < 2; ++k) dst[m][k] = *(const LAS bf16x8*)(lds + PG8_SA(b, h) + aoff + m * 2048 + k * 1024); } while (0)
; #define PG8_LDB(dst, b, h) do { _Pragma("unroll") for (int n = 0; n < 2; ++n) _Pragma("unroll") for (int k = 0; k < 2; ++k) dst[n][k] = *(const LAS bf16x8*)(lds + PG8_SB(b, h) + boff + n * 2048 + k * 1024); } while (0)
; #define PG8_MMA(ai, bj, At, Bt) do { __builtin_amdgcn_s_setprio(1); _Pragma("unroll") for (int m = 0; m < 4; ++m) _Pragma("unroll") for (int n = 0; n < 2; ++n) _Pragma("unroll") for (int k = 0; k < 2; ++k) \
;         acc[ai][bj][m][n] = __builtin_amdgcn_mfma_f32_16x16x32_bf16(Bt[n][k], At[m][k], acc[ai][bj][m][n], 0, 0, 0); __builtin_amdgcn_s_setprio(0); } while (0)
; #define PG8_WAIT_V(n) asm volatile("s_waitcnt vmcnt(" #n ")" ::: "memory")
; #define PG8_WAIT_L(n) asm volatile("s_waitcnt lgkmcnt(" #n ")" ::: "memory")
; #define PG8_BAR __builtin_amdgcn_s_barrier()
; #define PG8_SCHED __builtin_amdgcn_sched_barrier(0)
; template <class Epi>
; __device__ __forceinline__ void gemm_phase(LAS unsigned char* lds, const Gemm g, const StaticOrder& S, const Epi& E) {
;     ...
;             PG8_BAR; PG8_WAIT_L(0); PG8_MMA(0, 1, At, B1); PG8_BAR;
;             PG8_LDA(At, 0, 1); PG8_STAGE(PG8_SA(0, 0), a2, 0, 0);
;             PG8_BAR; PG8_WAIT_L(0); PG8_MMA(1, 0, At, B0); PG8_BAR; PG8_SCHED;
;             PG8_STAGE(PG8_SB(0, 1), b2, hB, 0);
;             PG8_WAIT_V(6); PG8_BAR; PG8_MMA(1, 1, At, B1); PG8_BAR;
;             PG8_LDB(B0, 1, 0); PG8_SCHED; PG8_LDA(At, 1, 0); PG8_STAGE(PG8_SA(0, 1), a2, hA, 0);
	s_waitcnt lgkmcnt(3)
	v_mfma_f32_16x16x32_bf16 v[80:83], v[212:215], v[144:147], v[80:83]
	s_waitcnt lgkmcnt(1)
	v_mfma_f32_16x16x32_bf16 v[32:35], v[240:243], v[144:147], v[32:35]
	v_mfma_f32_16x16x32_bf16 v[76:79], v[212:215], v[152:155], v[76:79]
	v_mfma_f32_16x16x32_bf16 v[28:31], v[240:243], v[152:155], v[28:31]
	v_mfma_f32_16x16x32_bf16 v[72:75], v[212:215], v[160:163], v[72:75]
	v_mfma_f32_16x16x32_bf16 v[24:27], v[240:243], v[160:163], v[24:27]
	v_mfma_f32_16x16x32_bf16 v[116:119], v[212:215], v[204:207], v[116:119]
	v_mfma_f32_16x16x32_bf16 v[112:115], v[240:243], v[204:207], v[112:115]
	v_mfma_f32_16x16x32_bf16 v[80:83], v[236:239], v[148:151], v[80:83]
	s_waitcnt lgkmcnt(0)
	v_mfma_f32_16x16x32_bf16 v[32:35], v[244:247], v[148:151], v[32:35]
	v_mfma_f32_16x16x32_bf16 v[76:79], v[236:239], v[156:159], v[76:79]
	v_mfma_f32_16x16x32_bf16 v[28:31], v[244:247], v[156:159], v[28:31]
	v_mfma_f32_16x16x32_bf16 v[72:75], v[236:239], v[164:167], v[72:75]
	v_mfma_f32_16x16x32_bf16 v[24:27], v[244:247], v[164:167], v[24:27]
	v_mfma_f32_16x16x32_bf16 v[116:119], v[236:239], v[208:211], v[116:119]
	v_mfma_f32_16x16x32_bf16 v[112:115], v[244:247], v[208:211], v[112:115]
	s_barrier
	ds_read_b128 v[144:147], v203 offset:16384
	ds_read_b128 v[148:151], v203 offset:17408
	ds_read_b128 v[152:155], v203 offset:18432
	ds_read_b128 v[156:159], v203 offset:19456
	ds_read_b128 v[160:163], v203 offset:20480
	ds_read_b128 v[164:167], v203 offset:21504
	ds_read_b128 v[204:207], v203 offset:22528
	ds_read_b128 v[208:211], v203 offset:23552
	s_mov_b32 m0, s24
	s_nop 0
	global_load_lds_dwordx4 v168, s[82:83]
	s_add_u32 s48, s82, 0x2000
	s_addc_u32 s49, s83, 0
	s_mov_b32 m0, s27
	s_nop 0
	global_load_lds_dwordx4 v168, s[48:49]
	s_barrier
	s_waitcnt lgkmcnt(7)
	v_mfma_f32_16x16x32_bf16 v[68:71], v[128:131], v[144:147], v[68:71]
	v_mfma_f32_16x16x32_bf16 v[20:23], v[136:139], v[144:147], v[20:23]
	s_waitcnt lgkmcnt(5)
	v_mfma_f32_16x16x32_bf16 v[64:67], v[128:131], v[152:155], v[64:67]
	v_mfma_f32_16x16x32_bf16 v[16:19], v[136:139], v[152:155], v[16:19]
	s_waitcnt lgkmcnt(3)
	v_mfma_f32_16x16x32_bf16 v[60:63], v[128:131], v[160:163], v[60:63]
	v_mfma_f32_16x16x32_bf16 v[12:15], v[136:139], v[160:163], v[12:15]
	s_waitcnt lgkmcnt(1)
	v_mfma_f32_16x16x32_bf16 v[108:111], v[128:131], v[204:207], v[108:111]
	v_mfma_f32_16x16x32_bf16 v[104:107], v[136:139], v[204:207], v[104:107]
	v_mfma_f32_16x16x32_bf16 v[68:71], v[132:135], v[148:151], v[68:71]
	v_mfma_f32_16x16x32_bf16 v[20:23], v[140:143], v[148:151], v[20:23]
	v_mfma_f32_16x16x32_bf16 v[64:67], v[132:135], v[156:159], v[64:67]
	v_mfma_f32_16x16x32_bf16 v[16:19], v[140:143], v[156:159], v[16:19]
	v_mfma_f32_16x16x32_bf16 v[60:63], v[132:135], v[164:167], v[60:63]
	v_mfma_f32_16x16x32_bf16 v[12:15], v[140:143], v[164:167], v[12:15]
	s_waitcnt lgkmcnt(0)
	v_mfma_f32_16x16x32_bf16 v[108:111], v[132:135], v[208:211], v[108:111]
	v_mfma_f32_16x16x32_bf16 v[104:107], v[140:143], v[208:211], v[104:107]
	s_barrier
	s_add_u32 s48, s78, 0x80000
	s_addc_u32 s49, s79, 0
	s_mov_b32 m0, s28
	s_nop 0
	global_load_lds_dwordx4 v168, s[48:49]
	s_add_u32 s48, s78, 0x82000
	s_addc_u32 s49, s79, 0
	s_mov_b32 m0, s29
	s_nop 0
	global_load_lds_dwordx4 v168, s[48:49]
	s_waitcnt vmcnt(10)
	s_barrier
	v_mfma_f32_16x16x32_bf16 v[56:59], v[212:215], v[144:147], v[56:59]
	v_mfma_f32_16x16x32_bf16 v[8:11], v[240:243], v[144:147], v[8:11]
	v_mfma_f32_16x16x32_bf16 v[52:55], v[212:215], v[152:155], v[52:55]
	v_mfma_f32_16x16x32_bf16 v[4:7], v[240:243], v[152:155], v[4:7]
	v_mfma_f32_16x16x32_bf16 v[48:51], v[212:215], v[160:163], v[48:51]
	v_mfma_f32_16x16x32_bf16 v[0:3], v[240:243], v[160:163], v[0:3]
	v_mfma_f32_16x16x32_bf16 v[100:103], v[212:215], v[204:207], v[100:103]
	v_mfma_f32_16x16x32_bf16 v[88:91], v[240:243], v[204:207], v[88:91]
	v_mfma_f32_16x16x32_bf16 v[56:59], v[236:239], v[148:151], v[56:59]
	v_mfma_f32_16x16x32_bf16 v[8:11], v[244:247], v[148:151], v[8:11]
	v_mfma_f32_16x16x32_bf16 v[52:55], v[236:239], v[156:159], v[52:55]
	v_mfma_f32_16x16x32_bf16 v[4:7], v[244:247], v[156:159], v[4:7]
	v_mfma_f32_16x16x32_bf16 v[48:51], v[236:239], v[164:167], v[48:51]
	v_mfma_f32_16x16x32_bf16 v[0:3], v[244:247], v[164:167], v[0:3]
	v_mfma_f32_16x16x32_bf16 v[100:103], v[236:239], v[208:211], v[100:103]
	v_mfma_f32_16x16x32_bf16 v[88:91], v[244:247], v[208:211], v[88:91]
	s_barrier
	ds_read_b128 v[128:131], v202 offset:32768
	ds_read_b128 v[132:135], v202 offset:33792
	ds_read_b128 v[136:139], v202 offset:34816
	ds_read_b128 v[140:143], v202 offset:35840
	ds_read_b128 v[144:147], v203 offset:32768
	ds_read_b128 v[148:151], v203 offset:33792
	ds_read_b128 v[152:155], v203 offset:34816
	ds_read_b128 v[156:159], v203 offset:35840
	ds_read_b128 v[160:163], v203 offset:36864
	ds_read_b128 v[164:167], v203 offset:37888
	ds_read_b128 v[204:207], v203 offset:38912
	ds_read_b128 v[208:211], v203 offset:39936
	s_add_u32 s48, s82, 0x80000
	s_addc_u32 s49, s83, 0
	s_mov_b32 m0, s30
	s_nop 0
	global_load_lds_dwordx4 v168, s[48:49]
	s_add_u32 s48, s82, 0x82000
	s_addc_u32 s49, s83, 0
	s_mov_b32 m0, s34
	s_nop 0
	global_load_lds_dwordx4 v168, s[48:49]
	s_waitcnt lgkmcnt(8)
	s_waitcnt vmcnt(10)
	s_barrier
; #define PG8_STAGE(bufoff, gbase, hoff, imm) do { _Pragma("unroll") for (int _i = 0; _i < 2; ++_i) { \
;         asm volatile("s_mov_b32 m0, %0\n\ts_nop 0\n\tglobal_load_lds_dwordx4 %1, %2" \
;             :: "s"(lds0 + (unsigned)((bufoff) + _i * 8192)), "v"(voff0), "s"((const char*)(gbase) + (size_t)(hoff) + (size_t)(_i * 8192)) : "memory"); } } while (0)
; #define PG8_LDA(dst, b, h) do { _Pragma("unroll") for (int m = 0; m < 4; ++m) _Pragma("unroll") for (int k = 0; k < 2; ++k) dst[m][k] = *(const LAS bf16x8*)(lds + PG8_SA(b, h) + aoff + m * 2048 + k * 1024); } while (0)
; #define PG8_LDB(dst, b, h) do { _Pragma("unroll") for (int n = 0; n < 2; ++n) _Pragma("unroll") for (int k = 0; k < 2; ++k) dst[n][k] = *(const LAS bf16x8*)(lds + PG8_SB(b, h) + boff + n * 2048 + k * 1024); } while (0)
; #define PG8_MMA(ai, bj, At, Bt) do { __builtin_amdgcn_s_setprio(1); _Pragma("unroll") for (int m = 0; m < 4; ++m) _Pragma("unroll") for (int n = 0; n < 2; ++n) _Pragma("unroll") for (int k = 0; k < 2; ++k) \
;         acc[ai][bj][m][n] = __builtin_amdgcn_mfma_f32_16x16x32_bf16(Bt[n][k], At[m][k], acc[ai][bj][m][n], 0, 0, 0); __builtin_amdgcn_s_setprio(0); } while (0)
; #define PG8_WAIT_V(n) asm volatile("s_waitcnt vmcnt(" #n ")" ::: "memory")
; #define PG8_WAIT_L(n) asm volatile("s_waitcnt lgkmcnt(" #n ")" ::: "memory")
; #define PG8_BAR __builtin_amdgcn_s_barrier()
; #define PG8_SCHED __builtin_amdgcn_sched_barrier(0)
; template <class Epi>
; __device__ __forceinline__ void gemm_phase(LAS unsigned char* lds, const Gemm g, const StaticOrder& S, const Epi& E) {
;     ...
;             PG8_WAIT_L(8); PG8_BAR; PG8_WAIT_L(0); PG8_MMA(0, 0, At, B0); PG8_BAR; PG8_SCHED;
;             PG8_LDB(B1, 1, 1); PG8_STAGE(PG8_SB(1, 0), b2 + KS, 0, 0);
;             PG8_BAR; PG8_WAIT_L(0); PG8_MMA(0, 1, At, B1); PG8_BAR;
;             PG8_LDA(At, 1, 1); PG8_STAGE(PG8_SA(1, 0), a2 + KS, 0, 0);
;             PG8_BAR; PG8_WAIT_L(0); PG8_MMA(1, 0, At, B0); PG8_BAR; PG8_SCHED;
;             PG8_STAGE(PG8_SB(1, 1), b2 + KS, hB, 0);
;             PG8_WAIT_V(6); PG8_BAR; PG8_MMA(1, 1, At, B1); PG8_BAR;
	s_waitcnt lgkmcnt(7)
	v_mfma_f32_16x16x32_bf16 v[96:99], v[128:131], v[144:147], v[96:99]
	v_mfma_f32_16x16x32_bf16 v[44:47], v[136:139], v[144:147], v[44:47]
	s_waitcnt lgkmcnt(5)
	v_mfma_f32_16x16x32_bf16 v[92:95], v[128:131], v[152:155], v[92:95]
	v_mfma_f32_16x16x32_bf16 v[40:43], v[136:139], v[152:155], v[40:43]
	s_waitcnt lgkmcnt(3)
	v_mfma_f32_16x16x32_bf16 v[84:87], v[128:131], v[160:163], v[84:87]
	v_mfma_f32_16x16x32_bf16 v[36:39], v[136:139], v[160:163], v[36:39]
	s_waitcnt lgkmcnt(1)
	v_mfma_f32_16x16x32_bf16 v[124:127], v[128:131], v[204:207], v[124:127]
	v_mfma_f32_16x16x32_bf16 v[120:123], v[136:139], v[204:207], v[120:123]
	v_mfma_f32_16x16x32_bf16 v[96:99], v[132:135], v[148:151], v[96:99]
	v_mfma_f32_16x16x32_bf16 v[44:47], v[140:143], v[148:151], v[44:47]
	v_mfma_f32_16x16x32_bf16 v[92:95], v[132:135], v[156:159], v[92:95]
	v_mfma_f32_16x16x32_bf16 v[40:43], v[140:143], v[156:159], v[40:43]
	v_mfma_f32_16x16x32_bf16 v[84:87], v[132:135], v[164:167], v[84:87]
	v_mfma_f32_16x16x32_bf16 v[36:39], v[140:143], v[164:167], v[36:39]
	s_waitcnt lgkmcnt(0)
	v_mfma_f32_16x16x32_bf16 v[124:127], v[132:135], v[208:211], v[124:127]
	v_mfma_f32_16x16x32_bf16 v[120:123], v[140:143], v[208:211], v[120:123]
	s_barrier
	ds_read_b128 v[212:215], v202 offset:49152
	ds_read_b128 v[236:239], v202 offset:50176
	ds_read_b128 v[240:243], v202 offset:51200
	ds_read_b128 v[244:247], v202 offset:52224
	s_add_u32 s48, s78, 0x4000
	s_addc_u32 s49, s79, 0
	s_mov_b32 m0, s38
	s_nop 0
	global_load_lds_dwordx4 v168, s[48:49]
	s_add_u32 s48, s78, 0x6000
	s_addc_u32 s49, s79, 0
	s_mov_b32 m0, s39
	s_nop 0
	global_load_lds_dwordx4 v168, s[48:49]
	s_waitcnt vmcnt(10)
	s_barrier
	s_waitcnt lgkmcnt(3)
	v_mfma_f32_16x16x32_bf16 v[80:83], v[212:215], v[144:147], v[80:83]
	s_waitcnt lgkmcnt(1)
	v_mfma_f32_16x16x32_bf16 v[32:35], v[240:243], v[144:147], v[32:35]
	v_mfma_f32_16x16x32_bf16 v[76:79], v[212:215], v[152:155], v[76:79]
	v_mfma_f32_16x16x32_bf16 v[28:31], v[240:243], v[152:155], v[28:31]
	v_mfma_f32_16x16x32_bf16 v[72:75], v[212:215], v[160:163], v[72:75]
	v_mfma_f32_16x16x32_bf16 v[24:27], v[240:243], v[160:163], v[24:27]
	v_mfma_f32_16x16x32_bf16 v[116:119], v[212:215], v[204:207], v[116:119]
	v_mfma_f32_16x16x32_bf16 v[112:115], v[240:243], v[204:207], v[112:115]
	v_mfma_f32_16x16x32_bf16 v[80:83], v[236:239], v[148:151], v[80:83]
	s_waitcnt lgkmcnt(0)
	v_mfma_f32_16x16x32_bf16 v[32:35], v[244:247], v[148:151], v[32:35]
	v_mfma_f32_16x16x32_bf16 v[76:79], v[236:239], v[156:159], v[76:79]
	v_mfma_f32_16x16x32_bf16 v[28:31], v[244:247], v[156:159], v[28:31]
	v_mfma_f32_16x16x32_bf16 v[72:75], v[236:239], v[164:167], v[72:75]
	v_mfma_f32_16x16x32_bf16 v[24:27], v[244:247], v[164:167], v[24:27]
	v_mfma_f32_16x16x32_bf16 v[116:119], v[236:239], v[208:211], v[116:119]
	v_mfma_f32_16x16x32_bf16 v[112:115], v[244:247], v[208:211], v[112:115]
	s_barrier
	ds_read_b128 v[144:147], v203 offset:49152
	ds_read_b128 v[148:151], v203 offset:50176
	ds_read_b128 v[152:155], v203 offset:51200
	ds_read_b128 v[156:159], v203 offset:52224
	ds_read_b128 v[160:163], v203 offset:53248
	ds_read_b128 v[164:167], v203 offset:54272
	ds_read_b128 v[204:207], v203 offset:55296
	ds_read_b128 v[208:211], v203 offset:56320
	s_add_u32 s48, s82, 0x4000
	s_addc_u32 s49, s83, 0
	s_mov_b32 m0, s40
	s_nop 0
	global_load_lds_dwordx4 v168, s[48:49]
	s_add_u32 s48, s82, 0x6000
	s_addc_u32 s49, s83, 0
	s_mov_b32 m0, s41
	s_nop 0
	global_load_lds_dwordx4 v168, s[48:49]
	s_barrier
	s_waitcnt lgkmcnt(7)
	v_mfma_f32_16x16x32_bf16 v[68:71], v[128:131], v[144:147], v[68:71]
	v_mfma_f32_16x16x32_bf16 v[20:23], v[136:139], v[144:147], v[20:23]
	s_waitcnt lgkmcnt(5)
	v_mfma_f32_16x16x32_bf16 v[64:67], v[128:131], v[152:155], v[64:67]
	v_mfma_f32_16x16x32_bf16 v[16:19], v[136:139], v[152:155], v[16:19]
	s_waitcnt lgkmcnt(3)
	v_mfma_f32_16x16x32_bf16 v[60:63], v[128:131], v[160:163], v[60:63]
	v_mfma_f32_16x16x32_bf16 v[12:15], v[136:139], v[160:163], v[12:15]
	s_waitcnt lgkmcnt(1)
	v_mfma_f32_16x16x32_bf16 v[108:111], v[128:131], v[204:207], v[108:111]
	v_mfma_f32_16x16x32_bf16 v[104:107], v[136:139], v[204:207], v[104:107]
	v_mfma_f32_16x16x32_bf16 v[68:71], v[132:135], v[148:151], v[68:71]
	v_mfma_f32_16x16x32_bf16 v[20:23], v[140:143], v[148:151], v[20:23]
	v_mfma_f32_16x16x32_bf16 v[64:67], v[132:135], v[156:159], v[64:67]
	v_mfma_f32_16x16x32_bf16 v[16:19], v[140:143], v[156:159], v[16:19]
	v_mfma_f32_16x16x32_bf16 v[60:63], v[132:135], v[164:167], v[60:63]
	v_mfma_f32_16x16x32_bf16 v[12:15], v[140:143], v[164:167], v[12:15]
	s_waitcnt lgkmcnt(0)
	v_mfma_f32_16x16x32_bf16 v[108:111], v[132:135], v[208:211], v[108:111]
	v_mfma_f32_16x16x32_bf16 v[104:107], v[140:143], v[208:211], v[104:107]
	s_barrier
	s_add_u32 s48, s78, 0x84000
	s_addc_u32 s49, s79, 0
	s_mov_b32 m0, s42
	s_nop 0
	global_load_lds_dwordx4 v168, s[48:49]
	s_add_u32 s48, s78, 0x86000
	s_addc_u32 s49, s79, 0
	s_mov_b32 m0, s43
	s_nop 0
	global_load_lds_dwordx4 v168, s[48:49]
	s_waitcnt vmcnt(10)
	s_barrier
	v_mfma_f32_16x16x32_bf16 v[56:59], v[212:215], v[144:147], v[56:59]
	v_mfma_f32_16x16x32_bf16 v[8:11], v[240:243], v[144:147], v[8:11]
	v_mfma_f32_16x16x32_bf16 v[52:55], v[212:215], v[152:155], v[52:55]
	v_mfma_f32_16x16x32_bf16 v[4:7], v[240:243], v[152:155], v[4:7]
	v_mfma_f32_16x16x32_bf16 v[48:51], v[212:215], v[160:163], v[48:51]
	v_mfma_f32_16x16x32_bf16 v[0:3], v[240:243], v[160:163], v[0:3]
	v_mfma_f32_16x16x32_bf16 v[100:103], v[212:215], v[204:207], v[100:103]
	v_mfma_f32_16x16x32_bf16 v[88:91], v[240:243], v[204:207], v[88:91]
	v_mfma_f32_16x16x32_bf16 v[56:59], v[236:239], v[148:151], v[56:59]
	v_mfma_f32_16x16x32_bf16 v[8:11], v[244:247], v[148:151], v[8:11]
	v_mfma_f32_16x16x32_bf16 v[52:55], v[236:239], v[156:159], v[52:55]
	v_mfma_f32_16x16x32_bf16 v[4:7], v[244:247], v[156:159], v[4:7]
	v_mfma_f32_16x16x32_bf16 v[48:51], v[236:239], v[164:167], v[48:51]
	v_mfma_f32_16x16x32_bf16 v[0:3], v[244:247], v[164:167], v[0:3]
	v_mfma_f32_16x16x32_bf16 v[100:103], v[236:239], v[208:211], v[100:103]
	v_mfma_f32_16x16x32_bf16 v[88:91], v[244:247], v[208:211], v[88:91]
	s_add_i32 s0, s0, 2
	s_add_u32 s9, s9, 0x8000
	s_addc_u32 s63, s63, 0
	s_cmp_gt_u32 s0, 29
	s_mov_b64 s[78:79], s[80:81]
	s_barrier
	s_cbranch_scc1 .LBB0_509

; #define PG8_STAGE(bufoff, gbase, hoff, imm) do { _Pragma("unroll") for (int _i = 0; _i < 2; ++_i) { \
;         asm volatile("s_mov_b32 m0, %0\n\ts_nop 0\n\tglobal_load_lds_dwordx4 %1, %2" \
;             :: "s"(lds0 + (unsigned)((bufoff) + _i * 8192)), "v"(voff0), "s"((const char*)(gbase) + (size_t)(hoff) + (size_t)(_i * 8192)) : "memory"); } } while (0)
; #define PG8_WAIT_V(n) asm volatile("s_waitcnt vmcnt(" #n ")" ::: "memory")
; #define PG8_BAR __builtin_amdgcn_s_barrier()
; template <class Epi>
; __device__ __forceinline__ void gemm_phase(LAS unsigned char* lds, const Gemm g, const StaticOrder& S, const Epi& E) {
;     ...
;     const unsigned lds0 = (unsigned)__builtin_amdgcn_readfirstlane((int)((unsigned)(size_t)lds + (unsigned)wid * 1024u));
;     const int aoff = lds_byte(wr * 64 + fr, fq * 8), boff = lds_byte(wc * 32 + fr, fq * 8);
;     ...
;     PG8_STAGE(PG8_SB(0, 0), cB, 0, 0); PG8_STAGE(PG8_SA(0, 0), cA, 0, 0); PG8_STAGE(PG8_SB(0, 1), cB, hB, 0); PG8_STAGE(PG8_SA(0, 1), cA, hA, 0);
;     if (wr == 1) PG8_BAR;
;     PG8_WAIT_V(4); PG8_BAR;
;     PG8_STAGE(PG8_SB(1, 0), cB + KS, 0, 0); PG8_STAGE(PG8_SA(1, 0), cA + KS, 0, 0); PG8_STAGE(PG8_SB(1, 1), cB + KS, hB, 0);
;     PG8_WAIT_V(6); PG8_BAR;
.LBB0_602:
	s_add_u32 s8, s4, 0x29c30000
	s_addc_u32 s9, s5, 0
	s_cmp_eq_u32 s13, 0
	s_cselect_b64 s[10:11], -1, 0
	s_and_b64 s[10:11], s[2:3], s[10:11]
	s_add_u32 s37, s4, 0x31c34000
	s_addc_u32 s38, s5, 0
	s_and_b64 s[10:11], s[10:11], exec
	s_cselect_b32 s11, s38, s9
	s_cselect_b32 s10, s37, s8
	s_add_u32 s37, s4, 0xa61c000
	v_lshrrev_b32_e32 v2, 1, v0
	s_addc_u32 s38, s5, 0
	v_and_b32_e32 v2, 24, v2
	s_lshl_b32 s0, s0, 5
	v_and_b32_e32 v1, 15, v0
	v_lshlrev_b32_e32 v3, 1, v2
	v_lshlrev_b32_e32 v0, 2, v0
	s_and_b32 s4, s0, 0x60
	v_lshl_or_b32 v233, s1, 6, v1
	v_lshl_or_b32 v1, v1, 6, v3
	s_lshl_b32 s1, s1, 13
	v_and_b32_e32 v0, 32, v0
	s_lshl_b32 s0, s4, 7
	s_add_i32 s39, s22, 0x18000
	v_bitop3_b32 v3, v1, s1, v0 bitop3:0xde
	v_bitop3_b32 v0, v1, s0, v0 bitop3:0xde
	s_add_u32 s0, s62, 0x4000
	s_addc_u32 s1, s63, 0
	s_add_i32 s40, s22, 0x1a000
	s_waitcnt vmcnt(4)
	s_barrier
	s_mov_b32 m0, s39
	s_nop 0
	global_load_lds_dwordx4 v188, s[0:1]
	s_add_u32 s0, s62, 0x6000
	s_addc_u32 s1, s63, 0
	s_add_i32 s41, s22, 0x8000
	s_mov_b32 m0, s40
	s_nop 0
	global_load_lds_dwordx4 v188, s[0:1]
	s_add_u32 s0, s60, 0x4000
	s_addc_u32 s1, s61, 0
	s_add_i32 s42, s22, 0xa000
	s_mov_b32 m0, s41
	s_nop 0
	global_load_lds_dwordx4 v188, s[0:1]
	s_add_u32 s0, s60, 0x6000
	s_addc_u32 s1, s61, 0
	s_add_i32 s43, s22, 0x1c000
	s_mov_b32 m0, s42
	s_nop 0
	global_load_lds_dwordx4 v188, s[0:1]
	s_add_u32 s0, s62, 0x84000
	s_addc_u32 s1, s63, 0
	s_add_i32 s66, s22, 0x1e000
	s_mov_b32 m0, s43
	s_nop 0
	global_load_lds_dwordx4 v188, s[0:1]
	s_add_u32 s0, s62, 0x86000
	s_addc_u32 s1, s63, 0
	s_mov_b32 m0, s66
	s_nop 0
	global_load_lds_dwordx4 v188, s[0:1]
	s_waitcnt vmcnt(6)
	v_readlane_b32 s0, v255, 15
	s_mov_b32 s34, 0
	s_add_i32 s67, s22, 0xc000
	s_add_i32 s68, s22, 0xe000
	v_or_b32_e32 v234, s4, v2
	v_add_u32_e32 v236, 0x10000, v0
	v_add_u32_e32 v237, 0, v3
	v_readlane_b32 s51, v255, 14
	s_mov_b32 s50, s0
	s_barrier
	v_readlane_b32 s1, v255, 16

; #define PG8_STAGE(bufoff, gbase, hoff, imm) do { _Pragma("unroll") for (int _i = 0; _i < 2; ++_i) { \
;         asm volatile("s_mov_b32 m0, %0\n\ts_nop 0\n\tglobal_load_lds_dwordx4 %1, %2" \
;             :: "s"(lds0 + (unsigned)((bufoff) + _i * 8192)), "v"(voff0), "s"((const char*)(gbase) + (size_t)(hoff) + (size_t)(_i * 8192)) : "memory"); } } while (0)
; #define PG8_LDA(dst, b, h) do { _Pragma("unroll") for (int m = 0; m < 4; ++m) _Pragma("unroll") for (int k = 0; k < 2; ++k) dst[m][k] = *(const LAS bf16x8*)(lds + PG8_SA(b, h) + aoff + m * 2048 + k * 1024); } while (0)
; #define PG8_LDB(dst, b, h) do { _Pragma("unroll") for (int n = 0; n < 2; ++n) _Pragma("unroll") for (int k = 0; k < 2; ++k) dst[n][k] = *(const LAS bf16x8*)(lds + PG8_SB(b, h) + boff + n * 2048 + k * 1024); } while (0)
; #define PG8_WAIT_L(n) asm volatile("s_waitcnt lgkmcnt(" #n ")" ::: "memory")
; #define PG8_BAR __builtin_amdgcn_s_barrier()
; #define PG8_SCHED __builtin_amdgcn_sched_barrier(0)
; template <class Epi>
; __device__ __forceinline__ void gemm_phase(LAS unsigned char* lds, const Gemm g, const StaticOrder& S, const Epi& E) {
;     ...
;         const bool has_next = S.next(ui + 1, nxt);
;         const char* nA = has_next ? (const char*)g.A + (size_t)nxt.pm * tstepA + (size_t)(nxt.pn >> g.gshift) * g.gstride : cA;
;         const char* nB = has_next ? (const char*)g.Bt + (size_t)nxt.pn * tstepB : cB;
;         for (int t = 0; t < nt; t += 2) {
;             const bool last = (t == nt - 2);
;             if (last) E.pre(cur, wid, lane, (unsigned)(size_t)(lds + STAGE_BYTES));
;             const char* aT = cA + (size_t)t * KS;
;             const char* a2 = last ? nA : aT + 2 * KS; const char* b2 = last ? nB : cB + (size_t)(t + 2) * KS;
;             PG8_LDB(B0, 0, 0); PG8_SCHED; PG8_LDA(At, 0, 0); PG8_STAGE(PG8_SA(1, 1), aT + KS, hA, 0);
;             PG8_WAIT_L(8); PG8_BAR; PG8_WAIT_L(0); PG8_MMA(0, 0, At, B0); PG8_BAR; PG8_SCHED;
;             PG8_LDB(B1, 0, 1); PG8_STAGE(PG8_SB(0, 0), b2, 0, 0);
;             PG8_BAR; PG8_WAIT_L(0); PG8_MMA(0, 1, At, B1); PG8_BAR;
;             PG8_LDA(At, 0, 1); PG8_STAGE(PG8_SA(0, 0), a2, 0, 0);
;             PG8_BAR; PG8_WAIT_L(0); PG8_MMA(1, 0, At, B0); PG8_BAR; PG8_SCHED;
.LBB0_609:
	s_ashr_i32 s55, s54, 31
	s_lshl_b64 s[0:1], s[54:55], 20
	v_cmp_lt_i64_e32 vcc, s[56:57], v[192:193]
	s_add_u32 s56, s6, s0
	s_addc_u32 s57, s7, s1
	s_and_b64 s[0:1], vcc, exec
	s_cselect_b32 s0, s57, s61
	s_cselect_b32 s1, s56, s60
	s_ashr_i32 s53, s52, 31
	s_lshl_b64 s[48:49], s[52:53], 20
	s_add_u32 s58, s17, s48
	s_addc_u32 s59, s21, s49
	s_and_b64 s[48:49], vcc, exec
	s_cselect_b32 s53, s59, s63
	s_cselect_b32 s55, s58, s62
	s_add_u32 s69, s62, 0x8000
	s_addc_u32 s70, s63, 0
	s_mov_b32 s71, -2
	s_waitcnt vmcnt(16)
	s_add_u32 s62, s60, 0x8000
	s_addc_u32 s63, s61, 0
	ds_read_b128 v[120:123], v236
	ds_read_b128 v[124:127], v236 offset:1024
	ds_read_b128 v[128:131], v236 offset:2048
	ds_read_b128 v[132:135], v236 offset:3072
	s_add_u32 s48, s60, 0x84000
	s_addc_u32 s49, s61, 0
	s_add_u32 s64, s60, 0x86000
	s_addc_u32 s65, s61, 0
	s_cmp_eq_u32 s71, 28
	s_cselect_b32 s61, s0, s63
	s_cselect_b32 s60, s1, s62
	ds_read_b128 v[136:139], v237
	ds_read_b128 v[140:143], v237 offset:1024
	ds_read_b128 v[152:155], v237 offset:2048
	ds_read_b128 v[156:159], v237 offset:3072
	ds_read_b128 v[160:163], v237 offset:4096
	ds_read_b128 v[164:167], v237 offset:5120
	ds_read_b128 v[168:171], v237 offset:6144
	ds_read_b128 v[172:175], v237 offset:7168
	s_mov_b32 m0, s67
	s_nop 0
	global_load_lds_dwordx4 v188, s[48:49]
	s_mov_b32 m0, s68
	s_nop 0
	global_load_lds_dwordx4 v188, s[64:65]
	s_waitcnt lgkmcnt(8)
	s_waitcnt vmcnt(10)
	s_barrier
	s_waitcnt lgkmcnt(7)
	v_mfma_f32_16x16x32_bf16 v[148:151], v[120:123], v[136:139], 0
	v_mfma_f32_16x16x32_bf16 v[144:147], v[128:131], v[136:139], 0
	s_waitcnt lgkmcnt(5)
	v_mfma_f32_16x16x32_bf16 v[108:111], v[120:123], v[152:155], 0
	v_mfma_f32_16x16x32_bf16 v[104:107], v[128:131], v[152:155], 0
	s_waitcnt lgkmcnt(3)
	v_mfma_f32_16x16x32_bf16 v[92:95], v[120:123], v[160:163], 0
	v_mfma_f32_16x16x32_bf16 v[88:91], v[128:131], v[160:163], 0
	s_waitcnt lgkmcnt(1)
	v_mfma_f32_16x16x32_bf16 v[76:79], v[120:123], v[168:171], 0
	v_mfma_f32_16x16x32_bf16 v[72:75], v[128:131], v[168:171], 0
	v_mfma_f32_16x16x32_bf16 v[148:151], v[124:127], v[140:143], v[148:151]
	v_mfma_f32_16x16x32_bf16 v[144:147], v[132:135], v[140:143], v[144:147]
	v_mfma_f32_16x16x32_bf16 v[108:111], v[124:127], v[156:159], v[108:111]
	v_mfma_f32_16x16x32_bf16 v[104:107], v[132:135], v[156:159], v[104:107]
	v_mfma_f32_16x16x32_bf16 v[92:95], v[124:127], v[164:167], v[92:95]
	v_mfma_f32_16x16x32_bf16 v[88:91], v[132:135], v[164:167], v[88:91]
	s_waitcnt lgkmcnt(0)
	v_mfma_f32_16x16x32_bf16 v[76:79], v[124:127], v[172:175], v[76:79]
	v_mfma_f32_16x16x32_bf16 v[72:75], v[132:135], v[172:175], v[72:75]
	s_barrier
	ds_read_b128 v[176:179], v236 offset:16384
	ds_read_b128 v[180:183], v236 offset:17408
	ds_read_b128 v[184:187], v236 offset:18432
	ds_read_b128 v[200:203], v236 offset:19456
	s_cselect_b32 s64, s55, s69
	s_cselect_b32 s65, s53, s70
	s_mov_b32 m0, s24
	s_nop 0
	global_load_lds_dwordx4 v188, s[64:65]
	s_add_u32 s48, s64, 0x2000
	s_addc_u32 s49, s65, 0
	s_mov_b32 m0, s25
	s_nop 0
	global_load_lds_dwordx4 v188, s[48:49]
	s_waitcnt vmcnt(10)
	s_barrier
	s_waitcnt lgkmcnt(3)
	v_mfma_f32_16x16x32_bf16 v[116:119], v[176:179], v[136:139], 0
	s_waitcnt lgkmcnt(1)
	v_mfma_f32_16x16x32_bf16 v[112:115], v[184:187], v[136:139], 0
	v_mfma_f32_16x16x32_bf16 v[100:103], v[176:179], v[152:155], 0
	v_mfma_f32_16x16x32_bf16 v[96:99], v[184:187], v[152:155], 0
	v_mfma_f32_16x16x32_bf16 v[84:87], v[176:179], v[160:163], 0
	v_mfma_f32_16x16x32_bf16 v[80:83], v[184:187], v[160:163], 0
	v_mfma_f32_16x16x32_bf16 v[68:71], v[176:179], v[168:171], 0
	v_mfma_f32_16x16x32_bf16 v[64:67], v[184:187], v[168:171], 0
	v_mfma_f32_16x16x32_bf16 v[116:119], v[180:183], v[140:143], v[116:119]
	s_waitcnt lgkmcnt(0)
	v_mfma_f32_16x16x32_bf16 v[112:115], v[200:203], v[140:143], v[112:115]
	v_mfma_f32_16x16x32_bf16 v[100:103], v[180:183], v[156:159], v[100:103]
	v_mfma_f32_16x16x32_bf16 v[96:99], v[200:203], v[156:159], v[96:99]
	v_mfma_f32_16x16x32_bf16 v[84:87], v[180:183], v[164:167], v[84:87]
	v_mfma_f32_16x16x32_bf16 v[80:83], v[200:203], v[164:167], v[80:83]
	v_mfma_f32_16x16x32_bf16 v[68:71], v[180:183], v[172:175], v[68:71]
	v_mfma_f32_16x16x32_bf16 v[64:67], v[200:203], v[172:175], v[64:67]
	s_barrier
	ds_read_b128 v[136:139], v237 offset:16384
	ds_read_b128 v[140:143], v237 offset:17408
	ds_read_b128 v[152:155], v237 offset:18432
	ds_read_b128 v[156:159], v237 offset:19456
	ds_read_b128 v[160:163], v237 offset:20480
	ds_read_b128 v[164:167], v237 offset:21504
	ds_read_b128 v[168:171], v237 offset:22528
	ds_read_b128 v[172:175], v237 offset:23552
	s_mov_b32 m0, s22
	s_nop 0
	global_load_lds_dwordx4 v188, s[60:61]
	s_add_u32 s48, s60, 0x2000
	s_addc_u32 s49, s61, 0
	s_mov_b32 m0, s26
	s_nop 0
	global_load_lds_dwordx4 v188, s[48:49]
	s_barrier
	s_waitcnt lgkmcnt(7)
	v_mfma_f32_16x16x32_bf16 v[60:63], v[120:123], v[136:139], 0
	v_mfma_f32_16x16x32_bf16 v[56:59], v[128:131], v[136:139], 0
	s_waitcnt lgkmcnt(5)
	v_mfma_f32_16x16x32_bf16 v[44:47], v[120:123], v[152:155], 0
	v_mfma_f32_16x16x32_bf16 v[40:43], v[128:131], v[152:155], 0
	s_waitcnt lgkmcnt(3)
	v_mfma_f32_16x16x32_bf16 v[28:31], v[120:123], v[160:163], 0
	v_mfma_f32_16x16x32_bf16 v[24:27], v[128:131], v[160:163], 0
	s_waitcnt lgkmcnt(1)
	v_mfma_f32_16x16x32_bf16 v[12:15], v[120:123], v[168:171], 0
	v_mfma_f32_16x16x32_bf16 v[8:11], v[128:131], v[168:171], 0
	v_mfma_f32_16x16x32_bf16 v[60:63], v[124:127], v[140:143], v[60:63]
	v_mfma_f32_16x16x32_bf16 v[56:59], v[132:135], v[140:143], v[56:59]
	v_mfma_f32_16x16x32_bf16 v[44:47], v[124:127], v[156:159], v[44:47]
	v_mfma_f32_16x16x32_bf16 v[40:43], v[132:135], v[156:159], v[40:43]
	v_mfma_f32_16x16x32_bf16 v[28:31], v[124:127], v[164:167], v[28:31]
	v_mfma_f32_16x16x32_bf16 v[24:27], v[132:135], v[164:167], v[24:27]
	s_waitcnt lgkmcnt(0)
	v_mfma_f32_16x16x32_bf16 v[12:15], v[124:127], v[172:175], v[12:15]
	v_mfma_f32_16x16x32_bf16 v[8:11], v[132:135], v[172:175], v[8:11]
	s_barrier
; #define PG8_STAGE(bufoff, gbase, hoff, imm) do { _Pragma("unroll") for (int _i = 0; _i < 2; ++_i) { \
;         asm volatile("s_mov_b32 m0, %0\n\ts_nop 0\n\tglobal_load_lds_dwordx4 %1, %2" \
;             :: "s"(lds0 + (unsigned)((bufoff) + _i * 8192)), "v"(voff0), "s"((const char*)(gbase) + (size_t)(hoff) + (size_t)(_i * 8192)) : "memory"); } } while (0)
; #define PG8_LDA(dst, b, h) do { _Pragma("unroll") for (int m = 0; m < 4; ++m) _Pragma("unroll") for (int k = 0; k < 2; ++k) dst[m][k] = *(const LAS bf16x8*)(lds + PG8_SA(b, h) + aoff + m * 2048 + k * 1024); } while (0)
; #define PG8_LDB(dst, b, h) do { _Pragma("unroll") for (int n = 0; n < 2; ++n) _Pragma("unroll") for (int k = 0; k < 2; ++k) dst[n][k] = *(const LAS bf16x8*)(lds + PG8_SB(b, h) + boff + n * 2048 + k * 1024); } while (0)
; #define PG8_MMA(ai, bj, At, Bt) do { __builtin_amdgcn_s_setprio(1); _Pragma("unroll") for (int m = 0; m < 4; ++m) _Pragma("unroll") for (int n = 0; n < 2; ++n) _Pragma("unroll") for (int k = 0; k < 2; ++k) \
;         acc[ai][bj][m][n] = __builtin_amdgcn_mfma_f32_16x16x32_bf16(Bt[n][k], At[m][k], acc[ai][bj][m][n], 0, 0, 0); __builtin_amdgcn_s_setprio(0); } while (0)
; #define PG8_WAIT_V(n) asm volatile("s_waitcnt vmcnt(" #n ")" ::: "memory")
; #define PG8_WAIT_L(n) asm volatile("s_waitcnt lgkmcnt(" #n ")" ::: "memory")
; #define PG8_BAR __builtin_amdgcn_s_barrier()
; #define PG8_SCHED __builtin_amdgcn_sched_barrier(0)
; template <class Epi>
; __device__ __forceinline__ void gemm_phase(LAS unsigned char* lds, const Gemm g, const StaticOrder& S, const Epi& E) {
;     ...
;             PG8_STAGE(PG8_SB(0, 1), b2, hB, 0);
;             PG8_WAIT_V(6); PG8_BAR; PG8_MMA(1, 1, At, B1); PG8_BAR;
;             PG8_LDB(B0, 1, 0); PG8_SCHED; PG8_LDA(At, 1, 0); PG8_STAGE(PG8_SA(0, 1), a2, hA, 0);
;             PG8_WAIT_L(8); PG8_BAR; PG8_WAIT_L(0); PG8_MMA(0, 0, At, B0); PG8_BAR; PG8_SCHED;
;             PG8_LDB(B1, 1, 1); PG8_STAGE(PG8_SB(1, 0), b2 + KS, 0, 0);
;             PG8_BAR; PG8_WAIT_L(0); PG8_MMA(0, 1, At, B1); PG8_BAR;
;             PG8_LDA(At, 1, 1); PG8_STAGE(PG8_SA(1, 0), a2 + KS, 0, 0);
	s_add_u32 s48, s64, 0x80000
	s_addc_u32 s49, s65, 0
	s_mov_b32 m0, s27
	s_nop 0
	global_load_lds_dwordx4 v188, s[48:49]
	s_add_u32 s48, s64, 0x82000
	s_addc_u32 s49, s65, 0
	s_mov_b32 m0, s28
	s_nop 0
	global_load_lds_dwordx4 v188, s[48:49]
	s_waitcnt vmcnt(10)
	s_barrier
	v_mfma_f32_16x16x32_bf16 v[52:55], v[176:179], v[136:139], 0
	v_mfma_f32_16x16x32_bf16 v[48:51], v[184:187], v[136:139], 0
	v_mfma_f32_16x16x32_bf16 v[36:39], v[176:179], v[152:155], 0
	v_mfma_f32_16x16x32_bf16 v[32:35], v[184:187], v[152:155], 0
	v_mfma_f32_16x16x32_bf16 v[20:23], v[176:179], v[160:163], 0
	v_mfma_f32_16x16x32_bf16 v[16:19], v[184:187], v[160:163], 0
	v_mfma_f32_16x16x32_bf16 v[4:7], v[176:179], v[168:171], 0
	v_mfma_f32_16x16x32_bf16 v[0:3], v[184:187], v[168:171], 0
	v_mfma_f32_16x16x32_bf16 v[52:55], v[180:183], v[140:143], v[52:55]
	v_mfma_f32_16x16x32_bf16 v[48:51], v[200:203], v[140:143], v[48:51]
	v_mfma_f32_16x16x32_bf16 v[36:39], v[180:183], v[156:159], v[36:39]
	v_mfma_f32_16x16x32_bf16 v[32:35], v[200:203], v[156:159], v[32:35]
	v_mfma_f32_16x16x32_bf16 v[20:23], v[180:183], v[164:167], v[20:23]
	v_mfma_f32_16x16x32_bf16 v[16:19], v[200:203], v[164:167], v[16:19]
	v_mfma_f32_16x16x32_bf16 v[4:7], v[180:183], v[172:175], v[4:7]
	v_mfma_f32_16x16x32_bf16 v[0:3], v[200:203], v[172:175], v[0:3]
	s_barrier
	ds_read_b128 v[120:123], v236 offset:32768
	ds_read_b128 v[124:127], v236 offset:33792
	ds_read_b128 v[128:131], v236 offset:34816
	ds_read_b128 v[132:135], v236 offset:35840
	ds_read_b128 v[136:139], v237 offset:32768
	ds_read_b128 v[140:143], v237 offset:33792
	ds_read_b128 v[152:155], v237 offset:34816
	ds_read_b128 v[156:159], v237 offset:35840
	ds_read_b128 v[160:163], v237 offset:36864
	ds_read_b128 v[164:167], v237 offset:37888
	ds_read_b128 v[168:171], v237 offset:38912
	ds_read_b128 v[172:175], v237 offset:39936
	s_add_u32 s48, s60, 0x80000
	s_addc_u32 s49, s61, 0
	s_mov_b32 m0, s29
	s_nop 0
	global_load_lds_dwordx4 v188, s[48:49]
	s_add_u32 s48, s60, 0x82000
	s_addc_u32 s49, s61, 0
	s_mov_b32 m0, s30
	s_nop 0
	global_load_lds_dwordx4 v188, s[48:49]
	s_waitcnt lgkmcnt(8)
	s_waitcnt vmcnt(10)
	s_barrier
	s_waitcnt lgkmcnt(7)
	v_mfma_f32_16x16x32_bf16 v[148:151], v[120:123], v[136:139], v[148:151]
	v_mfma_f32_16x16x32_bf16 v[144:147], v[128:131], v[136:139], v[144:147]
	s_waitcnt lgkmcnt(5)
	v_mfma_f32_16x16x32_bf16 v[108:111], v[120:123], v[152:155], v[108:111]
	v_mfma_f32_16x16x32_bf16 v[104:107], v[128:131], v[152:155], v[104:107]
	s_waitcnt lgkmcnt(3)
	v_mfma_f32_16x16x32_bf16 v[92:95], v[120:123], v[160:163], v[92:95]
	v_mfma_f32_16x16x32_bf16 v[88:91], v[128:131], v[160:163], v[88:91]
	s_waitcnt lgkmcnt(1)
	v_mfma_f32_16x16x32_bf16 v[76:79], v[120:123], v[168:171], v[76:79]
	v_mfma_f32_16x16x32_bf16 v[72:75], v[128:131], v[168:171], v[72:75]
	v_mfma_f32_16x16x32_bf16 v[148:151], v[124:127], v[140:143], v[148:151]
	v_mfma_f32_16x16x32_bf16 v[144:147], v[132:135], v[140:143], v[144:147]
	v_mfma_f32_16x16x32_bf16 v[108:111], v[124:127], v[156:159], v[108:111]
	v_mfma_f32_16x16x32_bf16 v[104:107], v[132:135], v[156:159], v[104:107]
	v_mfma_f32_16x16x32_bf16 v[92:95], v[124:127], v[164:167], v[92:95]
	v_mfma_f32_16x16x32_bf16 v[88:91], v[132:135], v[164:167], v[88:91]
	s_waitcnt lgkmcnt(0)
	v_mfma_f32_16x16x32_bf16 v[76:79], v[124:127], v[172:175], v[76:79]
	v_mfma_f32_16x16x32_bf16 v[72:75], v[132:135], v[172:175], v[72:75]
	s_barrier
	ds_read_b128 v[176:179], v236 offset:49152
	ds_read_b128 v[180:183], v236 offset:50176
	ds_read_b128 v[184:187], v236 offset:51200
	ds_read_b128 v[200:203], v236 offset:52224
	s_add_u32 s48, s64, 0x4000
	s_addc_u32 s49, s65, 0
	s_mov_b32 m0, s39
	s_nop 0
	global_load_lds_dwordx4 v188, s[48:49]
	s_add_u32 s48, s64, 0x6000
	s_addc_u32 s49, s65, 0
	s_mov_b32 m0, s40
	s_nop 0
	global_load_lds_dwordx4 v188, s[48:49]
	s_waitcnt vmcnt(10)
	s_barrier
	s_waitcnt lgkmcnt(3)
	v_mfma_f32_16x16x32_bf16 v[116:119], v[176:179], v[136:139], v[116:119]
	s_waitcnt lgkmcnt(1)
	v_mfma_f32_16x16x32_bf16 v[112:115], v[184:187], v[136:139], v[112:115]
	v_mfma_f32_16x16x32_bf16 v[100:103], v[176:179], v[152:155], v[100:103]
	v_mfma_f32_16x16x32_bf16 v[96:99], v[184:187], v[152:155], v[96:99]
	v_mfma_f32_16x16x32_bf16 v[84:87], v[176:179], v[160:163], v[84:87]
	v_mfma_f32_16x16x32_bf16 v[80:83], v[184:187], v[160:163], v[80:83]
	v_mfma_f32_16x16x32_bf16 v[68:71], v[176:179], v[168:171], v[68:71]
	v_mfma_f32_16x16x32_bf16 v[64:67], v[184:187], v[168:171], v[64:67]
	v_mfma_f32_16x16x32_bf16 v[116:119], v[180:183], v[140:143], v[116:119]
	s_waitcnt lgkmcnt(0)
	v_mfma_f32_16x16x32_bf16 v[112:115], v[200:203], v[140:143], v[112:115]
	v_mfma_f32_16x16x32_bf16 v[100:103], v[180:183], v[156:159], v[100:103]
	v_mfma_f32_16x16x32_bf16 v[96:99], v[200:203], v[156:159], v[96:99]
	v_mfma_f32_16x16x32_bf16 v[84:87], v[180:183], v[164:167], v[84:87]
	v_mfma_f32_16x16x32_bf16 v[80:83], v[200:203], v[164:167], v[80:83]
	v_mfma_f32_16x16x32_bf16 v[68:71], v[180:183], v[172:175], v[68:71]
	v_mfma_f32_16x16x32_bf16 v[64:67], v[200:203], v[172:175], v[64:67]
	s_barrier
	ds_read_b128 v[136:139], v237 offset:49152
	ds_read_b128 v[140:143], v237 offset:50176
	ds_read_b128 v[152:155], v237 offset:51200
	ds_read_b128 v[156:159], v237 offset:52224
	ds_read_b128 v[160:163], v237 offset:53248
	ds_read_b128 v[164:167], v237 offset:54272
	ds_read_b128 v[168:171], v237 offset:55296
	ds_read_b128 v[172:175], v237 offset:56320
	s_add_u32 s48, s60, 0x4000
	s_addc_u32 s49, s61, 0
	s_mov_b32 m0, s41
	s_nop 0
	global_load_lds_dwordx4 v188, s[48:49]
	s_add_u32 s48, s60, 0x6000
	s_addc_u32 s49, s61, 0
	s_mov_b32 m0, s42
	s_nop 0
	global_load_lds_dwordx4 v188, s[48:49]
	s_barrier
; #define PG8_STAGE(bufoff, gbase, hoff, imm) do { _Pragma("unroll") for (int _i = 0; _i < 2; ++_i) { \
;         asm volatile("s_mov_b32 m0, %0\n\ts_nop 0\n\tglobal_load_lds_dwordx4 %1, %2" \
;             :: "s"(lds0 + (unsigned)((bufoff) + _i * 8192)), "v"(voff0), "s"((const char*)(gbase) + (size_t)(hoff) + (size_t)(_i * 8192)) : "memory"); } } while (0)
; #define PG8_LDA(dst, b, h) do { _Pragma("unroll") for (int m = 0; m < 4; ++m) _Pragma("unroll") for (int k = 0; k < 2; ++k) dst[m][k] = *(const LAS bf16x8*)(lds + PG8_SA(b, h) + aoff + m * 2048 + k * 1024); } while (0)
; #define PG8_LDB(dst, b, h) do { _Pragma("unroll") for (int n = 0; n < 2; ++n) _Pragma("unroll") for (int k = 0; k < 2; ++k) dst[n][k] = *(const LAS bf16x8*)(lds + PG8_SB(b, h) + boff + n * 2048 + k * 1024); } while (0)
; #define PG8_WAIT_V(n) asm volatile("s_waitcnt vmcnt(" #n ")" ::: "memory")
; #define PG8_WAIT_L(n) asm volatile("s_waitcnt lgkmcnt(" #n ")" ::: "memory")
; #define PG8_BAR __builtin_amdgcn_s_barrier()
; template <class Epi>
; __device__ __forceinline__ void gemm_phase(LAS unsigned char* lds, const Gemm g, const StaticOrder& S, const Epi& E) {
;     ...
;             PG8_LDB(B0, 0, 0); PG8_SCHED; PG8_LDA(At, 0, 0); PG8_STAGE(PG8_SA(1, 1), aT + KS, hA, 0);
;             PG8_WAIT_L(8); PG8_BAR; PG8_WAIT_L(0); PG8_MMA(0, 0, At, B0); PG8_BAR; PG8_SCHED;
;             PG8_LDB(B1, 0, 1); PG8_STAGE(PG8_SB(0, 0), b2, 0, 0);
;             PG8_BAR; PG8_WAIT_L(0); PG8_MMA(0, 1, At, B1); PG8_BAR;
;             PG8_LDA(At, 0, 1); PG8_STAGE(PG8_SA(0, 0), a2, 0, 0);
;             PG8_BAR; PG8_WAIT_L(0); PG8_MMA(1, 0, At, B0); PG8_BAR; PG8_SCHED;
;             PG8_STAGE(PG8_SB(0, 1), b2, hB, 0);
;             PG8_WAIT_V(6); PG8_BAR; PG8_MMA(1, 1, At, B1); PG8_BAR;
;             PG8_LDB(B0, 1, 0); PG8_SCHED; PG8_LDA(At, 1, 0); PG8_STAGE(PG8_SA(0, 1), a2, hA, 0);
;             PG8_WAIT_L(8); PG8_BAR; PG8_WAIT_L(0); PG8_MMA(0, 0, At, B0); PG8_BAR; PG8_SCHED;
;             PG8_LDB(B1, 1, 1); PG8_STAGE(PG8_SB(1, 0), b2 + KS, 0, 0);
;             PG8_BAR; PG8_WAIT_L(0); PG8_MMA(0, 1, At, B1); PG8_BAR;
;             PG8_LDA(At, 1, 1); PG8_STAGE(PG8_SA(1, 0), a2 + KS, 0, 0);
;             PG8_BAR; PG8_WAIT_L(0); PG8_MMA(1, 0, At, B0); PG8_BAR; PG8_SCHED;
;             PG8_STAGE(PG8_SB(1, 1), b2 + KS, hB, 0);
;             PG8_WAIT_V(6); PG8_BAR; PG8_MMA(1, 1, At, B1); PG8_BAR;
	s_waitcnt lgkmcnt(7)
	v_mfma_f32_16x16x32_bf16 v[60:63], v[120:123], v[136:139], v[60:63]
	v_mfma_f32_16x16x32_bf16 v[56:59], v[128:131], v[136:139], v[56:59]
	s_waitcnt lgkmcnt(5)
	v_mfma_f32_16x16x32_bf16 v[44:47], v[120:123], v[152:155], v[44:47]
	v_mfma_f32_16x16x32_bf16 v[40:43], v[128:131], v[152:155], v[40:43]
	s_waitcnt lgkmcnt(3)
	v_mfma_f32_16x16x32_bf16 v[28:31], v[120:123], v[160:163], v[28:31]
	v_mfma_f32_16x16x32_bf16 v[24:27], v[128:131], v[160:163], v[24:27]
	s_waitcnt lgkmcnt(1)
	v_mfma_f32_16x16x32_bf16 v[12:15], v[120:123], v[168:171], v[12:15]
	v_mfma_f32_16x16x32_bf16 v[8:11], v[128:131], v[168:171], v[8:11]
	v_mfma_f32_16x16x32_bf16 v[60:63], v[124:127], v[140:143], v[60:63]
	v_mfma_f32_16x16x32_bf16 v[56:59], v[132:135], v[140:143], v[56:59]
	v_mfma_f32_16x16x32_bf16 v[44:47], v[124:127], v[156:159], v[44:47]
	v_mfma_f32_16x16x32_bf16 v[40:43], v[132:135], v[156:159], v[40:43]
	v_mfma_f32_16x16x32_bf16 v[28:31], v[124:127], v[164:167], v[28:31]
	v_mfma_f32_16x16x32_bf16 v[24:27], v[132:135], v[164:167], v[24:27]
	s_waitcnt lgkmcnt(0)
	v_mfma_f32_16x16x32_bf16 v[12:15], v[124:127], v[172:175], v[12:15]
	v_mfma_f32_16x16x32_bf16 v[8:11], v[132:135], v[172:175], v[8:11]
	s_barrier
	s_add_u32 s48, s64, 0x84000
	s_addc_u32 s49, s65, 0
	s_mov_b32 m0, s43
	s_nop 0
	global_load_lds_dwordx4 v188, s[48:49]
	s_add_u32 s48, s64, 0x86000
	s_addc_u32 s49, s65, 0
	s_mov_b32 m0, s66
	s_nop 0
	global_load_lds_dwordx4 v188, s[48:49]
	s_waitcnt vmcnt(10)
	s_barrier
	v_mfma_f32_16x16x32_bf16 v[52:55], v[176:179], v[136:139], v[52:55]
	v_mfma_f32_16x16x32_bf16 v[48:51], v[184:187], v[136:139], v[48:51]
	v_mfma_f32_16x16x32_bf16 v[36:39], v[176:179], v[152:155], v[36:39]
	v_mfma_f32_16x16x32_bf16 v[32:35], v[184:187], v[152:155], v[32:35]
	v_mfma_f32_16x16x32_bf16 v[20:23], v[176:179], v[160:163], v[20:23]
	v_mfma_f32_16x16x32_bf16 v[16:19], v[184:187], v[160:163], v[16:19]
	v_mfma_f32_16x16x32_bf16 v[4:7], v[176:179], v[168:171], v[4:7]
	v_mfma_f32_16x16x32_bf16 v[0:3], v[184:187], v[168:171], v[0:3]
	v_mfma_f32_16x16x32_bf16 v[52:55], v[180:183], v[140:143], v[52:55]
	v_mfma_f32_16x16x32_bf16 v[48:51], v[200:203], v[140:143], v[48:51]
	v_mfma_f32_16x16x32_bf16 v[36:39], v[180:183], v[156:159], v[36:39]
	v_mfma_f32_16x16x32_bf16 v[32:35], v[200:203], v[156:159], v[32:35]
	v_mfma_f32_16x16x32_bf16 v[20:23], v[180:183], v[164:167], v[20:23]
	v_mfma_f32_16x16x32_bf16 v[16:19], v[200:203], v[164:167], v[16:19]
	v_mfma_f32_16x16x32_bf16 v[4:7], v[180:183], v[172:175], v[4:7]
	v_mfma_f32_16x16x32_bf16 v[0:3], v[200:203], v[172:175], v[0:3]
	s_add_i32 s71, s71, 2
	s_add_u32 s69, s69, 0x8000
	s_addc_u32 s70, s70, 0
	s_cmp_gt_u32 s71, 29
	s_mov_b64 s[60:61], s[62:63]
	s_barrier
.LBB0_610:
	s_add_u32 s62, s60, 0x8000
	s_addc_u32 s63, s61, 0
	ds_read_b128 v[120:123], v236
	ds_read_b128 v[124:127], v236 offset:1024
	ds_read_b128 v[128:131], v236 offset:2048
	ds_read_b128 v[132:135], v236 offset:3072
	s_add_u32 s48, s60, 0x84000
	s_addc_u32 s49, s61, 0
	s_add_u32 s64, s60, 0x86000
	s_addc_u32 s65, s61, 0
	s_cmp_eq_u32 s71, 28
	s_cselect_b32 s61, s0, s63
	s_cselect_b32 s60, s1, s62
	ds_read_b128 v[136:139], v237
	ds_read_b128 v[140:143], v237 offset:1024
	ds_read_b128 v[152:155], v237 offset:2048
	ds_read_b128 v[156:159], v237 offset:3072
	ds_read_b128 v[160:163], v237 offset:4096
	ds_read_b128 v[164:167], v237 offset:5120
	ds_read_b128 v[168:171], v237 offset:6144
	ds_read_b128 v[172:175], v237 offset:7168
	s_mov_b32 m0, s67
	s_nop 0
	global_load_lds_dwordx4 v188, s[48:49]
	s_mov_b32 m0, s68
	s_nop 0
	global_load_lds_dwordx4 v188, s[64:65]
	s_waitcnt lgkmcnt(8)
	s_waitcnt vmcnt(10)
	s_barrier
	s_waitcnt lgkmcnt(7)
	v_mfma_f32_16x16x32_bf16 v[148:151], v[120:123], v[136:139], v[148:151]
	v_mfma_f32_16x16x32_bf16 v[144:147], v[128:131], v[136:139], v[144:147]
	s_waitcnt lgkmcnt(5)
	v_mfma_f32_16x16x32_bf16 v[108:111], v[120:123], v[152:155], v[108:111]
	v_mfma_f32_16x16x32_bf16 v[104:107], v[128:131], v[152:155], v[104:107]
	s_waitcnt lgkmcnt(3)
	v_mfma_f32_16x16x32_bf16 v[92:95], v[120:123], v[160:163], v[92:95]
	v_mfma_f32_16x16x32_bf16 v[88:91], v[128:131], v[160:163], v[88:91]
	s_waitcnt lgkmcnt(1)
	v_mfma_f32_16x16x32_bf16 v[76:79], v[120:123], v[168:171], v[76:79]
	v_mfma_f32_16x16x32_bf16 v[72:75], v[128:131], v[168:171], v[72:75]
	v_mfma_f32_16x16x32_bf16 v[148:151], v[124:127], v[140:143], v[148:151]
	v_mfma_f32_16x16x32_bf16 v[144:147], v[132:135], v[140:143], v[144:147]
	v_mfma_f32_16x16x32_bf16 v[108:111], v[124:127], v[156:159], v[108:111]
	v_mfma_f32_16x16x32_bf16 v[104:107], v[132:135], v[156:159], v[104:107]
	v_mfma_f32_16x16x32_bf16 v[92:95], v[124:127], v[164:167], v[92:95]
	v_mfma_f32_16x16x32_bf16 v[88:91], v[132:135], v[164:167], v[88:91]
	s_waitcnt lgkmcnt(0)
	v_mfma_f32_16x16x32_bf16 v[76:79], v[124:127], v[172:175], v[76:79]
	v_mfma_f32_16x16x32_bf16 v[72:75], v[132:135], v[172:175], v[72:75]
	s_barrier
	ds_read_b128 v[176:179], v236 offset:16384
	ds_read_b128 v[180:183], v236 offset:17408
	ds_read_b128 v[184:187], v236 offset:18432
	ds_read_b128 v[200:203], v236 offset:19456
	s_cselect_b32 s64, s55, s69
	s_cselect_b32 s65, s53, s70
	s_mov_b32 m0, s24
	s_nop 0
	global_load_lds_dwordx4 v188, s[64:65]
	s_add_u32 s48, s64, 0x2000
	s_addc_u32 s49, s65, 0
	s_mov_b32 m0, s25
	s_nop 0
	global_load_lds_dwordx4 v188, s[48:49]
	s_waitcnt vmcnt(10)
	s_barrier
; #define PG8_STAGE(bufoff, gbase, hoff, imm) do { _Pragma("unroll") for (int _i = 0; _i < 2; ++_i) { \
;         asm volatile("s_mov_b32 m0, %0\n\ts_nop 0\n\tglobal_load_lds_dwordx4 %1, %2" \
;             :: "s"(lds0 + (unsigned)((bufoff) + _i * 8192)), "v"(voff0), "s"((const char*)(gbase) + (size_t)(hoff) + (size_t)(_i * 8192)) : "memory"); } } while (0)
; #define PG8_LDA(dst, b, h) do { _Pragma("unroll") for (int m = 0; m < 4; ++m) _Pragma("unroll") for (int k = 0; k < 2; ++k) dst[m][k] = *(const LAS bf16x8*)(lds + PG8_SA(b, h) + aoff + m * 2048 + k * 1024); } while (0)
; #define PG8_LDB(dst, b, h) do { _Pragma("unroll") for (int n = 0; n < 2; ++n) _Pragma("unroll") for (int k = 0; k < 2; ++k) dst[n][k] = *(const LAS bf16x8*)(lds + PG8_SB(b, h) + boff + n * 2048 + k * 1024); } while (0)
; #define PG8_WAIT_V(n) asm volatile("s_waitcnt vmcnt(" #n ")" ::: "memory")
; #define PG8_WAIT_L(n) asm volatile("s_waitcnt lgkmcnt(" #n ")" ::: "memory")
; #define PG8_BAR __builtin_amdgcn_s_barrier()
; template <class Epi>
; __device__ __forceinline__ void gemm_phase(LAS unsigned char* lds, const Gemm g, const StaticOrder& S, const Epi& E) {
;     ...
;             PG8_LDB(B0, 0, 0); PG8_SCHED; PG8_LDA(At, 0, 0); PG8_STAGE(PG8_SA(1, 1), aT + KS, hA, 0);
;             PG8_WAIT_L(8); PG8_BAR; PG8_WAIT_L(0); PG8_MMA(0, 0, At, B0); PG8_BAR; PG8_SCHED;
;             PG8_LDB(B1, 0, 1); PG8_STAGE(PG8_SB(0, 0), b2, 0, 0);
;             PG8_BAR; PG8_WAIT_L(0); PG8_MMA(0, 1, At, B1); PG8_BAR;
;             PG8_LDA(At, 0, 1); PG8_STAGE(PG8_SA(0, 0), a2, 0, 0);
;             PG8_BAR; PG8_WAIT_L(0); PG8_MMA(1, 0, At, B0); PG8_BAR; PG8_SCHED;
;             PG8_STAGE(PG8_SB(0, 1), b2, hB, 0);
;             PG8_WAIT_V(6); PG8_BAR; PG8_MMA(1, 1, At, B1); PG8_BAR;
;             PG8_LDB(B0, 1, 0); PG8_SCHED; PG8_LDA(At, 1, 0); PG8_STAGE(PG8_SA(0, 1), a2, hA, 0);
;             PG8_WAIT_L(8); PG8_BAR; PG8_WAIT_L(0); PG8_MMA(0, 0, At, B0); PG8_BAR; PG8_SCHED;
;             PG8_LDB(B1, 1, 1); PG8_STAGE(PG8_SB(1, 0), b2 + KS, 0, 0);
;             PG8_BAR; PG8_WAIT_L(0); PG8_MMA(0, 1, At, B1); PG8_BAR;
;             PG8_LDA(At, 1, 1); PG8_STAGE(PG8_SA(1, 0), a2 + KS, 0, 0);
;             PG8_BAR; PG8_WAIT_L(0); PG8_MMA(1, 0, At, B0); PG8_BAR; PG8_SCHED;
;             PG8_STAGE(PG8_SB(1, 1), b2 + KS, hB, 0);
;             PG8_WAIT_V(6); PG8_BAR; PG8_MMA(1, 1, At, B1); PG8_BAR;
	s_waitcnt lgkmcnt(3)
	v_mfma_f32_16x16x32_bf16 v[116:119], v[176:179], v[136:139], v[116:119]
	s_waitcnt lgkmcnt(1)
	v_mfma_f32_16x16x32_bf16 v[112:115], v[184:187], v[136:139], v[112:115]
	v_mfma_f32_16x16x32_bf16 v[100:103], v[176:179], v[152:155], v[100:103]
	v_mfma_f32_16x16x32_bf16 v[96:99], v[184:187], v[152:155], v[96:99]
	v_mfma_f32_16x16x32_bf16 v[84:87], v[176:179], v[160:163], v[84:87]
	v_mfma_f32_16x16x32_bf16 v[80:83], v[184:187], v[160:163], v[80:83]
	v_mfma_f32_16x16x32_bf16 v[68:71], v[176:179], v[168:171], v[68:71]
	v_mfma_f32_16x16x32_bf16 v[64:67], v[184:187], v[168:171], v[64:67]
	v_mfma_f32_16x16x32_bf16 v[116:119], v[180:183], v[140:143], v[116:119]
	s_waitcnt lgkmcnt(0)
	v_mfma_f32_16x16x32_bf16 v[112:115], v[200:203], v[140:143], v[112:115]
	v_mfma_f32_16x16x32_bf16 v[100:103], v[180:183], v[156:159], v[100:103]
	v_mfma_f32_16x16x32_bf16 v[96:99], v[200:203], v[156:159], v[96:99]
	v_mfma_f32_16x16x32_bf16 v[84:87], v[180:183], v[164:167], v[84:87]
	v_mfma_f32_16x16x32_bf16 v[80:83], v[200:203], v[164:167], v[80:83]
	v_mfma_f32_16x16x32_bf16 v[68:71], v[180:183], v[172:175], v[68:71]
	v_mfma_f32_16x16x32_bf16 v[64:67], v[200:203], v[172:175], v[64:67]
	s_barrier
	ds_read_b128 v[136:139], v237 offset:16384
	ds_read_b128 v[140:143], v237 offset:17408
	ds_read_b128 v[152:155], v237 offset:18432
	ds_read_b128 v[156:159], v237 offset:19456
	ds_read_b128 v[160:163], v237 offset:20480
	ds_read_b128 v[164:167], v237 offset:21504
	ds_read_b128 v[168:171], v237 offset:22528
	ds_read_b128 v[172:175], v237 offset:23552
	s_mov_b32 m0, s22
	s_nop 0
	global_load_lds_dwordx4 v188, s[60:61]
	s_add_u32 s48, s60, 0x2000
	s_addc_u32 s49, s61, 0
	s_mov_b32 m0, s26
	s_nop 0
	global_load_lds_dwordx4 v188, s[48:49]
	s_barrier
	s_waitcnt lgkmcnt(7)
	v_mfma_f32_16x16x32_bf16 v[60:63], v[120:123], v[136:139], v[60:63]
	v_mfma_f32_16x16x32_bf16 v[56:59], v[128:131], v[136:139], v[56:59]
	s_waitcnt lgkmcnt(5)
	v_mfma_f32_16x16x32_bf16 v[44:47], v[120:123], v[152:155], v[44:47]
	v_mfma_f32_16x16x32_bf16 v[40:43], v[128:131], v[152:155], v[40:43]
	s_waitcnt lgkmcnt(3)
	v_mfma_f32_16x16x32_bf16 v[28:31], v[120:123], v[160:163], v[28:31]
	v_mfma_f32_16x16x32_bf16 v[24:27], v[128:131], v[160:163], v[24:27]
	s_waitcnt lgkmcnt(1)
	v_mfma_f32_16x16x32_bf16 v[12:15], v[120:123], v[168:171], v[12:15]
	v_mfma_f32_16x16x32_bf16 v[8:11], v[128:131], v[168:171], v[8:11]
	v_mfma_f32_16x16x32_bf16 v[60:63], v[124:127], v[140:143], v[60:63]
	v_mfma_f32_16x16x32_bf16 v[56:59], v[132:135], v[140:143], v[56:59]
	v_mfma_f32_16x16x32_bf16 v[44:47], v[124:127], v[156:159], v[44:47]
	v_mfma_f32_16x16x32_bf16 v[40:43], v[132:135], v[156:159], v[40:43]
	v_mfma_f32_16x16x32_bf16 v[28:31], v[124:127], v[164:167], v[28:31]
	v_mfma_f32_16x16x32_bf16 v[24:27], v[132:135], v[164:167], v[24:27]
	s_waitcnt lgkmcnt(0)
	v_mfma_f32_16x16x32_bf16 v[12:15], v[124:127], v[172:175], v[12:15]
	v_mfma_f32_16x16x32_bf16 v[8:11], v[132:135], v[172:175], v[8:11]
	s_barrier
	s_add_u32 s48, s64, 0x80000
	s_addc_u32 s49, s65, 0
	s_mov_b32 m0, s27
	s_nop 0
	global_load_lds_dwordx4 v188, s[48:49]
	s_add_u32 s48, s64, 0x82000
	s_addc_u32 s49, s65, 0
	s_mov_b32 m0, s28
	s_nop 0
	global_load_lds_dwordx4 v188, s[48:49]
	s_waitcnt vmcnt(10)
	s_barrier
	v_mfma_f32_16x16x32_bf16 v[52:55], v[176:179], v[136:139], v[52:55]
	v_mfma_f32_16x16x32_bf16 v[48:51], v[184:187], v[136:139], v[48:51]
	v_mfma_f32_16x16x32_bf16 v[36:39], v[176:179], v[152:155], v[36:39]
	v_mfma_f32_16x16x32_bf16 v[32:35], v[184:187], v[152:155], v[32:35]
	v_mfma_f32_16x16x32_bf16 v[20:23], v[176:179], v[160:163], v[20:23]
	v_mfma_f32_16x16x32_bf16 v[16:19], v[184:187], v[160:163], v[16:19]
	v_mfma_f32_16x16x32_bf16 v[4:7], v[176:179], v[168:171], v[4:7]
	v_mfma_f32_16x16x32_bf16 v[0:3], v[184:187], v[168:171], v[0:3]
	v_mfma_f32_16x16x32_bf16 v[52:55], v[180:183], v[140:143], v[52:55]
	v_mfma_f32_16x16x32_bf16 v[48:51], v[200:203], v[140:143], v[48:51]
	v_mfma_f32_16x16x32_bf16 v[36:39], v[180:183], v[156:159], v[36:39]
	v_mfma_f32_16x16x32_bf16 v[32:35], v[200:203], v[156:159], v[32:35]
	v_mfma_f32_16x16x32_bf16 v[20:23], v[180:183], v[164:167], v[20:23]
	v_mfma_f32_16x16x32_bf16 v[16:19], v[200:203], v[164:167], v[16:19]
	v_mfma_f32_16x16x32_bf16 v[4:7], v[180:183], v[172:175], v[4:7]
	v_mfma_f32_16x16x32_bf16 v[0:3], v[200:203], v[172:175], v[0:3]
	s_barrier
	ds_read_b128 v[120:123], v236 offset:32768
	ds_read_b128 v[124:127], v236 offset:33792
	ds_read_b128 v[128:131], v236 offset:34816
	ds_read_b128 v[132:135], v236 offset:35840
	ds_read_b128 v[136:139], v237 offset:32768
	ds_read_b128 v[140:143], v237 offset:33792
	ds_read_b128 v[152:155], v237 offset:34816
	ds_read_b128 v[156:159], v237 offset:35840
	ds_read_b128 v[160:163], v237 offset:36864
	ds_read_b128 v[164:167], v237 offset:37888
	ds_read_b128 v[168:171], v237 offset:38912
	ds_read_b128 v[172:175], v237 offset:39936
	s_add_u32 s48, s60, 0x80000
	s_addc_u32 s49, s61, 0
	s_mov_b32 m0, s29
	s_nop 0
	global_load_lds_dwordx4 v188, s[48:49]
	s_add_u32 s48, s60, 0x82000
	s_addc_u32 s49, s61, 0
	s_mov_b32 m0, s30
	s_nop 0
	global_load_lds_dwordx4 v188, s[48:49]
	s_waitcnt lgkmcnt(8)
	s_waitcnt vmcnt(10)
	s_barrier
; #define PG8_STAGE(bufoff, gbase, hoff, imm) do { _Pragma("unroll") for (int _i = 0; _i < 2; ++_i) { \
;         asm volatile("s_mov_b32 m0, %0\n\ts_nop 0\n\tglobal_load_lds_dwordx4 %1, %2" \
;             :: "s"(lds0 + (unsigned)((bufoff) + _i * 8192)), "v"(voff0), "s"((const char*)(gbase) + (size_t)(hoff) + (size_t)(_i * 8192)) : "memory"); } } while (0)
; #define PG8_LDA(dst, b, h) do { _Pragma("unroll") for (int m = 0; m < 4; ++m) _Pragma("unroll") for (int k = 0; k < 2; ++k) dst[m][k] = *(const LAS bf16x8*)(lds + PG8_SA(b, h) + aoff + m * 2048 + k * 1024); } while (0)
; #define PG8_LDB(dst, b, h) do { _Pragma("unroll") for (int n = 0; n < 2; ++n) _Pragma("unroll") for (int k = 0; k < 2; ++k) dst[n][k] = *(const LAS bf16x8*)(lds + PG8_SB(b, h) + boff + n * 2048 + k * 1024); } while (0)
; #define PG8_WAIT_V(n) asm volatile("s_waitcnt vmcnt(" #n ")" ::: "memory")
; #define PG8_WAIT_L(n) asm volatile("s_waitcnt lgkmcnt(" #n ")" ::: "memory")
; #define PG8_BAR __builtin_amdgcn_s_barrier()
; template <class Epi>
; __device__ __forceinline__ void gemm_phase(LAS unsigned char* lds, const Gemm g, const StaticOrder& S, const Epi& E) {
;     ...
;             PG8_LDB(B0, 0, 0); PG8_SCHED; PG8_LDA(At, 0, 0); PG8_STAGE(PG8_SA(1, 1), aT + KS, hA, 0);
;             PG8_WAIT_L(8); PG8_BAR; PG8_WAIT_L(0); PG8_MMA(0, 0, At, B0); PG8_BAR; PG8_SCHED;
;             PG8_LDB(B1, 0, 1); PG8_STAGE(PG8_SB(0, 0), b2, 0, 0);
;             PG8_BAR; PG8_WAIT_L(0); PG8_MMA(0, 1, At, B1); PG8_BAR;
;             PG8_LDA(At, 0, 1); PG8_STAGE(PG8_SA(0, 0), a2, 0, 0);
;             PG8_BAR; PG8_WAIT_L(0); PG8_MMA(1, 0, At, B0); PG8_BAR; PG8_SCHED;
;             PG8_STAGE(PG8_SB(0, 1), b2, hB, 0);
;             PG8_WAIT_V(6); PG8_BAR; PG8_MMA(1, 1, At, B1); PG8_BAR;
;             PG8_LDB(B0, 1, 0); PG8_SCHED; PG8_LDA(At, 1, 0); PG8_STAGE(PG8_SA(0, 1), a2, hA, 0);
;             PG8_WAIT_L(8); PG8_BAR; PG8_WAIT_L(0); PG8_MMA(0, 0, At, B0); PG8_BAR; PG8_SCHED;
;             PG8_LDB(B1, 1, 1); PG8_STAGE(PG8_SB(1, 0), b2 + KS, 0, 0);
;             PG8_BAR; PG8_WAIT_L(0); PG8_MMA(0, 1, At, B1); PG8_BAR;
;             PG8_LDA(At, 1, 1); PG8_STAGE(PG8_SA(1, 0), a2 + KS, 0, 0);
;             PG8_BAR; PG8_WAIT_L(0); PG8_MMA(1, 0, At, B0); PG8_BAR; PG8_SCHED;
;             PG8_STAGE(PG8_SB(1, 1), b2 + KS, hB, 0);
;             PG8_WAIT_V(6); PG8_BAR; PG8_MMA(1, 1, At, B1); PG8_BAR;
	s_waitcnt lgkmcnt(7)
	v_mfma_f32_16x16x32_bf16 v[148:151], v[120:123], v[136:139], v[148:151]
	v_mfma_f32_16x16x32_bf16 v[144:147], v[128:131], v[136:139], v[144:147]
	s_waitcnt lgkmcnt(5)
	v_mfma_f32_16x16x32_bf16 v[108:111], v[120:123], v[152:155], v[108:111]
	v_mfma_f32_16x16x32_bf16 v[104:107], v[128:131], v[152:155], v[104:107]
	s_waitcnt lgkmcnt(3)
	v_mfma_f32_16x16x32_bf16 v[92:95], v[120:123], v[160:163], v[92:95]
	v_mfma_f32_16x16x32_bf16 v[88:91], v[128:131], v[160:163], v[88:91]
	s_waitcnt lgkmcnt(1)
	v_mfma_f32_16x16x32_bf16 v[76:79], v[120:123], v[168:171], v[76:79]
	v_mfma_f32_16x16x32_bf16 v[72:75], v[128:131], v[168:171], v[72:75]
	v_mfma_f32_16x16x32_bf16 v[148:151], v[124:127], v[140:143], v[148:151]
	v_mfma_f32_16x16x32_bf16 v[144:147], v[132:135], v[140:143], v[144:147]
	v_mfma_f32_16x16x32_bf16 v[108:111], v[124:127], v[156:159], v[108:111]
	v_mfma_f32_16x16x32_bf16 v[104:107], v[132:135], v[156:159], v[104:107]
	v_mfma_f32_16x16x32_bf16 v[92:95], v[124:127], v[164:167], v[92:95]
	v_mfma_f32_16x16x32_bf16 v[88:91], v[132:135], v[164:167], v[88:91]
	s_waitcnt lgkmcnt(0)
	v_mfma_f32_16x16x32_bf16 v[76:79], v[124:127], v[172:175], v[76:79]
	v_mfma_f32_16x16x32_bf16 v[72:75], v[132:135], v[172:175], v[72:75]
	s_barrier
	ds_read_b128 v[176:179], v236 offset:49152
	ds_read_b128 v[180:183], v236 offset:50176
	ds_read_b128 v[184:187], v236 offset:51200
	ds_read_b128 v[200:203], v236 offset:52224
	s_add_u32 s48, s64, 0x4000
	s_addc_u32 s49, s65, 0
	s_mov_b32 m0, s39
	s_nop 0
	global_load_lds_dwordx4 v188, s[48:49]
	s_add_u32 s48, s64, 0x6000
	s_addc_u32 s49, s65, 0
	s_mov_b32 m0, s40
	s_nop 0
	global_load_lds_dwordx4 v188, s[48:49]
	s_waitcnt vmcnt(10)
	s_barrier
	s_waitcnt lgkmcnt(3)
	v_mfma_f32_16x16x32_bf16 v[116:119], v[176:179], v[136:139], v[116:119]
	s_waitcnt lgkmcnt(1)
	v_mfma_f32_16x16x32_bf16 v[112:115], v[184:187], v[136:139], v[112:115]
	v_mfma_f32_16x16x32_bf16 v[100:103], v[176:179], v[152:155], v[100:103]
	v_mfma_f32_16x16x32_bf16 v[96:99], v[184:187], v[152:155], v[96:99]
	v_mfma_f32_16x16x32_bf16 v[84:87], v[176:179], v[160:163], v[84:87]
	v_mfma_f32_16x16x32_bf16 v[80:83], v[184:187], v[160:163], v[80:83]
	v_mfma_f32_16x16x32_bf16 v[68:71], v[176:179], v[168:171], v[68:71]
	v_mfma_f32_16x16x32_bf16 v[64:67], v[184:187], v[168:171], v[64:67]
	v_mfma_f32_16x16x32_bf16 v[116:119], v[180:183], v[140:143], v[116:119]
	s_waitcnt lgkmcnt(0)
	v_mfma_f32_16x16x32_bf16 v[112:115], v[200:203], v[140:143], v[112:115]
	v_mfma_f32_16x16x32_bf16 v[100:103], v[180:183], v[156:159], v[100:103]
	v_mfma_f32_16x16x32_bf16 v[96:99], v[200:203], v[156:159], v[96:99]
	v_mfma_f32_16x16x32_bf16 v[84:87], v[180:183], v[164:167], v[84:87]
	v_mfma_f32_16x16x32_bf16 v[80:83], v[200:203], v[164:167], v[80:83]
	v_mfma_f32_16x16x32_bf16 v[68:71], v[180:183], v[172:175], v[68:71]
	v_mfma_f32_16x16x32_bf16 v[64:67], v[200:203], v[172:175], v[64:67]
	s_barrier
	ds_read_b128 v[136:139], v237 offset:49152
	ds_read_b128 v[140:143], v237 offset:50176
	ds_read_b128 v[152:155], v237 offset:51200
	ds_read_b128 v[156:159], v237 offset:52224
	ds_read_b128 v[160:163], v237 offset:53248
	ds_read_b128 v[164:167], v237 offset:54272
	ds_read_b128 v[168:171], v237 offset:55296
	ds_read_b128 v[172:175], v237 offset:56320
	s_add_u32 s48, s60, 0x4000
	s_addc_u32 s49, s61, 0
	s_mov_b32 m0, s41
	s_nop 0
	global_load_lds_dwordx4 v188, s[48:49]
	s_add_u32 s48, s60, 0x6000
	s_addc_u32 s49, s61, 0
	s_mov_b32 m0, s42
	s_nop 0
	global_load_lds_dwordx4 v188, s[48:49]
	s_barrier
	s_waitcnt lgkmcnt(7)
	v_mfma_f32_16x16x32_bf16 v[60:63], v[120:123], v[136:139], v[60:63]
	v_mfma_f32_16x16x32_bf16 v[56:59], v[128:131], v[136:139], v[56:59]
	s_waitcnt lgkmcnt(5)
	v_mfma_f32_16x16x32_bf16 v[44:47], v[120:123], v[152:155], v[44:47]
	v_mfma_f32_16x16x32_bf16 v[40:43], v[128:131], v[152:155], v[40:43]
	s_waitcnt lgkmcnt(3)
	v_mfma_f32_16x16x32_bf16 v[28:31], v[120:123], v[160:163], v[28:31]
	v_mfma_f32_16x16x32_bf16 v[24:27], v[128:131], v[160:163], v[24:27]
	s_waitcnt lgkmcnt(1)
	v_mfma_f32_16x16x32_bf16 v[12:15], v[120:123], v[168:171], v[12:15]
	v_mfma_f32_16x16x32_bf16 v[8:11], v[128:131], v[168:171], v[8:11]
	v_mfma_f32_16x16x32_bf16 v[60:63], v[124:127], v[140:143], v[60:63]
	v_mfma_f32_16x16x32_bf16 v[56:59], v[132:135], v[140:143], v[56:59]
	v_mfma_f32_16x16x32_bf16 v[44:47], v[124:127], v[156:159], v[44:47]
	v_mfma_f32_16x16x32_bf16 v[40:43], v[132:135], v[156:159], v[40:43]
	v_mfma_f32_16x16x32_bf16 v[28:31], v[124:127], v[164:167], v[28:31]
	v_mfma_f32_16x16x32_bf16 v[24:27], v[132:135], v[164:167], v[24:27]
	s_waitcnt lgkmcnt(0)
	v_mfma_f32_16x16x32_bf16 v[12:15], v[124:127], v[172:175], v[12:15]
	v_mfma_f32_16x16x32_bf16 v[8:11], v[132:135], v[172:175], v[8:11]
	s_barrier
	s_add_u32 s48, s64, 0x84000
	s_addc_u32 s49, s65, 0
	s_mov_b32 m0, s43
	s_nop 0
	global_load_lds_dwordx4 v188, s[48:49]
	s_add_u32 s48, s64, 0x86000
	s_addc_u32 s49, s65, 0
	s_mov_b32 m0, s66
	s_nop 0
	global_load_lds_dwordx4 v188, s[48:49]
	s_waitcnt vmcnt(10)
	s_barrier
	v_mfma_f32_16x16x32_bf16 v[52:55], v[176:179], v[136:139], v[52:55]
	v_mfma_f32_16x16x32_bf16 v[48:51], v[184:187], v[136:139], v[48:51]
	v_mfma_f32_16x16x32_bf16 v[36:39], v[176:179], v[152:155], v[36:39]
	v_mfma_f32_16x16x32_bf16 v[32:35], v[184:187], v[152:155], v[32:35]
	v_mfma_f32_16x16x32_bf16 v[20:23], v[176:179], v[160:163], v[20:23]
	v_mfma_f32_16x16x32_bf16 v[16:19], v[184:187], v[160:163], v[16:19]
	v_mfma_f32_16x16x32_bf16 v[4:7], v[176:179], v[168:171], v[4:7]
	v_mfma_f32_16x16x32_bf16 v[0:3], v[184:187], v[168:171], v[0:3]
	v_mfma_f32_16x16x32_bf16 v[52:55], v[180:183], v[140:143], v[52:55]
	v_mfma_f32_16x16x32_bf16 v[48:51], v[200:203], v[140:143], v[48:51]
	v_mfma_f32_16x16x32_bf16 v[36:39], v[180:183], v[156:159], v[36:39]
	v_mfma_f32_16x16x32_bf16 v[32:35], v[200:203], v[156:159], v[32:35]
	v_mfma_f32_16x16x32_bf16 v[20:23], v[180:183], v[164:167], v[20:23]
	v_mfma_f32_16x16x32_bf16 v[16:19], v[200:203], v[164:167], v[16:19]
	v_mfma_f32_16x16x32_bf16 v[4:7], v[180:183], v[172:175], v[4:7]
	v_mfma_f32_16x16x32_bf16 v[0:3], v[200:203], v[172:175], v[0:3]
	s_add_i32 s71, s71, 2
	s_add_u32 s69, s69, 0x8000
	s_addc_u32 s70, s70, 0
	s_cmp_gt_u32 s71, 29
	s_mov_b64 s[60:61], s[62:63]
	s_barrier
;     __device__ __forceinline__ void operator()(f32x4 (&acc)[2][2][4][2], const Unit& u, int wr, int wc, int fr, int fq, LAS unsigned char*) const {
;         const int b = u.pm >> 6;
;         const int col0 = u.pn * BM + wc * 32 + 8 * fq;
;         const size_t off0 = (size_t)(u.pm * BM + wr * 64 + fr) * D + col0;
;         f32x4 sc[2][2];
; #pragma unroll
;         for (int bj = 0; bj < 2; ++bj)
; #pragma unroll
;             for (int n = 0; n < 2; ++n) { f32x4 gt = *(const f32x4*)(gate + (size_t)b * MODW + col0 + bj * HALF + n * 4); sc[bj][n] = gt + 1.0f;
;                 if (cs) sc[bj][n] *= *(const f32x4*)(cs + col0 + bj * HALF + n * 4); }
;         if (IN_F32) {
; #pragma unroll
;             for (int ai = 0; ai < 2; ++ai) {
;                 f32x4 r[4][2][2];
; #pragma unroll
;                 for (int m = 0; m < 4; ++m)
; #pragma unroll
;                     for (int bj = 0; bj < 2; ++bj)
; #pragma unroll
;                         for (int n = 0; n < 2; ++n) r[m][bj][n] = *(const f32x4*)((const float*)in + off0 + (size_t)(ai * HALF + m * 16) * D + bj * HALF + n * 4);
; #pragma unroll
;                 for (int m = 0; m < 4; ++m)
; #pragma unroll
;                     for (int bj = 0; bj < 2; ++bj) { const f32x4 r0 = r[m][bj][0] + sc[bj][0] * acc[ai][bj][m][0], r1 = r[m][bj][1] + sc[bj][1] * acc[ai][bj][m][1];
;                         u32x4 w; w.x = cvt_pk_bf16(r0[0], r0[1]); w.y = cvt_pk_bf16(r0[2], r0[3]); w.z = cvt_pk_bf16(r1[0], r1[1]); w.w = cvt_pk_bf16(r1[2], r1[3]);
;                         *(u32x4*)(out + off0 + (size_t)(ai * HALF + m * 16) * D + bj * HALF) = w; }
;                 asm volatile("" ::: "memory");
;             }
;         } else {
;             u32x4 xb[2][4][2];
; #pragma unroll
;             for (int ai = 0; ai < 2; ++ai)
; #pragma unroll
;                 for (int m = 0; m < 4; ++m)
; #pragma unroll
;                     for (int bj = 0; bj < 2; ++bj) xb[ai][m][bj] = *(const u32x4*)((const bf16_t*)in + off0 + (size_t)(ai * HALF + m * 16) * D + bj * HALF);
; #pragma unroll
;             for (int ai = 0; ai < 2; ++ai)
; #pragma unroll
;                 for (int m = 0; m < 4; ++m)
; #pragma unroll
;                     for (int bj = 0; bj < 2; ++bj) { const u32x4 x = xb[ai][m][bj];
	s_cbranch_scc0 .LBB0_610
	s_ashr_i32 s0, s50, 6
	s_mul_hi_i32 s1, s0, 0xc000
	s_mul_i32 s0, s0, 0xc000
	v_lshl_or_b32 v128, s51, 8, v234
	s_add_u32 s0, s37, s0
	v_ashrrev_i32_e32 v129, 31, v128
	s_addc_u32 s1, s38, s1
	v_lshl_add_u64 v[130:131], v[128:129], 2, s[0:1]
	global_load_dwordx4 v[120:123], v[130:131], off offset:16
	global_load_dwordx4 v[124:127], v[130:131], off
	s_mov_b32 s51, s52
	s_mov_b64 s[62:63], s[58:59]
	s_mov_b64 s[60:61], s[56:57]
	s_waitcnt vmcnt(1)
	v_pk_add_f32 v[210:211], v[122:123], 1.0 op_sel_hi:[1,0]
	s_waitcnt vmcnt(0)
	v_pk_add_f32 v[214:215], v[126:127], 1.0 op_sel_hi:[1,0]
	v_pk_add_f32 v[212:213], v[124:125], 1.0 op_sel_hi:[1,0]
	v_pk_add_f32 v[208:209], v[120:121], 1.0 op_sel_hi:[1,0]
	global_load_dwordx4 v[120:123], v[130:131], off offset:528
	global_load_dwordx4 v[124:127], v[130:131], off offset:512
	s_waitcnt vmcnt(1)
	v_pk_add_f32 v[200:201], v[120:121], 1.0 op_sel_hi:[1,0]
	v_lshl_add_u32 v120, s50, 8, v233
	v_ashrrev_i32_e32 v121, 31, v120
	v_lshlrev_b64 v[120:121], 11, v[120:121]
	v_lshl_add_u64 v[120:121], v[120:121], 0, v[128:129]
	v_lshlrev_b64 v[216:217], 1, v[120:121]
	v_lshl_add_u64 v[120:121], s[8:9], 0, v[216:217]
	global_load_dwordx4 v[238:241], v[120:121], off
	global_load_dwordx4 v[184:187], v[120:121], off offset:256
	v_pk_add_f32 v[202:203], v[122:123], 1.0 op_sel_hi:[1,0]
	v_add_co_u32_e32 v122, vcc, s45, v120
	s_waitcnt vmcnt(2)
	v_pk_add_f32 v[206:207], v[126:127], 1.0 op_sel_hi:[1,0]
	v_addc_co_u32_e32 v123, vcc, 0, v121, vcc
	global_load_dwordx4 v[180:183], v[122:123], off
	global_load_dwordx4 v[176:179], v[122:123], off offset:256
	v_add_co_u32_e32 v122, vcc, s36, v120
	v_pk_add_f32 v[204:205], v[124:125], 1.0 op_sel_hi:[1,0]
	s_nop 0
	v_addc_co_u32_e32 v123, vcc, 0, v121, vcc
	global_load_dwordx4 v[172:175], v[122:123], off
	global_load_dwordx4 v[168:171], v[122:123], off offset:256
	v_add_co_u32_e32 v122, vcc, s23, v120
	s_mov_b32 s50, s54
	s_nop 0
	v_addc_co_u32_e32 v123, vcc, 0, v121, vcc
	global_load_dwordx4 v[164:167], v[122:123], off
	global_load_dwordx4 v[160:163], v[122:123], off offset:256
	v_add_co_u32_e32 v122, vcc, s93, v120
	s_waitcnt vmcnt(7)
	v_lshlrev_b32_e32 v230, 16, v238
	v_addc_co_u32_e32 v123, vcc, 0, v121, vcc
	global_load_dwordx4 v[156:159], v[122:123], off
	global_load_dwordx4 v[152:155], v[122:123], off offset:256
	v_add_co_u32_e32 v122, vcc, s33, v120
	v_and_b32_e32 v231, 0xffff0000, v238
	s_nop 0
	v_addc_co_u32_e32 v123, vcc, 0, v121, vcc
	global_load_dwordx4 v[140:143], v[122:123], off
	global_load_dwordx4 v[136:139], v[122:123], off offset:256
	v_add_co_u32_e32 v122, vcc, s18, v120
	v_lshlrev_b32_e32 v242, 16, v240
	s_nop 0
	v_addc_co_u32_e32 v123, vcc, 0, v121, vcc
	global_load_dwordx4 v[132:135], v[122:123], off
	global_load_dwordx4 v[128:131], v[122:123], off offset:256
	v_add_co_u32_e32 v120, vcc, s19, v120
	v_and_b32_e32 v243, 0xffff0000, v240
	s_nop 0
	v_addc_co_u32_e32 v121, vcc, 0, v121, vcc
	global_load_dwordx4 v[124:127], v[120:121], off
	s_nop 0
	global_load_dwordx4 v[120:123], v[120:121], off offset:256
	v_lshlrev_b32_e32 v238, 16, v239
	v_and_b32_e32 v239, 0xffff0000, v239
	v_lshlrev_b32_e32 v240, 16, v241
	v_and_b32_e32 v241, 0xffff0000, v241
	v_pk_fma_f32 v[148:149], v[148:149], v[212:213], v[230:231]
	v_pk_fma_f32 v[144:145], v[144:145], v[208:209], v[242:243]
	v_pk_fma_f32 v[150:151], v[150:151], v[214:215], v[238:239]
	v_pk_fma_f32 v[230:231], v[146:147], v[210:211], v[240:241]
	v_cvt_pk_bf16_f32 v146, v148, v149
	v_cvt_pk_bf16_f32 v147, v150, v151
	v_cvt_pk_bf16_f32 v148, v144, v145
	v_lshl_add_u64 v[144:145], s[10:11], 0, v[216:217]
	v_cvt_pk_bf16_f32 v149, v230, v231
	global_store_dwordx4 v[144:145], v[146:149], off
	s_waitcnt vmcnt(15)
	v_lshlrev_b32_e32 v150, 16, v186
	v_and_b32_e32 v151, 0xffff0000, v186
	v_lshlrev_b32_e32 v146, 16, v184
	v_and_b32_e32 v147, 0xffff0000, v184
	v_lshlrev_b32_e32 v148, 16, v185
	v_and_b32_e32 v149, 0xffff0000, v185
	v_lshlrev_b32_e32 v184, 16, v187
	v_and_b32_e32 v185, 0xffff0000, v187
	v_pk_fma_f32 v[118:119], v[118:119], v[206:207], v[148:149]
	v_pk_fma_f32 v[116:117], v[116:117], v[204:205], v[146:147]
	v_pk_fma_f32 v[146:147], v[114:115], v[202:203], v[184:185]
	v_pk_fma_f32 v[114:115], v[112:113], v[200:201], v[150:151]
	v_cvt_pk_bf16_f32 v112, v116, v117
	v_cvt_pk_bf16_f32 v113, v118, v119
	s_waitcnt vmcnt(14)
	v_lshlrev_b32_e32 v116, 16, v182
	v_cvt_pk_bf16_f32 v114, v114, v115
	v_cvt_pk_bf16_f32 v115, v146, v147
	global_store_dwordx4 v[144:145], v[112:115], off offset:256
	v_and_b32_e32 v117, 0xffff0000, v182
	v_lshlrev_b32_e32 v118, 16, v183
	v_lshlrev_b32_e32 v112, 16, v180
	v_and_b32_e32 v113, 0xffff0000, v180
	v_and_b32_e32 v119, 0xffff0000, v183
	v_pk_fma_f32 v[108:109], v[108:109], v[212:213], v[112:113]
	v_lshlrev_b32_e32 v114, 16, v181
	v_and_b32_e32 v115, 0xffff0000, v181
	v_pk_fma_f32 v[112:113], v[106:107], v[210:211], v[118:119]
	v_pk_fma_f32 v[106:107], v[104:105], v[208:209], v[116:117]
	v_cvt_pk_bf16_f32 v104, v108, v109
	v_add_co_u32_e32 v108, vcc, s45, v144
	v_pk_fma_f32 v[110:111], v[110:111], v[214:215], v[114:115]
	s_nop 0
	v_addc_co_u32_e32 v109, vcc, 0, v145, vcc
	v_cvt_pk_bf16_f32 v105, v110, v111
	v_cvt_pk_bf16_f32 v106, v106, v107
	v_cvt_pk_bf16_f32 v107, v112, v113
	global_store_dwordx4 v[108:109], v[104:107], off
	s_waitcnt vmcnt(15)
	v_lshlrev_b32_e32 v110, 16, v178
	v_and_b32_e32 v111, 0xffff0000, v178
	v_lshlrev_b32_e32 v104, 16, v176
	v_and_b32_e32 v105, 0xffff0000, v176
	v_lshlrev_b32_e32 v106, 16, v177
	v_and_b32_e32 v107, 0xffff0000, v177
	v_lshlrev_b32_e32 v112, 16, v179
	v_and_b32_e32 v113, 0xffff0000, v179
	v_pk_fma_f32 v[102:103], v[102:103], v[206:207], v[106:107]
	v_pk_fma_f32 v[100:101], v[100:101], v[204:205], v[104:105]
	v_pk_fma_f32 v[104:105], v[98:99], v[202:203], v[112:113]
	v_pk_fma_f32 v[98:99], v[96:97], v[200:201], v[110:111]
	v_cvt_pk_bf16_f32 v96, v100, v101
	v_cvt_pk_bf16_f32 v97, v102, v103
	s_waitcnt vmcnt(14)
; __device__ __forceinline__ unsigned cvt_pk_bf16(float lo, float hi) { unsigned r; asm volatile("v_cvt_pk_bf16_f32 %0, %1, %2" : "=v"(r) : "v"(lo), "v"(hi)); return r; }
;     __device__ __forceinline__ void operator()(f32x4 (&acc)[2][2][4][2], const Unit& u, int wr, int wc, int fr, int fq, LAS unsigned char*) const {
;     ...
;                     for (int bj = 0; bj < 2; ++bj) { const u32x4 x = xb[ai][m][bj];
;                         f32x4 r0 = (f32x4){__uint_as_float(x.x << 16), __uint_as_float(x.x & 0xffff0000u), __uint_as_float(x.y << 16), __uint_as_float(x.y & 0xffff0000u)};
;                         f32x4 r1 = (f32x4){__uint_as_float(x.z << 16), __uint_as_float(x.z & 0xffff0000u), __uint_as_float(x.w << 16), __uint_as_float(x.w & 0xffff0000u)};
;                         r0 += sc[bj][0] * acc[ai][bj][m][0]; r1 += sc[bj][1] * acc[ai][bj][m][1];
;                         u32x4 w; w.x = cvt_pk_bf16(r0[0], r0[1]); w.y = cvt_pk_bf16(r0[2], r0[3]); w.z = cvt_pk_bf16(r1[0], r1[1]); w.w = cvt_pk_bf16(r1[2], r1[3]);
;                         *(u32x4*)(out + off0 + (size_t)(ai * HALF + m * 16) * D + bj * HALF) = w; }
	v_lshlrev_b32_e32 v100, 16, v174
	v_cvt_pk_bf16_f32 v98, v98, v99
	v_cvt_pk_bf16_f32 v99, v104, v105
	global_store_dwordx4 v[108:109], v[96:99], off offset:256
	v_and_b32_e32 v101, 0xffff0000, v174
	v_lshlrev_b32_e32 v102, 16, v175
	v_lshlrev_b32_e32 v96, 16, v172
	v_and_b32_e32 v97, 0xffff0000, v172
	v_and_b32_e32 v103, 0xffff0000, v175
	v_pk_fma_f32 v[92:93], v[92:93], v[212:213], v[96:97]
	v_lshlrev_b32_e32 v98, 16, v173
	v_and_b32_e32 v99, 0xffff0000, v173
	v_pk_fma_f32 v[96:97], v[90:91], v[210:211], v[102:103]
	v_pk_fma_f32 v[90:91], v[88:89], v[208:209], v[100:101]
	v_cvt_pk_bf16_f32 v88, v92, v93
	v_add_co_u32_e32 v92, vcc, s36, v144
	v_pk_fma_f32 v[94:95], v[94:95], v[214:215], v[98:99]
	s_nop 0
	v_addc_co_u32_e32 v93, vcc, 0, v145, vcc
	v_cvt_pk_bf16_f32 v89, v94, v95
	v_cvt_pk_bf16_f32 v90, v90, v91
	v_cvt_pk_bf16_f32 v91, v96, v97
	global_store_dwordx4 v[92:93], v[88:91], off
	s_waitcnt vmcnt(15)
	v_lshlrev_b32_e32 v94, 16, v170
	v_and_b32_e32 v95, 0xffff0000, v170
	v_lshlrev_b32_e32 v88, 16, v168
	v_and_b32_e32 v89, 0xffff0000, v168
	v_lshlrev_b32_e32 v90, 16, v169
	v_and_b32_e32 v91, 0xffff0000, v169
	v_lshlrev_b32_e32 v96, 16, v171
	v_and_b32_e32 v97, 0xffff0000, v171
	v_pk_fma_f32 v[86:87], v[86:87], v[206:207], v[90:91]
	v_pk_fma_f32 v[84:85], v[84:85], v[204:205], v[88:89]
	v_pk_fma_f32 v[88:89], v[82:83], v[202:203], v[96:97]
	v_pk_fma_f32 v[82:83], v[80:81], v[200:201], v[94:95]
	v_cvt_pk_bf16_f32 v80, v84, v85
	v_cvt_pk_bf16_f32 v81, v86, v87
	s_waitcnt vmcnt(14)
	v_lshlrev_b32_e32 v84, 16, v166
	v_cvt_pk_bf16_f32 v82, v82, v83
	v_cvt_pk_bf16_f32 v83, v88, v89
	global_store_dwordx4 v[92:93], v[80:83], off offset:256
	v_and_b32_e32 v85, 0xffff0000, v166
	v_lshlrev_b32_e32 v86, 16, v167
	v_lshlrev_b32_e32 v80, 16, v164
	v_and_b32_e32 v81, 0xffff0000, v164
	v_and_b32_e32 v87, 0xffff0000, v167
	v_pk_fma_f32 v[76:77], v[76:77], v[212:213], v[80:81]
	v_lshlrev_b32_e32 v82, 16, v165
	v_and_b32_e32 v83, 0xffff0000, v165
	v_pk_fma_f32 v[80:81], v[74:75], v[210:211], v[86:87]
	v_pk_fma_f32 v[74:75], v[72:73], v[208:209], v[84:85]
	v_cvt_pk_bf16_f32 v72, v76, v77
	v_add_co_u32_e32 v76, vcc, s23, v144
	v_pk_fma_f32 v[78:79], v[78:79], v[214:215], v[82:83]
	s_nop 0
	v_addc_co_u32_e32 v77, vcc, 0, v145, vcc
	v_cvt_pk_bf16_f32 v73, v78, v79
	v_cvt_pk_bf16_f32 v74, v74, v75
	v_cvt_pk_bf16_f32 v75, v80, v81
	global_store_dwordx4 v[76:77], v[72:75], off
	s_waitcnt vmcnt(15)
	v_lshlrev_b32_e32 v78, 16, v162
	v_and_b32_e32 v79, 0xffff0000, v162
	v_lshlrev_b32_e32 v72, 16, v160
	v_and_b32_e32 v73, 0xffff0000, v160
	v_lshlrev_b32_e32 v74, 16, v161
	v_and_b32_e32 v75, 0xffff0000, v161
	v_lshlrev_b32_e32 v80, 16, v163
	v_and_b32_e32 v81, 0xffff0000, v163
	v_pk_fma_f32 v[70:71], v[70:71], v[206:207], v[74:75]
	v_pk_fma_f32 v[68:69], v[68:69], v[204:205], v[72:73]
	v_pk_fma_f32 v[72:73], v[66:67], v[202:203], v[80:81]
	v_pk_fma_f32 v[66:67], v[64:65], v[200:201], v[78:79]
	v_cvt_pk_bf16_f32 v64, v68, v69
	v_cvt_pk_bf16_f32 v65, v70, v71
	s_waitcnt vmcnt(14)
	v_lshlrev_b32_e32 v68, 16, v158
	v_cvt_pk_bf16_f32 v66, v66, v67
	v_cvt_pk_bf16_f32 v67, v72, v73
	global_store_dwordx4 v[76:77], v[64:67], off offset:256
	v_and_b32_e32 v69, 0xffff0000, v158
	v_lshlrev_b32_e32 v70, 16, v159
	v_lshlrev_b32_e32 v64, 16, v156
	v_and_b32_e32 v65, 0xffff0000, v156
	v_and_b32_e32 v71, 0xffff0000, v159
	v_pk_fma_f32 v[60:61], v[60:61], v[212:213], v[64:65]
	v_lshlrev_b32_e32 v66, 16, v157
	v_and_b32_e32 v67, 0xffff0000, v157
	v_pk_fma_f32 v[64:65], v[58:59], v[210:211], v[70:71]
	v_pk_fma_f32 v[58:59], v[56:57], v[208:209], v[68:69]
	v_cvt_pk_bf16_f32 v56, v60, v61
	v_add_co_u32_e32 v60, vcc, s93, v144
	v_pk_fma_f32 v[62:63], v[62:63], v[214:215], v[66:67]
	s_nop 0
	v_addc_co_u32_e32 v61, vcc, 0, v145, vcc
	v_cvt_pk_bf16_f32 v57, v62, v63
	v_cvt_pk_bf16_f32 v58, v58, v59
	v_cvt_pk_bf16_f32 v59, v64, v65
	global_store_dwordx4 v[60:61], v[56:59], off
	s_waitcnt vmcnt(15)
	v_lshlrev_b32_e32 v62, 16, v154
	v_and_b32_e32 v63, 0xffff0000, v154
	v_lshlrev_b32_e32 v56, 16, v152
	v_and_b32_e32 v57, 0xffff0000, v152
	v_lshlrev_b32_e32 v58, 16, v153
	v_and_b32_e32 v59, 0xffff0000, v153
	v_lshlrev_b32_e32 v64, 16, v155
	v_and_b32_e32 v65, 0xffff0000, v155
	v_pk_fma_f32 v[54:55], v[54:55], v[206:207], v[58:59]
	v_pk_fma_f32 v[52:53], v[52:53], v[204:205], v[56:57]
	v_pk_fma_f32 v[56:57], v[50:51], v[202:203], v[64:65]
	v_pk_fma_f32 v[50:51], v[48:49], v[200:201], v[62:63]
	v_cvt_pk_bf16_f32 v48, v52, v53
	v_cvt_pk_bf16_f32 v49, v54, v55
	s_waitcnt vmcnt(14)
; __device__ __forceinline__ unsigned cvt_pk_bf16(float lo, float hi) { unsigned r; asm volatile("v_cvt_pk_bf16_f32 %0, %1, %2" : "=v"(r) : "v"(lo), "v"(hi)); return r; }
; #define PG8_WAIT_V(n) asm volatile("s_waitcnt vmcnt(" #n ")" ::: "memory")
; #define PG8_BAR __builtin_amdgcn_s_barrier()
; template <class Epi>
; __device__ __forceinline__ void gemm_phase(LAS unsigned char* lds, const Gemm g, const StaticOrder& S, const Epi& E) {
;     ...
;         if (!has_next) break;
; #pragma unroll
;         for (int a = 0; a < 2; ++a)
; #pragma unroll
;             for (int b = 0; b < 2; ++b)
; #pragma unroll
;                 for (int m = 0; m < 4; ++m)
; #pragma unroll
;                     for (int n = 0; n < 2; ++n) acc[a][b][m][n] = (f32x4){0.f, 0.f, 0.f, 0.f};
;         cur = nxt; cA = nA; cB = nB; ++ui;
;     }
;     PG8_WAIT_V(0);
;     if (wr == 0) PG8_BAR;
;     PG8_BAR;
;     __device__ __forceinline__ void operator()(f32x4 (&acc)[2][2][4][2], const Unit& u, int wr, int wc, int fr, int fq, LAS unsigned char*) const {
;     ...
;                     for (int bj = 0; bj < 2; ++bj) { const u32x4 x = xb[ai][m][bj];
;                         f32x4 r0 = (f32x4){__uint_as_float(x.x << 16), __uint_as_float(x.x & 0xffff0000u), __uint_as_float(x.y << 16), __uint_as_float(x.y & 0xffff0000u)};
;                         f32x4 r1 = (f32x4){__uint_as_float(x.z << 16), __uint_as_float(x.z & 0xffff0000u), __uint_as_float(x.w << 16), __uint_as_float(x.w & 0xffff0000u)};
;                         r0 += sc[bj][0] * acc[ai][bj][m][0]; r1 += sc[bj][1] * acc[ai][bj][m][1];
;                         u32x4 w; w.x = cvt_pk_bf16(r0[0], r0[1]); w.y = cvt_pk_bf16(r0[2], r0[3]); w.z = cvt_pk_bf16(r1[0], r1[1]); w.w = cvt_pk_bf16(r1[2], r1[3]);
;                         *(u32x4*)(out + off0 + (size_t)(ai * HALF + m * 16) * D + bj * HALF) = w; }
	v_lshlrev_b32_e32 v52, 16, v142
	v_cvt_pk_bf16_f32 v50, v50, v51
	v_cvt_pk_bf16_f32 v51, v56, v57
	global_store_dwordx4 v[60:61], v[48:51], off offset:256
	v_and_b32_e32 v53, 0xffff0000, v142
	v_lshlrev_b32_e32 v54, 16, v143
	v_lshlrev_b32_e32 v48, 16, v140
	v_and_b32_e32 v49, 0xffff0000, v140
	v_and_b32_e32 v55, 0xffff0000, v143
	v_pk_fma_f32 v[44:45], v[44:45], v[212:213], v[48:49]
	v_lshlrev_b32_e32 v50, 16, v141
	v_and_b32_e32 v51, 0xffff0000, v141
	v_pk_fma_f32 v[48:49], v[42:43], v[210:211], v[54:55]
	v_pk_fma_f32 v[42:43], v[40:41], v[208:209], v[52:53]
	v_cvt_pk_bf16_f32 v40, v44, v45
	v_add_co_u32_e32 v44, vcc, s33, v144
	v_pk_fma_f32 v[46:47], v[46:47], v[214:215], v[50:51]
	s_nop 0
	v_addc_co_u32_e32 v45, vcc, 0, v145, vcc
	v_cvt_pk_bf16_f32 v41, v46, v47
	v_cvt_pk_bf16_f32 v42, v42, v43
	v_cvt_pk_bf16_f32 v43, v48, v49
	global_store_dwordx4 v[44:45], v[40:43], off
	s_waitcnt vmcnt(15)
	v_lshlrev_b32_e32 v46, 16, v138
	v_and_b32_e32 v47, 0xffff0000, v138
	v_lshlrev_b32_e32 v40, 16, v136
	v_and_b32_e32 v41, 0xffff0000, v136
	v_lshlrev_b32_e32 v42, 16, v137
	v_and_b32_e32 v43, 0xffff0000, v137
	v_lshlrev_b32_e32 v48, 16, v139
	v_and_b32_e32 v49, 0xffff0000, v139
	v_pk_fma_f32 v[38:39], v[38:39], v[206:207], v[42:43]
	v_pk_fma_f32 v[36:37], v[36:37], v[204:205], v[40:41]
	v_pk_fma_f32 v[40:41], v[34:35], v[202:203], v[48:49]
	v_pk_fma_f32 v[34:35], v[32:33], v[200:201], v[46:47]
	v_cvt_pk_bf16_f32 v32, v36, v37
	v_cvt_pk_bf16_f32 v33, v38, v39
	s_waitcnt vmcnt(14)
	v_lshlrev_b32_e32 v36, 16, v134
	v_cvt_pk_bf16_f32 v34, v34, v35
	v_cvt_pk_bf16_f32 v35, v40, v41
	global_store_dwordx4 v[44:45], v[32:35], off offset:256
	v_and_b32_e32 v37, 0xffff0000, v134
	v_lshlrev_b32_e32 v38, 16, v135
	v_lshlrev_b32_e32 v32, 16, v132
	v_and_b32_e32 v33, 0xffff0000, v132
	v_and_b32_e32 v39, 0xffff0000, v135
	v_pk_fma_f32 v[28:29], v[28:29], v[212:213], v[32:33]
	v_lshlrev_b32_e32 v34, 16, v133
	v_and_b32_e32 v35, 0xffff0000, v133
	v_pk_fma_f32 v[32:33], v[26:27], v[210:211], v[38:39]
	v_pk_fma_f32 v[26:27], v[24:25], v[208:209], v[36:37]
	v_cvt_pk_bf16_f32 v24, v28, v29
	v_add_co_u32_e32 v28, vcc, s18, v144
	v_pk_fma_f32 v[30:31], v[30:31], v[214:215], v[34:35]
	s_nop 0
	v_addc_co_u32_e32 v29, vcc, 0, v145, vcc
	v_cvt_pk_bf16_f32 v25, v30, v31
	v_cvt_pk_bf16_f32 v26, v26, v27
	v_cvt_pk_bf16_f32 v27, v32, v33
	global_store_dwordx4 v[28:29], v[24:27], off
	s_waitcnt vmcnt(15)
	v_lshlrev_b32_e32 v30, 16, v130
	v_and_b32_e32 v31, 0xffff0000, v130
	v_lshlrev_b32_e32 v24, 16, v128
	v_and_b32_e32 v25, 0xffff0000, v128
	v_lshlrev_b32_e32 v26, 16, v129
	v_and_b32_e32 v27, 0xffff0000, v129
	v_lshlrev_b32_e32 v32, 16, v131
	v_and_b32_e32 v33, 0xffff0000, v131
	v_pk_fma_f32 v[22:23], v[22:23], v[206:207], v[26:27]
	v_pk_fma_f32 v[20:21], v[20:21], v[204:205], v[24:25]
	v_pk_fma_f32 v[24:25], v[18:19], v[202:203], v[32:33]
	v_pk_fma_f32 v[18:19], v[16:17], v[200:201], v[30:31]
	v_cvt_pk_bf16_f32 v16, v20, v21
	v_cvt_pk_bf16_f32 v17, v22, v23
	s_waitcnt vmcnt(14)
	v_lshlrev_b32_e32 v20, 16, v126
	v_cvt_pk_bf16_f32 v18, v18, v19
	v_cvt_pk_bf16_f32 v19, v24, v25
	global_store_dwordx4 v[28:29], v[16:19], off offset:256
	v_and_b32_e32 v21, 0xffff0000, v126
	v_lshlrev_b32_e32 v22, 16, v127
	v_lshlrev_b32_e32 v16, 16, v124
	v_and_b32_e32 v17, 0xffff0000, v124
	v_and_b32_e32 v23, 0xffff0000, v127
	v_pk_fma_f32 v[12:13], v[12:13], v[212:213], v[16:17]
	v_lshlrev_b32_e32 v18, 16, v125
	v_and_b32_e32 v19, 0xffff0000, v125
	v_pk_fma_f32 v[16:17], v[10:11], v[210:211], v[22:23]
	v_pk_fma_f32 v[10:11], v[8:9], v[208:209], v[20:21]
	v_cvt_pk_bf16_f32 v8, v12, v13
	v_add_co_u32_e32 v12, vcc, s19, v144
	v_pk_fma_f32 v[14:15], v[14:15], v[214:215], v[18:19]
	s_nop 0
	v_addc_co_u32_e32 v13, vcc, 0, v145, vcc
	v_cvt_pk_bf16_f32 v9, v14, v15
	v_cvt_pk_bf16_f32 v10, v10, v11
	v_cvt_pk_bf16_f32 v11, v16, v17
	global_store_dwordx4 v[12:13], v[8:11], off
	s_waitcnt vmcnt(15)
	v_lshlrev_b32_e32 v14, 16, v122
	v_and_b32_e32 v15, 0xffff0000, v122
	v_lshlrev_b32_e32 v8, 16, v120
	v_and_b32_e32 v9, 0xffff0000, v120
	v_lshlrev_b32_e32 v16, 16, v123
	v_and_b32_e32 v17, 0xffff0000, v123
	v_lshlrev_b32_e32 v10, 16, v121
	v_and_b32_e32 v11, 0xffff0000, v121
	v_pk_fma_f32 v[4:5], v[4:5], v[204:205], v[8:9]
	v_pk_fma_f32 v[8:9], v[2:3], v[202:203], v[16:17]
	v_pk_fma_f32 v[2:3], v[0:1], v[200:201], v[14:15]
	s_and_b64 vcc, exec, s[4:5]
	v_pk_fma_f32 v[6:7], v[6:7], v[206:207], v[10:11]
	v_cvt_pk_bf16_f32 v0, v4, v5
	s_nop 0
	v_cvt_pk_bf16_f32 v1, v6, v7
	v_cvt_pk_bf16_f32 v2, v2, v3
	v_cvt_pk_bf16_f32 v3, v8, v9
	global_store_dwordx4 v[12:13], v[0:3], off offset:256
	s_cbranch_vccz .LBB0_603
	s_waitcnt vmcnt(0)
	s_cmpk_gt_u32 s16, 0xff
	v_readlane_b32 s38, v255, 44
	s_movk_i32 s30, 0x7ff
	s_cbranch_scc1 .LBB0_614
	s_barrier

; #define PG8_STAGE(bufoff, gbase, hoff, imm) do { _Pragma("unroll") for (int _i = 0; _i < 2; ++_i) { \
;         asm volatile("s_mov_b32 m0, %0\n\ts_nop 0\n\tglobal_load_lds_dwordx4 %1, %2" \
;             :: "s"(lds0 + (unsigned)((bufoff) + _i * 8192)), "v"(voff0), "s"((const char*)(gbase) + (size_t)(hoff) + (size_t)(_i * 8192)) : "memory"); } } while (0)
; #define PG8_WAIT_V(n) asm volatile("s_waitcnt vmcnt(" #n ")" ::: "memory")
; #define PG8_BAR __builtin_amdgcn_s_barrier()
; template <class Epi>
; __device__ __forceinline__ void gemm_phase(LAS unsigned char* lds, const Gemm g, const StaticOrder& S, const Epi& E) {
;     ...
;     const int wid = __builtin_amdgcn_readfirstlane(tid >> 6), lane = tid & 63, wr = wid >> 2, wc = wid & 3, fr = lane & 15, fq = lane >> 4;
;     const int K = g.K, nt = K / BK;
;     const unsigned voff0 = (unsigned)(tid * 16);
;     const unsigned hA = (unsigned)(g.lda * 256), hB = (unsigned)(K * 256);
;     constexpr int KS = 16384;
;     const size_t tstepA = (size_t)BM * g.lda * 2, tstepB = (size_t)BM * K * 2;
;     const unsigned lds0 = (unsigned)__builtin_amdgcn_readfirstlane((int)((unsigned)(size_t)lds + (unsigned)wid * 1024u));
;     const int aoff = lds_byte(wr * 64 + fr, fq * 8), boff = lds_byte(wc * 32 + fr, fq * 8);
;     ...
;     Unit cur, nxt; int ui = 0;
;     if (!S.next(0, cur)) return;
;     f32x4 acc[2][2][4][2];
; #pragma unroll
;     for (int a = 0; a < 2; ++a)
; #pragma unroll
;         for (int b = 0; b < 2; ++b)
; #pragma unroll
;             for (int m = 0; m < 4; ++m)
; #pragma unroll
;                 for (int n = 0; n < 2; ++n) acc[a][b][m][n] = (f32x4){0.f, 0.f, 0.f, 0.f};
;     bf16x8 At[4][2], B0[2][2], B1[2][2];
;     const char* cA = (const char*)g.A + (size_t)cur.pm * tstepA + (size_t)(cur.pn >> g.gshift) * g.gstride; const char* cB = (const char*)g.Bt + (size_t)cur.pn * tstepB;
;     PG8_STAGE(PG8_SB(0, 0), cB, 0, 0); PG8_STAGE(PG8_SA(0, 0), cA, 0, 0); PG8_STAGE(PG8_SB(0, 1), cB, hB, 0); PG8_STAGE(PG8_SA(0, 1), cA, hA, 0);
;     if (wr == 1) PG8_BAR;
;     PG8_WAIT_V(4); PG8_BAR;
;     PG8_STAGE(PG8_SB(1, 0), cB + KS, 0, 0); PG8_STAGE(PG8_SA(1, 0), cA + KS, 0, 0); PG8_STAGE(PG8_SB(1, 1), cB + KS, hB, 0);
;     PG8_WAIT_V(6); PG8_BAR;
.LBB0_733:
	s_add_u32 s30, s4, s88
	v_readlane_b32 s4, v255, 43
	s_addc_u32 s48, s5, 0
	s_mul_i32 s4, s4, 0xb000
	s_add_u32 s6, s6, s4
	s_addc_u32 s7, s7, 0
	s_add_u32 s52, s8, 0x12630000
	s_addc_u32 s53, s9, 0
	s_add_u32 s54, s8, 0x28630000
	s_addc_u32 s55, s9, 0
	s_add_u32 s56, s8, 0x29130000
	v_and_b32_e32 v1, 63, v0
	v_and_b32_e32 v153, 15, v0
	v_lshrrev_b32_e32 v2, 1, v0
	v_and_b32_e32 v154, 48, v0
	v_lshlrev_b32_e32 v0, 2, v0
	s_addc_u32 s57, s9, 0
	s_and_b32 s8, s0, 3
	s_lshl_b32 s4, s10, 13
	v_lshl_or_b32 v3, v153, 6, v154
	v_and_b32_e32 v0, 32, v0
	s_lshl_b32 s21, s10, 6
	s_waitcnt vmcnt(0)
	v_bitop3_b32 v4, v3, s4, v0 bitop3:0xde
	s_lshl_b32 s4, s8, 12
	s_add_i32 s16, s89, 0x18000
	v_bitop3_b32 v0, v3, s4, v0 bitop3:0xde
	s_add_u32 s4, s78, 0x4000
	s_addc_u32 s5, s79, 0
	s_add_i32 s17, s89, 0x1a000
	s_waitcnt vmcnt(4)
	s_barrier
	s_mov_b32 m0, s16
	s_nop 0
	global_load_lds_dwordx4 v152, s[4:5]
	s_add_u32 s4, s78, 0x6000
	s_addc_u32 s5, s79, 0
	s_add_i32 s24, s89, 0x8000
	s_mov_b32 m0, s17
	s_nop 0
	global_load_lds_dwordx4 v152, s[4:5]
	s_add_u32 s4, s76, 0x4000
	s_addc_u32 s5, s77, 0
	s_add_i32 s37, s89, 0xa000
	s_mov_b32 m0, s24
	s_nop 0
	global_load_lds_dwordx4 v152, s[4:5]
	s_add_u32 s4, s76, 0x6000
	s_addc_u32 s5, s77, 0
	s_add_i32 s97, s89, 0x1c000
	s_mov_b32 m0, s37
	s_nop 0
	global_load_lds_dwordx4 v152, s[4:5]
	s_add_u32 s4, s78, 0x84000
	s_addc_u32 s5, s79, 0
	s_add_i32 s38, s89, 0x1e000
	s_mov_b32 m0, s97
	s_nop 0
	global_load_lds_dwordx4 v152, s[4:5]
	s_add_u32 s4, s78, 0x86000
	s_addc_u32 s5, s79, 0
	s_cmp_lt_i32 s0, 4
	v_readlane_b32 s49, v255, 38
	s_mov_b32 m0, s38
	s_nop 0
	global_load_lds_dwordx4 v152, s[4:5]
	s_cselect_b64 s[58:59], -1, 0
	s_add_i32 s4, s49, s11
	s_add_i32 s39, s4, 0x2000
	s_add_i32 s34, s89, 0xc000
	s_add_u32 s4, s76, 0x84000
	s_addc_u32 s5, s77, 0
	s_mov_b32 m0, s34
	s_nop 0
	global_load_lds_dwordx4 v152, s[4:5]
	s_add_u32 s4, s76, 0x86000
	s_addc_u32 s5, s77, 0
	s_add_i32 s12, s89, 0xe000
	s_mov_b32 m0, s12
	s_nop 0
	global_load_lds_dwordx4 v152, s[4:5]
	s_lshl_b32 s9, s10, 11
	s_cmp_gt_i32 s10, 0
	s_cselect_b64 s[60:61], -1, 0
	s_cmp_gt_i32 s10, -2
	s_cselect_b64 s[64:65], -1, 0
	s_add_i32 s11, s49, s9
	s_cmpk_lt_u32 s1, 0x100
	s_cselect_b64 s[62:63], -1, 0
	s_bfe_u32 s12, s1, 0x10006
	s_lshl_b32 s1, s10, 3
	s_and_b32 s1, s1, 8
	v_cmp_gt_u32_e32 vcc, 2, v153
	s_or_b32 s1, s1, s12
	s_and_b64 s[66:67], s[62:63], vcc
	s_lshl_b32 s13, s1, 10
	s_add_i32 s25, s89, 0xe000
	s_mul_i32 s4, s0, 0xb000
	v_and_b32_e32 v2, 24, v2
	s_mul_hi_i32 s1, s0, 0xb000
	s_add_u32 s10, s30, s4
	s_addc_u32 s1, s48, s1
	v_lshl_or_b32 v155, s8, 5, v2
	v_lshlrev_b32_e32 v5, 10, v153
	s_cmp_eq_u32 s0, 3
	v_lshlrev_b32_e32 v2, 2, v155
	v_add_u32_e32 v6, s9, v5
	v_readlane_b32 s0, v255, 39
	v_readlane_b32 s8, v255, 40
	v_readlane_b32 s30, v255, 41
	v_readlane_b32 s48, v255, 42
	v_or_b32_e32 v5, 0xfffff800, v5
	s_waitcnt vmcnt(8)
	v_add_u32_e32 v3, s49, v2
	v_add_u32_e32 v157, s0, v2
	v_add_u32_e32 v158, s8, v2
	v_add_u32_e32 v159, s30, v2
	v_add_u32_e32 v160, s48, v2
	v_or_b32_e32 v8, 16, v2
	v_add_u32_e32 v9, s11, v5
	v_or_b32_e32 v10, 0x200, v2
	v_or_b32_e32 v2, 0x210, v2
	v_cmp_gt_u32_e32 vcc, 32, v1
	v_add_u32_e32 v6, 0xffffc800, v6
	v_add_u32_e32 v7, s9, v3
	v_add_u32_e32 v161, s0, v8
	v_add_u32_e32 v162, s8, v8
	v_add_u32_e32 v163, s30, v8
	v_add_u32_e32 v164, s48, v8
	v_add_u32_e32 v165, v9, v8
	v_add_u32_e32 v8, s11, v8
	v_add_u32_e32 v166, s0, v10
	v_add_u32_e32 v167, s8, v10
	v_add_u32_e32 v168, s30, v10
	v_add_u32_e32 v169, s48, v10
	v_add_u32_e32 v170, v9, v10
	v_add_u32_e32 v10, s11, v10
	v_add_u32_e32 v171, s0, v2
	v_add_u32_e32 v172, s8, v2
	v_add_u32_e32 v173, s30, v2
	v_add_u32_e32 v174, s48, v2
	v_add_u32_e32 v175, v9, v2
	v_add_u32_e32 v2, s11, v2
	v_cndmask_b32_e64 v1, v254, 0, vcc
	s_movk_i32 s0, 0x1f0
	s_cselect_b32 s30, s7, s1
	s_cselect_b32 s96, s6, s10
	v_readlane_b32 s6, v255, 29
	s_mov_b32 s86, s88
	s_mov_b32 s22, 0
	v_cmp_lt_u32_e64 s[4:5], 13, v153
	v_add_u32_e32 v156, -14, v153
	v_and_or_b32 v176, v152, s0, v1
	v_add_u32_e32 v177, 0x10000, v0
	v_add_u32_e32 v178, 0, v4
	v_add_u32_e32 v179, v3, v6
	v_add_u32_e32 v180, v8, v5
	v_add_u32_e32 v181, v10, v5
	v_add_u32_e32 v182, v2, v5
	v_add_u32_e32 v183, v7, v5
	v_readlane_b32 s1, v255, 22
	s_mov_b32 s88, s6
	s_barrier
	v_readlane_b32 s7, v255, 30
	s_branch .LBB0_735

; #define PG8_STAGE(bufoff, gbase, hoff, imm) do { _Pragma("unroll") for (int _i = 0; _i < 2; ++_i) { \
;         asm volatile("s_mov_b32 m0, %0\n\ts_nop 0\n\tglobal_load_lds_dwordx4 %1, %2" \
;             :: "s"(lds0 + (unsigned)((bufoff) + _i * 8192)), "v"(voff0), "s"((const char*)(gbase) + (size_t)(hoff) + (size_t)(_i * 8192)) : "memory"); } } while (0)
; #define PG8_LDA(dst, b, h) do { _Pragma("unroll") for (int m = 0; m < 4; ++m) _Pragma("unroll") for (int k = 0; k < 2; ++k) dst[m][k] = *(const LAS bf16x8*)(lds + PG8_SA(b, h) + aoff + m * 2048 + k * 1024); } while (0)
; #define PG8_LDB(dst, b, h) do { _Pragma("unroll") for (int n = 0; n < 2; ++n) _Pragma("unroll") for (int k = 0; k < 2; ++k) dst[n][k] = *(const LAS bf16x8*)(lds + PG8_SB(b, h) + boff + n * 2048 + k * 1024); } while (0)
; #define PG8_WAIT_V(n) asm volatile("s_waitcnt vmcnt(" #n ")" ::: "memory")
; #define PG8_WAIT_L(n) asm volatile("s_waitcnt lgkmcnt(" #n ")" ::: "memory")
; #define PG8_BAR __builtin_amdgcn_s_barrier()
; template <class Epi>
; __device__ __forceinline__ void gemm_phase(LAS unsigned char* lds, const Gemm g, const StaticOrder& S, const Epi& E) {
;     ...
;         const bool has_next = S.next(ui + 1, nxt);
;         const char* nA = has_next ? (const char*)g.A + (size_t)nxt.pm * tstepA + (size_t)(nxt.pn >> g.gshift) * g.gstride : cA;
;         const char* nB = has_next ? (const char*)g.Bt + (size_t)nxt.pn * tstepB : cB;
;         for (int t = 0; t < nt; t += 2) {
;             const bool last = (t == nt - 2);
;             if (last) E.pre(cur, wid, lane, (unsigned)(size_t)(lds + STAGE_BYTES));
;             const char* aT = cA + (size_t)t * KS;
;             const char* a2 = last ? nA : aT + 2 * KS; const char* b2 = last ? nB : cB + (size_t)(t + 2) * KS;
;             PG8_LDB(B0, 0, 0); PG8_SCHED; PG8_LDA(At, 0, 0); PG8_STAGE(PG8_SA(1, 1), aT + KS, hA, 0);
;             PG8_WAIT_L(8); PG8_BAR; PG8_WAIT_L(0); PG8_MMA(0, 0, At, B0); PG8_BAR; PG8_SCHED;
;             PG8_LDB(B1, 0, 1); PG8_STAGE(PG8_SB(0, 0), b2, 0, 0);
;             PG8_BAR; PG8_WAIT_L(0); PG8_MMA(0, 1, At, B1); PG8_BAR;
;             PG8_LDA(At, 0, 1); PG8_STAGE(PG8_SA(0, 0), a2, 0, 0);
;             PG8_BAR; PG8_WAIT_L(0); PG8_MMA(1, 0, At, B0); PG8_BAR; PG8_SCHED;
;             PG8_STAGE(PG8_SB(0, 1), b2, hB, 0);
;             PG8_WAIT_V(6); PG8_BAR; PG8_MMA(1, 1, At, B1); PG8_BAR;
.LBB0_737:
	s_ashr_i32 s71, s70, 31
	v_cmp_lt_i64_e32 vcc, s[8:9], v[198:199]
	s_lshl_b64 s[8:9], s[70:71], 20
	s_add_u32 s72, s26, s8
	s_addc_u32 s73, s27, s9
	s_and_b64 s[8:9], vcc, exec
	s_cselect_b32 s50, s73, s77
	s_cselect_b32 s51, s72, s76
	s_ashr_i32 s69, s68, 31
	s_lshl_b64 s[8:9], s[68:69], 20
	s_add_u32 s74, s84, s8
	s_addc_u32 s75, s85, s9
	s_and_b64 s[8:9], vcc, exec
	s_cselect_b32 s69, s75, s79
	s_cselect_b32 s0, s74, s78
	s_lshl_b32 s8, s1, 7
	s_ashr_i32 s9, s8, 31
	s_lshl_b64 s[10:11], s[8:9], 2
	s_add_u32 s10, s96, s10
	s_addc_u32 s11, s30, s11
	s_add_u32 s1, s78, 0x8000
	s_addc_u32 s9, s79, 0
	s_mov_b32 s71, -2
	ds_read_b128 v[128:131], v177
	ds_read_b128 v[132:135], v177 offset:1024
	ds_read_b128 v[136:139], v177 offset:2048
	ds_read_b128 v[140:143], v177 offset:3072
	s_mov_b64 s[82:83], 0
	s_add_u32 s78, s76, 0x8000
	s_addc_u32 s79, s77, 0
	s_and_b64 s[48:49], s[82:83], exec
	s_cselect_b32 s81, s50, s79
	s_cselect_b32 s80, s51, s78
	ds_read_b128 v[144:147], v178
	ds_read_b128 v[148:151], v178 offset:1024
	ds_read_b128 v[184:187], v178 offset:2048
	ds_read_b128 v[200:203], v178 offset:3072
	ds_read_b128 v[204:207], v178 offset:4096
	ds_read_b128 v[208:211], v178 offset:5120
	ds_read_b128 v[212:215], v178 offset:6144
	ds_read_b128 v[236:239], v178 offset:7168
	s_waitcnt lgkmcnt(8)
	s_waitcnt vmcnt(10)
	s_barrier
	s_waitcnt lgkmcnt(7)
	v_mfma_f32_16x16x32_bf16 v[116:119], v[128:131], v[144:147], 0
	v_mfma_f32_16x16x32_bf16 v[80:83], v[136:139], v[144:147], 0
	s_waitcnt lgkmcnt(5)
	v_mfma_f32_16x16x32_bf16 v[88:91], v[128:131], v[184:187], 0
	v_mfma_f32_16x16x32_bf16 v[84:87], v[136:139], v[184:187], 0
	s_waitcnt lgkmcnt(3)
	v_mfma_f32_16x16x32_bf16 v[120:123], v[128:131], v[204:207], 0
	v_mfma_f32_16x16x32_bf16 v[92:95], v[136:139], v[204:207], 0
	s_waitcnt lgkmcnt(1)
	v_mfma_f32_16x16x32_bf16 v[124:127], v[128:131], v[212:215], 0
	v_mfma_f32_16x16x32_bf16 v[96:99], v[136:139], v[212:215], 0
	v_mfma_f32_16x16x32_bf16 v[116:119], v[132:135], v[148:151], v[116:119]
	v_mfma_f32_16x16x32_bf16 v[80:83], v[140:143], v[148:151], v[80:83]
	v_mfma_f32_16x16x32_bf16 v[88:91], v[132:135], v[200:203], v[88:91]
	v_mfma_f32_16x16x32_bf16 v[84:87], v[140:143], v[200:203], v[84:87]
	v_mfma_f32_16x16x32_bf16 v[120:123], v[132:135], v[208:211], v[120:123]
	v_mfma_f32_16x16x32_bf16 v[92:95], v[140:143], v[208:211], v[92:95]
	s_waitcnt lgkmcnt(0)
	v_mfma_f32_16x16x32_bf16 v[124:127], v[132:135], v[236:239], v[124:127]
	v_mfma_f32_16x16x32_bf16 v[96:99], v[140:143], v[236:239], v[96:99]
	s_barrier
	ds_read_b128 v[240:243], v177 offset:16384
	ds_read_b128 v[244:247], v177 offset:17408
	ds_read_b128 v[248:251], v177 offset:18432
	ds_read_b128 v[230:233], v177 offset:19456
	s_and_b64 s[48:49], s[82:83], exec
	s_cselect_b32 s76, s0, s1
	s_cselect_b32 s77, s69, s9
	s_mov_b32 m0, s28
	s_nop 0
	global_load_lds_dwordx4 v152, s[76:77]
	s_add_u32 s48, s76, 0x2000
	s_addc_u32 s49, s77, 0
	s_mov_b32 m0, s29
	s_nop 0
	global_load_lds_dwordx4 v152, s[48:49]
	s_waitcnt vmcnt(10)
	s_barrier
	s_waitcnt lgkmcnt(3)
	v_mfma_f32_16x16x32_bf16 v[48:51], v[240:243], v[144:147], 0
	s_waitcnt lgkmcnt(1)
	v_mfma_f32_16x16x32_bf16 v[16:19], v[248:251], v[144:147], 0
	v_mfma_f32_16x16x32_bf16 v[52:55], v[240:243], v[184:187], 0
	v_mfma_f32_16x16x32_bf16 v[20:23], v[248:251], v[184:187], 0
	v_mfma_f32_16x16x32_bf16 v[56:59], v[240:243], v[204:207], 0
	v_mfma_f32_16x16x32_bf16 v[24:27], v[248:251], v[204:207], 0
	v_mfma_f32_16x16x32_bf16 v[60:63], v[240:243], v[212:215], 0
	v_mfma_f32_16x16x32_bf16 v[28:31], v[248:251], v[212:215], 0
	v_mfma_f32_16x16x32_bf16 v[48:51], v[244:247], v[148:151], v[48:51]
	s_waitcnt lgkmcnt(0)
	v_mfma_f32_16x16x32_bf16 v[16:19], v[230:233], v[148:151], v[16:19]
	v_mfma_f32_16x16x32_bf16 v[52:55], v[244:247], v[200:203], v[52:55]
	v_mfma_f32_16x16x32_bf16 v[20:23], v[230:233], v[200:203], v[20:23]
	v_mfma_f32_16x16x32_bf16 v[56:59], v[244:247], v[208:211], v[56:59]
	v_mfma_f32_16x16x32_bf16 v[24:27], v[230:233], v[208:211], v[24:27]
	v_mfma_f32_16x16x32_bf16 v[60:63], v[244:247], v[236:239], v[60:63]
	v_mfma_f32_16x16x32_bf16 v[28:31], v[230:233], v[236:239], v[28:31]
	s_barrier
	ds_read_b128 v[144:147], v178 offset:16384
	ds_read_b128 v[148:151], v178 offset:17408
	ds_read_b128 v[184:187], v178 offset:18432
	ds_read_b128 v[200:203], v178 offset:19456
	ds_read_b128 v[204:207], v178 offset:20480
	ds_read_b128 v[208:211], v178 offset:21504
	ds_read_b128 v[212:215], v178 offset:22528
	ds_read_b128 v[236:239], v178 offset:23552
	s_mov_b32 m0, s89
	s_nop 0
	global_load_lds_dwordx4 v152, s[80:81]
	s_add_u32 s48, s80, 0x2000
	s_addc_u32 s49, s81, 0
	s_mov_b32 m0, s40
	s_nop 0
	global_load_lds_dwordx4 v152, s[48:49]
	s_waitcnt vmcnt(10)
	s_barrier
	s_waitcnt lgkmcnt(7)
	v_mfma_f32_16x16x32_bf16 v[100:103], v[128:131], v[144:147], 0
	v_mfma_f32_16x16x32_bf16 v[64:67], v[136:139], v[144:147], 0
	s_waitcnt lgkmcnt(5)
	v_mfma_f32_16x16x32_bf16 v[104:107], v[128:131], v[184:187], 0
	v_mfma_f32_16x16x32_bf16 v[68:71], v[136:139], v[184:187], 0
	s_waitcnt lgkmcnt(3)
	v_mfma_f32_16x16x32_bf16 v[108:111], v[128:131], v[204:207], 0
	v_mfma_f32_16x16x32_bf16 v[72:75], v[136:139], v[204:207], 0
	s_waitcnt lgkmcnt(1)
	v_mfma_f32_16x16x32_bf16 v[112:115], v[128:131], v[212:215], 0
	v_mfma_f32_16x16x32_bf16 v[76:79], v[136:139], v[212:215], 0
	v_mfma_f32_16x16x32_bf16 v[100:103], v[132:135], v[148:151], v[100:103]
	v_mfma_f32_16x16x32_bf16 v[64:67], v[140:143], v[148:151], v[64:67]
	v_mfma_f32_16x16x32_bf16 v[104:107], v[132:135], v[200:203], v[104:107]
	v_mfma_f32_16x16x32_bf16 v[68:71], v[140:143], v[200:203], v[68:71]
	v_mfma_f32_16x16x32_bf16 v[108:111], v[132:135], v[208:211], v[108:111]
	v_mfma_f32_16x16x32_bf16 v[72:75], v[140:143], v[208:211], v[72:75]
	s_waitcnt lgkmcnt(0)
	v_mfma_f32_16x16x32_bf16 v[112:115], v[132:135], v[236:239], v[112:115]
	v_mfma_f32_16x16x32_bf16 v[76:79], v[140:143], v[236:239], v[76:79]
	s_barrier
; #define PG8_STAGE(bufoff, gbase, hoff, imm) do { _Pragma("unroll") for (int _i = 0; _i < 2; ++_i) { \
;         asm volatile("s_mov_b32 m0, %0\n\ts_nop 0\n\tglobal_load_lds_dwordx4 %1, %2" \
;             :: "s"(lds0 + (unsigned)((bufoff) + _i * 8192)), "v"(voff0), "s"((const char*)(gbase) + (size_t)(hoff) + (size_t)(_i * 8192)) : "memory"); } } while (0)
; #define PG8_LDA(dst, b, h) do { _Pragma("unroll") for (int m = 0; m < 4; ++m) _Pragma("unroll") for (int k = 0; k < 2; ++k) dst[m][k] = *(const LAS bf16x8*)(lds + PG8_SA(b, h) + aoff + m * 2048 + k * 1024); } while (0)
; #define PG8_LDB(dst, b, h) do { _Pragma("unroll") for (int n = 0; n < 2; ++n) _Pragma("unroll") for (int k = 0; k < 2; ++k) dst[n][k] = *(const LAS bf16x8*)(lds + PG8_SB(b, h) + boff + n * 2048 + k * 1024); } while (0)
; #define PG8_MMA(ai, bj, At, Bt) do { __builtin_amdgcn_s_setprio(1); _Pragma("unroll") for (int m = 0; m < 4; ++m) _Pragma("unroll") for (int n = 0; n < 2; ++n) _Pragma("unroll") for (int k = 0; k < 2; ++k) \
;         acc[ai][bj][m][n] = __builtin_amdgcn_mfma_f32_16x16x32_bf16(Bt[n][k], At[m][k], acc[ai][bj][m][n], 0, 0, 0); __builtin_amdgcn_s_setprio(0); } while (0)
; #define PG8_WAIT_V(n) asm volatile("s_waitcnt vmcnt(" #n ")" ::: "memory")
; #define PG8_WAIT_L(n) asm volatile("s_waitcnt lgkmcnt(" #n ")" ::: "memory")
; #define PG8_BAR __builtin_amdgcn_s_barrier()
; #define PG8_SCHED __builtin_amdgcn_sched_barrier(0)
; template <class Epi>
; __device__ __forceinline__ void gemm_phase(LAS unsigned char* lds, const Gemm g, const StaticOrder& S, const Epi& E) {
;     ...
;             PG8_STAGE(PG8_SB(0, 1), b2, hB, 0);
;             PG8_WAIT_V(6); PG8_BAR; PG8_MMA(1, 1, At, B1); PG8_BAR;
;             PG8_LDB(B0, 1, 0); PG8_SCHED; PG8_LDA(At, 1, 0); PG8_STAGE(PG8_SA(0, 1), a2, hA, 0);
;             PG8_WAIT_L(8); PG8_BAR; PG8_WAIT_L(0); PG8_MMA(0, 0, At, B0); PG8_BAR; PG8_SCHED;
;             PG8_LDB(B1, 1, 1); PG8_STAGE(PG8_SB(1, 0), b2 + KS, 0, 0);
;             PG8_BAR; PG8_WAIT_L(0); PG8_MMA(0, 1, At, B1); PG8_BAR;
;             PG8_LDA(At, 1, 1); PG8_STAGE(PG8_SA(1, 0), a2 + KS, 0, 0);
;             PG8_BAR; PG8_WAIT_L(0); PG8_MMA(1, 0, At, B0); PG8_BAR; PG8_SCHED;
;             PG8_STAGE(PG8_SB(1, 1), b2 + KS, hB, 0);
;             PG8_WAIT_V(6); PG8_BAR; PG8_MMA(1, 1, At, B1); PG8_BAR;
	ds_read_b128 v[128:131], v177 offset:32768
	ds_read_b128 v[132:135], v177 offset:33792
	ds_read_b128 v[136:139], v177 offset:34816
	ds_read_b128 v[140:143], v177 offset:35840
	s_add_u32 s48, s76, 0x80000
	s_addc_u32 s49, s77, 0
	s_mov_b32 m0, s41
	s_nop 0
	global_load_lds_dwordx4 v152, s[48:49]
	s_add_u32 s48, s76, 0x82000
	s_addc_u32 s49, s77, 0
	s_mov_b32 m0, s42
	s_nop 0
	global_load_lds_dwordx4 v152, s[48:49]
	s_add_u32 s48, s80, 0x80000
	s_addc_u32 s49, s81, 0
	s_mov_b32 m0, s43
	s_nop 0
	global_load_lds_dwordx4 v152, s[48:49]
	s_add_u32 s48, s80, 0x82000
	s_addc_u32 s49, s81, 0
	s_mov_b32 m0, s92
	s_nop 0
	global_load_lds_dwordx4 v152, s[48:49]
	s_waitcnt vmcnt(12)
	s_barrier
	v_mfma_f32_16x16x32_bf16 v[32:35], v[240:243], v[144:147], 0
	v_mfma_f32_16x16x32_bf16 v[0:3], v[248:251], v[144:147], 0
	v_mfma_f32_16x16x32_bf16 v[36:39], v[240:243], v[184:187], 0
	v_mfma_f32_16x16x32_bf16 v[4:7], v[248:251], v[184:187], 0
	v_mfma_f32_16x16x32_bf16 v[40:43], v[240:243], v[204:207], 0
	v_mfma_f32_16x16x32_bf16 v[8:11], v[248:251], v[204:207], 0
	v_mfma_f32_16x16x32_bf16 v[44:47], v[240:243], v[212:215], 0
	v_mfma_f32_16x16x32_bf16 v[12:15], v[248:251], v[212:215], 0
	v_mfma_f32_16x16x32_bf16 v[32:35], v[244:247], v[148:151], v[32:35]
	v_mfma_f32_16x16x32_bf16 v[0:3], v[230:233], v[148:151], v[0:3]
	v_mfma_f32_16x16x32_bf16 v[36:39], v[244:247], v[200:203], v[36:39]
	v_mfma_f32_16x16x32_bf16 v[4:7], v[230:233], v[200:203], v[4:7]
	v_mfma_f32_16x16x32_bf16 v[40:43], v[244:247], v[208:211], v[40:43]
	v_mfma_f32_16x16x32_bf16 v[8:11], v[230:233], v[208:211], v[8:11]
	v_mfma_f32_16x16x32_bf16 v[44:47], v[244:247], v[236:239], v[44:47]
	v_mfma_f32_16x16x32_bf16 v[12:15], v[230:233], v[236:239], v[12:15]
	s_barrier
	ds_read_b128 v[144:147], v178 offset:32768
	ds_read_b128 v[148:151], v178 offset:33792
	ds_read_b128 v[184:187], v178 offset:34816
	ds_read_b128 v[200:203], v178 offset:35840
	ds_read_b128 v[204:207], v178 offset:36864
	ds_read_b128 v[208:211], v178 offset:37888
	ds_read_b128 v[212:215], v178 offset:38912
	ds_read_b128 v[230:233], v178 offset:39936
	s_waitcnt lgkmcnt(8)
	s_waitcnt vmcnt(10)
	s_barrier
	s_waitcnt lgkmcnt(7)
	v_mfma_f32_16x16x32_bf16 v[116:119], v[128:131], v[144:147], v[116:119]
	v_mfma_f32_16x16x32_bf16 v[80:83], v[136:139], v[144:147], v[80:83]
	s_waitcnt lgkmcnt(5)
	v_mfma_f32_16x16x32_bf16 v[88:91], v[128:131], v[184:187], v[88:91]
	v_mfma_f32_16x16x32_bf16 v[84:87], v[136:139], v[184:187], v[84:87]
	s_waitcnt lgkmcnt(3)
	v_mfma_f32_16x16x32_bf16 v[120:123], v[128:131], v[204:207], v[120:123]
	v_mfma_f32_16x16x32_bf16 v[92:95], v[136:139], v[204:207], v[92:95]
	s_waitcnt lgkmcnt(1)
	v_mfma_f32_16x16x32_bf16 v[124:127], v[128:131], v[212:215], v[124:127]
	v_mfma_f32_16x16x32_bf16 v[96:99], v[136:139], v[212:215], v[96:99]
	v_mfma_f32_16x16x32_bf16 v[116:119], v[132:135], v[148:151], v[116:119]
	v_mfma_f32_16x16x32_bf16 v[80:83], v[140:143], v[148:151], v[80:83]
	v_mfma_f32_16x16x32_bf16 v[88:91], v[132:135], v[200:203], v[88:91]
	v_mfma_f32_16x16x32_bf16 v[84:87], v[140:143], v[200:203], v[84:87]
	v_mfma_f32_16x16x32_bf16 v[120:123], v[132:135], v[208:211], v[120:123]
	v_mfma_f32_16x16x32_bf16 v[92:95], v[140:143], v[208:211], v[92:95]
	s_waitcnt lgkmcnt(0)
	v_mfma_f32_16x16x32_bf16 v[124:127], v[132:135], v[230:233], v[124:127]
	v_mfma_f32_16x16x32_bf16 v[96:99], v[140:143], v[230:233], v[96:99]
	s_barrier
	ds_read_b128 v[236:239], v177 offset:49152
	ds_read_b128 v[240:243], v177 offset:50176
	ds_read_b128 v[244:247], v177 offset:51200
	ds_read_b128 v[248:251], v177 offset:52224
	s_add_u32 s48, s76, 0x4000
	s_addc_u32 s49, s77, 0
	s_mov_b32 m0, s16
	s_nop 0
	global_load_lds_dwordx4 v152, s[48:49]
	s_add_u32 s48, s76, 0x6000
	s_addc_u32 s49, s77, 0
	s_mov_b32 m0, s17
	s_nop 0
	global_load_lds_dwordx4 v152, s[48:49]
	s_waitcnt vmcnt(10)
	s_barrier
	s_waitcnt lgkmcnt(3)
	v_mfma_f32_16x16x32_bf16 v[48:51], v[236:239], v[144:147], v[48:51]
	s_waitcnt lgkmcnt(1)
	v_mfma_f32_16x16x32_bf16 v[16:19], v[244:247], v[144:147], v[16:19]
	v_mfma_f32_16x16x32_bf16 v[52:55], v[236:239], v[184:187], v[52:55]
	v_mfma_f32_16x16x32_bf16 v[20:23], v[244:247], v[184:187], v[20:23]
	v_mfma_f32_16x16x32_bf16 v[56:59], v[236:239], v[204:207], v[56:59]
	v_mfma_f32_16x16x32_bf16 v[24:27], v[244:247], v[204:207], v[24:27]
	v_mfma_f32_16x16x32_bf16 v[60:63], v[236:239], v[212:215], v[60:63]
	v_mfma_f32_16x16x32_bf16 v[28:31], v[244:247], v[212:215], v[28:31]
	v_mfma_f32_16x16x32_bf16 v[48:51], v[240:243], v[148:151], v[48:51]
	s_waitcnt lgkmcnt(0)
	v_mfma_f32_16x16x32_bf16 v[16:19], v[248:251], v[148:151], v[16:19]
	v_mfma_f32_16x16x32_bf16 v[52:55], v[240:243], v[200:203], v[52:55]
	v_mfma_f32_16x16x32_bf16 v[20:23], v[248:251], v[200:203], v[20:23]
	v_mfma_f32_16x16x32_bf16 v[56:59], v[240:243], v[208:211], v[56:59]
	v_mfma_f32_16x16x32_bf16 v[24:27], v[248:251], v[208:211], v[24:27]
	v_mfma_f32_16x16x32_bf16 v[60:63], v[240:243], v[230:233], v[60:63]
	v_mfma_f32_16x16x32_bf16 v[28:31], v[248:251], v[230:233], v[28:31]
	s_barrier
	ds_read_b128 v[144:147], v178 offset:49152
	ds_read_b128 v[148:151], v178 offset:50176
	ds_read_b128 v[184:187], v178 offset:51200
	ds_read_b128 v[200:203], v178 offset:52224
	ds_read_b128 v[204:207], v178 offset:53248
	ds_read_b128 v[208:211], v178 offset:54272
	ds_read_b128 v[212:215], v178 offset:55296
	ds_read_b128 v[230:233], v178 offset:56320
	s_add_u32 s48, s80, 0x4000
	s_addc_u32 s49, s81, 0
	s_mov_b32 m0, s24
	s_nop 0
	global_load_lds_dwordx4 v152, s[48:49]
	s_add_u32 s48, s80, 0x6000
	s_addc_u32 s49, s81, 0
	s_mov_b32 m0, s37
	s_nop 0
	global_load_lds_dwordx4 v152, s[48:49]
	s_waitcnt vmcnt(10)
	s_barrier
; #define PG8_STAGE(bufoff, gbase, hoff, imm) do { _Pragma("unroll") for (int _i = 0; _i < 2; ++_i) { \
;         asm volatile("s_mov_b32 m0, %0\n\ts_nop 0\n\tglobal_load_lds_dwordx4 %1, %2" \
;             :: "s"(lds0 + (unsigned)((bufoff) + _i * 8192)), "v"(voff0), "s"((const char*)(gbase) + (size_t)(hoff) + (size_t)(_i * 8192)) : "memory"); } } while (0)
; #define PG8_LDA(dst, b, h) do { _Pragma("unroll") for (int m = 0; m < 4; ++m) _Pragma("unroll") for (int k = 0; k < 2; ++k) dst[m][k] = *(const LAS bf16x8*)(lds + PG8_SA(b, h) + aoff + m * 2048 + k * 1024); } while (0)
; #define PG8_LDB(dst, b, h) do { _Pragma("unroll") for (int n = 0; n < 2; ++n) _Pragma("unroll") for (int k = 0; k < 2; ++k) dst[n][k] = *(const LAS bf16x8*)(lds + PG8_SB(b, h) + boff + n * 2048 + k * 1024); } while (0)
; #define PG8_WAIT_V(n) asm volatile("s_waitcnt vmcnt(" #n ")" ::: "memory")
; #define PG8_WAIT_L(n) asm volatile("s_waitcnt lgkmcnt(" #n ")" ::: "memory")
; #define PG8_BAR __builtin_amdgcn_s_barrier()
; template <class Epi>
; __device__ __forceinline__ void gemm_phase(LAS unsigned char* lds, const Gemm g, const StaticOrder& S, const Epi& E) {
;     ...
;             PG8_LDB(B0, 0, 0); PG8_SCHED; PG8_LDA(At, 0, 0); PG8_STAGE(PG8_SA(1, 1), aT + KS, hA, 0);
;             PG8_WAIT_L(8); PG8_BAR; PG8_WAIT_L(0); PG8_MMA(0, 0, At, B0); PG8_BAR; PG8_SCHED;
;             PG8_LDB(B1, 0, 1); PG8_STAGE(PG8_SB(0, 0), b2, 0, 0);
;             PG8_BAR; PG8_WAIT_L(0); PG8_MMA(0, 1, At, B1); PG8_BAR;
;             PG8_LDA(At, 0, 1); PG8_STAGE(PG8_SA(0, 0), a2, 0, 0);
;             PG8_BAR; PG8_WAIT_L(0); PG8_MMA(1, 0, At, B0); PG8_BAR; PG8_SCHED;
;             PG8_STAGE(PG8_SB(0, 1), b2, hB, 0);
;             PG8_WAIT_V(6); PG8_BAR; PG8_MMA(1, 1, At, B1); PG8_BAR;
;             PG8_LDB(B0, 1, 0); PG8_SCHED; PG8_LDA(At, 1, 0); PG8_STAGE(PG8_SA(0, 1), a2, hA, 0);
;             PG8_WAIT_L(8); PG8_BAR; PG8_WAIT_L(0); PG8_MMA(0, 0, At, B0); PG8_BAR; PG8_SCHED;
;             PG8_LDB(B1, 1, 1); PG8_STAGE(PG8_SB(1, 0), b2 + KS, 0, 0);
;             PG8_BAR; PG8_WAIT_L(0); PG8_MMA(0, 1, At, B1); PG8_BAR;
;             PG8_LDA(At, 1, 1); PG8_STAGE(PG8_SA(1, 0), a2 + KS, 0, 0);
;             PG8_BAR; PG8_WAIT_L(0); PG8_MMA(1, 0, At, B0); PG8_BAR; PG8_SCHED;
;             PG8_STAGE(PG8_SB(1, 1), b2 + KS, hB, 0);
;             PG8_WAIT_V(6); PG8_BAR; PG8_MMA(1, 1, At, B1); PG8_BAR;
	s_waitcnt lgkmcnt(7)
	v_mfma_f32_16x16x32_bf16 v[100:103], v[128:131], v[144:147], v[100:103]
	v_mfma_f32_16x16x32_bf16 v[64:67], v[136:139], v[144:147], v[64:67]
	s_waitcnt lgkmcnt(5)
	v_mfma_f32_16x16x32_bf16 v[104:107], v[128:131], v[184:187], v[104:107]
	v_mfma_f32_16x16x32_bf16 v[68:71], v[136:139], v[184:187], v[68:71]
	s_waitcnt lgkmcnt(3)
	v_mfma_f32_16x16x32_bf16 v[108:111], v[128:131], v[204:207], v[108:111]
	v_mfma_f32_16x16x32_bf16 v[72:75], v[136:139], v[204:207], v[72:75]
	s_waitcnt lgkmcnt(1)
	v_mfma_f32_16x16x32_bf16 v[112:115], v[128:131], v[212:215], v[112:115]
	v_mfma_f32_16x16x32_bf16 v[76:79], v[136:139], v[212:215], v[76:79]
	v_mfma_f32_16x16x32_bf16 v[100:103], v[132:135], v[148:151], v[100:103]
	v_mfma_f32_16x16x32_bf16 v[64:67], v[140:143], v[148:151], v[64:67]
	v_mfma_f32_16x16x32_bf16 v[104:107], v[132:135], v[200:203], v[104:107]
	v_mfma_f32_16x16x32_bf16 v[68:71], v[140:143], v[200:203], v[68:71]
	v_mfma_f32_16x16x32_bf16 v[108:111], v[132:135], v[208:211], v[108:111]
	v_mfma_f32_16x16x32_bf16 v[72:75], v[140:143], v[208:211], v[72:75]
	s_waitcnt lgkmcnt(0)
	v_mfma_f32_16x16x32_bf16 v[112:115], v[132:135], v[230:233], v[112:115]
	v_mfma_f32_16x16x32_bf16 v[76:79], v[140:143], v[230:233], v[76:79]
	s_barrier
	ds_read_b128 v[128:131], v177
	ds_read_b128 v[132:135], v177 offset:1024
	ds_read_b128 v[136:139], v177 offset:2048
	ds_read_b128 v[140:143], v177 offset:3072
	s_add_u32 s48, s76, 0x84000
	s_addc_u32 s49, s77, 0
	s_mov_b32 m0, s97
	s_nop 0
	global_load_lds_dwordx4 v152, s[48:49]
	s_add_u32 s48, s76, 0x86000
	s_addc_u32 s49, s77, 0
	s_mov_b32 m0, s38
	s_nop 0
	global_load_lds_dwordx4 v152, s[48:49]
	s_add_u32 s48, s80, 0x84000
	s_addc_u32 s49, s81, 0
	s_mov_b32 m0, s34
	s_nop 0
	global_load_lds_dwordx4 v152, s[48:49]
	s_add_u32 s48, s80, 0x86000
	s_addc_u32 s49, s81, 0
	s_mov_b32 m0, s25
	s_nop 0
	global_load_lds_dwordx4 v152, s[48:49]
	s_waitcnt vmcnt(12)
	s_barrier
	v_mfma_f32_16x16x32_bf16 v[32:35], v[236:239], v[144:147], v[32:35]
	v_mfma_f32_16x16x32_bf16 v[0:3], v[244:247], v[144:147], v[0:3]
	v_mfma_f32_16x16x32_bf16 v[36:39], v[236:239], v[184:187], v[36:39]
	v_mfma_f32_16x16x32_bf16 v[4:7], v[244:247], v[184:187], v[4:7]
	v_mfma_f32_16x16x32_bf16 v[40:43], v[236:239], v[204:207], v[40:43]
	v_mfma_f32_16x16x32_bf16 v[8:11], v[244:247], v[204:207], v[8:11]
	v_mfma_f32_16x16x32_bf16 v[44:47], v[236:239], v[212:215], v[44:47]
	v_mfma_f32_16x16x32_bf16 v[12:15], v[244:247], v[212:215], v[12:15]
	v_mfma_f32_16x16x32_bf16 v[32:35], v[240:243], v[148:151], v[32:35]
	v_mfma_f32_16x16x32_bf16 v[0:3], v[248:251], v[148:151], v[0:3]
	v_mfma_f32_16x16x32_bf16 v[36:39], v[240:243], v[200:203], v[36:39]
	v_mfma_f32_16x16x32_bf16 v[4:7], v[248:251], v[200:203], v[4:7]
	v_mfma_f32_16x16x32_bf16 v[40:43], v[240:243], v[208:211], v[40:43]
	v_mfma_f32_16x16x32_bf16 v[8:11], v[248:251], v[208:211], v[8:11]
	v_mfma_f32_16x16x32_bf16 v[44:47], v[240:243], v[230:233], v[44:47]
	v_mfma_f32_16x16x32_bf16 v[12:15], v[248:251], v[230:233], v[12:15]
	s_add_i32 s71, s71, 2
	s_add_u32 s1, s1, 0x8000
	s_addc_u32 s9, s9, 0
	s_cmp_gt_u32 s71, 29
	s_mov_b64 s[76:77], s[78:79]
	s_barrier
	s_branch .LBB0_739
.LBB0_738:
	s_add_u32 s78, s76, 0x8000
	s_addc_u32 s79, s77, 0
	s_and_b64 s[48:49], s[82:83], exec
	s_cselect_b32 s81, s50, s79
	s_cselect_b32 s80, s51, s78
	ds_read_b128 v[144:147], v178
	ds_read_b128 v[148:151], v178 offset:1024
	ds_read_b128 v[184:187], v178 offset:2048
	ds_read_b128 v[200:203], v178 offset:3072
	ds_read_b128 v[204:207], v178 offset:4096
	ds_read_b128 v[208:211], v178 offset:5120
	ds_read_b128 v[212:215], v178 offset:6144
	ds_read_b128 v[236:239], v178 offset:7168
	s_waitcnt lgkmcnt(8)
	s_waitcnt vmcnt(10)
	s_barrier
	s_waitcnt lgkmcnt(7)
	v_mfma_f32_16x16x32_bf16 v[116:119], v[128:131], v[144:147], v[116:119]
	v_mfma_f32_16x16x32_bf16 v[80:83], v[136:139], v[144:147], v[80:83]
	s_waitcnt lgkmcnt(5)
	v_mfma_f32_16x16x32_bf16 v[88:91], v[128:131], v[184:187], v[88:91]
	v_mfma_f32_16x16x32_bf16 v[84:87], v[136:139], v[184:187], v[84:87]
	s_waitcnt lgkmcnt(3)
	v_mfma_f32_16x16x32_bf16 v[120:123], v[128:131], v[204:207], v[120:123]
	v_mfma_f32_16x16x32_bf16 v[92:95], v[136:139], v[204:207], v[92:95]
	s_waitcnt lgkmcnt(1)
	v_mfma_f32_16x16x32_bf16 v[124:127], v[128:131], v[212:215], v[124:127]
	v_mfma_f32_16x16x32_bf16 v[96:99], v[136:139], v[212:215], v[96:99]
	v_mfma_f32_16x16x32_bf16 v[116:119], v[132:135], v[148:151], v[116:119]
	v_mfma_f32_16x16x32_bf16 v[80:83], v[140:143], v[148:151], v[80:83]
	v_mfma_f32_16x16x32_bf16 v[88:91], v[132:135], v[200:203], v[88:91]
	v_mfma_f32_16x16x32_bf16 v[84:87], v[140:143], v[200:203], v[84:87]
	v_mfma_f32_16x16x32_bf16 v[120:123], v[132:135], v[208:211], v[120:123]
	v_mfma_f32_16x16x32_bf16 v[92:95], v[140:143], v[208:211], v[92:95]
	s_waitcnt lgkmcnt(0)
	v_mfma_f32_16x16x32_bf16 v[124:127], v[132:135], v[236:239], v[124:127]
	v_mfma_f32_16x16x32_bf16 v[96:99], v[140:143], v[236:239], v[96:99]
	s_barrier
	ds_read_b128 v[240:243], v177 offset:16384
	ds_read_b128 v[244:247], v177 offset:17408
	ds_read_b128 v[248:251], v177 offset:18432
	ds_read_b128 v[230:233], v177 offset:19456
	s_and_b64 s[48:49], s[82:83], exec
	s_cselect_b32 s76, s0, s1
	s_cselect_b32 s77, s69, s9
	s_mov_b32 m0, s28
	s_nop 0
	global_load_lds_dwordx4 v152, s[76:77]
	s_add_u32 s48, s76, 0x2000
	s_addc_u32 s49, s77, 0
	s_mov_b32 m0, s29
	s_nop 0
	global_load_lds_dwordx4 v152, s[48:49]
	s_waitcnt vmcnt(10)
	s_barrier
; #define PG8_STAGE(bufoff, gbase, hoff, imm) do { _Pragma("unroll") for (int _i = 0; _i < 2; ++_i) { \
;         asm volatile("s_mov_b32 m0, %0\n\ts_nop 0\n\tglobal_load_lds_dwordx4 %1, %2" \
;             :: "s"(lds0 + (unsigned)((bufoff) + _i * 8192)), "v"(voff0), "s"((const char*)(gbase) + (size_t)(hoff) + (size_t)(_i * 8192)) : "memory"); } } while (0)
; #define PG8_LDA(dst, b, h) do { _Pragma("unroll") for (int m = 0; m < 4; ++m) _Pragma("unroll") for (int k = 0; k < 2; ++k) dst[m][k] = *(const LAS bf16x8*)(lds + PG8_SA(b, h) + aoff + m * 2048 + k * 1024); } while (0)
; #define PG8_LDB(dst, b, h) do { _Pragma("unroll") for (int n = 0; n < 2; ++n) _Pragma("unroll") for (int k = 0; k < 2; ++k) dst[n][k] = *(const LAS bf16x8*)(lds + PG8_SB(b, h) + boff + n * 2048 + k * 1024); } while (0)
; #define PG8_WAIT_V(n) asm volatile("s_waitcnt vmcnt(" #n ")" ::: "memory")
; #define PG8_WAIT_L(n) asm volatile("s_waitcnt lgkmcnt(" #n ")" ::: "memory")
; #define PG8_BAR __builtin_amdgcn_s_barrier()
; template <class Epi>
; __device__ __forceinline__ void gemm_phase(LAS unsigned char* lds, const Gemm g, const StaticOrder& S, const Epi& E) {
;     ...
;             PG8_LDB(B0, 0, 0); PG8_SCHED; PG8_LDA(At, 0, 0); PG8_STAGE(PG8_SA(1, 1), aT + KS, hA, 0);
;             PG8_WAIT_L(8); PG8_BAR; PG8_WAIT_L(0); PG8_MMA(0, 0, At, B0); PG8_BAR; PG8_SCHED;
;             PG8_LDB(B1, 0, 1); PG8_STAGE(PG8_SB(0, 0), b2, 0, 0);
;             PG8_BAR; PG8_WAIT_L(0); PG8_MMA(0, 1, At, B1); PG8_BAR;
;             PG8_LDA(At, 0, 1); PG8_STAGE(PG8_SA(0, 0), a2, 0, 0);
;             PG8_BAR; PG8_WAIT_L(0); PG8_MMA(1, 0, At, B0); PG8_BAR; PG8_SCHED;
;             PG8_STAGE(PG8_SB(0, 1), b2, hB, 0);
;             PG8_WAIT_V(6); PG8_BAR; PG8_MMA(1, 1, At, B1); PG8_BAR;
;             PG8_LDB(B0, 1, 0); PG8_SCHED; PG8_LDA(At, 1, 0); PG8_STAGE(PG8_SA(0, 1), a2, hA, 0);
;             PG8_WAIT_L(8); PG8_BAR; PG8_WAIT_L(0); PG8_MMA(0, 0, At, B0); PG8_BAR; PG8_SCHED;
;             PG8_LDB(B1, 1, 1); PG8_STAGE(PG8_SB(1, 0), b2 + KS, 0, 0);
;             PG8_BAR; PG8_WAIT_L(0); PG8_MMA(0, 1, At, B1); PG8_BAR;
;             PG8_LDA(At, 1, 1); PG8_STAGE(PG8_SA(1, 0), a2 + KS, 0, 0);
;             PG8_BAR; PG8_WAIT_L(0); PG8_MMA(1, 0, At, B0); PG8_BAR; PG8_SCHED;
;             PG8_STAGE(PG8_SB(1, 1), b2 + KS, hB, 0);
;             PG8_WAIT_V(6); PG8_BAR; PG8_MMA(1, 1, At, B1); PG8_BAR;
	s_waitcnt lgkmcnt(3)
	v_mfma_f32_16x16x32_bf16 v[48:51], v[240:243], v[144:147], v[48:51]
	s_waitcnt lgkmcnt(1)
	v_mfma_f32_16x16x32_bf16 v[16:19], v[248:251], v[144:147], v[16:19]
	v_mfma_f32_16x16x32_bf16 v[52:55], v[240:243], v[184:187], v[52:55]
	v_mfma_f32_16x16x32_bf16 v[20:23], v[248:251], v[184:187], v[20:23]
	v_mfma_f32_16x16x32_bf16 v[56:59], v[240:243], v[204:207], v[56:59]
	v_mfma_f32_16x16x32_bf16 v[24:27], v[248:251], v[204:207], v[24:27]
	v_mfma_f32_16x16x32_bf16 v[60:63], v[240:243], v[212:215], v[60:63]
	v_mfma_f32_16x16x32_bf16 v[28:31], v[248:251], v[212:215], v[28:31]
	v_mfma_f32_16x16x32_bf16 v[48:51], v[244:247], v[148:151], v[48:51]
	s_waitcnt lgkmcnt(0)
	v_mfma_f32_16x16x32_bf16 v[16:19], v[230:233], v[148:151], v[16:19]
	v_mfma_f32_16x16x32_bf16 v[52:55], v[244:247], v[200:203], v[52:55]
	v_mfma_f32_16x16x32_bf16 v[20:23], v[230:233], v[200:203], v[20:23]
	v_mfma_f32_16x16x32_bf16 v[56:59], v[244:247], v[208:211], v[56:59]
	v_mfma_f32_16x16x32_bf16 v[24:27], v[230:233], v[208:211], v[24:27]
	v_mfma_f32_16x16x32_bf16 v[60:63], v[244:247], v[236:239], v[60:63]
	v_mfma_f32_16x16x32_bf16 v[28:31], v[230:233], v[236:239], v[28:31]
	s_barrier
	ds_read_b128 v[144:147], v178 offset:16384
	ds_read_b128 v[148:151], v178 offset:17408
	ds_read_b128 v[184:187], v178 offset:18432
	ds_read_b128 v[200:203], v178 offset:19456
	ds_read_b128 v[204:207], v178 offset:20480
	ds_read_b128 v[208:211], v178 offset:21504
	ds_read_b128 v[212:215], v178 offset:22528
	ds_read_b128 v[236:239], v178 offset:23552
	s_mov_b32 m0, s89
	s_nop 0
	global_load_lds_dwordx4 v152, s[80:81]
	s_add_u32 s48, s80, 0x2000
	s_addc_u32 s49, s81, 0
	s_mov_b32 m0, s40
	s_nop 0
	global_load_lds_dwordx4 v152, s[48:49]
	s_waitcnt vmcnt(10)
	s_barrier
	s_waitcnt lgkmcnt(7)
	v_mfma_f32_16x16x32_bf16 v[100:103], v[128:131], v[144:147], v[100:103]
	v_mfma_f32_16x16x32_bf16 v[64:67], v[136:139], v[144:147], v[64:67]
	s_waitcnt lgkmcnt(5)
	v_mfma_f32_16x16x32_bf16 v[104:107], v[128:131], v[184:187], v[104:107]
	v_mfma_f32_16x16x32_bf16 v[68:71], v[136:139], v[184:187], v[68:71]
	s_waitcnt lgkmcnt(3)
	v_mfma_f32_16x16x32_bf16 v[108:111], v[128:131], v[204:207], v[108:111]
	v_mfma_f32_16x16x32_bf16 v[72:75], v[136:139], v[204:207], v[72:75]
	s_waitcnt lgkmcnt(1)
	v_mfma_f32_16x16x32_bf16 v[112:115], v[128:131], v[212:215], v[112:115]
	v_mfma_f32_16x16x32_bf16 v[76:79], v[136:139], v[212:215], v[76:79]
	v_mfma_f32_16x16x32_bf16 v[100:103], v[132:135], v[148:151], v[100:103]
	v_mfma_f32_16x16x32_bf16 v[64:67], v[140:143], v[148:151], v[64:67]
	v_mfma_f32_16x16x32_bf16 v[104:107], v[132:135], v[200:203], v[104:107]
	v_mfma_f32_16x16x32_bf16 v[68:71], v[140:143], v[200:203], v[68:71]
	v_mfma_f32_16x16x32_bf16 v[108:111], v[132:135], v[208:211], v[108:111]
	v_mfma_f32_16x16x32_bf16 v[72:75], v[140:143], v[208:211], v[72:75]
	s_waitcnt lgkmcnt(0)
	v_mfma_f32_16x16x32_bf16 v[112:115], v[132:135], v[236:239], v[112:115]
	v_mfma_f32_16x16x32_bf16 v[76:79], v[140:143], v[236:239], v[76:79]
	s_barrier
	ds_read_b128 v[128:131], v177 offset:32768
	ds_read_b128 v[132:135], v177 offset:33792
	ds_read_b128 v[136:139], v177 offset:34816
	ds_read_b128 v[140:143], v177 offset:35840
	s_add_u32 s48, s76, 0x80000
	s_addc_u32 s49, s77, 0
	s_mov_b32 m0, s41
	s_nop 0
	global_load_lds_dwordx4 v152, s[48:49]
	s_add_u32 s48, s76, 0x82000
	s_addc_u32 s49, s77, 0
	s_mov_b32 m0, s42
	s_nop 0
	global_load_lds_dwordx4 v152, s[48:49]
	s_add_u32 s48, s80, 0x80000
	s_addc_u32 s49, s81, 0
	s_mov_b32 m0, s43
	s_nop 0
	global_load_lds_dwordx4 v152, s[48:49]
	s_add_u32 s48, s80, 0x82000
	s_addc_u32 s49, s81, 0
	s_mov_b32 m0, s92
	s_nop 0
	global_load_lds_dwordx4 v152, s[48:49]
	s_waitcnt vmcnt(12)
	s_barrier
	v_mfma_f32_16x16x32_bf16 v[32:35], v[240:243], v[144:147], v[32:35]
	v_mfma_f32_16x16x32_bf16 v[0:3], v[248:251], v[144:147], v[0:3]
	v_mfma_f32_16x16x32_bf16 v[36:39], v[240:243], v[184:187], v[36:39]
	v_mfma_f32_16x16x32_bf16 v[4:7], v[248:251], v[184:187], v[4:7]
	v_mfma_f32_16x16x32_bf16 v[40:43], v[240:243], v[204:207], v[40:43]
	v_mfma_f32_16x16x32_bf16 v[8:11], v[248:251], v[204:207], v[8:11]
	v_mfma_f32_16x16x32_bf16 v[44:47], v[240:243], v[212:215], v[44:47]
	v_mfma_f32_16x16x32_bf16 v[12:15], v[248:251], v[212:215], v[12:15]
	v_mfma_f32_16x16x32_bf16 v[32:35], v[244:247], v[148:151], v[32:35]
	v_mfma_f32_16x16x32_bf16 v[0:3], v[230:233], v[148:151], v[0:3]
	v_mfma_f32_16x16x32_bf16 v[36:39], v[244:247], v[200:203], v[36:39]
	v_mfma_f32_16x16x32_bf16 v[4:7], v[230:233], v[200:203], v[4:7]
	v_mfma_f32_16x16x32_bf16 v[40:43], v[244:247], v[208:211], v[40:43]
	v_mfma_f32_16x16x32_bf16 v[8:11], v[230:233], v[208:211], v[8:11]
	v_mfma_f32_16x16x32_bf16 v[44:47], v[244:247], v[236:239], v[44:47]
	v_mfma_f32_16x16x32_bf16 v[12:15], v[230:233], v[236:239], v[12:15]
	s_barrier
	ds_read_b128 v[144:147], v178 offset:32768
	ds_read_b128 v[148:151], v178 offset:33792
	ds_read_b128 v[184:187], v178 offset:34816
	ds_read_b128 v[200:203], v178 offset:35840
	ds_read_b128 v[204:207], v178 offset:36864
	ds_read_b128 v[208:211], v178 offset:37888
	ds_read_b128 v[212:215], v178 offset:38912
	ds_read_b128 v[230:233], v178 offset:39936
	s_waitcnt lgkmcnt(8)
	s_waitcnt vmcnt(10)
	s_barrier
; #define PG8_STAGE(bufoff, gbase, hoff, imm) do { _Pragma("unroll") for (int _i = 0; _i < 2; ++_i) { \
;         asm volatile("s_mov_b32 m0, %0\n\ts_nop 0\n\tglobal_load_lds_dwordx4 %1, %2" \
;             :: "s"(lds0 + (unsigned)((bufoff) + _i * 8192)), "v"(voff0), "s"((const char*)(gbase) + (size_t)(hoff) + (size_t)(_i * 8192)) : "memory"); } } while (0)
; #define PG8_LDA(dst, b, h) do { _Pragma("unroll") for (int m = 0; m < 4; ++m) _Pragma("unroll") for (int k = 0; k < 2; ++k) dst[m][k] = *(const LAS bf16x8*)(lds + PG8_SA(b, h) + aoff + m * 2048 + k * 1024); } while (0)
; #define PG8_LDB(dst, b, h) do { _Pragma("unroll") for (int n = 0; n < 2; ++n) _Pragma("unroll") for (int k = 0; k < 2; ++k) dst[n][k] = *(const LAS bf16x8*)(lds + PG8_SB(b, h) + boff + n * 2048 + k * 1024); } while (0)
; #define PG8_WAIT_V(n) asm volatile("s_waitcnt vmcnt(" #n ")" ::: "memory")
; #define PG8_WAIT_L(n) asm volatile("s_waitcnt lgkmcnt(" #n ")" ::: "memory")
; #define PG8_BAR __builtin_amdgcn_s_barrier()
; template <class Epi>
; __device__ __forceinline__ void gemm_phase(LAS unsigned char* lds, const Gemm g, const StaticOrder& S, const Epi& E) {
;     ...
;             PG8_LDB(B0, 0, 0); PG8_SCHED; PG8_LDA(At, 0, 0); PG8_STAGE(PG8_SA(1, 1), aT + KS, hA, 0);
;             PG8_WAIT_L(8); PG8_BAR; PG8_WAIT_L(0); PG8_MMA(0, 0, At, B0); PG8_BAR; PG8_SCHED;
;             PG8_LDB(B1, 0, 1); PG8_STAGE(PG8_SB(0, 0), b2, 0, 0);
;             PG8_BAR; PG8_WAIT_L(0); PG8_MMA(0, 1, At, B1); PG8_BAR;
;             PG8_LDA(At, 0, 1); PG8_STAGE(PG8_SA(0, 0), a2, 0, 0);
;             PG8_BAR; PG8_WAIT_L(0); PG8_MMA(1, 0, At, B0); PG8_BAR; PG8_SCHED;
;             PG8_STAGE(PG8_SB(0, 1), b2, hB, 0);
;             PG8_WAIT_V(6); PG8_BAR; PG8_MMA(1, 1, At, B1); PG8_BAR;
;             PG8_LDB(B0, 1, 0); PG8_SCHED; PG8_LDA(At, 1, 0); PG8_STAGE(PG8_SA(0, 1), a2, hA, 0);
;             PG8_WAIT_L(8); PG8_BAR; PG8_WAIT_L(0); PG8_MMA(0, 0, At, B0); PG8_BAR; PG8_SCHED;
;             PG8_LDB(B1, 1, 1); PG8_STAGE(PG8_SB(1, 0), b2 + KS, 0, 0);
;             PG8_BAR; PG8_WAIT_L(0); PG8_MMA(0, 1, At, B1); PG8_BAR;
;             PG8_LDA(At, 1, 1); PG8_STAGE(PG8_SA(1, 0), a2 + KS, 0, 0);
;             PG8_BAR; PG8_WAIT_L(0); PG8_MMA(1, 0, At, B0); PG8_BAR; PG8_SCHED;
;             PG8_STAGE(PG8_SB(1, 1), b2 + KS, hB, 0);
;             PG8_WAIT_V(6); PG8_BAR; PG8_MMA(1, 1, At, B1); PG8_BAR;
	s_waitcnt lgkmcnt(7)
	v_mfma_f32_16x16x32_bf16 v[116:119], v[128:131], v[144:147], v[116:119]
	v_mfma_f32_16x16x32_bf16 v[80:83], v[136:139], v[144:147], v[80:83]
	s_waitcnt lgkmcnt(5)
	v_mfma_f32_16x16x32_bf16 v[88:91], v[128:131], v[184:187], v[88:91]
	v_mfma_f32_16x16x32_bf16 v[84:87], v[136:139], v[184:187], v[84:87]
	s_waitcnt lgkmcnt(3)
	v_mfma_f32_16x16x32_bf16 v[120:123], v[128:131], v[204:207], v[120:123]
	v_mfma_f32_16x16x32_bf16 v[92:95], v[136:139], v[204:207], v[92:95]
	s_waitcnt lgkmcnt(1)
	v_mfma_f32_16x16x32_bf16 v[124:127], v[128:131], v[212:215], v[124:127]
	v_mfma_f32_16x16x32_bf16 v[96:99], v[136:139], v[212:215], v[96:99]
	v_mfma_f32_16x16x32_bf16 v[116:119], v[132:135], v[148:151], v[116:119]
	v_mfma_f32_16x16x32_bf16 v[80:83], v[140:143], v[148:151], v[80:83]
	v_mfma_f32_16x16x32_bf16 v[88:91], v[132:135], v[200:203], v[88:91]
	v_mfma_f32_16x16x32_bf16 v[84:87], v[140:143], v[200:203], v[84:87]
	v_mfma_f32_16x16x32_bf16 v[120:123], v[132:135], v[208:211], v[120:123]
	v_mfma_f32_16x16x32_bf16 v[92:95], v[140:143], v[208:211], v[92:95]
	s_waitcnt lgkmcnt(0)
	v_mfma_f32_16x16x32_bf16 v[124:127], v[132:135], v[230:233], v[124:127]
	v_mfma_f32_16x16x32_bf16 v[96:99], v[140:143], v[230:233], v[96:99]
	s_barrier
	ds_read_b128 v[236:239], v177 offset:49152
	ds_read_b128 v[240:243], v177 offset:50176
	ds_read_b128 v[244:247], v177 offset:51200
	ds_read_b128 v[248:251], v177 offset:52224
	s_add_u32 s48, s76, 0x4000
	s_addc_u32 s49, s77, 0
	s_mov_b32 m0, s16
	s_nop 0
	global_load_lds_dwordx4 v152, s[48:49]
	s_add_u32 s48, s76, 0x6000
	s_addc_u32 s49, s77, 0
	s_mov_b32 m0, s17
	s_nop 0
	global_load_lds_dwordx4 v152, s[48:49]
	s_waitcnt vmcnt(10)
	s_barrier
	s_waitcnt lgkmcnt(3)
	v_mfma_f32_16x16x32_bf16 v[48:51], v[236:239], v[144:147], v[48:51]
	s_waitcnt lgkmcnt(1)
	v_mfma_f32_16x16x32_bf16 v[16:19], v[244:247], v[144:147], v[16:19]
	v_mfma_f32_16x16x32_bf16 v[52:55], v[236:239], v[184:187], v[52:55]
	v_mfma_f32_16x16x32_bf16 v[20:23], v[244:247], v[184:187], v[20:23]
	v_mfma_f32_16x16x32_bf16 v[56:59], v[236:239], v[204:207], v[56:59]
	v_mfma_f32_16x16x32_bf16 v[24:27], v[244:247], v[204:207], v[24:27]
	v_mfma_f32_16x16x32_bf16 v[60:63], v[236:239], v[212:215], v[60:63]
	v_mfma_f32_16x16x32_bf16 v[28:31], v[244:247], v[212:215], v[28:31]
	v_mfma_f32_16x16x32_bf16 v[48:51], v[240:243], v[148:151], v[48:51]
	s_waitcnt lgkmcnt(0)
	v_mfma_f32_16x16x32_bf16 v[16:19], v[248:251], v[148:151], v[16:19]
	v_mfma_f32_16x16x32_bf16 v[52:55], v[240:243], v[200:203], v[52:55]
	v_mfma_f32_16x16x32_bf16 v[20:23], v[248:251], v[200:203], v[20:23]
	v_mfma_f32_16x16x32_bf16 v[56:59], v[240:243], v[208:211], v[56:59]
	v_mfma_f32_16x16x32_bf16 v[24:27], v[248:251], v[208:211], v[24:27]
	v_mfma_f32_16x16x32_bf16 v[60:63], v[240:243], v[230:233], v[60:63]
	v_mfma_f32_16x16x32_bf16 v[28:31], v[248:251], v[230:233], v[28:31]
	s_barrier
	ds_read_b128 v[144:147], v178 offset:49152
	ds_read_b128 v[148:151], v178 offset:50176
	ds_read_b128 v[184:187], v178 offset:51200
	ds_read_b128 v[200:203], v178 offset:52224
	ds_read_b128 v[204:207], v178 offset:53248
	ds_read_b128 v[208:211], v178 offset:54272
	ds_read_b128 v[212:215], v178 offset:55296
	ds_read_b128 v[230:233], v178 offset:56320
	s_add_u32 s48, s80, 0x4000
	s_addc_u32 s49, s81, 0
	s_mov_b32 m0, s24
	s_nop 0
	global_load_lds_dwordx4 v152, s[48:49]
	s_add_u32 s48, s80, 0x6000
	s_addc_u32 s49, s81, 0
	s_mov_b32 m0, s37
	s_nop 0
	global_load_lds_dwordx4 v152, s[48:49]
	s_waitcnt vmcnt(10)
	s_barrier
	s_waitcnt lgkmcnt(7)
	v_mfma_f32_16x16x32_bf16 v[100:103], v[128:131], v[144:147], v[100:103]
	v_mfma_f32_16x16x32_bf16 v[64:67], v[136:139], v[144:147], v[64:67]
	s_waitcnt lgkmcnt(5)
	v_mfma_f32_16x16x32_bf16 v[104:107], v[128:131], v[184:187], v[104:107]
	v_mfma_f32_16x16x32_bf16 v[68:71], v[136:139], v[184:187], v[68:71]
	s_waitcnt lgkmcnt(3)
	v_mfma_f32_16x16x32_bf16 v[108:111], v[128:131], v[204:207], v[108:111]
	v_mfma_f32_16x16x32_bf16 v[72:75], v[136:139], v[204:207], v[72:75]
	s_waitcnt lgkmcnt(1)
	v_mfma_f32_16x16x32_bf16 v[112:115], v[128:131], v[212:215], v[112:115]
	v_mfma_f32_16x16x32_bf16 v[76:79], v[136:139], v[212:215], v[76:79]
	v_mfma_f32_16x16x32_bf16 v[100:103], v[132:135], v[148:151], v[100:103]
	v_mfma_f32_16x16x32_bf16 v[64:67], v[140:143], v[148:151], v[64:67]
	v_mfma_f32_16x16x32_bf16 v[104:107], v[132:135], v[200:203], v[104:107]
	v_mfma_f32_16x16x32_bf16 v[68:71], v[140:143], v[200:203], v[68:71]
	v_mfma_f32_16x16x32_bf16 v[108:111], v[132:135], v[208:211], v[108:111]
	v_mfma_f32_16x16x32_bf16 v[72:75], v[140:143], v[208:211], v[72:75]
	s_waitcnt lgkmcnt(0)
	v_mfma_f32_16x16x32_bf16 v[112:115], v[132:135], v[230:233], v[112:115]
	v_mfma_f32_16x16x32_bf16 v[76:79], v[140:143], v[230:233], v[76:79]
	s_barrier
	ds_read_b128 v[128:131], v177
	ds_read_b128 v[132:135], v177 offset:1024
	ds_read_b128 v[136:139], v177 offset:2048
	ds_read_b128 v[140:143], v177 offset:3072
	s_add_u32 s48, s76, 0x84000
	s_addc_u32 s49, s77, 0
	s_mov_b32 m0, s97
	s_nop 0
	global_load_lds_dwordx4 v152, s[48:49]
	s_add_u32 s48, s76, 0x86000
	s_addc_u32 s49, s77, 0
	s_mov_b32 m0, s38
	s_nop 0
	global_load_lds_dwordx4 v152, s[48:49]
	s_add_u32 s48, s80, 0x84000
	s_addc_u32 s49, s81, 0
	s_mov_b32 m0, s34
	s_nop 0
	global_load_lds_dwordx4 v152, s[48:49]
	s_add_u32 s48, s80, 0x86000
	s_addc_u32 s49, s81, 0
	s_mov_b32 m0, s25
	s_nop 0
	global_load_lds_dwordx4 v152, s[48:49]
	s_waitcnt vmcnt(12)
	s_barrier
	v_mfma_f32_16x16x32_bf16 v[32:35], v[236:239], v[144:147], v[32:35]
	v_mfma_f32_16x16x32_bf16 v[0:3], v[244:247], v[144:147], v[0:3]
	v_mfma_f32_16x16x32_bf16 v[36:39], v[236:239], v[184:187], v[36:39]
	v_mfma_f32_16x16x32_bf16 v[4:7], v[244:247], v[184:187], v[4:7]
	v_mfma_f32_16x16x32_bf16 v[40:43], v[236:239], v[204:207], v[40:43]
	v_mfma_f32_16x16x32_bf16 v[8:11], v[244:247], v[204:207], v[8:11]
	v_mfma_f32_16x16x32_bf16 v[44:47], v[236:239], v[212:215], v[44:47]
	v_mfma_f32_16x16x32_bf16 v[12:15], v[244:247], v[212:215], v[12:15]
	v_mfma_f32_16x16x32_bf16 v[32:35], v[240:243], v[148:151], v[32:35]
	v_mfma_f32_16x16x32_bf16 v[0:3], v[248:251], v[148:151], v[0:3]
	v_mfma_f32_16x16x32_bf16 v[36:39], v[240:243], v[200:203], v[36:39]
	v_mfma_f32_16x16x32_bf16 v[4:7], v[248:251], v[200:203], v[4:7]
	v_mfma_f32_16x16x32_bf16 v[40:43], v[240:243], v[208:211], v[40:43]
	v_mfma_f32_16x16x32_bf16 v[8:11], v[248:251], v[208:211], v[8:11]
	v_mfma_f32_16x16x32_bf16 v[44:47], v[240:243], v[230:233], v[44:47]
	v_mfma_f32_16x16x32_bf16 v[12:15], v[248:251], v[230:233], v[12:15]
	s_add_i32 s71, s71, 2
	s_add_u32 s1, s1, 0x8000
	s_addc_u32 s9, s9, 0
	s_cmp_gt_u32 s71, 29
	s_mov_b64 s[76:77], s[78:79]
	s_barrier
	s_cbranch_scc1 .LBB0_741

; #define PG8_STAGE(bufoff, gbase, hoff, imm) do { _Pragma("unroll") for (int _i = 0; _i < 2; ++_i) { \
;         asm volatile("s_mov_b32 m0, %0\n\ts_nop 0\n\tglobal_load_lds_dwordx4 %1, %2" \
;             :: "s"(lds0 + (unsigned)((bufoff) + _i * 8192)), "v"(voff0), "s"((const char*)(gbase) + (size_t)(hoff) + (size_t)(_i * 8192)) : "memory"); } } while (0)
; #define PG8_WAIT_V(n) asm volatile("s_waitcnt vmcnt(" #n ")" ::: "memory")
; #define PG8_BAR __builtin_amdgcn_s_barrier()
; template <class Epi>
; __device__ __forceinline__ void gemm_phase(LAS unsigned char* lds, const Gemm g, const StaticOrder& S, const Epi& E) {
;     ...
;     const int wid = __builtin_amdgcn_readfirstlane(tid >> 6), lane = tid & 63, wr = wid >> 2, wc = wid & 3, fr = lane & 15, fq = lane >> 4;
;     const int K = g.K, nt = K / BK;
;     const unsigned voff0 = (unsigned)(tid * 16);
;     const unsigned hA = (unsigned)(g.lda * 256), hB = (unsigned)(K * 256);
;     constexpr int KS = 16384;
;     const size_t tstepA = (size_t)BM * g.lda * 2, tstepB = (size_t)BM * K * 2;
;     const unsigned lds0 = (unsigned)__builtin_amdgcn_readfirstlane((int)((unsigned)(size_t)lds + (unsigned)wid * 1024u));
;     const int aoff = lds_byte(wr * 64 + fr, fq * 8), boff = lds_byte(wc * 32 + fr, fq * 8);
;     ...
;     Unit cur, nxt; int ui = 0;
;     if (!S.next(0, cur)) return;
;     f32x4 acc[2][2][4][2];
; #pragma unroll
;     for (int a = 0; a < 2; ++a)
; #pragma unroll
;         for (int b = 0; b < 2; ++b)
; #pragma unroll
;             for (int m = 0; m < 4; ++m)
; #pragma unroll
;                 for (int n = 0; n < 2; ++n) acc[a][b][m][n] = (f32x4){0.f, 0.f, 0.f, 0.f};
;     bf16x8 At[4][2], B0[2][2], B1[2][2];
;     const char* cA = (const char*)g.A + (size_t)cur.pm * tstepA + (size_t)(cur.pn >> g.gshift) * g.gstride; const char* cB = (const char*)g.Bt + (size_t)cur.pn * tstepB;
;     PG8_STAGE(PG8_SB(0, 0), cB, 0, 0); PG8_STAGE(PG8_SA(0, 0), cA, 0, 0); PG8_STAGE(PG8_SB(0, 1), cB, hB, 0); PG8_STAGE(PG8_SA(0, 1), cA, hA, 0);
;     if (wr == 1) PG8_BAR;
;     PG8_WAIT_V(4); PG8_BAR;
;     PG8_STAGE(PG8_SB(1, 0), cB + KS, 0, 0); PG8_STAGE(PG8_SA(1, 0), cA + KS, 0, 0); PG8_STAGE(PG8_SB(1, 1), cB + KS, hB, 0);
;     PG8_WAIT_V(6); PG8_BAR;
.LBB0_848:
	s_add_u32 s52, s8, 0x29c30000
	s_addc_u32 s53, s9, 0
	s_cmp_eq_u32 s17, 0
	s_cselect_b64 s[4:5], -1, 0
	s_and_b64 s[4:5], s[2:3], s[4:5]
	s_add_u32 s6, s8, 0x31c34000
	s_addc_u32 s7, s9, 0
	s_and_b64 s[4:5], s[4:5], exec
	s_cselect_b32 s55, s7, s53
	s_cselect_b32 s54, s6, s52
	s_add_u32 s4, s8, s16
	s_addc_u32 s5, s9, 0
	s_add_u32 s39, s4, 0xa60a000
	v_lshrrev_b32_e32 v2, 1, v0
	s_addc_u32 s40, s5, 0
	v_and_b32_e32 v2, 24, v2
	s_lshl_b32 s0, s0, 5
	v_and_b32_e32 v1, 15, v0
	v_lshlrev_b32_e32 v3, 1, v2
	v_lshlrev_b32_e32 v0, 2, v0
	s_and_b32 s4, s0, 0x60
	v_lshl_or_b32 v233, s1, 6, v1
	v_lshl_or_b32 v1, v1, 6, v3
	s_lshl_b32 s1, s1, 13
	v_and_b32_e32 v0, 32, v0
	s_lshl_b32 s0, s4, 7
	s_add_i32 s41, s25, 0x18000
	v_bitop3_b32 v3, v1, s1, v0 bitop3:0xde
	v_bitop3_b32 v0, v1, s0, v0 bitop3:0xde
	s_add_u32 s0, s58, 0x4000
	s_addc_u32 s1, s59, 0
	s_add_i32 s42, s25, 0x1a000
	s_waitcnt vmcnt(4)
	s_barrier
	s_mov_b32 m0, s41
	s_nop 0
	global_load_lds_dwordx4 v188, s[0:1]
	s_add_u32 s0, s58, 0x6000
	s_addc_u32 s1, s59, 0
	s_add_i32 s43, s25, 0x8000
	s_mov_b32 m0, s42
	s_nop 0
	global_load_lds_dwordx4 v188, s[0:1]
	s_add_u32 s0, s56, 0x4000
	s_addc_u32 s1, s57, 0
	s_add_i32 s62, s25, 0xa000
	s_mov_b32 m0, s43
	s_nop 0
	global_load_lds_dwordx4 v188, s[0:1]
	s_add_u32 s0, s56, 0x6000
	s_addc_u32 s1, s57, 0
	s_add_i32 s63, s25, 0x1c000
	s_mov_b32 m0, s62
	s_nop 0
	global_load_lds_dwordx4 v188, s[0:1]
	s_add_u32 s0, s58, 0x164000
	s_addc_u32 s1, s59, 0
	s_add_i32 s64, s25, 0x1e000
	s_mov_b32 m0, s63
	s_nop 0
	global_load_lds_dwordx4 v188, s[0:1]
	s_add_u32 s0, s58, 0x166000
	s_addc_u32 s1, s59, 0
	s_mov_b32 m0, s64
	s_nop 0
	global_load_lds_dwordx4 v188, s[0:1]
	s_waitcnt vmcnt(6)
	v_readlane_b32 s0, v255, 15
	s_mov_b32 s38, 0
	s_add_i32 s65, s25, 0xc000
	s_add_i32 s66, s25, 0xe000
	v_or_b32_e32 v234, s4, v2
	v_add_u32_e32 v236, 0x10000, v0
	v_add_u32_e32 v237, 0, v3
	v_readlane_b32 s51, v255, 14
	s_mov_b32 s50, s0
	s_barrier
	v_readlane_b32 s1, v255, 16

; #define PG8_STAGE(bufoff, gbase, hoff, imm) do { _Pragma("unroll") for (int _i = 0; _i < 2; ++_i) { \
;         asm volatile("s_mov_b32 m0, %0\n\ts_nop 0\n\tglobal_load_lds_dwordx4 %1, %2" \
;             :: "s"(lds0 + (unsigned)((bufoff) + _i * 8192)), "v"(voff0), "s"((const char*)(gbase) + (size_t)(hoff) + (size_t)(_i * 8192)) : "memory"); } } while (0)
; #define PG8_LDA(dst, b, h) do { _Pragma("unroll") for (int m = 0; m < 4; ++m) _Pragma("unroll") for (int k = 0; k < 2; ++k) dst[m][k] = *(const LAS bf16x8*)(lds + PG8_SA(b, h) + aoff + m * 2048 + k * 1024); } while (0)
; #define PG8_LDB(dst, b, h) do { _Pragma("unroll") for (int n = 0; n < 2; ++n) _Pragma("unroll") for (int k = 0; k < 2; ++k) dst[n][k] = *(const LAS bf16x8*)(lds + PG8_SB(b, h) + boff + n * 2048 + k * 1024); } while (0)
; #define PG8_MMA(ai, bj, At, Bt) do { __builtin_amdgcn_s_setprio(1); _Pragma("unroll") for (int m = 0; m < 4; ++m) _Pragma("unroll") for (int n = 0; n < 2; ++n) _Pragma("unroll") for (int k = 0; k < 2; ++k) \
;         acc[ai][bj][m][n] = __builtin_amdgcn_mfma_f32_16x16x32_bf16(Bt[n][k], At[m][k], acc[ai][bj][m][n], 0, 0, 0); __builtin_amdgcn_s_setprio(0); } while (0)
; #define PG8_WAIT_V(n) asm volatile("s_waitcnt vmcnt(" #n ")" ::: "memory")
; #define PG8_BAR __builtin_amdgcn_s_barrier()
; template <class Epi>
; __device__ __forceinline__ void gemm_phase(LAS unsigned char* lds, const Gemm g, const StaticOrder& S, const Epi& E) {
;     ...
;         for (int t = 0; t < nt; t += 2) {
;             const bool last = (t == nt - 2);
;             if (last) E.pre(cur, wid, lane, (unsigned)(size_t)(lds + STAGE_BYTES));
;             const char* aT = cA + (size_t)t * KS;
;             const char* a2 = last ? nA : aT + 2 * KS; const char* b2 = last ? nB : cB + (size_t)(t + 2) * KS;
;             PG8_LDB(B0, 0, 0); PG8_SCHED; PG8_LDA(At, 0, 0); PG8_STAGE(PG8_SA(1, 1), aT + KS, hA, 0);
;             PG8_WAIT_L(8); PG8_BAR; PG8_WAIT_L(0); PG8_MMA(0, 0, At, B0); PG8_BAR; PG8_SCHED;
;             PG8_LDB(B1, 0, 1); PG8_STAGE(PG8_SB(0, 0), b2, 0, 0);
;             PG8_BAR; PG8_WAIT_L(0); PG8_MMA(0, 1, At, B1); PG8_BAR;
;             PG8_LDA(At, 0, 1); PG8_STAGE(PG8_SA(0, 0), a2, 0, 0);
;             PG8_BAR; PG8_WAIT_L(0); PG8_MMA(1, 0, At, B0); PG8_BAR; PG8_SCHED;
;             PG8_STAGE(PG8_SB(0, 1), b2, hB, 0);
;             PG8_WAIT_V(6); PG8_BAR; PG8_MMA(1, 1, At, B1); PG8_BAR;
.LBB0_859:
	s_add_u32 s0, s58, 0x8000
	s_addc_u32 s1, s59, 0
	s_mov_b32 s69, -2
	s_waitcnt vmcnt(16)
	s_add_u32 s58, s56, 0x8000
	s_addc_u32 s59, s57, 0
	ds_read_b128 v[120:123], v236
	ds_read_b128 v[124:127], v236 offset:1024
	ds_read_b128 v[128:131], v236 offset:2048
	ds_read_b128 v[132:135], v236 offset:3072
	s_add_u32 s48, s56, 0x164000
	s_addc_u32 s49, s57, 0
	s_add_u32 s60, s56, 0x166000
	s_addc_u32 s61, s57, 0
	s_cmpk_eq_i32 s69, 0x54
	s_cselect_b32 s57, s7, s59
	s_cselect_b32 s56, s6, s58
	ds_read_b128 v[136:139], v237
	ds_read_b128 v[140:143], v237 offset:1024
	ds_read_b128 v[152:155], v237 offset:2048
	ds_read_b128 v[156:159], v237 offset:3072
	ds_read_b128 v[160:163], v237 offset:4096
	ds_read_b128 v[164:167], v237 offset:5120
	ds_read_b128 v[168:171], v237 offset:6144
	ds_read_b128 v[172:175], v237 offset:7168
	s_mov_b32 m0, s65
	s_nop 0
	global_load_lds_dwordx4 v188, s[48:49]
	s_mov_b32 m0, s66
	s_nop 0
	global_load_lds_dwordx4 v188, s[60:61]
	s_waitcnt lgkmcnt(8)
	s_waitcnt vmcnt(10)
	s_barrier
	s_waitcnt lgkmcnt(7)
	v_mfma_f32_16x16x32_bf16 v[148:151], v[120:123], v[136:139], 0
	v_mfma_f32_16x16x32_bf16 v[144:147], v[128:131], v[136:139], 0
	s_waitcnt lgkmcnt(5)
	v_mfma_f32_16x16x32_bf16 v[108:111], v[120:123], v[152:155], 0
	v_mfma_f32_16x16x32_bf16 v[104:107], v[128:131], v[152:155], 0
	s_waitcnt lgkmcnt(3)
	v_mfma_f32_16x16x32_bf16 v[92:95], v[120:123], v[160:163], 0
	v_mfma_f32_16x16x32_bf16 v[88:91], v[128:131], v[160:163], 0
	s_waitcnt lgkmcnt(1)
	v_mfma_f32_16x16x32_bf16 v[76:79], v[120:123], v[168:171], 0
	v_mfma_f32_16x16x32_bf16 v[72:75], v[128:131], v[168:171], 0
	v_mfma_f32_16x16x32_bf16 v[148:151], v[124:127], v[140:143], v[148:151]
	v_mfma_f32_16x16x32_bf16 v[144:147], v[132:135], v[140:143], v[144:147]
	v_mfma_f32_16x16x32_bf16 v[108:111], v[124:127], v[156:159], v[108:111]
	v_mfma_f32_16x16x32_bf16 v[104:107], v[132:135], v[156:159], v[104:107]
	v_mfma_f32_16x16x32_bf16 v[92:95], v[124:127], v[164:167], v[92:95]
	v_mfma_f32_16x16x32_bf16 v[88:91], v[132:135], v[164:167], v[88:91]
	s_waitcnt lgkmcnt(0)
	v_mfma_f32_16x16x32_bf16 v[76:79], v[124:127], v[172:175], v[76:79]
	v_mfma_f32_16x16x32_bf16 v[72:75], v[132:135], v[172:175], v[72:75]
	s_barrier
	ds_read_b128 v[176:179], v236 offset:16384
	ds_read_b128 v[180:183], v236 offset:17408
	ds_read_b128 v[184:187], v236 offset:18432
	ds_read_b128 v[200:203], v236 offset:19456
	s_cselect_b32 s60, s8, s0
	s_cselect_b32 s61, s9, s1
	s_mov_b32 m0, s26
	s_nop 0
	global_load_lds_dwordx4 v188, s[60:61]
	s_add_u32 s48, s60, 0x2000
	s_addc_u32 s49, s61, 0
	s_mov_b32 m0, s27
	s_nop 0
	global_load_lds_dwordx4 v188, s[48:49]
	s_waitcnt vmcnt(10)
	s_barrier
	s_waitcnt lgkmcnt(3)
	v_mfma_f32_16x16x32_bf16 v[116:119], v[176:179], v[136:139], 0
	s_waitcnt lgkmcnt(1)
	v_mfma_f32_16x16x32_bf16 v[112:115], v[184:187], v[136:139], 0
	v_mfma_f32_16x16x32_bf16 v[100:103], v[176:179], v[152:155], 0
	v_mfma_f32_16x16x32_bf16 v[96:99], v[184:187], v[152:155], 0
	v_mfma_f32_16x16x32_bf16 v[84:87], v[176:179], v[160:163], 0
	v_mfma_f32_16x16x32_bf16 v[80:83], v[184:187], v[160:163], 0
	v_mfma_f32_16x16x32_bf16 v[68:71], v[176:179], v[168:171], 0
	v_mfma_f32_16x16x32_bf16 v[64:67], v[184:187], v[168:171], 0
	v_mfma_f32_16x16x32_bf16 v[116:119], v[180:183], v[140:143], v[116:119]
	s_waitcnt lgkmcnt(0)
	v_mfma_f32_16x16x32_bf16 v[112:115], v[200:203], v[140:143], v[112:115]
	v_mfma_f32_16x16x32_bf16 v[100:103], v[180:183], v[156:159], v[100:103]
	v_mfma_f32_16x16x32_bf16 v[96:99], v[200:203], v[156:159], v[96:99]
	v_mfma_f32_16x16x32_bf16 v[84:87], v[180:183], v[164:167], v[84:87]
	v_mfma_f32_16x16x32_bf16 v[80:83], v[200:203], v[164:167], v[80:83]
	v_mfma_f32_16x16x32_bf16 v[68:71], v[180:183], v[172:175], v[68:71]
	v_mfma_f32_16x16x32_bf16 v[64:67], v[200:203], v[172:175], v[64:67]
	s_barrier
	ds_read_b128 v[136:139], v237 offset:16384
	ds_read_b128 v[140:143], v237 offset:17408
	ds_read_b128 v[152:155], v237 offset:18432
	ds_read_b128 v[156:159], v237 offset:19456
	ds_read_b128 v[160:163], v237 offset:20480
	ds_read_b128 v[164:167], v237 offset:21504
	ds_read_b128 v[168:171], v237 offset:22528
	ds_read_b128 v[172:175], v237 offset:23552
	s_mov_b32 m0, s25
	s_nop 0
	global_load_lds_dwordx4 v188, s[56:57]
	s_add_u32 s48, s56, 0x2000
	s_addc_u32 s49, s57, 0
	s_mov_b32 m0, s28
	s_nop 0
	global_load_lds_dwordx4 v188, s[48:49]
	s_barrier
	s_waitcnt lgkmcnt(7)
	v_mfma_f32_16x16x32_bf16 v[60:63], v[120:123], v[136:139], 0
	v_mfma_f32_16x16x32_bf16 v[56:59], v[128:131], v[136:139], 0
	s_waitcnt lgkmcnt(5)
	v_mfma_f32_16x16x32_bf16 v[44:47], v[120:123], v[152:155], 0
	v_mfma_f32_16x16x32_bf16 v[40:43], v[128:131], v[152:155], 0
	s_waitcnt lgkmcnt(3)
	v_mfma_f32_16x16x32_bf16 v[28:31], v[120:123], v[160:163], 0
	v_mfma_f32_16x16x32_bf16 v[24:27], v[128:131], v[160:163], 0
	s_waitcnt lgkmcnt(1)
	v_mfma_f32_16x16x32_bf16 v[12:15], v[120:123], v[168:171], 0
	v_mfma_f32_16x16x32_bf16 v[8:11], v[128:131], v[168:171], 0
	v_mfma_f32_16x16x32_bf16 v[60:63], v[124:127], v[140:143], v[60:63]
	v_mfma_f32_16x16x32_bf16 v[56:59], v[132:135], v[140:143], v[56:59]
	v_mfma_f32_16x16x32_bf16 v[44:47], v[124:127], v[156:159], v[44:47]
	v_mfma_f32_16x16x32_bf16 v[40:43], v[132:135], v[156:159], v[40:43]
	v_mfma_f32_16x16x32_bf16 v[28:31], v[124:127], v[164:167], v[28:31]
	v_mfma_f32_16x16x32_bf16 v[24:27], v[132:135], v[164:167], v[24:27]
	s_waitcnt lgkmcnt(0)
	v_mfma_f32_16x16x32_bf16 v[12:15], v[124:127], v[172:175], v[12:15]
	v_mfma_f32_16x16x32_bf16 v[8:11], v[132:135], v[172:175], v[8:11]
	s_barrier
; #define PG8_STAGE(bufoff, gbase, hoff, imm) do { _Pragma("unroll") for (int _i = 0; _i < 2; ++_i) { \
;         asm volatile("s_mov_b32 m0, %0\n\ts_nop 0\n\tglobal_load_lds_dwordx4 %1, %2" \
;             :: "s"(lds0 + (unsigned)((bufoff) + _i * 8192)), "v"(voff0), "s"((const char*)(gbase) + (size_t)(hoff) + (size_t)(_i * 8192)) : "memory"); } } while (0)
; #define PG8_LDA(dst, b, h) do { _Pragma("unroll") for (int m = 0; m < 4; ++m) _Pragma("unroll") for (int k = 0; k < 2; ++k) dst[m][k] = *(const LAS bf16x8*)(lds + PG8_SA(b, h) + aoff + m * 2048 + k * 1024); } while (0)
; #define PG8_LDB(dst, b, h) do { _Pragma("unroll") for (int n = 0; n < 2; ++n) _Pragma("unroll") for (int k = 0; k < 2; ++k) dst[n][k] = *(const LAS bf16x8*)(lds + PG8_SB(b, h) + boff + n * 2048 + k * 1024); } while (0)
; #define PG8_MMA(ai, bj, At, Bt) do { __builtin_amdgcn_s_setprio(1); _Pragma("unroll") for (int m = 0; m < 4; ++m) _Pragma("unroll") for (int n = 0; n < 2; ++n) _Pragma("unroll") for (int k = 0; k < 2; ++k) \
;         acc[ai][bj][m][n] = __builtin_amdgcn_mfma_f32_16x16x32_bf16(Bt[n][k], At[m][k], acc[ai][bj][m][n], 0, 0, 0); __builtin_amdgcn_s_setprio(0); } while (0)
; #define PG8_WAIT_V(n) asm volatile("s_waitcnt vmcnt(" #n ")" ::: "memory")
; #define PG8_WAIT_L(n) asm volatile("s_waitcnt lgkmcnt(" #n ")" ::: "memory")
; template <class Epi>
; __device__ __forceinline__ void gemm_phase(LAS unsigned char* lds, const Gemm g, const StaticOrder& S, const Epi& E) {
;     ...
;             PG8_LDA(At, 0, 1); PG8_STAGE(PG8_SA(0, 0), a2, 0, 0);
;             PG8_BAR; PG8_WAIT_L(0); PG8_MMA(1, 0, At, B0); PG8_BAR; PG8_SCHED;
;             PG8_STAGE(PG8_SB(0, 1), b2, hB, 0);
;             PG8_WAIT_V(6); PG8_BAR; PG8_MMA(1, 1, At, B1); PG8_BAR;
;             PG8_LDB(B0, 1, 0); PG8_SCHED; PG8_LDA(At, 1, 0); PG8_STAGE(PG8_SA(0, 1), a2, hA, 0);
;             PG8_WAIT_L(8); PG8_BAR; PG8_WAIT_L(0); PG8_MMA(0, 0, At, B0); PG8_BAR; PG8_SCHED;
;             PG8_LDB(B1, 1, 1); PG8_STAGE(PG8_SB(1, 0), b2 + KS, 0, 0);
;             PG8_BAR; PG8_WAIT_L(0); PG8_MMA(0, 1, At, B1); PG8_BAR;
;             PG8_LDA(At, 1, 1); PG8_STAGE(PG8_SA(1, 0), a2 + KS, 0, 0);
;             PG8_BAR; PG8_WAIT_L(0); PG8_MMA(1, 0, At, B0); PG8_BAR; PG8_SCHED;
;             PG8_STAGE(PG8_SB(1, 1), b2 + KS, hB, 0);
;             PG8_WAIT_V(6); PG8_BAR; PG8_MMA(1, 1, At, B1); PG8_BAR;
	s_add_u32 s48, s60, 0x160000
	s_addc_u32 s49, s61, 0
	s_mov_b32 m0, s29
	s_nop 0
	global_load_lds_dwordx4 v188, s[48:49]
	s_add_u32 s48, s60, 0x162000
	s_addc_u32 s49, s61, 0
	s_mov_b32 m0, s30
	s_nop 0
	global_load_lds_dwordx4 v188, s[48:49]
	s_waitcnt vmcnt(10)
	s_barrier
	v_mfma_f32_16x16x32_bf16 v[52:55], v[176:179], v[136:139], 0
	v_mfma_f32_16x16x32_bf16 v[48:51], v[184:187], v[136:139], 0
	v_mfma_f32_16x16x32_bf16 v[36:39], v[176:179], v[152:155], 0
	v_mfma_f32_16x16x32_bf16 v[32:35], v[184:187], v[152:155], 0
	v_mfma_f32_16x16x32_bf16 v[20:23], v[176:179], v[160:163], 0
	v_mfma_f32_16x16x32_bf16 v[16:19], v[184:187], v[160:163], 0
	v_mfma_f32_16x16x32_bf16 v[4:7], v[176:179], v[168:171], 0
	v_mfma_f32_16x16x32_bf16 v[0:3], v[184:187], v[168:171], 0
	v_mfma_f32_16x16x32_bf16 v[52:55], v[180:183], v[140:143], v[52:55]
	v_mfma_f32_16x16x32_bf16 v[48:51], v[200:203], v[140:143], v[48:51]
	v_mfma_f32_16x16x32_bf16 v[36:39], v[180:183], v[156:159], v[36:39]
	v_mfma_f32_16x16x32_bf16 v[32:35], v[200:203], v[156:159], v[32:35]
	v_mfma_f32_16x16x32_bf16 v[20:23], v[180:183], v[164:167], v[20:23]
	v_mfma_f32_16x16x32_bf16 v[16:19], v[200:203], v[164:167], v[16:19]
	v_mfma_f32_16x16x32_bf16 v[4:7], v[180:183], v[172:175], v[4:7]
	v_mfma_f32_16x16x32_bf16 v[0:3], v[200:203], v[172:175], v[0:3]
	s_barrier
	ds_read_b128 v[120:123], v236 offset:32768
	ds_read_b128 v[124:127], v236 offset:33792
	ds_read_b128 v[128:131], v236 offset:34816
	ds_read_b128 v[132:135], v236 offset:35840
	ds_read_b128 v[136:139], v237 offset:32768
	ds_read_b128 v[140:143], v237 offset:33792
	ds_read_b128 v[152:155], v237 offset:34816
	ds_read_b128 v[156:159], v237 offset:35840
	ds_read_b128 v[160:163], v237 offset:36864
	ds_read_b128 v[164:167], v237 offset:37888
	ds_read_b128 v[168:171], v237 offset:38912
	ds_read_b128 v[172:175], v237 offset:39936
	s_add_u32 s48, s56, 0x160000
	s_addc_u32 s49, s57, 0
	s_mov_b32 m0, s34
	s_nop 0
	global_load_lds_dwordx4 v188, s[48:49]
	s_add_u32 s48, s56, 0x162000
	s_addc_u32 s49, s57, 0
	s_mov_b32 m0, s37
	s_nop 0
	global_load_lds_dwordx4 v188, s[48:49]
	s_waitcnt lgkmcnt(8)
	s_waitcnt vmcnt(10)
	s_barrier
	s_waitcnt lgkmcnt(7)
	v_mfma_f32_16x16x32_bf16 v[148:151], v[120:123], v[136:139], v[148:151]
	v_mfma_f32_16x16x32_bf16 v[144:147], v[128:131], v[136:139], v[144:147]
	s_waitcnt lgkmcnt(5)
	v_mfma_f32_16x16x32_bf16 v[108:111], v[120:123], v[152:155], v[108:111]
	v_mfma_f32_16x16x32_bf16 v[104:107], v[128:131], v[152:155], v[104:107]
	s_waitcnt lgkmcnt(3)
	v_mfma_f32_16x16x32_bf16 v[92:95], v[120:123], v[160:163], v[92:95]
	v_mfma_f32_16x16x32_bf16 v[88:91], v[128:131], v[160:163], v[88:91]
	s_waitcnt lgkmcnt(1)
	v_mfma_f32_16x16x32_bf16 v[76:79], v[120:123], v[168:171], v[76:79]
	v_mfma_f32_16x16x32_bf16 v[72:75], v[128:131], v[168:171], v[72:75]
	v_mfma_f32_16x16x32_bf16 v[148:151], v[124:127], v[140:143], v[148:151]
	v_mfma_f32_16x16x32_bf16 v[144:147], v[132:135], v[140:143], v[144:147]
	v_mfma_f32_16x16x32_bf16 v[108:111], v[124:127], v[156:159], v[108:111]
	v_mfma_f32_16x16x32_bf16 v[104:107], v[132:135], v[156:159], v[104:107]
	v_mfma_f32_16x16x32_bf16 v[92:95], v[124:127], v[164:167], v[92:95]
	v_mfma_f32_16x16x32_bf16 v[88:91], v[132:135], v[164:167], v[88:91]
	s_waitcnt lgkmcnt(0)
	v_mfma_f32_16x16x32_bf16 v[76:79], v[124:127], v[172:175], v[76:79]
	v_mfma_f32_16x16x32_bf16 v[72:75], v[132:135], v[172:175], v[72:75]
	s_barrier
	ds_read_b128 v[176:179], v236 offset:49152
	ds_read_b128 v[180:183], v236 offset:50176
	ds_read_b128 v[184:187], v236 offset:51200
	ds_read_b128 v[200:203], v236 offset:52224
	s_add_u32 s48, s60, 0x4000
	s_addc_u32 s49, s61, 0
	s_mov_b32 m0, s41
	s_nop 0
	global_load_lds_dwordx4 v188, s[48:49]
	s_add_u32 s48, s60, 0x6000
	s_addc_u32 s49, s61, 0
	s_mov_b32 m0, s42
	s_nop 0
	global_load_lds_dwordx4 v188, s[48:49]
	s_waitcnt vmcnt(10)
	s_barrier
	s_waitcnt lgkmcnt(3)
	v_mfma_f32_16x16x32_bf16 v[116:119], v[176:179], v[136:139], v[116:119]
	s_waitcnt lgkmcnt(1)
	v_mfma_f32_16x16x32_bf16 v[112:115], v[184:187], v[136:139], v[112:115]
	v_mfma_f32_16x16x32_bf16 v[100:103], v[176:179], v[152:155], v[100:103]
	v_mfma_f32_16x16x32_bf16 v[96:99], v[184:187], v[152:155], v[96:99]
	v_mfma_f32_16x16x32_bf16 v[84:87], v[176:179], v[160:163], v[84:87]
	v_mfma_f32_16x16x32_bf16 v[80:83], v[184:187], v[160:163], v[80:83]
	v_mfma_f32_16x16x32_bf16 v[68:71], v[176:179], v[168:171], v[68:71]
	v_mfma_f32_16x16x32_bf16 v[64:67], v[184:187], v[168:171], v[64:67]
	v_mfma_f32_16x16x32_bf16 v[116:119], v[180:183], v[140:143], v[116:119]
	s_waitcnt lgkmcnt(0)
	v_mfma_f32_16x16x32_bf16 v[112:115], v[200:203], v[140:143], v[112:115]
	v_mfma_f32_16x16x32_bf16 v[100:103], v[180:183], v[156:159], v[100:103]
	v_mfma_f32_16x16x32_bf16 v[96:99], v[200:203], v[156:159], v[96:99]
	v_mfma_f32_16x16x32_bf16 v[84:87], v[180:183], v[164:167], v[84:87]
	v_mfma_f32_16x16x32_bf16 v[80:83], v[200:203], v[164:167], v[80:83]
	v_mfma_f32_16x16x32_bf16 v[68:71], v[180:183], v[172:175], v[68:71]
	v_mfma_f32_16x16x32_bf16 v[64:67], v[200:203], v[172:175], v[64:67]
	s_barrier
	ds_read_b128 v[136:139], v237 offset:49152
	ds_read_b128 v[140:143], v237 offset:50176
	ds_read_b128 v[152:155], v237 offset:51200
	ds_read_b128 v[156:159], v237 offset:52224
	ds_read_b128 v[160:163], v237 offset:53248
	ds_read_b128 v[164:167], v237 offset:54272
	ds_read_b128 v[168:171], v237 offset:55296
	ds_read_b128 v[172:175], v237 offset:56320
	s_add_u32 s48, s56, 0x4000
	s_addc_u32 s49, s57, 0
	s_mov_b32 m0, s43
	s_nop 0
	global_load_lds_dwordx4 v188, s[48:49]
	s_add_u32 s48, s56, 0x6000
	s_addc_u32 s49, s57, 0
	s_mov_b32 m0, s62
	s_nop 0
	global_load_lds_dwordx4 v188, s[48:49]
	s_barrier
; #define PG8_STAGE(bufoff, gbase, hoff, imm) do { _Pragma("unroll") for (int _i = 0; _i < 2; ++_i) { \
;         asm volatile("s_mov_b32 m0, %0\n\ts_nop 0\n\tglobal_load_lds_dwordx4 %1, %2" \
;             :: "s"(lds0 + (unsigned)((bufoff) + _i * 8192)), "v"(voff0), "s"((const char*)(gbase) + (size_t)(hoff) + (size_t)(_i * 8192)) : "memory"); } } while (0)
; #define PG8_LDA(dst, b, h) do { _Pragma("unroll") for (int m = 0; m < 4; ++m) _Pragma("unroll") for (int k = 0; k < 2; ++k) dst[m][k] = *(const LAS bf16x8*)(lds + PG8_SA(b, h) + aoff + m * 2048 + k * 1024); } while (0)
; #define PG8_LDB(dst, b, h) do { _Pragma("unroll") for (int n = 0; n < 2; ++n) _Pragma("unroll") for (int k = 0; k < 2; ++k) dst[n][k] = *(const LAS bf16x8*)(lds + PG8_SB(b, h) + boff + n * 2048 + k * 1024); } while (0)
; #define PG8_WAIT_V(n) asm volatile("s_waitcnt vmcnt(" #n ")" ::: "memory")
; #define PG8_WAIT_L(n) asm volatile("s_waitcnt lgkmcnt(" #n ")" ::: "memory")
; #define PG8_BAR __builtin_amdgcn_s_barrier()
; template <class Epi>
; __device__ __forceinline__ void gemm_phase(LAS unsigned char* lds, const Gemm g, const StaticOrder& S, const Epi& E) {
;     ...
;             PG8_LDB(B0, 0, 0); PG8_SCHED; PG8_LDA(At, 0, 0); PG8_STAGE(PG8_SA(1, 1), aT + KS, hA, 0);
;             PG8_WAIT_L(8); PG8_BAR; PG8_WAIT_L(0); PG8_MMA(0, 0, At, B0); PG8_BAR; PG8_SCHED;
;             PG8_LDB(B1, 0, 1); PG8_STAGE(PG8_SB(0, 0), b2, 0, 0);
;             PG8_BAR; PG8_WAIT_L(0); PG8_MMA(0, 1, At, B1); PG8_BAR;
;             PG8_LDA(At, 0, 1); PG8_STAGE(PG8_SA(0, 0), a2, 0, 0);
;             PG8_BAR; PG8_WAIT_L(0); PG8_MMA(1, 0, At, B0); PG8_BAR; PG8_SCHED;
;             PG8_STAGE(PG8_SB(0, 1), b2, hB, 0);
;             PG8_WAIT_V(6); PG8_BAR; PG8_MMA(1, 1, At, B1); PG8_BAR;
;             PG8_LDB(B0, 1, 0); PG8_SCHED; PG8_LDA(At, 1, 0); PG8_STAGE(PG8_SA(0, 1), a2, hA, 0);
;             PG8_WAIT_L(8); PG8_BAR; PG8_WAIT_L(0); PG8_MMA(0, 0, At, B0); PG8_BAR; PG8_SCHED;
;             PG8_LDB(B1, 1, 1); PG8_STAGE(PG8_SB(1, 0), b2 + KS, 0, 0);
;             PG8_BAR; PG8_WAIT_L(0); PG8_MMA(0, 1, At, B1); PG8_BAR;
;             PG8_LDA(At, 1, 1); PG8_STAGE(PG8_SA(1, 0), a2 + KS, 0, 0);
;             PG8_BAR; PG8_WAIT_L(0); PG8_MMA(1, 0, At, B0); PG8_BAR; PG8_SCHED;
;             PG8_STAGE(PG8_SB(1, 1), b2 + KS, hB, 0);
;             PG8_WAIT_V(6); PG8_BAR; PG8_MMA(1, 1, At, B1); PG8_BAR;
	s_waitcnt lgkmcnt(7)
	v_mfma_f32_16x16x32_bf16 v[60:63], v[120:123], v[136:139], v[60:63]
	v_mfma_f32_16x16x32_bf16 v[56:59], v[128:131], v[136:139], v[56:59]
	s_waitcnt lgkmcnt(5)
	v_mfma_f32_16x16x32_bf16 v[44:47], v[120:123], v[152:155], v[44:47]
	v_mfma_f32_16x16x32_bf16 v[40:43], v[128:131], v[152:155], v[40:43]
	s_waitcnt lgkmcnt(3)
	v_mfma_f32_16x16x32_bf16 v[28:31], v[120:123], v[160:163], v[28:31]
	v_mfma_f32_16x16x32_bf16 v[24:27], v[128:131], v[160:163], v[24:27]
	s_waitcnt lgkmcnt(1)
	v_mfma_f32_16x16x32_bf16 v[12:15], v[120:123], v[168:171], v[12:15]
	v_mfma_f32_16x16x32_bf16 v[8:11], v[128:131], v[168:171], v[8:11]
	v_mfma_f32_16x16x32_bf16 v[60:63], v[124:127], v[140:143], v[60:63]
	v_mfma_f32_16x16x32_bf16 v[56:59], v[132:135], v[140:143], v[56:59]
	v_mfma_f32_16x16x32_bf16 v[44:47], v[124:127], v[156:159], v[44:47]
	v_mfma_f32_16x16x32_bf16 v[40:43], v[132:135], v[156:159], v[40:43]
	v_mfma_f32_16x16x32_bf16 v[28:31], v[124:127], v[164:167], v[28:31]
	v_mfma_f32_16x16x32_bf16 v[24:27], v[132:135], v[164:167], v[24:27]
	s_waitcnt lgkmcnt(0)
	v_mfma_f32_16x16x32_bf16 v[12:15], v[124:127], v[172:175], v[12:15]
	v_mfma_f32_16x16x32_bf16 v[8:11], v[132:135], v[172:175], v[8:11]
	s_barrier
	s_add_u32 s48, s60, 0x164000
	s_addc_u32 s49, s61, 0
	s_mov_b32 m0, s63
	s_nop 0
	global_load_lds_dwordx4 v188, s[48:49]
	s_add_u32 s48, s60, 0x166000
	s_addc_u32 s49, s61, 0
	s_mov_b32 m0, s64
	s_nop 0
	global_load_lds_dwordx4 v188, s[48:49]
	s_waitcnt vmcnt(10)
	s_barrier
	v_mfma_f32_16x16x32_bf16 v[52:55], v[176:179], v[136:139], v[52:55]
	v_mfma_f32_16x16x32_bf16 v[48:51], v[184:187], v[136:139], v[48:51]
	v_mfma_f32_16x16x32_bf16 v[36:39], v[176:179], v[152:155], v[36:39]
	v_mfma_f32_16x16x32_bf16 v[32:35], v[184:187], v[152:155], v[32:35]
	v_mfma_f32_16x16x32_bf16 v[20:23], v[176:179], v[160:163], v[20:23]
	v_mfma_f32_16x16x32_bf16 v[16:19], v[184:187], v[160:163], v[16:19]
	v_mfma_f32_16x16x32_bf16 v[4:7], v[176:179], v[168:171], v[4:7]
	v_mfma_f32_16x16x32_bf16 v[0:3], v[184:187], v[168:171], v[0:3]
	v_mfma_f32_16x16x32_bf16 v[52:55], v[180:183], v[140:143], v[52:55]
	v_mfma_f32_16x16x32_bf16 v[48:51], v[200:203], v[140:143], v[48:51]
	v_mfma_f32_16x16x32_bf16 v[36:39], v[180:183], v[156:159], v[36:39]
	v_mfma_f32_16x16x32_bf16 v[32:35], v[200:203], v[156:159], v[32:35]
	v_mfma_f32_16x16x32_bf16 v[20:23], v[180:183], v[164:167], v[20:23]
	v_mfma_f32_16x16x32_bf16 v[16:19], v[200:203], v[164:167], v[16:19]
	v_mfma_f32_16x16x32_bf16 v[4:7], v[180:183], v[172:175], v[4:7]
	v_mfma_f32_16x16x32_bf16 v[0:3], v[200:203], v[172:175], v[0:3]
	s_add_i32 s69, s69, 2
	s_add_u32 s0, s0, 0x8000
	s_addc_u32 s1, s1, 0
	s_cmpk_gt_u32 s69, 0x55
	s_mov_b64 s[56:57], s[58:59]
	s_barrier
.LBB0_860:
	s_add_u32 s58, s56, 0x8000
	s_addc_u32 s59, s57, 0
	ds_read_b128 v[120:123], v236
	ds_read_b128 v[124:127], v236 offset:1024
	ds_read_b128 v[128:131], v236 offset:2048
	ds_read_b128 v[132:135], v236 offset:3072
	s_add_u32 s48, s56, 0x164000
	s_addc_u32 s49, s57, 0
	s_add_u32 s60, s56, 0x166000
	s_addc_u32 s61, s57, 0
	s_cmpk_eq_i32 s69, 0x54
	s_cselect_b32 s57, s7, s59
	s_cselect_b32 s56, s6, s58
	ds_read_b128 v[136:139], v237
	ds_read_b128 v[140:143], v237 offset:1024
	ds_read_b128 v[152:155], v237 offset:2048
	ds_read_b128 v[156:159], v237 offset:3072
	ds_read_b128 v[160:163], v237 offset:4096
	ds_read_b128 v[164:167], v237 offset:5120
	ds_read_b128 v[168:171], v237 offset:6144
	ds_read_b128 v[172:175], v237 offset:7168
	s_mov_b32 m0, s65
	s_nop 0
	global_load_lds_dwordx4 v188, s[48:49]
	s_mov_b32 m0, s66
	s_nop 0
	global_load_lds_dwordx4 v188, s[60:61]
	s_waitcnt lgkmcnt(8)
	s_waitcnt vmcnt(10)
	s_barrier
	s_waitcnt lgkmcnt(7)
	v_mfma_f32_16x16x32_bf16 v[148:151], v[120:123], v[136:139], v[148:151]
	v_mfma_f32_16x16x32_bf16 v[144:147], v[128:131], v[136:139], v[144:147]
	s_waitcnt lgkmcnt(5)
	v_mfma_f32_16x16x32_bf16 v[108:111], v[120:123], v[152:155], v[108:111]
	v_mfma_f32_16x16x32_bf16 v[104:107], v[128:131], v[152:155], v[104:107]
	s_waitcnt lgkmcnt(3)
	v_mfma_f32_16x16x32_bf16 v[92:95], v[120:123], v[160:163], v[92:95]
	v_mfma_f32_16x16x32_bf16 v[88:91], v[128:131], v[160:163], v[88:91]
	s_waitcnt lgkmcnt(1)
	v_mfma_f32_16x16x32_bf16 v[76:79], v[120:123], v[168:171], v[76:79]
	v_mfma_f32_16x16x32_bf16 v[72:75], v[128:131], v[168:171], v[72:75]
	v_mfma_f32_16x16x32_bf16 v[148:151], v[124:127], v[140:143], v[148:151]
	v_mfma_f32_16x16x32_bf16 v[144:147], v[132:135], v[140:143], v[144:147]
	v_mfma_f32_16x16x32_bf16 v[108:111], v[124:127], v[156:159], v[108:111]
	v_mfma_f32_16x16x32_bf16 v[104:107], v[132:135], v[156:159], v[104:107]
	v_mfma_f32_16x16x32_bf16 v[92:95], v[124:127], v[164:167], v[92:95]
	v_mfma_f32_16x16x32_bf16 v[88:91], v[132:135], v[164:167], v[88:91]
	s_waitcnt lgkmcnt(0)
	v_mfma_f32_16x16x32_bf16 v[76:79], v[124:127], v[172:175], v[76:79]
	v_mfma_f32_16x16x32_bf16 v[72:75], v[132:135], v[172:175], v[72:75]
	s_barrier
	ds_read_b128 v[176:179], v236 offset:16384
	ds_read_b128 v[180:183], v236 offset:17408
	ds_read_b128 v[184:187], v236 offset:18432
	ds_read_b128 v[200:203], v236 offset:19456
	s_cselect_b32 s60, s8, s0
	s_cselect_b32 s61, s9, s1
	s_mov_b32 m0, s26
	s_nop 0
	global_load_lds_dwordx4 v188, s[60:61]
	s_add_u32 s48, s60, 0x2000
	s_addc_u32 s49, s61, 0
	s_mov_b32 m0, s27
	s_nop 0
	global_load_lds_dwordx4 v188, s[48:49]
	s_waitcnt vmcnt(10)
	s_barrier
; #define PG8_STAGE(bufoff, gbase, hoff, imm) do { _Pragma("unroll") for (int _i = 0; _i < 2; ++_i) { \
;         asm volatile("s_mov_b32 m0, %0\n\ts_nop 0\n\tglobal_load_lds_dwordx4 %1, %2" \
;             :: "s"(lds0 + (unsigned)((bufoff) + _i * 8192)), "v"(voff0), "s"((const char*)(gbase) + (size_t)(hoff) + (size_t)(_i * 8192)) : "memory"); } } while (0)
; #define PG8_LDA(dst, b, h) do { _Pragma("unroll") for (int m = 0; m < 4; ++m) _Pragma("unroll") for (int k = 0; k < 2; ++k) dst[m][k] = *(const LAS bf16x8*)(lds + PG8_SA(b, h) + aoff + m * 2048 + k * 1024); } while (0)
; #define PG8_LDB(dst, b, h) do { _Pragma("unroll") for (int n = 0; n < 2; ++n) _Pragma("unroll") for (int k = 0; k < 2; ++k) dst[n][k] = *(const LAS bf16x8*)(lds + PG8_SB(b, h) + boff + n * 2048 + k * 1024); } while (0)
; #define PG8_WAIT_V(n) asm volatile("s_waitcnt vmcnt(" #n ")" ::: "memory")
; #define PG8_WAIT_L(n) asm volatile("s_waitcnt lgkmcnt(" #n ")" ::: "memory")
; #define PG8_BAR __builtin_amdgcn_s_barrier()
; template <class Epi>
; __device__ __forceinline__ void gemm_phase(LAS unsigned char* lds, const Gemm g, const StaticOrder& S, const Epi& E) {
;     ...
;             PG8_LDB(B0, 0, 0); PG8_SCHED; PG8_LDA(At, 0, 0); PG8_STAGE(PG8_SA(1, 1), aT + KS, hA, 0);
;             PG8_WAIT_L(8); PG8_BAR; PG8_WAIT_L(0); PG8_MMA(0, 0, At, B0); PG8_BAR; PG8_SCHED;
;             PG8_LDB(B1, 0, 1); PG8_STAGE(PG8_SB(0, 0), b2, 0, 0);
;             PG8_BAR; PG8_WAIT_L(0); PG8_MMA(0, 1, At, B1); PG8_BAR;
;             PG8_LDA(At, 0, 1); PG8_STAGE(PG8_SA(0, 0), a2, 0, 0);
;             PG8_BAR; PG8_WAIT_L(0); PG8_MMA(1, 0, At, B0); PG8_BAR; PG8_SCHED;
;             PG8_STAGE(PG8_SB(0, 1), b2, hB, 0);
;             PG8_WAIT_V(6); PG8_BAR; PG8_MMA(1, 1, At, B1); PG8_BAR;
;             PG8_LDB(B0, 1, 0); PG8_SCHED; PG8_LDA(At, 1, 0); PG8_STAGE(PG8_SA(0, 1), a2, hA, 0);
;             PG8_WAIT_L(8); PG8_BAR; PG8_WAIT_L(0); PG8_MMA(0, 0, At, B0); PG8_BAR; PG8_SCHED;
;             PG8_LDB(B1, 1, 1); PG8_STAGE(PG8_SB(1, 0), b2 + KS, 0, 0);
;             PG8_BAR; PG8_WAIT_L(0); PG8_MMA(0, 1, At, B1); PG8_BAR;
;             PG8_LDA(At, 1, 1); PG8_STAGE(PG8_SA(1, 0), a2 + KS, 0, 0);
;             PG8_BAR; PG8_WAIT_L(0); PG8_MMA(1, 0, At, B0); PG8_BAR; PG8_SCHED;
;             PG8_STAGE(PG8_SB(1, 1), b2 + KS, hB, 0);
;             PG8_WAIT_V(6); PG8_BAR; PG8_MMA(1, 1, At, B1); PG8_BAR;
	s_waitcnt lgkmcnt(3)
	v_mfma_f32_16x16x32_bf16 v[116:119], v[176:179], v[136:139], v[116:119]
	s_waitcnt lgkmcnt(1)
	v_mfma_f32_16x16x32_bf16 v[112:115], v[184:187], v[136:139], v[112:115]
	v_mfma_f32_16x16x32_bf16 v[100:103], v[176:179], v[152:155], v[100:103]
	v_mfma_f32_16x16x32_bf16 v[96:99], v[184:187], v[152:155], v[96:99]
	v_mfma_f32_16x16x32_bf16 v[84:87], v[176:179], v[160:163], v[84:87]
	v_mfma_f32_16x16x32_bf16 v[80:83], v[184:187], v[160:163], v[80:83]
	v_mfma_f32_16x16x32_bf16 v[68:71], v[176:179], v[168:171], v[68:71]
	v_mfma_f32_16x16x32_bf16 v[64:67], v[184:187], v[168:171], v[64:67]
	v_mfma_f32_16x16x32_bf16 v[116:119], v[180:183], v[140:143], v[116:119]
	s_waitcnt lgkmcnt(0)
	v_mfma_f32_16x16x32_bf16 v[112:115], v[200:203], v[140:143], v[112:115]
	v_mfma_f32_16x16x32_bf16 v[100:103], v[180:183], v[156:159], v[100:103]
	v_mfma_f32_16x16x32_bf16 v[96:99], v[200:203], v[156:159], v[96:99]
	v_mfma_f32_16x16x32_bf16 v[84:87], v[180:183], v[164:167], v[84:87]
	v_mfma_f32_16x16x32_bf16 v[80:83], v[200:203], v[164:167], v[80:83]
	v_mfma_f32_16x16x32_bf16 v[68:71], v[180:183], v[172:175], v[68:71]
	v_mfma_f32_16x16x32_bf16 v[64:67], v[200:203], v[172:175], v[64:67]
	s_barrier
	ds_read_b128 v[136:139], v237 offset:16384
	ds_read_b128 v[140:143], v237 offset:17408
	ds_read_b128 v[152:155], v237 offset:18432
	ds_read_b128 v[156:159], v237 offset:19456
	ds_read_b128 v[160:163], v237 offset:20480
	ds_read_b128 v[164:167], v237 offset:21504
	ds_read_b128 v[168:171], v237 offset:22528
	ds_read_b128 v[172:175], v237 offset:23552
	s_mov_b32 m0, s25
	s_nop 0
	global_load_lds_dwordx4 v188, s[56:57]
	s_add_u32 s48, s56, 0x2000
	s_addc_u32 s49, s57, 0
	s_mov_b32 m0, s28
	s_nop 0
	global_load_lds_dwordx4 v188, s[48:49]
	s_barrier
	s_waitcnt lgkmcnt(7)
	v_mfma_f32_16x16x32_bf16 v[60:63], v[120:123], v[136:139], v[60:63]
	v_mfma_f32_16x16x32_bf16 v[56:59], v[128:131], v[136:139], v[56:59]
	s_waitcnt lgkmcnt(5)
	v_mfma_f32_16x16x32_bf16 v[44:47], v[120:123], v[152:155], v[44:47]
	v_mfma_f32_16x16x32_bf16 v[40:43], v[128:131], v[152:155], v[40:43]
	s_waitcnt lgkmcnt(3)
	v_mfma_f32_16x16x32_bf16 v[28:31], v[120:123], v[160:163], v[28:31]
	v_mfma_f32_16x16x32_bf16 v[24:27], v[128:131], v[160:163], v[24:27]
	s_waitcnt lgkmcnt(1)
	v_mfma_f32_16x16x32_bf16 v[12:15], v[120:123], v[168:171], v[12:15]
	v_mfma_f32_16x16x32_bf16 v[8:11], v[128:131], v[168:171], v[8:11]
	v_mfma_f32_16x16x32_bf16 v[60:63], v[124:127], v[140:143], v[60:63]
	v_mfma_f32_16x16x32_bf16 v[56:59], v[132:135], v[140:143], v[56:59]
	v_mfma_f32_16x16x32_bf16 v[44:47], v[124:127], v[156:159], v[44:47]
	v_mfma_f32_16x16x32_bf16 v[40:43], v[132:135], v[156:159], v[40:43]
	v_mfma_f32_16x16x32_bf16 v[28:31], v[124:127], v[164:167], v[28:31]
	v_mfma_f32_16x16x32_bf16 v[24:27], v[132:135], v[164:167], v[24:27]
	s_waitcnt lgkmcnt(0)
	v_mfma_f32_16x16x32_bf16 v[12:15], v[124:127], v[172:175], v[12:15]
	v_mfma_f32_16x16x32_bf16 v[8:11], v[132:135], v[172:175], v[8:11]
	s_barrier
	s_add_u32 s48, s60, 0x160000
	s_addc_u32 s49, s61, 0
	s_mov_b32 m0, s29
	s_nop 0
	global_load_lds_dwordx4 v188, s[48:49]
	s_add_u32 s48, s60, 0x162000
	s_addc_u32 s49, s61, 0
	s_mov_b32 m0, s30
	s_nop 0
	global_load_lds_dwordx4 v188, s[48:49]
	s_waitcnt vmcnt(10)
	s_barrier
	v_mfma_f32_16x16x32_bf16 v[52:55], v[176:179], v[136:139], v[52:55]
	v_mfma_f32_16x16x32_bf16 v[48:51], v[184:187], v[136:139], v[48:51]
	v_mfma_f32_16x16x32_bf16 v[36:39], v[176:179], v[152:155], v[36:39]
	v_mfma_f32_16x16x32_bf16 v[32:35], v[184:187], v[152:155], v[32:35]
	v_mfma_f32_16x16x32_bf16 v[20:23], v[176:179], v[160:163], v[20:23]
	v_mfma_f32_16x16x32_bf16 v[16:19], v[184:187], v[160:163], v[16:19]
	v_mfma_f32_16x16x32_bf16 v[4:7], v[176:179], v[168:171], v[4:7]
	v_mfma_f32_16x16x32_bf16 v[0:3], v[184:187], v[168:171], v[0:3]
	v_mfma_f32_16x16x32_bf16 v[52:55], v[180:183], v[140:143], v[52:55]
	v_mfma_f32_16x16x32_bf16 v[48:51], v[200:203], v[140:143], v[48:51]
	v_mfma_f32_16x16x32_bf16 v[36:39], v[180:183], v[156:159], v[36:39]
	v_mfma_f32_16x16x32_bf16 v[32:35], v[200:203], v[156:159], v[32:35]
	v_mfma_f32_16x16x32_bf16 v[20:23], v[180:183], v[164:167], v[20:23]
	v_mfma_f32_16x16x32_bf16 v[16:19], v[200:203], v[164:167], v[16:19]
	v_mfma_f32_16x16x32_bf16 v[4:7], v[180:183], v[172:175], v[4:7]
	v_mfma_f32_16x16x32_bf16 v[0:3], v[200:203], v[172:175], v[0:3]
	s_barrier
	ds_read_b128 v[120:123], v236 offset:32768
	ds_read_b128 v[124:127], v236 offset:33792
	ds_read_b128 v[128:131], v236 offset:34816
	ds_read_b128 v[132:135], v236 offset:35840
	ds_read_b128 v[136:139], v237 offset:32768
	ds_read_b128 v[140:143], v237 offset:33792
	ds_read_b128 v[152:155], v237 offset:34816
	ds_read_b128 v[156:159], v237 offset:35840
	ds_read_b128 v[160:163], v237 offset:36864
	ds_read_b128 v[164:167], v237 offset:37888
	ds_read_b128 v[168:171], v237 offset:38912
	ds_read_b128 v[172:175], v237 offset:39936
	s_add_u32 s48, s56, 0x160000
	s_addc_u32 s49, s57, 0
	s_mov_b32 m0, s34
	s_nop 0
	global_load_lds_dwordx4 v188, s[48:49]
	s_add_u32 s48, s56, 0x162000
	s_addc_u32 s49, s57, 0
	s_mov_b32 m0, s37
	s_nop 0
	global_load_lds_dwordx4 v188, s[48:49]
	s_waitcnt lgkmcnt(8)
	s_waitcnt vmcnt(10)
	s_barrier
; #define PG8_STAGE(bufoff, gbase, hoff, imm) do { _Pragma("unroll") for (int _i = 0; _i < 2; ++_i) { \
;         asm volatile("s_mov_b32 m0, %0\n\ts_nop 0\n\tglobal_load_lds_dwordx4 %1, %2" \
;             :: "s"(lds0 + (unsigned)((bufoff) + _i * 8192)), "v"(voff0), "s"((const char*)(gbase) + (size_t)(hoff) + (size_t)(_i * 8192)) : "memory"); } } while (0)
; #define PG8_LDA(dst, b, h) do { _Pragma("unroll") for (int m = 0; m < 4; ++m) _Pragma("unroll") for (int k = 0; k < 2; ++k) dst[m][k] = *(const LAS bf16x8*)(lds + PG8_SA(b, h) + aoff + m * 2048 + k * 1024); } while (0)
; #define PG8_LDB(dst, b, h) do { _Pragma("unroll") for (int n = 0; n < 2; ++n) _Pragma("unroll") for (int k = 0; k < 2; ++k) dst[n][k] = *(const LAS bf16x8*)(lds + PG8_SB(b, h) + boff + n * 2048 + k * 1024); } while (0)
; #define PG8_WAIT_V(n) asm volatile("s_waitcnt vmcnt(" #n ")" ::: "memory")
; #define PG8_WAIT_L(n) asm volatile("s_waitcnt lgkmcnt(" #n ")" ::: "memory")
; #define PG8_BAR __builtin_amdgcn_s_barrier()
; template <class Epi>
; __device__ __forceinline__ void gemm_phase(LAS unsigned char* lds, const Gemm g, const StaticOrder& S, const Epi& E) {
;     ...
;             PG8_LDB(B0, 0, 0); PG8_SCHED; PG8_LDA(At, 0, 0); PG8_STAGE(PG8_SA(1, 1), aT + KS, hA, 0);
;             PG8_WAIT_L(8); PG8_BAR; PG8_WAIT_L(0); PG8_MMA(0, 0, At, B0); PG8_BAR; PG8_SCHED;
;             PG8_LDB(B1, 0, 1); PG8_STAGE(PG8_SB(0, 0), b2, 0, 0);
;             PG8_BAR; PG8_WAIT_L(0); PG8_MMA(0, 1, At, B1); PG8_BAR;
;             PG8_LDA(At, 0, 1); PG8_STAGE(PG8_SA(0, 0), a2, 0, 0);
;             PG8_BAR; PG8_WAIT_L(0); PG8_MMA(1, 0, At, B0); PG8_BAR; PG8_SCHED;
;             PG8_STAGE(PG8_SB(0, 1), b2, hB, 0);
;             PG8_WAIT_V(6); PG8_BAR; PG8_MMA(1, 1, At, B1); PG8_BAR;
;             PG8_LDB(B0, 1, 0); PG8_SCHED; PG8_LDA(At, 1, 0); PG8_STAGE(PG8_SA(0, 1), a2, hA, 0);
;             PG8_WAIT_L(8); PG8_BAR; PG8_WAIT_L(0); PG8_MMA(0, 0, At, B0); PG8_BAR; PG8_SCHED;
;             PG8_LDB(B1, 1, 1); PG8_STAGE(PG8_SB(1, 0), b2 + KS, 0, 0);
;             PG8_BAR; PG8_WAIT_L(0); PG8_MMA(0, 1, At, B1); PG8_BAR;
;             PG8_LDA(At, 1, 1); PG8_STAGE(PG8_SA(1, 0), a2 + KS, 0, 0);
;             PG8_BAR; PG8_WAIT_L(0); PG8_MMA(1, 0, At, B0); PG8_BAR; PG8_SCHED;
;             PG8_STAGE(PG8_SB(1, 1), b2 + KS, hB, 0);
;             PG8_WAIT_V(6); PG8_BAR; PG8_MMA(1, 1, At, B1); PG8_BAR;
	s_waitcnt lgkmcnt(7)
	v_mfma_f32_16x16x32_bf16 v[148:151], v[120:123], v[136:139], v[148:151]
	v_mfma_f32_16x16x32_bf16 v[144:147], v[128:131], v[136:139], v[144:147]
	s_waitcnt lgkmcnt(5)
	v_mfma_f32_16x16x32_bf16 v[108:111], v[120:123], v[152:155], v[108:111]
	v_mfma_f32_16x16x32_bf16 v[104:107], v[128:131], v[152:155], v[104:107]
	s_waitcnt lgkmcnt(3)
	v_mfma_f32_16x16x32_bf16 v[92:95], v[120:123], v[160:163], v[92:95]
	v_mfma_f32_16x16x32_bf16 v[88:91], v[128:131], v[160:163], v[88:91]
	s_waitcnt lgkmcnt(1)
	v_mfma_f32_16x16x32_bf16 v[76:79], v[120:123], v[168:171], v[76:79]
	v_mfma_f32_16x16x32_bf16 v[72:75], v[128:131], v[168:171], v[72:75]
	v_mfma_f32_16x16x32_bf16 v[148:151], v[124:127], v[140:143], v[148:151]
	v_mfma_f32_16x16x32_bf16 v[144:147], v[132:135], v[140:143], v[144:147]
	v_mfma_f32_16x16x32_bf16 v[108:111], v[124:127], v[156:159], v[108:111]
	v_mfma_f32_16x16x32_bf16 v[104:107], v[132:135], v[156:159], v[104:107]
	v_mfma_f32_16x16x32_bf16 v[92:95], v[124:127], v[164:167], v[92:95]
	v_mfma_f32_16x16x32_bf16 v[88:91], v[132:135], v[164:167], v[88:91]
	s_waitcnt lgkmcnt(0)
	v_mfma_f32_16x16x32_bf16 v[76:79], v[124:127], v[172:175], v[76:79]
	v_mfma_f32_16x16x32_bf16 v[72:75], v[132:135], v[172:175], v[72:75]
	s_barrier
	ds_read_b128 v[176:179], v236 offset:49152
	ds_read_b128 v[180:183], v236 offset:50176
	ds_read_b128 v[184:187], v236 offset:51200
	ds_read_b128 v[200:203], v236 offset:52224
	s_add_u32 s48, s60, 0x4000
	s_addc_u32 s49, s61, 0
	s_mov_b32 m0, s41
	s_nop 0
	global_load_lds_dwordx4 v188, s[48:49]
	s_add_u32 s48, s60, 0x6000
	s_addc_u32 s49, s61, 0
	s_mov_b32 m0, s42
	s_nop 0
	global_load_lds_dwordx4 v188, s[48:49]
	s_waitcnt vmcnt(10)
	s_barrier
	s_waitcnt lgkmcnt(3)
	v_mfma_f32_16x16x32_bf16 v[116:119], v[176:179], v[136:139], v[116:119]
	s_waitcnt lgkmcnt(1)
	v_mfma_f32_16x16x32_bf16 v[112:115], v[184:187], v[136:139], v[112:115]
	v_mfma_f32_16x16x32_bf16 v[100:103], v[176:179], v[152:155], v[100:103]
	v_mfma_f32_16x16x32_bf16 v[96:99], v[184:187], v[152:155], v[96:99]
	v_mfma_f32_16x16x32_bf16 v[84:87], v[176:179], v[160:163], v[84:87]
	v_mfma_f32_16x16x32_bf16 v[80:83], v[184:187], v[160:163], v[80:83]
	v_mfma_f32_16x16x32_bf16 v[68:71], v[176:179], v[168:171], v[68:71]
	v_mfma_f32_16x16x32_bf16 v[64:67], v[184:187], v[168:171], v[64:67]
	v_mfma_f32_16x16x32_bf16 v[116:119], v[180:183], v[140:143], v[116:119]
	s_waitcnt lgkmcnt(0)
	v_mfma_f32_16x16x32_bf16 v[112:115], v[200:203], v[140:143], v[112:115]
	v_mfma_f32_16x16x32_bf16 v[100:103], v[180:183], v[156:159], v[100:103]
	v_mfma_f32_16x16x32_bf16 v[96:99], v[200:203], v[156:159], v[96:99]
	v_mfma_f32_16x16x32_bf16 v[84:87], v[180:183], v[164:167], v[84:87]
	v_mfma_f32_16x16x32_bf16 v[80:83], v[200:203], v[164:167], v[80:83]
	v_mfma_f32_16x16x32_bf16 v[68:71], v[180:183], v[172:175], v[68:71]
	v_mfma_f32_16x16x32_bf16 v[64:67], v[200:203], v[172:175], v[64:67]
	s_barrier
	ds_read_b128 v[136:139], v237 offset:49152
	ds_read_b128 v[140:143], v237 offset:50176
	ds_read_b128 v[152:155], v237 offset:51200
	ds_read_b128 v[156:159], v237 offset:52224
	ds_read_b128 v[160:163], v237 offset:53248
	ds_read_b128 v[164:167], v237 offset:54272
	ds_read_b128 v[168:171], v237 offset:55296
	ds_read_b128 v[172:175], v237 offset:56320
	s_add_u32 s48, s56, 0x4000
	s_addc_u32 s49, s57, 0
	s_mov_b32 m0, s43
	s_nop 0
	global_load_lds_dwordx4 v188, s[48:49]
	s_add_u32 s48, s56, 0x6000
	s_addc_u32 s49, s57, 0
	s_mov_b32 m0, s62
	s_nop 0
	global_load_lds_dwordx4 v188, s[48:49]
	s_barrier
	s_waitcnt lgkmcnt(7)
	v_mfma_f32_16x16x32_bf16 v[60:63], v[120:123], v[136:139], v[60:63]
	v_mfma_f32_16x16x32_bf16 v[56:59], v[128:131], v[136:139], v[56:59]
	s_waitcnt lgkmcnt(5)
	v_mfma_f32_16x16x32_bf16 v[44:47], v[120:123], v[152:155], v[44:47]
	v_mfma_f32_16x16x32_bf16 v[40:43], v[128:131], v[152:155], v[40:43]
	s_waitcnt lgkmcnt(3)
	v_mfma_f32_16x16x32_bf16 v[28:31], v[120:123], v[160:163], v[28:31]
	v_mfma_f32_16x16x32_bf16 v[24:27], v[128:131], v[160:163], v[24:27]
	s_waitcnt lgkmcnt(1)
	v_mfma_f32_16x16x32_bf16 v[12:15], v[120:123], v[168:171], v[12:15]
	v_mfma_f32_16x16x32_bf16 v[8:11], v[128:131], v[168:171], v[8:11]
	v_mfma_f32_16x16x32_bf16 v[60:63], v[124:127], v[140:143], v[60:63]
	v_mfma_f32_16x16x32_bf16 v[56:59], v[132:135], v[140:143], v[56:59]
	v_mfma_f32_16x16x32_bf16 v[44:47], v[124:127], v[156:159], v[44:47]
	v_mfma_f32_16x16x32_bf16 v[40:43], v[132:135], v[156:159], v[40:43]
	v_mfma_f32_16x16x32_bf16 v[28:31], v[124:127], v[164:167], v[28:31]
	v_mfma_f32_16x16x32_bf16 v[24:27], v[132:135], v[164:167], v[24:27]
	s_waitcnt lgkmcnt(0)
	v_mfma_f32_16x16x32_bf16 v[12:15], v[124:127], v[172:175], v[12:15]
	v_mfma_f32_16x16x32_bf16 v[8:11], v[132:135], v[172:175], v[8:11]
	s_barrier
	s_add_u32 s48, s60, 0x164000
	s_addc_u32 s49, s61, 0
	s_mov_b32 m0, s63
	s_nop 0
	global_load_lds_dwordx4 v188, s[48:49]
	s_add_u32 s48, s60, 0x166000
	s_addc_u32 s49, s61, 0
	s_mov_b32 m0, s64
	s_nop 0
	global_load_lds_dwordx4 v188, s[48:49]
	s_waitcnt vmcnt(10)
	s_barrier
	v_mfma_f32_16x16x32_bf16 v[52:55], v[176:179], v[136:139], v[52:55]
	v_mfma_f32_16x16x32_bf16 v[48:51], v[184:187], v[136:139], v[48:51]
	v_mfma_f32_16x16x32_bf16 v[36:39], v[176:179], v[152:155], v[36:39]
	v_mfma_f32_16x16x32_bf16 v[32:35], v[184:187], v[152:155], v[32:35]
	v_mfma_f32_16x16x32_bf16 v[20:23], v[176:179], v[160:163], v[20:23]
	v_mfma_f32_16x16x32_bf16 v[16:19], v[184:187], v[160:163], v[16:19]
	v_mfma_f32_16x16x32_bf16 v[4:7], v[176:179], v[168:171], v[4:7]
	v_mfma_f32_16x16x32_bf16 v[0:3], v[184:187], v[168:171], v[0:3]
	v_mfma_f32_16x16x32_bf16 v[52:55], v[180:183], v[140:143], v[52:55]
	v_mfma_f32_16x16x32_bf16 v[48:51], v[200:203], v[140:143], v[48:51]
	v_mfma_f32_16x16x32_bf16 v[36:39], v[180:183], v[156:159], v[36:39]
	v_mfma_f32_16x16x32_bf16 v[32:35], v[200:203], v[156:159], v[32:35]
	v_mfma_f32_16x16x32_bf16 v[20:23], v[180:183], v[164:167], v[20:23]
	v_mfma_f32_16x16x32_bf16 v[16:19], v[200:203], v[164:167], v[16:19]
	v_mfma_f32_16x16x32_bf16 v[4:7], v[180:183], v[172:175], v[4:7]
	v_mfma_f32_16x16x32_bf16 v[0:3], v[200:203], v[172:175], v[0:3]
	s_add_i32 s69, s69, 2
	s_add_u32 s0, s0, 0x8000
	s_addc_u32 s1, s1, 0
	s_cmpk_gt_u32 s69, 0x55
	s_mov_b64 s[56:57], s[58:59]
	s_barrier
;     __device__ __forceinline__ void operator()(f32x4 (&acc)[2][2][4][2], const Unit& u, int wr, int wc, int fr, int fq, LAS unsigned char*) const {
;         const int b = u.pm >> 6;
;         const int col0 = u.pn * BM + wc * 32 + 8 * fq;
;         const size_t off0 = (size_t)(u.pm * BM + wr * 64 + fr) * D + col0;
;         f32x4 sc[2][2];
; #pragma unroll
;         for (int bj = 0; bj < 2; ++bj)
; #pragma unroll
;             for (int n = 0; n < 2; ++n) { f32x4 gt = *(const f32x4*)(gate + (size_t)b * MODW + col0 + bj * HALF + n * 4); sc[bj][n] = gt + 1.0f;
;                 if (cs) sc[bj][n] *= *(const f32x4*)(cs + col0 + bj * HALF + n * 4); }
;         if (IN_F32) {
; #pragma unroll
;             for (int ai = 0; ai < 2; ++ai) {
;                 f32x4 r[4][2][2];
; #pragma unroll
;                 for (int m = 0; m < 4; ++m)
; #pragma unroll
;                     for (int bj = 0; bj < 2; ++bj)
; #pragma unroll
;                         for (int n = 0; n < 2; ++n) r[m][bj][n] = *(const f32x4*)((const float*)in + off0 + (size_t)(ai * HALF + m * 16) * D + bj * HALF + n * 4);
; #pragma unroll
;                 for (int m = 0; m < 4; ++m)
; #pragma unroll
;                     for (int bj = 0; bj < 2; ++bj) { const f32x4 r0 = r[m][bj][0] + sc[bj][0] * acc[ai][bj][m][0], r1 = r[m][bj][1] + sc[bj][1] * acc[ai][bj][m][1];
;                         u32x4 w; w.x = cvt_pk_bf16(r0[0], r0[1]); w.y = cvt_pk_bf16(r0[2], r0[3]); w.z = cvt_pk_bf16(r1[0], r1[1]); w.w = cvt_pk_bf16(r1[2], r1[3]);
;                         *(u32x4*)(out + off0 + (size_t)(ai * HALF + m * 16) * D + bj * HALF) = w; }
;                 asm volatile("" ::: "memory");
;             }
;         } else {
;             u32x4 xb[2][4][2];
; #pragma unroll
;             for (int ai = 0; ai < 2; ++ai)
; #pragma unroll
;                 for (int m = 0; m < 4; ++m)
; #pragma unroll
;                     for (int bj = 0; bj < 2; ++bj) xb[ai][m][bj] = *(const u32x4*)((const bf16_t*)in + off0 + (size_t)(ai * HALF + m * 16) * D + bj * HALF);
; #pragma unroll
;             for (int ai = 0; ai < 2; ++ai)
; #pragma unroll
;                 for (int m = 0; m < 4; ++m)
; #pragma unroll
;                     for (int bj = 0; bj < 2; ++bj) { const u32x4 x = xb[ai][m][bj];
	s_cbranch_scc0 .LBB0_860
	s_ashr_i32 s0, s50, 6
	s_mul_hi_i32 s1, s0, 0xc000
	s_mul_i32 s0, s0, 0xc000
	v_lshl_or_b32 v128, s51, 8, v234
	s_add_u32 s0, s39, s0
	v_ashrrev_i32_e32 v129, 31, v128
	s_addc_u32 s1, s40, s1
	v_lshl_add_u64 v[130:131], v[128:129], 2, s[0:1]
	global_load_dwordx4 v[120:123], v[130:131], off offset:16
	global_load_dwordx4 v[124:127], v[130:131], off
	s_mov_b32 s51, s67
	s_mov_b64 s[58:59], s[8:9]
	s_mov_b64 s[56:57], s[6:7]
	s_waitcnt vmcnt(1)
	v_pk_add_f32 v[210:211], v[122:123], 1.0 op_sel_hi:[1,0]
	s_waitcnt vmcnt(0)
	v_pk_add_f32 v[214:215], v[126:127], 1.0 op_sel_hi:[1,0]
	v_pk_add_f32 v[212:213], v[124:125], 1.0 op_sel_hi:[1,0]
	v_pk_add_f32 v[208:209], v[120:121], 1.0 op_sel_hi:[1,0]
	global_load_dwordx4 v[120:123], v[130:131], off offset:528
	global_load_dwordx4 v[124:127], v[130:131], off offset:512
	s_waitcnt vmcnt(1)
	v_pk_add_f32 v[200:201], v[120:121], 1.0 op_sel_hi:[1,0]
	v_lshl_add_u32 v120, s50, 8, v233
	v_ashrrev_i32_e32 v121, 31, v120
	v_lshlrev_b64 v[120:121], 11, v[120:121]
	v_lshl_add_u64 v[120:121], v[120:121], 0, v[128:129]
	v_lshlrev_b64 v[216:217], 1, v[120:121]
	v_lshl_add_u64 v[120:121], s[52:53], 0, v[216:217]
	global_load_dwordx4 v[238:241], v[120:121], off
	global_load_dwordx4 v[184:187], v[120:121], off offset:256
	v_pk_add_f32 v[202:203], v[122:123], 1.0 op_sel_hi:[1,0]
	v_add_co_u32_e32 v122, vcc, s45, v120
	s_waitcnt vmcnt(2)
	v_pk_add_f32 v[206:207], v[126:127], 1.0 op_sel_hi:[1,0]
	v_addc_co_u32_e32 v123, vcc, 0, v121, vcc
	global_load_dwordx4 v[180:183], v[122:123], off
	global_load_dwordx4 v[176:179], v[122:123], off offset:256
	v_add_co_u32_e32 v122, vcc, s36, v120
	v_pk_add_f32 v[204:205], v[124:125], 1.0 op_sel_hi:[1,0]
	s_nop 0
	v_addc_co_u32_e32 v123, vcc, 0, v121, vcc
	global_load_dwordx4 v[172:175], v[122:123], off
	global_load_dwordx4 v[168:171], v[122:123], off offset:256
	v_add_co_u32_e32 v122, vcc, s23, v120
	s_mov_b32 s50, s68
	s_nop 0
	v_addc_co_u32_e32 v123, vcc, 0, v121, vcc
	global_load_dwordx4 v[164:167], v[122:123], off
	global_load_dwordx4 v[160:163], v[122:123], off offset:256
	v_add_co_u32_e32 v122, vcc, s93, v120
	s_waitcnt vmcnt(7)
	v_lshlrev_b32_e32 v230, 16, v238
	v_addc_co_u32_e32 v123, vcc, 0, v121, vcc
	global_load_dwordx4 v[156:159], v[122:123], off
	global_load_dwordx4 v[152:155], v[122:123], off offset:256
	v_add_co_u32_e32 v122, vcc, s33, v120
	v_and_b32_e32 v231, 0xffff0000, v238
	s_nop 0
	v_addc_co_u32_e32 v123, vcc, 0, v121, vcc
	global_load_dwordx4 v[140:143], v[122:123], off
	global_load_dwordx4 v[136:139], v[122:123], off offset:256
	v_add_co_u32_e32 v122, vcc, s18, v120
	v_lshlrev_b32_e32 v242, 16, v240
	s_nop 0
	v_addc_co_u32_e32 v123, vcc, 0, v121, vcc
	global_load_dwordx4 v[132:135], v[122:123], off
	global_load_dwordx4 v[128:131], v[122:123], off offset:256
	v_add_co_u32_e32 v120, vcc, s19, v120
	v_and_b32_e32 v243, 0xffff0000, v240
	s_nop 0
	v_addc_co_u32_e32 v121, vcc, 0, v121, vcc
	global_load_dwordx4 v[124:127], v[120:121], off
	s_nop 0
	global_load_dwordx4 v[120:123], v[120:121], off offset:256
	v_lshlrev_b32_e32 v238, 16, v239
	v_and_b32_e32 v239, 0xffff0000, v239
	v_lshlrev_b32_e32 v240, 16, v241
	v_and_b32_e32 v241, 0xffff0000, v241
	v_pk_fma_f32 v[148:149], v[148:149], v[212:213], v[230:231]
	v_pk_fma_f32 v[144:145], v[144:145], v[208:209], v[242:243]
	v_pk_fma_f32 v[150:151], v[150:151], v[214:215], v[238:239]
	v_pk_fma_f32 v[230:231], v[146:147], v[210:211], v[240:241]
	v_cvt_pk_bf16_f32 v146, v148, v149
	v_cvt_pk_bf16_f32 v147, v150, v151
	v_cvt_pk_bf16_f32 v148, v144, v145
	v_lshl_add_u64 v[144:145], s[54:55], 0, v[216:217]
	v_cvt_pk_bf16_f32 v149, v230, v231
	global_store_dwordx4 v[144:145], v[146:149], off
	s_waitcnt vmcnt(15)
	v_lshlrev_b32_e32 v150, 16, v186
	v_and_b32_e32 v151, 0xffff0000, v186
	v_lshlrev_b32_e32 v146, 16, v184
	v_and_b32_e32 v147, 0xffff0000, v184
	v_lshlrev_b32_e32 v148, 16, v185
	v_and_b32_e32 v149, 0xffff0000, v185
	v_lshlrev_b32_e32 v184, 16, v187
	v_and_b32_e32 v185, 0xffff0000, v187
	v_pk_fma_f32 v[118:119], v[118:119], v[206:207], v[148:149]
	v_pk_fma_f32 v[116:117], v[116:117], v[204:205], v[146:147]
	v_pk_fma_f32 v[146:147], v[114:115], v[202:203], v[184:185]
	v_pk_fma_f32 v[114:115], v[112:113], v[200:201], v[150:151]
	v_cvt_pk_bf16_f32 v112, v116, v117
	v_cvt_pk_bf16_f32 v113, v118, v119
	s_waitcnt vmcnt(14)
	v_lshlrev_b32_e32 v116, 16, v182
	v_cvt_pk_bf16_f32 v114, v114, v115
	v_cvt_pk_bf16_f32 v115, v146, v147
	global_store_dwordx4 v[144:145], v[112:115], off offset:256
	v_and_b32_e32 v117, 0xffff0000, v182
	v_lshlrev_b32_e32 v118, 16, v183
	v_lshlrev_b32_e32 v112, 16, v180
	v_and_b32_e32 v113, 0xffff0000, v180
	v_and_b32_e32 v119, 0xffff0000, v183
	v_pk_fma_f32 v[108:109], v[108:109], v[212:213], v[112:113]
	v_lshlrev_b32_e32 v114, 16, v181
	v_and_b32_e32 v115, 0xffff0000, v181
	v_pk_fma_f32 v[112:113], v[106:107], v[210:211], v[118:119]
	v_pk_fma_f32 v[106:107], v[104:105], v[208:209], v[116:117]
	v_cvt_pk_bf16_f32 v104, v108, v109
	v_add_co_u32_e32 v108, vcc, s45, v144
	v_pk_fma_f32 v[110:111], v[110:111], v[214:215], v[114:115]
	s_nop 0
	v_addc_co_u32_e32 v109, vcc, 0, v145, vcc
	v_cvt_pk_bf16_f32 v105, v110, v111
	v_cvt_pk_bf16_f32 v106, v106, v107
	v_cvt_pk_bf16_f32 v107, v112, v113
	global_store_dwordx4 v[108:109], v[104:107], off
	s_waitcnt vmcnt(15)
	v_lshlrev_b32_e32 v110, 16, v178
	v_and_b32_e32 v111, 0xffff0000, v178
	v_lshlrev_b32_e32 v104, 16, v176
	v_and_b32_e32 v105, 0xffff0000, v176
	v_lshlrev_b32_e32 v106, 16, v177
	v_and_b32_e32 v107, 0xffff0000, v177
	v_lshlrev_b32_e32 v112, 16, v179
	v_and_b32_e32 v113, 0xffff0000, v179
	v_pk_fma_f32 v[102:103], v[102:103], v[206:207], v[106:107]
	v_pk_fma_f32 v[100:101], v[100:101], v[204:205], v[104:105]
	v_pk_fma_f32 v[104:105], v[98:99], v[202:203], v[112:113]
	v_pk_fma_f32 v[98:99], v[96:97], v[200:201], v[110:111]
	v_cvt_pk_bf16_f32 v96, v100, v101
	v_cvt_pk_bf16_f32 v97, v102, v103
	s_waitcnt vmcnt(14)
; __device__ __forceinline__ unsigned cvt_pk_bf16(float lo, float hi) { unsigned r; asm volatile("v_cvt_pk_bf16_f32 %0, %1, %2" : "=v"(r) : "v"(lo), "v"(hi)); return r; }
;     __device__ __forceinline__ void operator()(f32x4 (&acc)[2][2][4][2], const Unit& u, int wr, int wc, int fr, int fq, LAS unsigned char*) const {
;     ...
;                     for (int bj = 0; bj < 2; ++bj) { const u32x4 x = xb[ai][m][bj];
;                         f32x4 r0 = (f32x4){__uint_as_float(x.x << 16), __uint_as_float(x.x & 0xffff0000u), __uint_as_float(x.y << 16), __uint_as_float(x.y & 0xffff0000u)};
;                         f32x4 r1 = (f32x4){__uint_as_float(x.z << 16), __uint_as_float(x.z & 0xffff0000u), __uint_as_float(x.w << 16), __uint_as_float(x.w & 0xffff0000u)};
;                         r0 += sc[bj][0] * acc[ai][bj][m][0]; r1 += sc[bj][1] * acc[ai][bj][m][1];
;                         u32x4 w; w.x = cvt_pk_bf16(r0[0], r0[1]); w.y = cvt_pk_bf16(r0[2], r0[3]); w.z = cvt_pk_bf16(r1[0], r1[1]); w.w = cvt_pk_bf16(r1[2], r1[3]);
;                         *(u32x4*)(out + off0 + (size_t)(ai * HALF + m * 16) * D + bj * HALF) = w; }
	v_lshlrev_b32_e32 v100, 16, v174
	v_cvt_pk_bf16_f32 v98, v98, v99
	v_cvt_pk_bf16_f32 v99, v104, v105
	global_store_dwordx4 v[108:109], v[96:99], off offset:256
	v_and_b32_e32 v101, 0xffff0000, v174
	v_lshlrev_b32_e32 v102, 16, v175
	v_lshlrev_b32_e32 v96, 16, v172
	v_and_b32_e32 v97, 0xffff0000, v172
	v_and_b32_e32 v103, 0xffff0000, v175
	v_pk_fma_f32 v[92:93], v[92:93], v[212:213], v[96:97]
	v_lshlrev_b32_e32 v98, 16, v173
	v_and_b32_e32 v99, 0xffff0000, v173
	v_pk_fma_f32 v[96:97], v[90:91], v[210:211], v[102:103]
	v_pk_fma_f32 v[90:91], v[88:89], v[208:209], v[100:101]
	v_cvt_pk_bf16_f32 v88, v92, v93
	v_add_co_u32_e32 v92, vcc, s36, v144
	v_pk_fma_f32 v[94:95], v[94:95], v[214:215], v[98:99]
	s_nop 0
	v_addc_co_u32_e32 v93, vcc, 0, v145, vcc
	v_cvt_pk_bf16_f32 v89, v94, v95
	v_cvt_pk_bf16_f32 v90, v90, v91
	v_cvt_pk_bf16_f32 v91, v96, v97
	global_store_dwordx4 v[92:93], v[88:91], off
	s_waitcnt vmcnt(15)
	v_lshlrev_b32_e32 v94, 16, v170
	v_and_b32_e32 v95, 0xffff0000, v170
	v_lshlrev_b32_e32 v88, 16, v168
	v_and_b32_e32 v89, 0xffff0000, v168
	v_lshlrev_b32_e32 v90, 16, v169
	v_and_b32_e32 v91, 0xffff0000, v169
	v_lshlrev_b32_e32 v96, 16, v171
	v_and_b32_e32 v97, 0xffff0000, v171
	v_pk_fma_f32 v[86:87], v[86:87], v[206:207], v[90:91]
	v_pk_fma_f32 v[84:85], v[84:85], v[204:205], v[88:89]
	v_pk_fma_f32 v[88:89], v[82:83], v[202:203], v[96:97]
	v_pk_fma_f32 v[82:83], v[80:81], v[200:201], v[94:95]
	v_cvt_pk_bf16_f32 v80, v84, v85
	v_cvt_pk_bf16_f32 v81, v86, v87
	s_waitcnt vmcnt(14)
	v_lshlrev_b32_e32 v84, 16, v166
	v_cvt_pk_bf16_f32 v82, v82, v83
	v_cvt_pk_bf16_f32 v83, v88, v89
	global_store_dwordx4 v[92:93], v[80:83], off offset:256
	v_and_b32_e32 v85, 0xffff0000, v166
	v_lshlrev_b32_e32 v86, 16, v167
	v_lshlrev_b32_e32 v80, 16, v164
	v_and_b32_e32 v81, 0xffff0000, v164
	v_and_b32_e32 v87, 0xffff0000, v167
	v_pk_fma_f32 v[76:77], v[76:77], v[212:213], v[80:81]
	v_lshlrev_b32_e32 v82, 16, v165
	v_and_b32_e32 v83, 0xffff0000, v165
	v_pk_fma_f32 v[80:81], v[74:75], v[210:211], v[86:87]
	v_pk_fma_f32 v[74:75], v[72:73], v[208:209], v[84:85]
	v_cvt_pk_bf16_f32 v72, v76, v77
	v_add_co_u32_e32 v76, vcc, s23, v144
	v_pk_fma_f32 v[78:79], v[78:79], v[214:215], v[82:83]
	s_nop 0
	v_addc_co_u32_e32 v77, vcc, 0, v145, vcc
	v_cvt_pk_bf16_f32 v73, v78, v79
	v_cvt_pk_bf16_f32 v74, v74, v75
	v_cvt_pk_bf16_f32 v75, v80, v81
	global_store_dwordx4 v[76:77], v[72:75], off
	s_waitcnt vmcnt(15)
	v_lshlrev_b32_e32 v78, 16, v162
	v_and_b32_e32 v79, 0xffff0000, v162
	v_lshlrev_b32_e32 v72, 16, v160
	v_and_b32_e32 v73, 0xffff0000, v160
	v_lshlrev_b32_e32 v74, 16, v161
	v_and_b32_e32 v75, 0xffff0000, v161
	v_lshlrev_b32_e32 v80, 16, v163
	v_and_b32_e32 v81, 0xffff0000, v163
	v_pk_fma_f32 v[70:71], v[70:71], v[206:207], v[74:75]
	v_pk_fma_f32 v[68:69], v[68:69], v[204:205], v[72:73]
	v_pk_fma_f32 v[72:73], v[66:67], v[202:203], v[80:81]
	v_pk_fma_f32 v[66:67], v[64:65], v[200:201], v[78:79]
	v_cvt_pk_bf16_f32 v64, v68, v69
	v_cvt_pk_bf16_f32 v65, v70, v71
	s_waitcnt vmcnt(14)
	v_lshlrev_b32_e32 v68, 16, v158
	v_cvt_pk_bf16_f32 v66, v66, v67
	v_cvt_pk_bf16_f32 v67, v72, v73
	global_store_dwordx4 v[76:77], v[64:67], off offset:256
	v_and_b32_e32 v69, 0xffff0000, v158
	v_lshlrev_b32_e32 v70, 16, v159
	v_lshlrev_b32_e32 v64, 16, v156
	v_and_b32_e32 v65, 0xffff0000, v156
	v_and_b32_e32 v71, 0xffff0000, v159
	v_pk_fma_f32 v[60:61], v[60:61], v[212:213], v[64:65]
	v_lshlrev_b32_e32 v66, 16, v157
	v_and_b32_e32 v67, 0xffff0000, v157
	v_pk_fma_f32 v[64:65], v[58:59], v[210:211], v[70:71]
	v_pk_fma_f32 v[58:59], v[56:57], v[208:209], v[68:69]
	v_cvt_pk_bf16_f32 v56, v60, v61
	v_add_co_u32_e32 v60, vcc, s93, v144
	v_pk_fma_f32 v[62:63], v[62:63], v[214:215], v[66:67]
	s_nop 0
	v_addc_co_u32_e32 v61, vcc, 0, v145, vcc
	v_cvt_pk_bf16_f32 v57, v62, v63
	v_cvt_pk_bf16_f32 v58, v58, v59
	v_cvt_pk_bf16_f32 v59, v64, v65
	global_store_dwordx4 v[60:61], v[56:59], off
	s_waitcnt vmcnt(15)
	v_lshlrev_b32_e32 v62, 16, v154
	v_and_b32_e32 v63, 0xffff0000, v154
	v_lshlrev_b32_e32 v56, 16, v152
	v_and_b32_e32 v57, 0xffff0000, v152
	v_lshlrev_b32_e32 v58, 16, v153
	v_and_b32_e32 v59, 0xffff0000, v153
	v_lshlrev_b32_e32 v64, 16, v155
	v_and_b32_e32 v65, 0xffff0000, v155
	v_pk_fma_f32 v[54:55], v[54:55], v[206:207], v[58:59]
	v_pk_fma_f32 v[52:53], v[52:53], v[204:205], v[56:57]
	v_pk_fma_f32 v[56:57], v[50:51], v[202:203], v[64:65]
	v_pk_fma_f32 v[50:51], v[48:49], v[200:201], v[62:63]
	v_cvt_pk_bf16_f32 v48, v52, v53
	v_cvt_pk_bf16_f32 v49, v54, v55
	s_waitcnt vmcnt(14)
; __device__ __forceinline__ unsigned cvt_pk_bf16(float lo, float hi) { unsigned r; asm volatile("v_cvt_pk_bf16_f32 %0, %1, %2" : "=v"(r) : "v"(lo), "v"(hi)); return r; }
; #define PG8_WAIT_V(n) asm volatile("s_waitcnt vmcnt(" #n ")" ::: "memory")
; #define PG8_BAR __builtin_amdgcn_s_barrier()
; template <class Epi>
; __device__ __forceinline__ void gemm_phase(LAS unsigned char* lds, const Gemm g, const StaticOrder& S, const Epi& E) {
;     ...
;         if (!has_next) break;
; #pragma unroll
;         for (int a = 0; a < 2; ++a)
; #pragma unroll
;             for (int b = 0; b < 2; ++b)
; #pragma unroll
;                 for (int m = 0; m < 4; ++m)
; #pragma unroll
;                     for (int n = 0; n < 2; ++n) acc[a][b][m][n] = (f32x4){0.f, 0.f, 0.f, 0.f};
;         cur = nxt; cA = nA; cB = nB; ++ui;
;     }
;     PG8_WAIT_V(0);
;     if (wr == 0) PG8_BAR;
;     PG8_BAR;
;     __device__ __forceinline__ void operator()(f32x4 (&acc)[2][2][4][2], const Unit& u, int wr, int wc, int fr, int fq, LAS unsigned char*) const {
;     ...
;                     for (int bj = 0; bj < 2; ++bj) { const u32x4 x = xb[ai][m][bj];
;                         f32x4 r0 = (f32x4){__uint_as_float(x.x << 16), __uint_as_float(x.x & 0xffff0000u), __uint_as_float(x.y << 16), __uint_as_float(x.y & 0xffff0000u)};
;                         f32x4 r1 = (f32x4){__uint_as_float(x.z << 16), __uint_as_float(x.z & 0xffff0000u), __uint_as_float(x.w << 16), __uint_as_float(x.w & 0xffff0000u)};
;                         r0 += sc[bj][0] * acc[ai][bj][m][0]; r1 += sc[bj][1] * acc[ai][bj][m][1];
;                         u32x4 w; w.x = cvt_pk_bf16(r0[0], r0[1]); w.y = cvt_pk_bf16(r0[2], r0[3]); w.z = cvt_pk_bf16(r1[0], r1[1]); w.w = cvt_pk_bf16(r1[2], r1[3]);
;                         *(u32x4*)(out + off0 + (size_t)(ai * HALF + m * 16) * D + bj * HALF) = w; }
	v_lshlrev_b32_e32 v52, 16, v142
	v_cvt_pk_bf16_f32 v50, v50, v51
	v_cvt_pk_bf16_f32 v51, v56, v57
	global_store_dwordx4 v[60:61], v[48:51], off offset:256
	v_and_b32_e32 v53, 0xffff0000, v142
	v_lshlrev_b32_e32 v54, 16, v143
	v_lshlrev_b32_e32 v48, 16, v140
	v_and_b32_e32 v49, 0xffff0000, v140
	v_and_b32_e32 v55, 0xffff0000, v143
	v_pk_fma_f32 v[44:45], v[44:45], v[212:213], v[48:49]
	v_lshlrev_b32_e32 v50, 16, v141
	v_and_b32_e32 v51, 0xffff0000, v141
	v_pk_fma_f32 v[48:49], v[42:43], v[210:211], v[54:55]
	v_pk_fma_f32 v[42:43], v[40:41], v[208:209], v[52:53]
	v_cvt_pk_bf16_f32 v40, v44, v45
	v_add_co_u32_e32 v44, vcc, s33, v144
	v_pk_fma_f32 v[46:47], v[46:47], v[214:215], v[50:51]
	s_nop 0
	v_addc_co_u32_e32 v45, vcc, 0, v145, vcc
	v_cvt_pk_bf16_f32 v41, v46, v47
	v_cvt_pk_bf16_f32 v42, v42, v43
	v_cvt_pk_bf16_f32 v43, v48, v49
	global_store_dwordx4 v[44:45], v[40:43], off
	s_waitcnt vmcnt(15)
	v_lshlrev_b32_e32 v46, 16, v138
	v_and_b32_e32 v47, 0xffff0000, v138
	v_lshlrev_b32_e32 v40, 16, v136
	v_and_b32_e32 v41, 0xffff0000, v136
	v_lshlrev_b32_e32 v42, 16, v137
	v_and_b32_e32 v43, 0xffff0000, v137
	v_lshlrev_b32_e32 v48, 16, v139
	v_and_b32_e32 v49, 0xffff0000, v139
	v_pk_fma_f32 v[38:39], v[38:39], v[206:207], v[42:43]
	v_pk_fma_f32 v[36:37], v[36:37], v[204:205], v[40:41]
	v_pk_fma_f32 v[40:41], v[34:35], v[202:203], v[48:49]
	v_pk_fma_f32 v[34:35], v[32:33], v[200:201], v[46:47]
	v_cvt_pk_bf16_f32 v32, v36, v37
	v_cvt_pk_bf16_f32 v33, v38, v39
	s_waitcnt vmcnt(14)
	v_lshlrev_b32_e32 v36, 16, v134
	v_cvt_pk_bf16_f32 v34, v34, v35
	v_cvt_pk_bf16_f32 v35, v40, v41
	global_store_dwordx4 v[44:45], v[32:35], off offset:256
	v_and_b32_e32 v37, 0xffff0000, v134
	v_lshlrev_b32_e32 v38, 16, v135
	v_lshlrev_b32_e32 v32, 16, v132
	v_and_b32_e32 v33, 0xffff0000, v132
	v_and_b32_e32 v39, 0xffff0000, v135
	v_pk_fma_f32 v[28:29], v[28:29], v[212:213], v[32:33]
	v_lshlrev_b32_e32 v34, 16, v133
	v_and_b32_e32 v35, 0xffff0000, v133
	v_pk_fma_f32 v[32:33], v[26:27], v[210:211], v[38:39]
	v_pk_fma_f32 v[26:27], v[24:25], v[208:209], v[36:37]
	v_cvt_pk_bf16_f32 v24, v28, v29
	v_add_co_u32_e32 v28, vcc, s18, v144
	v_pk_fma_f32 v[30:31], v[30:31], v[214:215], v[34:35]
	s_nop 0
	v_addc_co_u32_e32 v29, vcc, 0, v145, vcc
	v_cvt_pk_bf16_f32 v25, v30, v31
	v_cvt_pk_bf16_f32 v26, v26, v27
	v_cvt_pk_bf16_f32 v27, v32, v33
	global_store_dwordx4 v[28:29], v[24:27], off
	s_waitcnt vmcnt(15)
	v_lshlrev_b32_e32 v30, 16, v130
	v_and_b32_e32 v31, 0xffff0000, v130
	v_lshlrev_b32_e32 v24, 16, v128
	v_and_b32_e32 v25, 0xffff0000, v128
	v_lshlrev_b32_e32 v26, 16, v129
	v_and_b32_e32 v27, 0xffff0000, v129
	v_lshlrev_b32_e32 v32, 16, v131
	v_and_b32_e32 v33, 0xffff0000, v131
	v_pk_fma_f32 v[22:23], v[22:23], v[206:207], v[26:27]
	v_pk_fma_f32 v[20:21], v[20:21], v[204:205], v[24:25]
	v_pk_fma_f32 v[24:25], v[18:19], v[202:203], v[32:33]
	v_pk_fma_f32 v[18:19], v[16:17], v[200:201], v[30:31]
	v_cvt_pk_bf16_f32 v16, v20, v21
	v_cvt_pk_bf16_f32 v17, v22, v23
	s_waitcnt vmcnt(14)
	v_lshlrev_b32_e32 v20, 16, v126
	v_cvt_pk_bf16_f32 v18, v18, v19
	v_cvt_pk_bf16_f32 v19, v24, v25
	global_store_dwordx4 v[28:29], v[16:19], off offset:256
	v_and_b32_e32 v21, 0xffff0000, v126
	v_lshlrev_b32_e32 v22, 16, v127
	v_lshlrev_b32_e32 v16, 16, v124
	v_and_b32_e32 v17, 0xffff0000, v124
	v_and_b32_e32 v23, 0xffff0000, v127
	v_pk_fma_f32 v[12:13], v[12:13], v[212:213], v[16:17]
	v_lshlrev_b32_e32 v18, 16, v125
	v_and_b32_e32 v19, 0xffff0000, v125
	v_pk_fma_f32 v[16:17], v[10:11], v[210:211], v[22:23]
	v_pk_fma_f32 v[10:11], v[8:9], v[208:209], v[20:21]
	v_cvt_pk_bf16_f32 v8, v12, v13
	v_add_co_u32_e32 v12, vcc, s19, v144
	v_pk_fma_f32 v[14:15], v[14:15], v[214:215], v[18:19]
	s_nop 0
	v_addc_co_u32_e32 v13, vcc, 0, v145, vcc
	v_cvt_pk_bf16_f32 v9, v14, v15
	v_cvt_pk_bf16_f32 v10, v10, v11
	v_cvt_pk_bf16_f32 v11, v16, v17
	global_store_dwordx4 v[12:13], v[8:11], off
	s_waitcnt vmcnt(15)
	v_lshlrev_b32_e32 v14, 16, v122
	v_and_b32_e32 v15, 0xffff0000, v122
	v_lshlrev_b32_e32 v8, 16, v120
	v_and_b32_e32 v9, 0xffff0000, v120
	v_lshlrev_b32_e32 v16, 16, v123
	v_and_b32_e32 v17, 0xffff0000, v123
	v_lshlrev_b32_e32 v10, 16, v121
	v_and_b32_e32 v11, 0xffff0000, v121
	v_pk_fma_f32 v[4:5], v[4:5], v[204:205], v[8:9]
	v_pk_fma_f32 v[8:9], v[2:3], v[202:203], v[16:17]
	v_pk_fma_f32 v[2:3], v[0:1], v[200:201], v[14:15]
	s_and_b64 vcc, exec, s[4:5]
	v_pk_fma_f32 v[6:7], v[6:7], v[206:207], v[10:11]
	v_cvt_pk_bf16_f32 v0, v4, v5
	s_nop 0
	v_cvt_pk_bf16_f32 v1, v6, v7
	v_cvt_pk_bf16_f32 v2, v2, v3
	v_cvt_pk_bf16_f32 v3, v8, v9
	global_store_dwordx4 v[12:13], v[0:3], off offset:256
	s_cbranch_vccz .LBB0_849
	s_waitcnt vmcnt(0)
	s_cmpk_gt_u32 s21, 0xff
	v_readlane_b32 s38, v255, 44
	s_cbranch_scc1 .LBB0_864
	s_barrier
